# load segments: closing vmcnt and lgkmcnt waits merged into one s_waitcnt
# baseline (speedup 1.0000x reference)
.LBB0_251:
	s_ashr_i32 s13, s12, 31
	s_lshl_b64 s[14:15], s[12:13], 19
	s_add_u32 s14, s29, s14
	s_addc_u32 s15, s38, s15
	s_and_b64 s[16:17], s[4:5], exec
	s_cselect_b32 s13, s15, s23
	s_cselect_b32 s19, s14, s22
	s_ashr_i32 s11, s10, 31
	s_lshl_b64 s[16:17], s[10:11], 19
	s_add_u32 s16, s39, s16
	s_addc_u32 s17, s40, s17
	s_and_b64 s[24:25], s[4:5], exec
	s_cselect_b32 s11, s17, s21
	s_cselect_b32 s61, s16, s20
	s_add_u32 s62, s20, 0x100
	s_addc_u32 s63, s21, 0
	s_add_u32 s20, s22, 0x40080
	s_addc_u32 s21, s23, 0
	s_mov_b32 s68, -2
	s_add_u32 s22, s20, 0xfffc0080
	s_addc_u32 s23, s21, -1
	s_add_i32 s64, 0, 0x10000
	s_cmp_eq_u32 s68, 12
	s_cselect_b32 s25, s13, s23
	s_cselect_b32 s24, s19, s22
	s_cselect_b32 s23, s11, s63
	s_cselect_b32 s22, s61, s62
	s_lshl_b32 s74, s18, 8
	v_add_u32_e32 v178, s74, v168
	v_ashrrev_i32_e32 v179, 31, v178
	v_lshlrev_b64 v[178:179], 6, v[178:179]
	v_lshl_add_u64 v[178:179], s[70:71], 0, v[178:179]
	s_and_saveexec_b64 s[78:79], s[2:3]
	global_load_dwordx4 v[238:241], v[178:179], off
	global_load_dwordx4 v[242:245], v[178:179], off offset:16
	global_load_dwordx4 v[246:249], v[178:179], off offset:32
	global_load_dwordx4 v[250:253], v[178:179], off offset:48
	s_mov_b64 exec, s[78:79]
	s_add_i32 s69, 0, 0x14000
	v_add_u32_e32 v140, s64, v167
	v_add_u32_e32 v164, s69, v167
	ds_read_b128 v[48:51], v140
	ds_read_b128 v[56:59], v140 offset:1024
	ds_read_b128 v[136:139], v140 offset:2048
	ds_read_b128 v[140:143], v140 offset:3072
	ds_read_b128 v[156:159], v164
	ds_read_b128 v[160:163], v164 offset:1024
	ds_read_b128 v[182:185], v164 offset:2048
	ds_read_b128 v[186:189], v164 offset:3072
	s_add_i32 m0, s49, 0xc000
	ds_read_b128 v[190:193], v172
	ds_read_b128 v[194:197], v172 offset:1024
	ds_read_b128 v[198:201], v172 offset:2048
	ds_read_b128 v[202:205], v172 offset:3072
	ds_read_b128 v[206:209], v172 offset:4096
	ds_read_b128 v[210:213], v172 offset:5120
	ds_read_b128 v[228:231], v172 offset:6144
	ds_read_b128 v[232:235], v172 offset:7168
	global_load_lds_dwordx4 v154, s[20:21]
	s_add_i32 m0, s49, 0xe000
	s_nop 0
	global_load_lds_dwordx4 v152, s[20:21]
	s_waitcnt vmcnt(12) lgkmcnt(0)
	s_barrier
	s_setprio 1
	v_mfma_f32_16x16x32_bf16 v[132:135], v[48:51], v[190:193], 0
	v_mfma_f32_16x16x32_bf16 v[124:127], v[136:139], v[190:193], 0
	v_mfma_f32_16x16x32_bf16 v[116:119], v[48:51], v[198:201], 0
	v_mfma_f32_16x16x32_bf16 v[112:115], v[136:139], v[198:201], 0
	v_mfma_f32_16x16x32_bf16 v[100:103], v[48:51], v[206:209], 0
	v_mfma_f32_16x16x32_bf16 v[96:99], v[136:139], v[206:209], 0
	v_mfma_f32_16x16x32_bf16 v[84:87], v[48:51], v[228:231], 0
	v_mfma_f32_16x16x32_bf16 v[80:83], v[136:139], v[228:231], 0
	v_mfma_f32_16x16x32_bf16 v[132:135], v[56:59], v[194:197], v[132:135]
	v_mfma_f32_16x16x32_bf16 v[124:127], v[140:143], v[194:197], v[124:127]
	v_mfma_f32_16x16x32_bf16 v[116:119], v[56:59], v[202:205], v[116:119]
	v_mfma_f32_16x16x32_bf16 v[112:115], v[140:143], v[202:205], v[112:115]
	v_mfma_f32_16x16x32_bf16 v[100:103], v[56:59], v[210:213], v[100:103]
	v_mfma_f32_16x16x32_bf16 v[96:99], v[140:143], v[210:213], v[96:99]
	v_mfma_f32_16x16x32_bf16 v[84:87], v[56:59], v[232:235], v[84:87]
	v_mfma_f32_16x16x32_bf16 v[80:83], v[140:143], v[232:235], v[80:83]
	v_mfma_f32_16x16x32_bf16 v[128:131], v[156:159], v[190:193], 0
	v_mfma_f32_16x16x32_bf16 v[120:123], v[182:185], v[190:193], 0
	v_mfma_f32_16x16x32_bf16 v[108:111], v[156:159], v[198:201], 0
	v_mfma_f32_16x16x32_bf16 v[104:107], v[182:185], v[198:201], 0
	v_mfma_f32_16x16x32_bf16 v[92:95], v[156:159], v[206:209], 0
	v_mfma_f32_16x16x32_bf16 v[88:91], v[182:185], v[206:209], 0
	v_mfma_f32_16x16x32_bf16 v[76:79], v[156:159], v[228:231], 0
	v_mfma_f32_16x16x32_bf16 v[72:75], v[182:185], v[228:231], 0
	v_mfma_f32_16x16x32_bf16 v[128:131], v[160:163], v[194:197], v[128:131]
	v_mfma_f32_16x16x32_bf16 v[120:123], v[186:189], v[194:197], v[120:123]
	v_mfma_f32_16x16x32_bf16 v[108:111], v[160:163], v[202:205], v[108:111]
	v_mfma_f32_16x16x32_bf16 v[104:107], v[186:189], v[202:205], v[104:107]
	s_setprio 2
	s_barrier
	v_mfma_f32_16x16x32_bf16 v[92:95], v[160:163], v[210:213], v[92:95]
	v_mfma_f32_16x16x32_bf16 v[88:91], v[186:189], v[210:213], v[88:91]
	v_mfma_f32_16x16x32_bf16 v[76:79], v[160:163], v[232:235], v[76:79]
	v_mfma_f32_16x16x32_bf16 v[72:75], v[186:189], v[232:235], v[72:75]
	s_setprio 0
	s_add_i32 s64, s64, s41
	s_add_u32 s94, s22, s34
	s_addc_u32 s95, s23, s35
	s_mov_b32 m0, s64
	ds_read_b128 v[190:193], v172 offset:16384
	ds_read_b128 v[194:197], v172 offset:17408
	ds_read_b128 v[198:201], v172 offset:18432
	ds_read_b128 v[202:205], v172 offset:19456
	ds_read_b128 v[206:209], v172 offset:20480
	ds_read_b128 v[210:213], v172 offset:21504
	ds_read_b128 v[228:231], v172 offset:22528
	ds_read_b128 v[232:235], v172 offset:23552
	global_load_lds_dwordx4 v148, s[22:23]
	s_add_i32 m0, s64, 0x2000
	s_add_u32 s64, s22, 0x40000
	s_addc_u32 s65, s23, 0
	s_add_i32 s69, s69, s41
	global_load_lds_dwordx4 v144, s[22:23]
	s_mov_b32 m0, s69
	s_nop 0
	global_load_lds_dwordx4 v148, s[64:65]
	s_add_i32 m0, s69, 0x2000
	s_nop 0
	global_load_lds_dwordx4 v144, s[64:65]
	s_add_u32 s98, s24, s34
	s_addc_u32 s99, s25, s35
	s_mov_b32 m0, s49
	s_nop 0
	global_load_lds_dwordx4 v150, s[24:25]
	s_mov_b32 m0, s50
	s_nop 0
	global_load_lds_dwordx4 v146, s[24:25]
	s_waitcnt vmcnt(8) lgkmcnt(0)
	s_barrier
	s_setprio 1
	v_mfma_f32_16x16x32_bf16 v[68:71], v[48:51], v[190:193], 0
	v_mfma_f32_16x16x32_bf16 v[64:67], v[136:139], v[190:193], 0
	v_mfma_f32_16x16x32_bf16 v[44:47], v[48:51], v[198:201], 0
	v_mfma_f32_16x16x32_bf16 v[40:43], v[136:139], v[198:201], 0
	v_mfma_f32_16x16x32_bf16 v[28:31], v[48:51], v[206:209], 0
	v_mfma_f32_16x16x32_bf16 v[24:27], v[136:139], v[206:209], 0
	v_mfma_f32_16x16x32_bf16 v[12:15], v[48:51], v[228:231], 0
	v_mfma_f32_16x16x32_bf16 v[8:11], v[136:139], v[228:231], 0
	v_mfma_f32_16x16x32_bf16 v[68:71], v[56:59], v[194:197], v[68:71]
	v_mfma_f32_16x16x32_bf16 v[64:67], v[140:143], v[194:197], v[64:67]
	v_mfma_f32_16x16x32_bf16 v[44:47], v[56:59], v[202:205], v[44:47]
	v_mfma_f32_16x16x32_bf16 v[40:43], v[140:143], v[202:205], v[40:43]
	v_mfma_f32_16x16x32_bf16 v[28:31], v[56:59], v[210:213], v[28:31]
	v_mfma_f32_16x16x32_bf16 v[24:27], v[140:143], v[210:213], v[24:27]
	v_mfma_f32_16x16x32_bf16 v[12:15], v[56:59], v[232:235], v[12:15]
	v_mfma_f32_16x16x32_bf16 v[8:11], v[140:143], v[232:235], v[8:11]
	v_mfma_f32_16x16x32_bf16 v[52:55], v[182:185], v[190:193], 0
	v_mfma_f32_16x16x32_bf16 v[36:39], v[156:159], v[198:201], 0
	v_mfma_f32_16x16x32_bf16 v[32:35], v[182:185], v[198:201], 0
	v_mfma_f32_16x16x32_bf16 v[20:23], v[156:159], v[206:209], 0
	v_mfma_f32_16x16x32_bf16 v[16:19], v[182:185], v[206:209], 0
	v_mfma_f32_16x16x32_bf16 v[4:7], v[156:159], v[228:231], 0
	v_mfma_f32_16x16x32_bf16 v[0:3], v[182:185], v[228:231], 0
	v_mfma_f32_16x16x32_bf16 v[48:51], v[156:159], v[190:193], 0
	v_mfma_f32_16x16x32_bf16 v[52:55], v[186:189], v[194:197], v[52:55]
	v_mfma_f32_16x16x32_bf16 v[36:39], v[160:163], v[202:205], v[36:39]
	v_mfma_f32_16x16x32_bf16 v[32:35], v[186:189], v[202:205], v[32:35]
	v_mfma_f32_16x16x32_bf16 v[20:23], v[160:163], v[210:213], v[20:23]
	s_setprio 2
	s_barrier
	v_mfma_f32_16x16x32_bf16 v[16:19], v[186:189], v[210:213], v[16:19]
	v_mfma_f32_16x16x32_bf16 v[4:7], v[160:163], v[232:235], v[4:7]
	v_mfma_f32_16x16x32_bf16 v[0:3], v[186:189], v[232:235], v[0:3]
	v_mfma_f32_16x16x32_bf16 v[48:51], v[160:163], v[194:197], v[48:51]
	s_setprio 0
	s_and_saveexec_b64 s[78:79], s[2:3]
	v_add_f32_e32 v238, v238, v239
	v_add_f32_e32 v240, v240, v241
	v_add_f32_e32 v242, v242, v243
	v_add_f32_e32 v244, v244, v245
	v_add_f32_e32 v246, v246, v247
	v_add_f32_e32 v248, v248, v249
	v_add_f32_e32 v250, v250, v251
	v_add_f32_e32 v252, v252, v253
	v_add_f32_e32 v238, v238, v240
	v_add_f32_e32 v242, v242, v244
	v_add_f32_e32 v246, v246, v248
	v_add_f32_e32 v250, v250, v252
	v_add_f32_e32 v238, v238, v242
	v_add_f32_e32 v246, v246, v250
	v_add_f32_e32 v238, v238, v246
	v_fmamk_f32 v238, v238, 0x3a800000, v216
	v_rsq_f32_e32 v238, v238
	s_nop 0
	ds_write_b32 v169, v238
	s_mov_b64 exec, s[78:79]
	s_add_i32 s64, 0, 0x18000
	s_add_i32 s65, 0, 0x1c000
	v_add_u32_e32 v140, s64, v167
	v_add_u32_e32 v173, s65, v167
	ds_read_b128 v[56:59], v140
	ds_read_b128 v[60:63], v140 offset:1024
	ds_read_b128 v[136:139], v140 offset:2048
	ds_read_b128 v[140:143], v140 offset:3072
	ds_read_b128 v[156:159], v173
	ds_read_b128 v[160:163], v173 offset:1024
	ds_read_b128 v[182:185], v173 offset:2048
	ds_read_b128 v[186:189], v173 offset:3072
	s_add_u32 s24, s24, 0x40000
	s_addc_u32 s25, s25, 0
	s_mov_b32 m0, s51
	ds_read_b128 v[190:193], v172 offset:32768
	ds_read_b128 v[194:197], v172 offset:33792
	ds_read_b128 v[198:201], v172 offset:34816
	ds_read_b128 v[202:205], v172 offset:35840
	ds_read_b128 v[206:209], v172 offset:36864
	ds_read_b128 v[210:213], v172 offset:37888
	ds_read_b128 v[228:231], v172 offset:38912
	ds_read_b128 v[232:235], v172 offset:39936
	global_load_lds_dwordx4 v150, s[24:25]
	s_mov_b32 m0, s52
	s_nop 0
	global_load_lds_dwordx4 v146, s[24:25]
	s_waitcnt vmcnt(8) lgkmcnt(0)
	s_barrier
	s_setprio 1
	v_mfma_f32_16x16x32_bf16 v[132:135], v[56:59], v[190:193], v[132:135]
	v_mfma_f32_16x16x32_bf16 v[124:127], v[136:139], v[190:193], v[124:127]
	v_mfma_f32_16x16x32_bf16 v[116:119], v[56:59], v[198:201], v[116:119]
	v_mfma_f32_16x16x32_bf16 v[112:115], v[136:139], v[198:201], v[112:115]
	v_mfma_f32_16x16x32_bf16 v[100:103], v[56:59], v[206:209], v[100:103]
	v_mfma_f32_16x16x32_bf16 v[96:99], v[136:139], v[206:209], v[96:99]
	v_mfma_f32_16x16x32_bf16 v[84:87], v[56:59], v[228:231], v[84:87]
	v_mfma_f32_16x16x32_bf16 v[80:83], v[136:139], v[228:231], v[80:83]
	v_mfma_f32_16x16x32_bf16 v[132:135], v[60:63], v[194:197], v[132:135]
	v_mfma_f32_16x16x32_bf16 v[124:127], v[140:143], v[194:197], v[124:127]
	v_mfma_f32_16x16x32_bf16 v[116:119], v[60:63], v[202:205], v[116:119]
	v_mfma_f32_16x16x32_bf16 v[112:115], v[140:143], v[202:205], v[112:115]
	v_mfma_f32_16x16x32_bf16 v[100:103], v[60:63], v[210:213], v[100:103]
	v_mfma_f32_16x16x32_bf16 v[96:99], v[140:143], v[210:213], v[96:99]
	v_mfma_f32_16x16x32_bf16 v[84:87], v[60:63], v[232:235], v[84:87]
	v_mfma_f32_16x16x32_bf16 v[80:83], v[140:143], v[232:235], v[80:83]
	v_mfma_f32_16x16x32_bf16 v[128:131], v[156:159], v[190:193], v[128:131]
	v_mfma_f32_16x16x32_bf16 v[120:123], v[182:185], v[190:193], v[120:123]
	v_mfma_f32_16x16x32_bf16 v[108:111], v[156:159], v[198:201], v[108:111]
	v_mfma_f32_16x16x32_bf16 v[104:107], v[182:185], v[198:201], v[104:107]
	v_mfma_f32_16x16x32_bf16 v[92:95], v[156:159], v[206:209], v[92:95]
	v_mfma_f32_16x16x32_bf16 v[88:91], v[182:185], v[206:209], v[88:91]
	v_mfma_f32_16x16x32_bf16 v[76:79], v[156:159], v[228:231], v[76:79]
	v_mfma_f32_16x16x32_bf16 v[72:75], v[182:185], v[228:231], v[72:75]
	v_mfma_f32_16x16x32_bf16 v[128:131], v[160:163], v[194:197], v[128:131]
	v_mfma_f32_16x16x32_bf16 v[120:123], v[186:189], v[194:197], v[120:123]
	v_mfma_f32_16x16x32_bf16 v[108:111], v[160:163], v[202:205], v[108:111]
	v_mfma_f32_16x16x32_bf16 v[104:107], v[186:189], v[202:205], v[104:107]
	s_setprio 2
	s_barrier
	v_mfma_f32_16x16x32_bf16 v[92:95], v[160:163], v[210:213], v[92:95]
	v_mfma_f32_16x16x32_bf16 v[88:91], v[186:189], v[210:213], v[88:91]
	v_mfma_f32_16x16x32_bf16 v[76:79], v[160:163], v[232:235], v[76:79]
	v_mfma_f32_16x16x32_bf16 v[72:75], v[186:189], v[232:235], v[72:75]
	s_setprio 0
	s_min_i32 s74, s18, 0x80
	s_ashr_i32 s74, s74, 3
	s_mul_hi_i32 s75, s74, 0x5800
	s_mulk_i32 s74, 0x5800
	s_add_u32 s74, s53, s74
	s_addc_u32 s75, s54, s75
	s_lshl_b32 s76, s60, 8
	s_ashr_i32 s77, s76, 31
	s_lshl_b64 s[76:77], s[76:77], 2
	s_add_u32 s74, s74, s76
	s_addc_u32 s75, s75, s77
	s_add_u32 s74, s74, s59
	s_addc_u32 s75, s75, 0
	v_lshl_add_u64 v[178:179], s[74:75], 0, v[176:177]
	global_load_dwordx4 v[238:241], v[178:179], off
	global_load_dwordx4 v[242:245], v[178:179], off offset:16
	global_load_dwordx4 v[246:249], v[178:179], off offset:512
	global_load_dwordx4 v[250:253], v[178:179], off offset:528
	s_add_i32 s24, s64, s41
	s_mov_b32 m0, s24
	ds_read_b128 v[190:193], v172 offset:49152
	ds_read_b128 v[194:197], v172 offset:50176
	ds_read_b128 v[198:201], v172 offset:51200
	ds_read_b128 v[202:205], v172 offset:52224
	ds_read_b128 v[206:209], v172 offset:53248
	ds_read_b128 v[210:213], v172 offset:54272
	ds_read_b128 v[228:231], v172 offset:55296
	ds_read_b128 v[232:235], v172 offset:56320
	global_load_lds_dwordx4 v148, s[94:95]
	s_add_i32 m0, s24, 0x2000
	s_add_u32 s22, s22, 0x40080
	s_addc_u32 s23, s23, 0
	s_add_i32 s24, s65, s41
	global_load_lds_dwordx4 v144, s[94:95]
	s_mov_b32 m0, s24
	s_nop 0
	global_load_lds_dwordx4 v148, s[22:23]
	s_add_i32 m0, s24, 0x2000
	s_nop 0
	global_load_lds_dwordx4 v144, s[22:23]
	s_mov_b32 m0, s55
	s_nop 0
	global_load_lds_dwordx4 v150, s[98:99]
	s_mov_b32 m0, s56
	s_nop 0
	global_load_lds_dwordx4 v146, s[98:99]
	s_waitcnt vmcnt(12) lgkmcnt(0)
	s_barrier
	s_setprio 1
	v_mfma_f32_16x16x32_bf16 v[68:71], v[56:59], v[190:193], v[68:71]
	v_mfma_f32_16x16x32_bf16 v[64:67], v[136:139], v[190:193], v[64:67]
	v_mfma_f32_16x16x32_bf16 v[44:47], v[56:59], v[198:201], v[44:47]
	v_mfma_f32_16x16x32_bf16 v[40:43], v[136:139], v[198:201], v[40:43]
	v_mfma_f32_16x16x32_bf16 v[28:31], v[56:59], v[206:209], v[28:31]
	v_mfma_f32_16x16x32_bf16 v[24:27], v[136:139], v[206:209], v[24:27]
	v_mfma_f32_16x16x32_bf16 v[12:15], v[56:59], v[228:231], v[12:15]
	v_mfma_f32_16x16x32_bf16 v[8:11], v[136:139], v[228:231], v[8:11]
	v_mfma_f32_16x16x32_bf16 v[68:71], v[60:63], v[194:197], v[68:71]
	v_mfma_f32_16x16x32_bf16 v[64:67], v[140:143], v[194:197], v[64:67]
	v_mfma_f32_16x16x32_bf16 v[44:47], v[60:63], v[202:205], v[44:47]
	v_mfma_f32_16x16x32_bf16 v[40:43], v[140:143], v[202:205], v[40:43]
	v_mfma_f32_16x16x32_bf16 v[28:31], v[60:63], v[210:213], v[28:31]
	v_mfma_f32_16x16x32_bf16 v[24:27], v[140:143], v[210:213], v[24:27]
	v_mfma_f32_16x16x32_bf16 v[12:15], v[60:63], v[232:235], v[12:15]
	v_mfma_f32_16x16x32_bf16 v[8:11], v[140:143], v[232:235], v[8:11]
	v_mfma_f32_16x16x32_bf16 v[48:51], v[156:159], v[190:193], v[48:51]
	v_mfma_f32_16x16x32_bf16 v[60:63], v[160:163], v[194:197], v[48:51]
	v_mfma_f32_16x16x32_bf16 v[48:51], v[182:185], v[190:193], v[52:55]
	v_mfma_f32_16x16x32_bf16 v[36:39], v[156:159], v[198:201], v[36:39]
	v_mfma_f32_16x16x32_bf16 v[32:35], v[182:185], v[198:201], v[32:35]
	v_mfma_f32_16x16x32_bf16 v[20:23], v[156:159], v[206:209], v[20:23]
	v_mfma_f32_16x16x32_bf16 v[16:19], v[182:185], v[206:209], v[16:19]
	v_mfma_f32_16x16x32_bf16 v[4:7], v[156:159], v[228:231], v[4:7]
	v_mfma_f32_16x16x32_bf16 v[0:3], v[182:185], v[228:231], v[0:3]
	v_mfma_f32_16x16x32_bf16 v[52:55], v[186:189], v[194:197], v[48:51]
	v_mfma_f32_16x16x32_bf16 v[36:39], v[160:163], v[202:205], v[36:39]
	v_mfma_f32_16x16x32_bf16 v[32:35], v[186:189], v[202:205], v[32:35]
	s_setprio 2
	s_barrier
	v_mfma_f32_16x16x32_bf16 v[20:23], v[160:163], v[210:213], v[20:23]
	v_mfma_f32_16x16x32_bf16 v[16:19], v[186:189], v[210:213], v[16:19]
	v_mfma_f32_16x16x32_bf16 v[4:7], v[160:163], v[232:235], v[4:7]
	v_mfma_f32_16x16x32_bf16 v[0:3], v[186:189], v[232:235], v[0:3]
	s_setprio 0
	s_add_i32 s68, s68, 2
	s_add_u32 s62, s62, 0x100
	s_addc_u32 s63, s63, 0
	s_add_u32 s20, s20, 0x100
	s_addc_u32 s21, s21, 0
	s_cmp_gt_u32 s68, 13
.LBB0_252:
	s_add_u32 s22, s20, 0xfffc0080
	s_addc_u32 s23, s21, -1
	s_add_i32 s64, 0, 0x10000
	s_cmp_eq_u32 s68, 12
	s_cselect_b32 s25, s13, s23
	s_cselect_b32 s24, s19, s22
	s_cselect_b32 s23, s11, s63
	s_cselect_b32 s22, s61, s62
	s_add_i32 s69, 0, 0x14000
	v_add_u32_e32 v140, s64, v167
	v_add_u32_e32 v164, s69, v167
	ds_read_b128 v[48:51], v140
	ds_read_b128 v[56:59], v140 offset:1024
	ds_read_b128 v[136:139], v140 offset:2048
	ds_read_b128 v[140:143], v140 offset:3072
	ds_read_b128 v[156:159], v164
	ds_read_b128 v[160:163], v164 offset:1024
	ds_read_b128 v[182:185], v164 offset:2048
	ds_read_b128 v[186:189], v164 offset:3072
	s_add_i32 m0, s49, 0xc000
	ds_read_b128 v[190:193], v172
	ds_read_b128 v[194:197], v172 offset:1024
	ds_read_b128 v[198:201], v172 offset:2048
	ds_read_b128 v[202:205], v172 offset:3072
	ds_read_b128 v[206:209], v172 offset:4096
	ds_read_b128 v[210:213], v172 offset:5120
	ds_read_b128 v[228:231], v172 offset:6144
	ds_read_b128 v[232:235], v172 offset:7168
	global_load_lds_dwordx4 v154, s[20:21]
	s_add_i32 m0, s49, 0xe000
	s_nop 0
	global_load_lds_dwordx4 v152, s[20:21]
	s_waitcnt vmcnt(8) lgkmcnt(0)
	s_barrier
	s_setprio 1
	v_mfma_f32_16x16x32_bf16 v[132:135], v[48:51], v[190:193], v[132:135]
	v_mfma_f32_16x16x32_bf16 v[124:127], v[136:139], v[190:193], v[124:127]
	v_mfma_f32_16x16x32_bf16 v[116:119], v[48:51], v[198:201], v[116:119]
	v_mfma_f32_16x16x32_bf16 v[112:115], v[136:139], v[198:201], v[112:115]
	v_mfma_f32_16x16x32_bf16 v[100:103], v[48:51], v[206:209], v[100:103]
	v_mfma_f32_16x16x32_bf16 v[96:99], v[136:139], v[206:209], v[96:99]
	v_mfma_f32_16x16x32_bf16 v[84:87], v[48:51], v[228:231], v[84:87]
	v_mfma_f32_16x16x32_bf16 v[80:83], v[136:139], v[228:231], v[80:83]
	v_mfma_f32_16x16x32_bf16 v[132:135], v[56:59], v[194:197], v[132:135]
	v_mfma_f32_16x16x32_bf16 v[124:127], v[140:143], v[194:197], v[124:127]
	v_mfma_f32_16x16x32_bf16 v[116:119], v[56:59], v[202:205], v[116:119]
	v_mfma_f32_16x16x32_bf16 v[112:115], v[140:143], v[202:205], v[112:115]
	v_mfma_f32_16x16x32_bf16 v[100:103], v[56:59], v[210:213], v[100:103]
	v_mfma_f32_16x16x32_bf16 v[96:99], v[140:143], v[210:213], v[96:99]
	v_mfma_f32_16x16x32_bf16 v[84:87], v[56:59], v[232:235], v[84:87]
	v_mfma_f32_16x16x32_bf16 v[80:83], v[140:143], v[232:235], v[80:83]
	v_mfma_f32_16x16x32_bf16 v[128:131], v[156:159], v[190:193], v[128:131]
	v_mfma_f32_16x16x32_bf16 v[120:123], v[182:185], v[190:193], v[120:123]
	v_mfma_f32_16x16x32_bf16 v[108:111], v[156:159], v[198:201], v[108:111]
	v_mfma_f32_16x16x32_bf16 v[104:107], v[182:185], v[198:201], v[104:107]
	v_mfma_f32_16x16x32_bf16 v[92:95], v[156:159], v[206:209], v[92:95]
	v_mfma_f32_16x16x32_bf16 v[88:91], v[182:185], v[206:209], v[88:91]
	v_mfma_f32_16x16x32_bf16 v[76:79], v[156:159], v[228:231], v[76:79]
	v_mfma_f32_16x16x32_bf16 v[72:75], v[182:185], v[228:231], v[72:75]
	v_mfma_f32_16x16x32_bf16 v[128:131], v[160:163], v[194:197], v[128:131]
	v_mfma_f32_16x16x32_bf16 v[120:123], v[186:189], v[194:197], v[120:123]
	v_mfma_f32_16x16x32_bf16 v[108:111], v[160:163], v[202:205], v[108:111]
	v_mfma_f32_16x16x32_bf16 v[104:107], v[186:189], v[202:205], v[104:107]
	s_setprio 2
	s_barrier
	v_mfma_f32_16x16x32_bf16 v[92:95], v[160:163], v[210:213], v[92:95]
	v_mfma_f32_16x16x32_bf16 v[88:91], v[186:189], v[210:213], v[88:91]
	v_mfma_f32_16x16x32_bf16 v[76:79], v[160:163], v[232:235], v[76:79]
	v_mfma_f32_16x16x32_bf16 v[72:75], v[186:189], v[232:235], v[72:75]
	s_setprio 0
	s_add_i32 s64, s64, s41
	s_add_u32 s94, s22, s34
	s_addc_u32 s95, s23, s35
	s_mov_b32 m0, s64
	ds_read_b128 v[190:193], v172 offset:16384
	ds_read_b128 v[194:197], v172 offset:17408
	ds_read_b128 v[198:201], v172 offset:18432
	ds_read_b128 v[202:205], v172 offset:19456
	ds_read_b128 v[206:209], v172 offset:20480
	ds_read_b128 v[210:213], v172 offset:21504
	ds_read_b128 v[228:231], v172 offset:22528
	ds_read_b128 v[232:235], v172 offset:23552
	global_load_lds_dwordx4 v148, s[22:23]
	s_add_i32 m0, s64, 0x2000
	s_add_u32 s64, s22, 0x40000
	s_addc_u32 s65, s23, 0
	s_add_i32 s69, s69, s41
	global_load_lds_dwordx4 v144, s[22:23]
	s_mov_b32 m0, s69
	s_nop 0
	global_load_lds_dwordx4 v148, s[64:65]
	s_add_i32 m0, s69, 0x2000
	s_nop 0
	global_load_lds_dwordx4 v144, s[64:65]
	s_add_u32 s98, s24, s34
	s_addc_u32 s99, s25, s35
	s_mov_b32 m0, s49
	s_nop 0
	global_load_lds_dwordx4 v150, s[24:25]
	s_mov_b32 m0, s50
	s_nop 0
	global_load_lds_dwordx4 v146, s[24:25]
	s_waitcnt vmcnt(8) lgkmcnt(0)
	s_barrier
	s_setprio 1
	v_mfma_f32_16x16x32_bf16 v[68:71], v[48:51], v[190:193], v[68:71]
	v_mfma_f32_16x16x32_bf16 v[64:67], v[136:139], v[190:193], v[64:67]
	v_mfma_f32_16x16x32_bf16 v[44:47], v[48:51], v[198:201], v[44:47]
	v_mfma_f32_16x16x32_bf16 v[40:43], v[136:139], v[198:201], v[40:43]
	v_mfma_f32_16x16x32_bf16 v[28:31], v[48:51], v[206:209], v[28:31]
	v_mfma_f32_16x16x32_bf16 v[24:27], v[136:139], v[206:209], v[24:27]
	v_mfma_f32_16x16x32_bf16 v[12:15], v[48:51], v[228:231], v[12:15]
	v_mfma_f32_16x16x32_bf16 v[8:11], v[136:139], v[228:231], v[8:11]
	v_mfma_f32_16x16x32_bf16 v[68:71], v[56:59], v[194:197], v[68:71]
	v_mfma_f32_16x16x32_bf16 v[64:67], v[140:143], v[194:197], v[64:67]
	v_mfma_f32_16x16x32_bf16 v[44:47], v[56:59], v[202:205], v[44:47]
	v_mfma_f32_16x16x32_bf16 v[40:43], v[140:143], v[202:205], v[40:43]
	v_mfma_f32_16x16x32_bf16 v[28:31], v[56:59], v[210:213], v[28:31]
	v_mfma_f32_16x16x32_bf16 v[24:27], v[140:143], v[210:213], v[24:27]
	v_mfma_f32_16x16x32_bf16 v[12:15], v[56:59], v[232:235], v[12:15]
	v_mfma_f32_16x16x32_bf16 v[8:11], v[140:143], v[232:235], v[8:11]
	v_mfma_f32_16x16x32_bf16 v[52:55], v[182:185], v[190:193], v[52:55]
	v_mfma_f32_16x16x32_bf16 v[36:39], v[156:159], v[198:201], v[36:39]
	v_mfma_f32_16x16x32_bf16 v[32:35], v[182:185], v[198:201], v[32:35]
	v_mfma_f32_16x16x32_bf16 v[20:23], v[156:159], v[206:209], v[20:23]
	v_mfma_f32_16x16x32_bf16 v[16:19], v[182:185], v[206:209], v[16:19]
	v_mfma_f32_16x16x32_bf16 v[4:7], v[156:159], v[228:231], v[4:7]
	v_mfma_f32_16x16x32_bf16 v[0:3], v[182:185], v[228:231], v[0:3]
	v_mfma_f32_16x16x32_bf16 v[48:51], v[156:159], v[190:193], v[60:63]
	v_mfma_f32_16x16x32_bf16 v[52:55], v[186:189], v[194:197], v[52:55]
	v_mfma_f32_16x16x32_bf16 v[36:39], v[160:163], v[202:205], v[36:39]
	v_mfma_f32_16x16x32_bf16 v[32:35], v[186:189], v[202:205], v[32:35]
	v_mfma_f32_16x16x32_bf16 v[20:23], v[160:163], v[210:213], v[20:23]
	s_setprio 2
	s_barrier
	v_mfma_f32_16x16x32_bf16 v[16:19], v[186:189], v[210:213], v[16:19]
	v_mfma_f32_16x16x32_bf16 v[4:7], v[160:163], v[232:235], v[4:7]
	v_mfma_f32_16x16x32_bf16 v[0:3], v[186:189], v[232:235], v[0:3]
	v_mfma_f32_16x16x32_bf16 v[48:51], v[160:163], v[194:197], v[48:51]
	s_setprio 0
	s_add_i32 s64, 0, 0x18000
	s_add_i32 s65, 0, 0x1c000
	v_add_u32_e32 v140, s64, v167
	v_add_u32_e32 v173, s65, v167
	ds_read_b128 v[56:59], v140
	ds_read_b128 v[60:63], v140 offset:1024
	ds_read_b128 v[136:139], v140 offset:2048
	ds_read_b128 v[140:143], v140 offset:3072
	ds_read_b128 v[156:159], v173
	ds_read_b128 v[160:163], v173 offset:1024
	ds_read_b128 v[182:185], v173 offset:2048
	ds_read_b128 v[186:189], v173 offset:3072
	s_add_u32 s24, s24, 0x40000
	s_addc_u32 s25, s25, 0
	s_mov_b32 m0, s51
	ds_read_b128 v[190:193], v172 offset:32768
	ds_read_b128 v[194:197], v172 offset:33792
	ds_read_b128 v[198:201], v172 offset:34816
	ds_read_b128 v[202:205], v172 offset:35840
	ds_read_b128 v[206:209], v172 offset:36864
	ds_read_b128 v[210:213], v172 offset:37888
	ds_read_b128 v[228:231], v172 offset:38912
	ds_read_b128 v[232:235], v172 offset:39936
	global_load_lds_dwordx4 v150, s[24:25]
	s_mov_b32 m0, s52
	s_nop 0
	global_load_lds_dwordx4 v146, s[24:25]
	s_waitcnt vmcnt(8) lgkmcnt(0)
	s_barrier
	s_setprio 1
	v_mfma_f32_16x16x32_bf16 v[132:135], v[56:59], v[190:193], v[132:135]
	v_mfma_f32_16x16x32_bf16 v[124:127], v[136:139], v[190:193], v[124:127]
	v_mfma_f32_16x16x32_bf16 v[116:119], v[56:59], v[198:201], v[116:119]
	v_mfma_f32_16x16x32_bf16 v[112:115], v[136:139], v[198:201], v[112:115]
	v_mfma_f32_16x16x32_bf16 v[100:103], v[56:59], v[206:209], v[100:103]
	v_mfma_f32_16x16x32_bf16 v[96:99], v[136:139], v[206:209], v[96:99]
	v_mfma_f32_16x16x32_bf16 v[84:87], v[56:59], v[228:231], v[84:87]
	v_mfma_f32_16x16x32_bf16 v[80:83], v[136:139], v[228:231], v[80:83]
	v_mfma_f32_16x16x32_bf16 v[132:135], v[60:63], v[194:197], v[132:135]
	v_mfma_f32_16x16x32_bf16 v[124:127], v[140:143], v[194:197], v[124:127]
	v_mfma_f32_16x16x32_bf16 v[116:119], v[60:63], v[202:205], v[116:119]
	v_mfma_f32_16x16x32_bf16 v[112:115], v[140:143], v[202:205], v[112:115]
	v_mfma_f32_16x16x32_bf16 v[100:103], v[60:63], v[210:213], v[100:103]
	v_mfma_f32_16x16x32_bf16 v[96:99], v[140:143], v[210:213], v[96:99]
	v_mfma_f32_16x16x32_bf16 v[84:87], v[60:63], v[232:235], v[84:87]
	v_mfma_f32_16x16x32_bf16 v[80:83], v[140:143], v[232:235], v[80:83]
	v_mfma_f32_16x16x32_bf16 v[128:131], v[156:159], v[190:193], v[128:131]
	v_mfma_f32_16x16x32_bf16 v[120:123], v[182:185], v[190:193], v[120:123]
	v_mfma_f32_16x16x32_bf16 v[108:111], v[156:159], v[198:201], v[108:111]
	v_mfma_f32_16x16x32_bf16 v[104:107], v[182:185], v[198:201], v[104:107]
	v_mfma_f32_16x16x32_bf16 v[92:95], v[156:159], v[206:209], v[92:95]
	v_mfma_f32_16x16x32_bf16 v[88:91], v[182:185], v[206:209], v[88:91]
	v_mfma_f32_16x16x32_bf16 v[76:79], v[156:159], v[228:231], v[76:79]
	v_mfma_f32_16x16x32_bf16 v[72:75], v[182:185], v[228:231], v[72:75]
	v_mfma_f32_16x16x32_bf16 v[128:131], v[160:163], v[194:197], v[128:131]
	v_mfma_f32_16x16x32_bf16 v[120:123], v[186:189], v[194:197], v[120:123]
	v_mfma_f32_16x16x32_bf16 v[108:111], v[160:163], v[202:205], v[108:111]
	v_mfma_f32_16x16x32_bf16 v[104:107], v[186:189], v[202:205], v[104:107]
	s_setprio 2
	s_barrier
	v_mfma_f32_16x16x32_bf16 v[92:95], v[160:163], v[210:213], v[92:95]
	v_mfma_f32_16x16x32_bf16 v[88:91], v[186:189], v[210:213], v[88:91]
	v_mfma_f32_16x16x32_bf16 v[76:79], v[160:163], v[232:235], v[76:79]
	v_mfma_f32_16x16x32_bf16 v[72:75], v[186:189], v[232:235], v[72:75]
	s_setprio 0
	s_add_i32 s24, s64, s41
	s_mov_b32 m0, s24
	ds_read_b128 v[190:193], v172 offset:49152
	ds_read_b128 v[194:197], v172 offset:50176
	ds_read_b128 v[198:201], v172 offset:51200
	ds_read_b128 v[202:205], v172 offset:52224
	ds_read_b128 v[206:209], v172 offset:53248
	ds_read_b128 v[210:213], v172 offset:54272
	ds_read_b128 v[228:231], v172 offset:55296
	ds_read_b128 v[232:235], v172 offset:56320
	global_load_lds_dwordx4 v148, s[94:95]
	s_add_i32 m0, s24, 0x2000
	s_add_u32 s22, s22, 0x40080
	s_addc_u32 s23, s23, 0
	s_add_i32 s24, s65, s41
	global_load_lds_dwordx4 v144, s[94:95]
	s_mov_b32 m0, s24
	s_nop 0
	global_load_lds_dwordx4 v148, s[22:23]
	s_add_i32 m0, s24, 0x2000
	s_nop 0
	global_load_lds_dwordx4 v144, s[22:23]
	s_mov_b32 m0, s55
	s_nop 0
	global_load_lds_dwordx4 v150, s[98:99]
	s_mov_b32 m0, s56
	s_nop 0
	global_load_lds_dwordx4 v146, s[98:99]
	s_waitcnt vmcnt(8) lgkmcnt(0)
	s_barrier
	s_setprio 1
	v_mfma_f32_16x16x32_bf16 v[68:71], v[56:59], v[190:193], v[68:71]
	v_mfma_f32_16x16x32_bf16 v[64:67], v[136:139], v[190:193], v[64:67]
	v_mfma_f32_16x16x32_bf16 v[44:47], v[56:59], v[198:201], v[44:47]
	v_mfma_f32_16x16x32_bf16 v[40:43], v[136:139], v[198:201], v[40:43]
	v_mfma_f32_16x16x32_bf16 v[28:31], v[56:59], v[206:209], v[28:31]
	v_mfma_f32_16x16x32_bf16 v[24:27], v[136:139], v[206:209], v[24:27]
	v_mfma_f32_16x16x32_bf16 v[12:15], v[56:59], v[228:231], v[12:15]
	v_mfma_f32_16x16x32_bf16 v[8:11], v[136:139], v[228:231], v[8:11]
	v_mfma_f32_16x16x32_bf16 v[68:71], v[60:63], v[194:197], v[68:71]
	v_mfma_f32_16x16x32_bf16 v[64:67], v[140:143], v[194:197], v[64:67]
	v_mfma_f32_16x16x32_bf16 v[44:47], v[60:63], v[202:205], v[44:47]
	v_mfma_f32_16x16x32_bf16 v[40:43], v[140:143], v[202:205], v[40:43]
	v_mfma_f32_16x16x32_bf16 v[28:31], v[60:63], v[210:213], v[28:31]
	v_mfma_f32_16x16x32_bf16 v[24:27], v[140:143], v[210:213], v[24:27]
	v_mfma_f32_16x16x32_bf16 v[12:15], v[60:63], v[232:235], v[12:15]
	v_mfma_f32_16x16x32_bf16 v[8:11], v[140:143], v[232:235], v[8:11]
	v_mfma_f32_16x16x32_bf16 v[48:51], v[156:159], v[190:193], v[48:51]
	v_mfma_f32_16x16x32_bf16 v[60:63], v[160:163], v[194:197], v[48:51]
	v_mfma_f32_16x16x32_bf16 v[48:51], v[182:185], v[190:193], v[52:55]
	v_mfma_f32_16x16x32_bf16 v[36:39], v[156:159], v[198:201], v[36:39]
	v_mfma_f32_16x16x32_bf16 v[32:35], v[182:185], v[198:201], v[32:35]
	v_mfma_f32_16x16x32_bf16 v[20:23], v[156:159], v[206:209], v[20:23]
	v_mfma_f32_16x16x32_bf16 v[16:19], v[182:185], v[206:209], v[16:19]
	v_mfma_f32_16x16x32_bf16 v[4:7], v[156:159], v[228:231], v[4:7]
	v_mfma_f32_16x16x32_bf16 v[0:3], v[182:185], v[228:231], v[0:3]
	v_mfma_f32_16x16x32_bf16 v[52:55], v[186:189], v[194:197], v[48:51]
	v_mfma_f32_16x16x32_bf16 v[36:39], v[160:163], v[202:205], v[36:39]
	v_mfma_f32_16x16x32_bf16 v[32:35], v[186:189], v[202:205], v[32:35]
	s_setprio 2
	s_barrier
	v_mfma_f32_16x16x32_bf16 v[20:23], v[160:163], v[210:213], v[20:23]
	v_mfma_f32_16x16x32_bf16 v[16:19], v[186:189], v[210:213], v[16:19]
	v_mfma_f32_16x16x32_bf16 v[4:7], v[160:163], v[232:235], v[4:7]
	v_mfma_f32_16x16x32_bf16 v[0:3], v[186:189], v[232:235], v[0:3]
	s_setprio 0
	s_add_i32 s68, s68, 2
	s_add_u32 s62, s62, 0x100
	s_addc_u32 s63, s63, 0
	s_add_u32 s20, s20, 0x100
	s_addc_u32 s21, s21, 0
	s_cmp_gt_u32 s68, 13
	s_cbranch_scc0 .LBB0_252
	s_and_b64 vcc, exec, s[8:9]
	s_cbranch_vccz .LBB0_255
	s_barrier

.LBB0_261:
	ds_read_b32 v0, v214
	s_waitcnt lgkmcnt(0)
	v_readfirstlane_b32 s44, v0
	ds_read_b32 v0, v215
	s_getreg_b32 s0, hwreg(HW_REG_XCC_ID, 0, 4)
	s_waitcnt vmcnt(0) lgkmcnt(0)
	s_barrier
	v_readfirstlane_b32 s62, v0
	s_mov_b64 s[38:39], exec
	v_readlane_b32 s2, v255, 0
	v_readlane_b32 s3, v255, 1
	s_and_b64 s[2:3], s[38:39], s[2:3]
	s_mov_b64 exec, s[2:3]
	s_cbranch_execz .LBB0_305
	s_waitcnt vmcnt(0) expcnt(0) lgkmcnt(0)
	buffer_inv sc1
	ds_read_b32 v2, v217
	ds_read_b32 v0, v218
	s_and_b32 s63, s0, 15
	s_waitcnt lgkmcnt(1)
	v_cmp_ne_u32_e32 vcc, 0, v2
	s_cbranch_vccnz .LBB0_276
	s_add_u32 s0, s44, 0x600200
	s_addc_u32 s1, s62, 0
	s_add_u32 s2, s44, 0x600400
	s_addc_u32 s3, s62, 0
	s_add_u32 s4, s44, 0x600500
	s_addc_u32 s5, s62, 0
	s_add_u32 s6, s44, 0x600600
	s_addc_u32 s7, s62, 0
	s_add_u32 s8, s44, 0x600700
	s_addc_u32 s9, s62, 0
	s_add_u32 s10, s44, 0x600800
	s_addc_u32 s11, s62, 0
	s_add_u32 s12, s44, 0x600900
	s_addc_u32 s13, s62, 0
	s_add_u32 s14, s44, 0x600a00
	s_addc_u32 s15, s62, 0
	s_add_u32 s16, s44, 0x600b00
	s_addc_u32 s17, s62, 0
	s_add_u32 s18, s44, 0x600c00
	s_addc_u32 s19, s62, 0
	s_add_u32 s20, s44, 0x600d00
	s_addc_u32 s21, s62, 0
	s_add_u32 s22, s44, 0x600e00
	s_addc_u32 s23, s62, 0
	s_add_u32 s24, s44, 0x600f00
	s_addc_u32 s25, s62, 0
	s_add_u32 s26, s44, 0x601000
	s_addc_u32 s27, s62, 0
	s_add_u32 s28, s44, 0x601100
	s_addc_u32 s29, s62, 0
	s_add_u32 s40, s44, 0x601200
	s_addc_u32 s41, s62, 0
	s_add_u32 s42, s44, 0x601300
	s_addc_u32 s43, s62, 0
	s_mov_b32 s64, 1
	s_mov_b64 s[48:49], 0
	s_branch .LBB0_266

.LBB0_318:
	s_ashr_i32 s15, s14, 31
	s_lshl_b64 s[16:17], s[14:15], 19
	s_add_u32 s16, s37, s16
	s_addc_u32 s17, s42, s17
	s_and_b64 s[18:19], s[6:7], exec
	s_cselect_b32 s9, s17, s25
	s_cselect_b32 s15, s16, s24
	s_ashr_i32 s13, s12, 31
	s_lshl_b64 s[18:19], s[12:13], 19
	s_add_u32 s18, s38, s18
	s_addc_u32 s19, s39, s19
	s_and_b64 s[26:27], s[6:7], exec
	s_cselect_b32 s13, s19, s23
	s_cselect_b32 s21, s18, s22
	s_add_u32 s44, s22, 0x100
	s_addc_u32 s62, s23, 0
	s_add_u32 s22, s24, 0x40080
	s_addc_u32 s23, s25, 0
	s_mov_b32 s63, -2
	s_add_u32 s24, s22, 0xfffc0080
	s_addc_u32 s25, s23, -1
	s_add_i32 s64, 0, 0x10000
	s_cmp_eq_u32 s63, 12
	s_cselect_b32 s27, s9, s25
	s_cselect_b32 s26, s15, s24
	s_cselect_b32 s25, s13, s62
	s_cselect_b32 s24, s21, s44
	s_add_i32 s68, 0, 0x14000
	v_add_u32_e32 v112, s64, v159
	v_add_u32_e32 v165, s68, v159
	ds_read_b128 v[96:99], v112
	ds_read_b128 v[100:103], v112 offset:1024
	ds_read_b128 v[108:111], v112 offset:2048
	ds_read_b128 v[112:115], v112 offset:3072
	ds_read_b128 v[154:157], v165
	ds_read_b128 v[166:169], v165 offset:1024
	ds_read_b128 v[170:173], v165 offset:2048
	ds_read_b128 v[182:185], v165 offset:3072
	s_add_i32 m0, s50, 0xc000
	ds_read_b128 v[186:189], v164
	ds_read_b128 v[190:193], v164 offset:1024
	ds_read_b128 v[194:197], v164 offset:2048
	ds_read_b128 v[198:201], v164 offset:3072
	ds_read_b128 v[202:205], v164 offset:4096
	ds_read_b128 v[206:209], v164 offset:5120
	ds_read_b128 v[210:213], v164 offset:6144
	ds_read_b128 v[228:231], v164 offset:7168
	global_load_lds_dwordx4 v152, s[22:23]
	s_add_i32 m0, s50, 0xe000
	s_nop 0
	global_load_lds_dwordx4 v150, s[22:23]
	s_waitcnt vmcnt(8) lgkmcnt(0)
	s_barrier
	s_setprio 1
	v_mfma_f32_16x16x32_bf16 v[140:143], v[96:99], v[186:189], 0
	v_mfma_f32_16x16x32_bf16 v[136:139], v[108:111], v[186:189], 0
	v_mfma_f32_16x16x32_bf16 v[124:127], v[96:99], v[194:197], 0
	v_mfma_f32_16x16x32_bf16 v[120:123], v[108:111], v[194:197], 0
	v_mfma_f32_16x16x32_bf16 v[92:95], v[96:99], v[202:205], 0
	v_mfma_f32_16x16x32_bf16 v[88:91], v[108:111], v[202:205], 0
	v_mfma_f32_16x16x32_bf16 v[76:79], v[96:99], v[210:213], 0
	v_mfma_f32_16x16x32_bf16 v[72:75], v[108:111], v[210:213], 0
	v_mfma_f32_16x16x32_bf16 v[140:143], v[100:103], v[190:193], v[140:143]
	v_mfma_f32_16x16x32_bf16 v[136:139], v[112:115], v[190:193], v[136:139]
	v_mfma_f32_16x16x32_bf16 v[124:127], v[100:103], v[198:201], v[124:127]
	v_mfma_f32_16x16x32_bf16 v[120:123], v[112:115], v[198:201], v[120:123]
	v_mfma_f32_16x16x32_bf16 v[92:95], v[100:103], v[206:209], v[92:95]
	v_mfma_f32_16x16x32_bf16 v[88:91], v[112:115], v[206:209], v[88:91]
	v_mfma_f32_16x16x32_bf16 v[76:79], v[100:103], v[228:231], v[76:79]
	v_mfma_f32_16x16x32_bf16 v[72:75], v[112:115], v[228:231], v[72:75]
	v_mfma_f32_16x16x32_bf16 v[132:135], v[154:157], v[186:189], 0
	v_mfma_f32_16x16x32_bf16 v[128:131], v[170:173], v[186:189], 0
	v_mfma_f32_16x16x32_bf16 v[116:119], v[154:157], v[194:197], 0
	v_mfma_f32_16x16x32_bf16 v[104:107], v[170:173], v[194:197], 0
	v_mfma_f32_16x16x32_bf16 v[84:87], v[154:157], v[202:205], 0
	v_mfma_f32_16x16x32_bf16 v[80:83], v[170:173], v[202:205], 0
	v_mfma_f32_16x16x32_bf16 v[68:71], v[154:157], v[210:213], 0
	v_mfma_f32_16x16x32_bf16 v[64:67], v[170:173], v[210:213], 0
	v_mfma_f32_16x16x32_bf16 v[132:135], v[166:169], v[190:193], v[132:135]
	v_mfma_f32_16x16x32_bf16 v[128:131], v[182:185], v[190:193], v[128:131]
	v_mfma_f32_16x16x32_bf16 v[116:119], v[166:169], v[198:201], v[116:119]
	v_mfma_f32_16x16x32_bf16 v[104:107], v[182:185], v[198:201], v[104:107]
	s_setprio 2
	s_barrier
	v_mfma_f32_16x16x32_bf16 v[84:87], v[166:169], v[206:209], v[84:87]
	v_mfma_f32_16x16x32_bf16 v[80:83], v[182:185], v[206:209], v[80:83]
	v_mfma_f32_16x16x32_bf16 v[68:71], v[166:169], v[228:231], v[68:71]
	v_mfma_f32_16x16x32_bf16 v[64:67], v[182:185], v[228:231], v[64:67]
	s_setprio 0
	s_add_i32 s64, s64, s43
	s_add_u32 s94, s24, s34
	s_addc_u32 s95, s25, s35
	s_mov_b32 m0, s64
	ds_read_b128 v[186:189], v164 offset:16384
	ds_read_b128 v[190:193], v164 offset:17408
	ds_read_b128 v[194:197], v164 offset:18432
	ds_read_b128 v[198:201], v164 offset:19456
	ds_read_b128 v[202:205], v164 offset:20480
	ds_read_b128 v[206:209], v164 offset:21504
	ds_read_b128 v[210:213], v164 offset:22528
	ds_read_b128 v[228:231], v164 offset:23552
	global_load_lds_dwordx4 v176, s[24:25]
	s_add_i32 m0, s64, 0x2000
	s_add_u32 s64, s24, 0x40000
	s_addc_u32 s65, s25, 0
	s_add_i32 s68, s68, s43
	global_load_lds_dwordx4 v148, s[24:25]
	s_mov_b32 m0, s68
	s_nop 0
	global_load_lds_dwordx4 v176, s[64:65]
	s_add_i32 m0, s68, 0x2000
	s_nop 0
	global_load_lds_dwordx4 v148, s[64:65]
	s_add_u32 s98, s26, s34
	s_addc_u32 s99, s27, s35
	s_mov_b32 m0, s50
	s_nop 0
	global_load_lds_dwordx4 v144, s[26:27]
	s_mov_b32 m0, s51
	s_nop 0
	global_load_lds_dwordx4 v146, s[26:27]
	s_waitcnt vmcnt(8) lgkmcnt(0)
	s_barrier
	s_setprio 1
	v_mfma_f32_16x16x32_bf16 v[60:63], v[96:99], v[186:189], 0
	v_mfma_f32_16x16x32_bf16 v[56:59], v[108:111], v[186:189], 0
	v_mfma_f32_16x16x32_bf16 v[44:47], v[96:99], v[194:197], 0
	v_mfma_f32_16x16x32_bf16 v[40:43], v[108:111], v[194:197], 0
	v_mfma_f32_16x16x32_bf16 v[28:31], v[96:99], v[202:205], 0
	v_mfma_f32_16x16x32_bf16 v[24:27], v[108:111], v[202:205], 0
	v_mfma_f32_16x16x32_bf16 v[12:15], v[96:99], v[210:213], 0
	v_mfma_f32_16x16x32_bf16 v[8:11], v[108:111], v[210:213], 0
	v_mfma_f32_16x16x32_bf16 v[60:63], v[100:103], v[190:193], v[60:63]
	v_mfma_f32_16x16x32_bf16 v[56:59], v[112:115], v[190:193], v[56:59]
	v_mfma_f32_16x16x32_bf16 v[44:47], v[100:103], v[198:201], v[44:47]
	v_mfma_f32_16x16x32_bf16 v[40:43], v[112:115], v[198:201], v[40:43]
	v_mfma_f32_16x16x32_bf16 v[28:31], v[100:103], v[206:209], v[28:31]
	v_mfma_f32_16x16x32_bf16 v[24:27], v[112:115], v[206:209], v[24:27]
	v_mfma_f32_16x16x32_bf16 v[12:15], v[100:103], v[228:231], v[12:15]
	v_mfma_f32_16x16x32_bf16 v[8:11], v[112:115], v[228:231], v[8:11]
	v_mfma_f32_16x16x32_bf16 v[52:55], v[154:157], v[186:189], 0
	v_mfma_f32_16x16x32_bf16 v[48:51], v[170:173], v[186:189], 0
	v_mfma_f32_16x16x32_bf16 v[36:39], v[154:157], v[194:197], 0
	v_mfma_f32_16x16x32_bf16 v[32:35], v[170:173], v[194:197], 0
	v_mfma_f32_16x16x32_bf16 v[20:23], v[154:157], v[202:205], 0
	v_mfma_f32_16x16x32_bf16 v[16:19], v[170:173], v[202:205], 0
	v_mfma_f32_16x16x32_bf16 v[4:7], v[154:157], v[210:213], 0
	v_mfma_f32_16x16x32_bf16 v[0:3], v[170:173], v[210:213], 0
	v_mfma_f32_16x16x32_bf16 v[52:55], v[166:169], v[190:193], v[52:55]
	v_mfma_f32_16x16x32_bf16 v[48:51], v[182:185], v[190:193], v[48:51]
	v_mfma_f32_16x16x32_bf16 v[36:39], v[166:169], v[198:201], v[36:39]
	v_mfma_f32_16x16x32_bf16 v[32:35], v[182:185], v[198:201], v[32:35]
	s_setprio 2
	s_barrier
	v_mfma_f32_16x16x32_bf16 v[20:23], v[166:169], v[206:209], v[20:23]
	v_mfma_f32_16x16x32_bf16 v[16:19], v[182:185], v[206:209], v[16:19]
	v_mfma_f32_16x16x32_bf16 v[4:7], v[166:169], v[228:231], v[4:7]
	v_mfma_f32_16x16x32_bf16 v[0:3], v[182:185], v[228:231], v[0:3]
	s_setprio 0
	s_add_i32 s64, 0, 0x18000
	s_add_i32 s65, 0, 0x1c000
	v_add_u32_e32 v112, s64, v159
	v_add_u32_e32 v165, s65, v159
	ds_read_b128 v[96:99], v112
	ds_read_b128 v[100:103], v112 offset:1024
	ds_read_b128 v[108:111], v112 offset:2048
	ds_read_b128 v[112:115], v112 offset:3072
	ds_read_b128 v[154:157], v165
	ds_read_b128 v[166:169], v165 offset:1024
	ds_read_b128 v[170:173], v165 offset:2048
	ds_read_b128 v[182:185], v165 offset:3072
	s_add_u32 s26, s26, 0x40000
	s_addc_u32 s27, s27, 0
	s_mov_b32 m0, s52
	ds_read_b128 v[186:189], v164 offset:32768
	ds_read_b128 v[190:193], v164 offset:33792
	ds_read_b128 v[194:197], v164 offset:34816
	ds_read_b128 v[198:201], v164 offset:35840
	ds_read_b128 v[202:205], v164 offset:36864
	ds_read_b128 v[206:209], v164 offset:37888
	ds_read_b128 v[210:213], v164 offset:38912
	ds_read_b128 v[228:231], v164 offset:39936
	global_load_lds_dwordx4 v144, s[26:27]
	s_mov_b32 m0, s53
	s_nop 0
	global_load_lds_dwordx4 v146, s[26:27]
	s_waitcnt vmcnt(8) lgkmcnt(0)
	s_barrier
	s_setprio 1
	v_mfma_f32_16x16x32_bf16 v[140:143], v[96:99], v[186:189], v[140:143]
	v_mfma_f32_16x16x32_bf16 v[136:139], v[108:111], v[186:189], v[136:139]
	v_mfma_f32_16x16x32_bf16 v[124:127], v[96:99], v[194:197], v[124:127]
	v_mfma_f32_16x16x32_bf16 v[120:123], v[108:111], v[194:197], v[120:123]
	v_mfma_f32_16x16x32_bf16 v[92:95], v[96:99], v[202:205], v[92:95]
	v_mfma_f32_16x16x32_bf16 v[88:91], v[108:111], v[202:205], v[88:91]
	v_mfma_f32_16x16x32_bf16 v[76:79], v[96:99], v[210:213], v[76:79]
	v_mfma_f32_16x16x32_bf16 v[72:75], v[108:111], v[210:213], v[72:75]
	v_mfma_f32_16x16x32_bf16 v[140:143], v[100:103], v[190:193], v[140:143]
	v_mfma_f32_16x16x32_bf16 v[136:139], v[112:115], v[190:193], v[136:139]
	v_mfma_f32_16x16x32_bf16 v[124:127], v[100:103], v[198:201], v[124:127]
	v_mfma_f32_16x16x32_bf16 v[120:123], v[112:115], v[198:201], v[120:123]
	v_mfma_f32_16x16x32_bf16 v[92:95], v[100:103], v[206:209], v[92:95]
	v_mfma_f32_16x16x32_bf16 v[88:91], v[112:115], v[206:209], v[88:91]
	v_mfma_f32_16x16x32_bf16 v[76:79], v[100:103], v[228:231], v[76:79]
	v_mfma_f32_16x16x32_bf16 v[72:75], v[112:115], v[228:231], v[72:75]
	v_mfma_f32_16x16x32_bf16 v[132:135], v[154:157], v[186:189], v[132:135]
	v_mfma_f32_16x16x32_bf16 v[128:131], v[170:173], v[186:189], v[128:131]
	v_mfma_f32_16x16x32_bf16 v[116:119], v[154:157], v[194:197], v[116:119]
	v_mfma_f32_16x16x32_bf16 v[104:107], v[170:173], v[194:197], v[104:107]
	v_mfma_f32_16x16x32_bf16 v[84:87], v[154:157], v[202:205], v[84:87]
	v_mfma_f32_16x16x32_bf16 v[80:83], v[170:173], v[202:205], v[80:83]
	v_mfma_f32_16x16x32_bf16 v[68:71], v[154:157], v[210:213], v[68:71]
	v_mfma_f32_16x16x32_bf16 v[64:67], v[170:173], v[210:213], v[64:67]
	v_mfma_f32_16x16x32_bf16 v[132:135], v[166:169], v[190:193], v[132:135]
	v_mfma_f32_16x16x32_bf16 v[128:131], v[182:185], v[190:193], v[128:131]
	v_mfma_f32_16x16x32_bf16 v[116:119], v[166:169], v[198:201], v[116:119]
	v_mfma_f32_16x16x32_bf16 v[104:107], v[182:185], v[198:201], v[104:107]
	s_setprio 2
	s_barrier
	v_mfma_f32_16x16x32_bf16 v[84:87], v[166:169], v[206:209], v[84:87]
	v_mfma_f32_16x16x32_bf16 v[80:83], v[182:185], v[206:209], v[80:83]
	v_mfma_f32_16x16x32_bf16 v[68:71], v[166:169], v[228:231], v[68:71]
	v_mfma_f32_16x16x32_bf16 v[64:67], v[182:185], v[228:231], v[64:67]
	s_setprio 0
	s_add_i32 s26, s64, s43
	s_mov_b32 m0, s26
	ds_read_b128 v[186:189], v164 offset:49152
	ds_read_b128 v[190:193], v164 offset:50176
	ds_read_b128 v[194:197], v164 offset:51200
	ds_read_b128 v[198:201], v164 offset:52224
	ds_read_b128 v[202:205], v164 offset:53248
	ds_read_b128 v[206:209], v164 offset:54272
	ds_read_b128 v[210:213], v164 offset:55296
	ds_read_b128 v[228:231], v164 offset:56320
	global_load_lds_dwordx4 v176, s[94:95]
	s_add_i32 m0, s26, 0x2000
	s_add_u32 s24, s24, 0x40080
	s_addc_u32 s25, s25, 0
	s_add_i32 s26, s65, s43
	global_load_lds_dwordx4 v148, s[94:95]
	s_mov_b32 m0, s26
	s_nop 0
	global_load_lds_dwordx4 v176, s[24:25]
	s_add_i32 m0, s26, 0x2000
	s_nop 0
	global_load_lds_dwordx4 v148, s[24:25]
	s_mov_b32 m0, s57
	s_nop 0
	global_load_lds_dwordx4 v144, s[98:99]
	s_mov_b32 m0, s58
	s_nop 0
	global_load_lds_dwordx4 v146, s[98:99]
	s_waitcnt vmcnt(8) lgkmcnt(0)
	s_barrier
	s_setprio 1
	v_mfma_f32_16x16x32_bf16 v[60:63], v[96:99], v[186:189], v[60:63]
	v_mfma_f32_16x16x32_bf16 v[56:59], v[108:111], v[186:189], v[56:59]
	v_mfma_f32_16x16x32_bf16 v[44:47], v[96:99], v[194:197], v[44:47]
	v_mfma_f32_16x16x32_bf16 v[40:43], v[108:111], v[194:197], v[40:43]
	v_mfma_f32_16x16x32_bf16 v[28:31], v[96:99], v[202:205], v[28:31]
	v_mfma_f32_16x16x32_bf16 v[24:27], v[108:111], v[202:205], v[24:27]
	v_mfma_f32_16x16x32_bf16 v[12:15], v[96:99], v[210:213], v[12:15]
	v_mfma_f32_16x16x32_bf16 v[8:11], v[108:111], v[210:213], v[8:11]
	v_mfma_f32_16x16x32_bf16 v[60:63], v[100:103], v[190:193], v[60:63]
	v_mfma_f32_16x16x32_bf16 v[56:59], v[112:115], v[190:193], v[56:59]
	v_mfma_f32_16x16x32_bf16 v[44:47], v[100:103], v[198:201], v[44:47]
	v_mfma_f32_16x16x32_bf16 v[40:43], v[112:115], v[198:201], v[40:43]
	v_mfma_f32_16x16x32_bf16 v[28:31], v[100:103], v[206:209], v[28:31]
	v_mfma_f32_16x16x32_bf16 v[24:27], v[112:115], v[206:209], v[24:27]
	v_mfma_f32_16x16x32_bf16 v[12:15], v[100:103], v[228:231], v[12:15]
	v_mfma_f32_16x16x32_bf16 v[8:11], v[112:115], v[228:231], v[8:11]
	v_mfma_f32_16x16x32_bf16 v[52:55], v[154:157], v[186:189], v[52:55]
	v_mfma_f32_16x16x32_bf16 v[48:51], v[170:173], v[186:189], v[48:51]
	v_mfma_f32_16x16x32_bf16 v[36:39], v[154:157], v[194:197], v[36:39]
	v_mfma_f32_16x16x32_bf16 v[32:35], v[170:173], v[194:197], v[32:35]
	v_mfma_f32_16x16x32_bf16 v[20:23], v[154:157], v[202:205], v[20:23]
	v_mfma_f32_16x16x32_bf16 v[16:19], v[170:173], v[202:205], v[16:19]
	v_mfma_f32_16x16x32_bf16 v[4:7], v[154:157], v[210:213], v[4:7]
	v_mfma_f32_16x16x32_bf16 v[0:3], v[170:173], v[210:213], v[0:3]
	v_mfma_f32_16x16x32_bf16 v[52:55], v[166:169], v[190:193], v[52:55]
	v_mfma_f32_16x16x32_bf16 v[48:51], v[182:185], v[190:193], v[48:51]
	v_mfma_f32_16x16x32_bf16 v[36:39], v[166:169], v[198:201], v[36:39]
	v_mfma_f32_16x16x32_bf16 v[32:35], v[182:185], v[198:201], v[32:35]
	s_setprio 2
	s_barrier
	v_mfma_f32_16x16x32_bf16 v[20:23], v[166:169], v[206:209], v[20:23]
	v_mfma_f32_16x16x32_bf16 v[16:19], v[182:185], v[206:209], v[16:19]
	v_mfma_f32_16x16x32_bf16 v[4:7], v[166:169], v[228:231], v[4:7]
	v_mfma_f32_16x16x32_bf16 v[0:3], v[182:185], v[228:231], v[0:3]
	s_setprio 0
	s_add_i32 s63, s63, 2
	s_add_u32 s44, s44, 0x100
	s_addc_u32 s62, s62, 0
	s_add_u32 s22, s22, 0x100
	s_addc_u32 s23, s23, 0
	s_cmp_gt_u32 s63, 13
	s_cbranch_scc1 .Lpeel_exit_0
.LBB0_319:
	s_add_u32 s24, s22, 0xfffc0080
	s_addc_u32 s25, s23, -1
	s_add_i32 s64, 0, 0x10000
	s_cmp_eq_u32 s63, 12
	s_cselect_b32 s27, s9, s25
	s_cselect_b32 s26, s15, s24
	s_cselect_b32 s25, s13, s62
	s_cselect_b32 s24, s21, s44
	s_add_i32 s68, 0, 0x14000
	v_add_u32_e32 v112, s64, v159
	v_add_u32_e32 v165, s68, v159
	ds_read_b128 v[96:99], v112
	ds_read_b128 v[100:103], v112 offset:1024
	ds_read_b128 v[108:111], v112 offset:2048
	ds_read_b128 v[112:115], v112 offset:3072
	ds_read_b128 v[154:157], v165
	ds_read_b128 v[166:169], v165 offset:1024
	ds_read_b128 v[170:173], v165 offset:2048
	ds_read_b128 v[182:185], v165 offset:3072
	s_add_i32 m0, s50, 0xc000
	ds_read_b128 v[186:189], v164
	ds_read_b128 v[190:193], v164 offset:1024
	ds_read_b128 v[194:197], v164 offset:2048
	ds_read_b128 v[198:201], v164 offset:3072
	ds_read_b128 v[202:205], v164 offset:4096
	ds_read_b128 v[206:209], v164 offset:5120
	ds_read_b128 v[210:213], v164 offset:6144
	ds_read_b128 v[228:231], v164 offset:7168
	global_load_lds_dwordx4 v152, s[22:23]
	s_add_i32 m0, s50, 0xe000
	s_nop 0
	global_load_lds_dwordx4 v150, s[22:23]
	s_waitcnt vmcnt(8) lgkmcnt(0)
	s_barrier
	s_setprio 1
	v_mfma_f32_16x16x32_bf16 v[140:143], v[96:99], v[186:189], v[140:143]
	v_mfma_f32_16x16x32_bf16 v[136:139], v[108:111], v[186:189], v[136:139]
	v_mfma_f32_16x16x32_bf16 v[124:127], v[96:99], v[194:197], v[124:127]
	v_mfma_f32_16x16x32_bf16 v[120:123], v[108:111], v[194:197], v[120:123]
	v_mfma_f32_16x16x32_bf16 v[92:95], v[96:99], v[202:205], v[92:95]
	v_mfma_f32_16x16x32_bf16 v[88:91], v[108:111], v[202:205], v[88:91]
	v_mfma_f32_16x16x32_bf16 v[76:79], v[96:99], v[210:213], v[76:79]
	v_mfma_f32_16x16x32_bf16 v[72:75], v[108:111], v[210:213], v[72:75]
	v_mfma_f32_16x16x32_bf16 v[140:143], v[100:103], v[190:193], v[140:143]
	v_mfma_f32_16x16x32_bf16 v[136:139], v[112:115], v[190:193], v[136:139]
	v_mfma_f32_16x16x32_bf16 v[124:127], v[100:103], v[198:201], v[124:127]
	v_mfma_f32_16x16x32_bf16 v[120:123], v[112:115], v[198:201], v[120:123]
	v_mfma_f32_16x16x32_bf16 v[92:95], v[100:103], v[206:209], v[92:95]
	v_mfma_f32_16x16x32_bf16 v[88:91], v[112:115], v[206:209], v[88:91]
	v_mfma_f32_16x16x32_bf16 v[76:79], v[100:103], v[228:231], v[76:79]
	v_mfma_f32_16x16x32_bf16 v[72:75], v[112:115], v[228:231], v[72:75]
	v_mfma_f32_16x16x32_bf16 v[132:135], v[154:157], v[186:189], v[132:135]
	v_mfma_f32_16x16x32_bf16 v[128:131], v[170:173], v[186:189], v[128:131]
	v_mfma_f32_16x16x32_bf16 v[116:119], v[154:157], v[194:197], v[116:119]
	v_mfma_f32_16x16x32_bf16 v[104:107], v[170:173], v[194:197], v[104:107]
	v_mfma_f32_16x16x32_bf16 v[84:87], v[154:157], v[202:205], v[84:87]
	v_mfma_f32_16x16x32_bf16 v[80:83], v[170:173], v[202:205], v[80:83]
	v_mfma_f32_16x16x32_bf16 v[68:71], v[154:157], v[210:213], v[68:71]
	v_mfma_f32_16x16x32_bf16 v[64:67], v[170:173], v[210:213], v[64:67]
	v_mfma_f32_16x16x32_bf16 v[132:135], v[166:169], v[190:193], v[132:135]
	v_mfma_f32_16x16x32_bf16 v[128:131], v[182:185], v[190:193], v[128:131]
	v_mfma_f32_16x16x32_bf16 v[116:119], v[166:169], v[198:201], v[116:119]
	v_mfma_f32_16x16x32_bf16 v[104:107], v[182:185], v[198:201], v[104:107]
	s_setprio 2
	s_barrier
	v_mfma_f32_16x16x32_bf16 v[84:87], v[166:169], v[206:209], v[84:87]
	v_mfma_f32_16x16x32_bf16 v[80:83], v[182:185], v[206:209], v[80:83]
	v_mfma_f32_16x16x32_bf16 v[68:71], v[166:169], v[228:231], v[68:71]
	v_mfma_f32_16x16x32_bf16 v[64:67], v[182:185], v[228:231], v[64:67]
	s_setprio 0
	s_add_i32 s64, s64, s43
	s_add_u32 s94, s24, s34
	s_addc_u32 s95, s25, s35
	s_mov_b32 m0, s64
	ds_read_b128 v[186:189], v164 offset:16384
	ds_read_b128 v[190:193], v164 offset:17408
	ds_read_b128 v[194:197], v164 offset:18432
	ds_read_b128 v[198:201], v164 offset:19456
	ds_read_b128 v[202:205], v164 offset:20480
	ds_read_b128 v[206:209], v164 offset:21504
	ds_read_b128 v[210:213], v164 offset:22528
	ds_read_b128 v[228:231], v164 offset:23552
	global_load_lds_dwordx4 v176, s[24:25]
	s_add_i32 m0, s64, 0x2000
	s_add_u32 s64, s24, 0x40000
	s_addc_u32 s65, s25, 0
	s_add_i32 s68, s68, s43
	global_load_lds_dwordx4 v148, s[24:25]
	s_mov_b32 m0, s68
	s_nop 0
	global_load_lds_dwordx4 v176, s[64:65]
	s_add_i32 m0, s68, 0x2000
	s_nop 0
	global_load_lds_dwordx4 v148, s[64:65]
	s_add_u32 s98, s26, s34
	s_addc_u32 s99, s27, s35
	s_mov_b32 m0, s50
	s_nop 0
	global_load_lds_dwordx4 v144, s[26:27]
	s_mov_b32 m0, s51
	s_nop 0
	global_load_lds_dwordx4 v146, s[26:27]
	s_waitcnt vmcnt(8) lgkmcnt(0)
	s_barrier
	s_setprio 1
	v_mfma_f32_16x16x32_bf16 v[60:63], v[96:99], v[186:189], v[60:63]
	v_mfma_f32_16x16x32_bf16 v[56:59], v[108:111], v[186:189], v[56:59]
	v_mfma_f32_16x16x32_bf16 v[44:47], v[96:99], v[194:197], v[44:47]
	v_mfma_f32_16x16x32_bf16 v[40:43], v[108:111], v[194:197], v[40:43]
	v_mfma_f32_16x16x32_bf16 v[28:31], v[96:99], v[202:205], v[28:31]
	v_mfma_f32_16x16x32_bf16 v[24:27], v[108:111], v[202:205], v[24:27]
	v_mfma_f32_16x16x32_bf16 v[12:15], v[96:99], v[210:213], v[12:15]
	v_mfma_f32_16x16x32_bf16 v[8:11], v[108:111], v[210:213], v[8:11]
	v_mfma_f32_16x16x32_bf16 v[60:63], v[100:103], v[190:193], v[60:63]
	v_mfma_f32_16x16x32_bf16 v[56:59], v[112:115], v[190:193], v[56:59]
	v_mfma_f32_16x16x32_bf16 v[44:47], v[100:103], v[198:201], v[44:47]
	v_mfma_f32_16x16x32_bf16 v[40:43], v[112:115], v[198:201], v[40:43]
	v_mfma_f32_16x16x32_bf16 v[28:31], v[100:103], v[206:209], v[28:31]
	v_mfma_f32_16x16x32_bf16 v[24:27], v[112:115], v[206:209], v[24:27]
	v_mfma_f32_16x16x32_bf16 v[12:15], v[100:103], v[228:231], v[12:15]
	v_mfma_f32_16x16x32_bf16 v[8:11], v[112:115], v[228:231], v[8:11]
	v_mfma_f32_16x16x32_bf16 v[52:55], v[154:157], v[186:189], v[52:55]
	v_mfma_f32_16x16x32_bf16 v[48:51], v[170:173], v[186:189], v[48:51]
	v_mfma_f32_16x16x32_bf16 v[36:39], v[154:157], v[194:197], v[36:39]
	v_mfma_f32_16x16x32_bf16 v[32:35], v[170:173], v[194:197], v[32:35]
	v_mfma_f32_16x16x32_bf16 v[20:23], v[154:157], v[202:205], v[20:23]
	v_mfma_f32_16x16x32_bf16 v[16:19], v[170:173], v[202:205], v[16:19]
	v_mfma_f32_16x16x32_bf16 v[4:7], v[154:157], v[210:213], v[4:7]
	v_mfma_f32_16x16x32_bf16 v[0:3], v[170:173], v[210:213], v[0:3]
	v_mfma_f32_16x16x32_bf16 v[52:55], v[166:169], v[190:193], v[52:55]
	v_mfma_f32_16x16x32_bf16 v[48:51], v[182:185], v[190:193], v[48:51]
	v_mfma_f32_16x16x32_bf16 v[36:39], v[166:169], v[198:201], v[36:39]
	v_mfma_f32_16x16x32_bf16 v[32:35], v[182:185], v[198:201], v[32:35]
	s_setprio 2
	s_barrier
	v_mfma_f32_16x16x32_bf16 v[20:23], v[166:169], v[206:209], v[20:23]
	v_mfma_f32_16x16x32_bf16 v[16:19], v[182:185], v[206:209], v[16:19]
	v_mfma_f32_16x16x32_bf16 v[4:7], v[166:169], v[228:231], v[4:7]
	v_mfma_f32_16x16x32_bf16 v[0:3], v[182:185], v[228:231], v[0:3]
	s_setprio 0
	s_add_i32 s64, 0, 0x18000
	s_add_i32 s65, 0, 0x1c000
	v_add_u32_e32 v112, s64, v159
	v_add_u32_e32 v165, s65, v159
	ds_read_b128 v[96:99], v112
	ds_read_b128 v[100:103], v112 offset:1024
	ds_read_b128 v[108:111], v112 offset:2048
	ds_read_b128 v[112:115], v112 offset:3072
	ds_read_b128 v[154:157], v165
	ds_read_b128 v[166:169], v165 offset:1024
	ds_read_b128 v[170:173], v165 offset:2048
	ds_read_b128 v[182:185], v165 offset:3072
	s_add_u32 s26, s26, 0x40000
	s_addc_u32 s27, s27, 0
	s_mov_b32 m0, s52
	ds_read_b128 v[186:189], v164 offset:32768
	ds_read_b128 v[190:193], v164 offset:33792
	ds_read_b128 v[194:197], v164 offset:34816
	ds_read_b128 v[198:201], v164 offset:35840
	ds_read_b128 v[202:205], v164 offset:36864
	ds_read_b128 v[206:209], v164 offset:37888
	ds_read_b128 v[210:213], v164 offset:38912
	ds_read_b128 v[228:231], v164 offset:39936
	global_load_lds_dwordx4 v144, s[26:27]
	s_mov_b32 m0, s53
	s_nop 0
	global_load_lds_dwordx4 v146, s[26:27]
	s_waitcnt vmcnt(8) lgkmcnt(0)
	s_barrier
	s_setprio 1
	v_mfma_f32_16x16x32_bf16 v[140:143], v[96:99], v[186:189], v[140:143]
	v_mfma_f32_16x16x32_bf16 v[136:139], v[108:111], v[186:189], v[136:139]
	v_mfma_f32_16x16x32_bf16 v[124:127], v[96:99], v[194:197], v[124:127]
	v_mfma_f32_16x16x32_bf16 v[120:123], v[108:111], v[194:197], v[120:123]
	v_mfma_f32_16x16x32_bf16 v[92:95], v[96:99], v[202:205], v[92:95]
	v_mfma_f32_16x16x32_bf16 v[88:91], v[108:111], v[202:205], v[88:91]
	v_mfma_f32_16x16x32_bf16 v[76:79], v[96:99], v[210:213], v[76:79]
	v_mfma_f32_16x16x32_bf16 v[72:75], v[108:111], v[210:213], v[72:75]
	v_mfma_f32_16x16x32_bf16 v[140:143], v[100:103], v[190:193], v[140:143]
	v_mfma_f32_16x16x32_bf16 v[136:139], v[112:115], v[190:193], v[136:139]
	v_mfma_f32_16x16x32_bf16 v[124:127], v[100:103], v[198:201], v[124:127]
	v_mfma_f32_16x16x32_bf16 v[120:123], v[112:115], v[198:201], v[120:123]
	v_mfma_f32_16x16x32_bf16 v[92:95], v[100:103], v[206:209], v[92:95]
	v_mfma_f32_16x16x32_bf16 v[88:91], v[112:115], v[206:209], v[88:91]
	v_mfma_f32_16x16x32_bf16 v[76:79], v[100:103], v[228:231], v[76:79]
	v_mfma_f32_16x16x32_bf16 v[72:75], v[112:115], v[228:231], v[72:75]
	v_mfma_f32_16x16x32_bf16 v[132:135], v[154:157], v[186:189], v[132:135]
	v_mfma_f32_16x16x32_bf16 v[128:131], v[170:173], v[186:189], v[128:131]
	v_mfma_f32_16x16x32_bf16 v[116:119], v[154:157], v[194:197], v[116:119]
	v_mfma_f32_16x16x32_bf16 v[104:107], v[170:173], v[194:197], v[104:107]
	v_mfma_f32_16x16x32_bf16 v[84:87], v[154:157], v[202:205], v[84:87]
	v_mfma_f32_16x16x32_bf16 v[80:83], v[170:173], v[202:205], v[80:83]
	v_mfma_f32_16x16x32_bf16 v[68:71], v[154:157], v[210:213], v[68:71]
	v_mfma_f32_16x16x32_bf16 v[64:67], v[170:173], v[210:213], v[64:67]
	v_mfma_f32_16x16x32_bf16 v[132:135], v[166:169], v[190:193], v[132:135]
	v_mfma_f32_16x16x32_bf16 v[128:131], v[182:185], v[190:193], v[128:131]
	v_mfma_f32_16x16x32_bf16 v[116:119], v[166:169], v[198:201], v[116:119]
	v_mfma_f32_16x16x32_bf16 v[104:107], v[182:185], v[198:201], v[104:107]
	s_setprio 2
	s_barrier
	v_mfma_f32_16x16x32_bf16 v[84:87], v[166:169], v[206:209], v[84:87]
	v_mfma_f32_16x16x32_bf16 v[80:83], v[182:185], v[206:209], v[80:83]
	v_mfma_f32_16x16x32_bf16 v[68:71], v[166:169], v[228:231], v[68:71]
	v_mfma_f32_16x16x32_bf16 v[64:67], v[182:185], v[228:231], v[64:67]
	s_setprio 0
	s_add_i32 s26, s64, s43
	s_mov_b32 m0, s26
	ds_read_b128 v[186:189], v164 offset:49152
	ds_read_b128 v[190:193], v164 offset:50176
	ds_read_b128 v[194:197], v164 offset:51200
	ds_read_b128 v[198:201], v164 offset:52224
	ds_read_b128 v[202:205], v164 offset:53248
	ds_read_b128 v[206:209], v164 offset:54272
	ds_read_b128 v[210:213], v164 offset:55296
	ds_read_b128 v[228:231], v164 offset:56320
	global_load_lds_dwordx4 v176, s[94:95]
	s_add_i32 m0, s26, 0x2000
	s_add_u32 s24, s24, 0x40080
	s_addc_u32 s25, s25, 0
	s_add_i32 s26, s65, s43
	global_load_lds_dwordx4 v148, s[94:95]
	s_mov_b32 m0, s26
	s_nop 0
	global_load_lds_dwordx4 v176, s[24:25]
	s_add_i32 m0, s26, 0x2000
	s_nop 0
	global_load_lds_dwordx4 v148, s[24:25]
	s_mov_b32 m0, s57
	s_nop 0
	global_load_lds_dwordx4 v144, s[98:99]
	s_mov_b32 m0, s58
	s_nop 0
	global_load_lds_dwordx4 v146, s[98:99]
	s_waitcnt vmcnt(8) lgkmcnt(0)
	s_barrier
	s_setprio 1
	v_mfma_f32_16x16x32_bf16 v[60:63], v[96:99], v[186:189], v[60:63]
	v_mfma_f32_16x16x32_bf16 v[56:59], v[108:111], v[186:189], v[56:59]
	v_mfma_f32_16x16x32_bf16 v[44:47], v[96:99], v[194:197], v[44:47]
	v_mfma_f32_16x16x32_bf16 v[40:43], v[108:111], v[194:197], v[40:43]
	v_mfma_f32_16x16x32_bf16 v[28:31], v[96:99], v[202:205], v[28:31]
	v_mfma_f32_16x16x32_bf16 v[24:27], v[108:111], v[202:205], v[24:27]
	v_mfma_f32_16x16x32_bf16 v[12:15], v[96:99], v[210:213], v[12:15]
	v_mfma_f32_16x16x32_bf16 v[8:11], v[108:111], v[210:213], v[8:11]
	v_mfma_f32_16x16x32_bf16 v[60:63], v[100:103], v[190:193], v[60:63]
	v_mfma_f32_16x16x32_bf16 v[56:59], v[112:115], v[190:193], v[56:59]
	v_mfma_f32_16x16x32_bf16 v[44:47], v[100:103], v[198:201], v[44:47]
	v_mfma_f32_16x16x32_bf16 v[40:43], v[112:115], v[198:201], v[40:43]
	v_mfma_f32_16x16x32_bf16 v[28:31], v[100:103], v[206:209], v[28:31]
	v_mfma_f32_16x16x32_bf16 v[24:27], v[112:115], v[206:209], v[24:27]
	v_mfma_f32_16x16x32_bf16 v[12:15], v[100:103], v[228:231], v[12:15]
	v_mfma_f32_16x16x32_bf16 v[8:11], v[112:115], v[228:231], v[8:11]
	v_mfma_f32_16x16x32_bf16 v[52:55], v[154:157], v[186:189], v[52:55]
	v_mfma_f32_16x16x32_bf16 v[48:51], v[170:173], v[186:189], v[48:51]
	v_mfma_f32_16x16x32_bf16 v[36:39], v[154:157], v[194:197], v[36:39]
	v_mfma_f32_16x16x32_bf16 v[32:35], v[170:173], v[194:197], v[32:35]
	v_mfma_f32_16x16x32_bf16 v[20:23], v[154:157], v[202:205], v[20:23]
	v_mfma_f32_16x16x32_bf16 v[16:19], v[170:173], v[202:205], v[16:19]
	v_mfma_f32_16x16x32_bf16 v[4:7], v[154:157], v[210:213], v[4:7]
	v_mfma_f32_16x16x32_bf16 v[0:3], v[170:173], v[210:213], v[0:3]
	v_mfma_f32_16x16x32_bf16 v[52:55], v[166:169], v[190:193], v[52:55]
	v_mfma_f32_16x16x32_bf16 v[48:51], v[182:185], v[190:193], v[48:51]
	v_mfma_f32_16x16x32_bf16 v[36:39], v[166:169], v[198:201], v[36:39]
	v_mfma_f32_16x16x32_bf16 v[32:35], v[182:185], v[198:201], v[32:35]
	s_setprio 2
	s_barrier
	v_mfma_f32_16x16x32_bf16 v[20:23], v[166:169], v[206:209], v[20:23]
	v_mfma_f32_16x16x32_bf16 v[16:19], v[182:185], v[206:209], v[16:19]
	v_mfma_f32_16x16x32_bf16 v[4:7], v[166:169], v[228:231], v[4:7]
	v_mfma_f32_16x16x32_bf16 v[0:3], v[182:185], v[228:231], v[0:3]
	s_setprio 0
	s_add_i32 s63, s63, 2
	s_add_u32 s44, s44, 0x100
	s_addc_u32 s62, s62, 0
	s_add_u32 s22, s22, 0x100
	s_addc_u32 s23, s23, 0
	s_cmp_gt_u32 s63, 13
	s_cbranch_scc0 .LBB0_319

.LBB0_360:
	ds_read_b32 v0, v214
	s_waitcnt lgkmcnt(0)
	v_readfirstlane_b32 s43, v0
	ds_read_b32 v0, v215
	s_getreg_b32 s0, hwreg(HW_REG_XCC_ID, 0, 4)
	s_waitcnt vmcnt(0) lgkmcnt(0)
	s_barrier
	v_readfirstlane_b32 s44, v0
	s_mov_b64 s[38:39], exec
	v_readlane_b32 s2, v255, 0
	v_readlane_b32 s3, v255, 1
	s_and_b64 s[2:3], s[38:39], s[2:3]
	s_mov_b64 exec, s[2:3]
	s_cbranch_execz .LBB0_404
	s_waitcnt vmcnt(0) expcnt(0) lgkmcnt(0)
	buffer_inv sc1
	ds_read_b32 v2, v217
	ds_read_b32 v0, v218
	s_and_b32 s62, s0, 15
	s_waitcnt lgkmcnt(1)
	v_cmp_ne_u32_e32 vcc, 0, v2
	s_cbranch_vccnz .LBB0_375
	s_add_u32 s0, s43, 0x600200
	s_addc_u32 s1, s44, 0
	s_add_u32 s2, s43, 0x600400
	s_addc_u32 s3, s44, 0
	s_add_u32 s4, s43, 0x600500
	s_addc_u32 s5, s44, 0
	s_add_u32 s6, s43, 0x600600
	s_addc_u32 s7, s44, 0
	s_add_u32 s8, s43, 0x600700
	s_addc_u32 s9, s44, 0
	s_add_u32 s10, s43, 0x600800
	s_addc_u32 s11, s44, 0
	s_add_u32 s12, s43, 0x600900
	s_addc_u32 s13, s44, 0
	s_add_u32 s14, s43, 0x600a00
	s_addc_u32 s15, s44, 0
	s_add_u32 s16, s43, 0x600b00
	s_addc_u32 s17, s44, 0
	s_add_u32 s18, s43, 0x600c00
	s_addc_u32 s19, s44, 0
	s_add_u32 s20, s43, 0x600d00
	s_addc_u32 s21, s44, 0
	s_add_u32 s22, s43, 0x600e00
	s_addc_u32 s23, s44, 0
	s_add_u32 s24, s43, 0x600f00
	s_addc_u32 s25, s44, 0
	s_add_u32 s26, s43, 0x601000
	s_addc_u32 s27, s44, 0
	s_add_u32 s28, s43, 0x601100
	s_addc_u32 s29, s44, 0
	s_add_u32 s50, s43, 0x601200
	s_addc_u32 s51, s44, 0
	s_add_u32 s52, s43, 0x601300
	s_addc_u32 s53, s44, 0
	s_mov_b32 s63, 1
	s_mov_b64 s[54:55], 0
	s_branch .LBB0_365

.LBB0_412:
	s_ashr_i32 s11, s10, 31
	s_lshl_b64 s[12:13], s[10:11], 18
	s_add_u32 s12, s48, s12
	s_addc_u32 s13, s49, s13
	s_and_b64 s[14:15], s[2:3], exec
	s_cselect_b32 s27, s13, s21
	s_cselect_b32 s26, s12, s20
	s_ashr_i32 s9, s8, 31
	s_lshl_b64 s[14:15], s[8:9], 17
	s_add_u32 s14, s38, s14
	s_addc_u32 s15, s39, s15
	s_and_b64 s[24:25], s[2:3], exec
	s_cselect_b32 s25, s15, s23
	s_cselect_b32 s24, s14, s22
	s_add_i32 s11, 0, 0x10000
	s_add_i32 s17, 0, 0x14000
	v_add_u32_e32 v175, s11, v141
	v_add_u32_e32 v178, s17, v141
	ds_read_b128 v[0:3], v175
	ds_read_b128 v[4:7], v175 offset:1024
	ds_read_b128 v[8:11], v175 offset:2048
	ds_read_b128 v[12:15], v175 offset:3072
	ds_read_b128 v[16:19], v178
	ds_read_b128 v[20:23], v178 offset:1024
	ds_read_b128 v[24:27], v178 offset:2048
	ds_read_b128 v[28:31], v178 offset:3072
	s_add_u32 s58, s20, 0x20080
	s_addc_u32 s59, s21, 0
	s_add_i32 s62, s19, 0xc000
	v_lshl_add_u64 v[64:65], s[58:59], 0, v[132:133]
	s_mov_b32 m0, s62
	s_add_i32 s9, s19, 0xe000
	ds_read_b128 v[32:35], v143
	ds_read_b128 v[36:39], v143 offset:1024
	ds_read_b128 v[40:43], v143 offset:2048
	ds_read_b128 v[44:47], v143 offset:3072
	ds_read_b128 v[48:51], v143 offset:4096
	ds_read_b128 v[52:55], v143 offset:5120
	ds_read_b128 v[56:59], v143 offset:6144
	ds_read_b128 v[60:63], v143 offset:7168
	global_load_lds_dwordx4 v[64:65], off
	v_lshl_add_u64 v[64:65], s[58:59], 0, v[130:131]
	s_mov_b32 m0, s9
	s_nop 0
	global_load_lds_dwordx4 v[64:65], off
	s_waitcnt vmcnt(8) lgkmcnt(0)
	s_barrier
	s_setprio 1
	v_mfma_f32_16x16x32_bf16 v[64:67], v[0:3], v[32:35], 0
	v_mfma_f32_16x16x32_bf16 v[68:71], v[8:11], v[32:35], 0
	v_mfma_f32_16x16x32_bf16 v[72:75], v[0:3], v[40:43], 0
	v_mfma_f32_16x16x32_bf16 v[76:79], v[8:11], v[40:43], 0
	v_mfma_f32_16x16x32_bf16 v[80:83], v[0:3], v[48:51], 0
	v_mfma_f32_16x16x32_bf16 v[84:87], v[8:11], v[48:51], 0
	v_mfma_f32_16x16x32_bf16 v[88:91], v[0:3], v[56:59], 0
	v_mfma_f32_16x16x32_bf16 v[92:95], v[8:11], v[56:59], 0
	v_mfma_f32_16x16x32_bf16 v[64:67], v[4:7], v[36:39], v[64:67]
	v_mfma_f32_16x16x32_bf16 v[68:71], v[12:15], v[36:39], v[68:71]
	v_mfma_f32_16x16x32_bf16 v[72:75], v[4:7], v[44:47], v[72:75]
	v_mfma_f32_16x16x32_bf16 v[76:79], v[12:15], v[44:47], v[76:79]
	v_mfma_f32_16x16x32_bf16 v[80:83], v[4:7], v[52:55], v[80:83]
	v_mfma_f32_16x16x32_bf16 v[84:87], v[12:15], v[52:55], v[84:87]
	v_mfma_f32_16x16x32_bf16 v[88:91], v[4:7], v[60:63], v[88:91]
	v_mfma_f32_16x16x32_bf16 v[92:95], v[12:15], v[60:63], v[92:95]
	v_mfma_f32_16x16x32_bf16 v[96:99], v[16:19], v[32:35], 0
	v_mfma_f32_16x16x32_bf16 v[32:35], v[24:27], v[32:35], 0
	v_mfma_f32_16x16x32_bf16 v[96:99], v[20:23], v[36:39], v[96:99]
	v_mfma_f32_16x16x32_bf16 v[32:35], v[28:31], v[36:39], v[32:35]
	v_mfma_f32_16x16x32_bf16 v[36:39], v[16:19], v[40:43], 0
	v_mfma_f32_16x16x32_bf16 v[40:43], v[24:27], v[40:43], 0
	v_mfma_f32_16x16x32_bf16 v[36:39], v[20:23], v[44:47], v[36:39]
	v_mfma_f32_16x16x32_bf16 v[40:43], v[28:31], v[44:47], v[40:43]
	v_mfma_f32_16x16x32_bf16 v[44:47], v[16:19], v[48:51], 0
	v_mfma_f32_16x16x32_bf16 v[48:51], v[24:27], v[48:51], 0
	v_mfma_f32_16x16x32_bf16 v[44:47], v[20:23], v[52:55], v[44:47]
	v_mfma_f32_16x16x32_bf16 v[48:51], v[28:31], v[52:55], v[48:51]
	s_setprio 2
	s_barrier
	v_mfma_f32_16x16x32_bf16 v[52:55], v[16:19], v[56:59], 0
	v_mfma_f32_16x16x32_bf16 v[56:59], v[24:27], v[56:59], 0
	v_mfma_f32_16x16x32_bf16 v[52:55], v[20:23], v[60:63], v[52:55]
	v_mfma_f32_16x16x32_bf16 v[56:59], v[28:31], v[60:63], v[56:59]
	s_setprio 0
	s_add_i32 s58, s11, s43
	v_lshl_add_u64 v[138:139], s[22:23], 0, v[176:177]
	s_mov_b64 s[68:69], 0x100
	s_add_i32 s11, s58, 0x2000
	v_lshl_add_u64 v[134:135], v[138:139], 0, s[68:69]
	s_mov_b32 m0, s58
	v_lshl_add_u64 v[172:173], s[22:23], 0, v[128:129]
	s_add_u32 s64, s22, 0x10100
	ds_read_b128 v[60:63], v143 offset:16384
	ds_read_b128 v[100:103], v143 offset:17408
	ds_read_b128 v[104:107], v143 offset:18432
	ds_read_b128 v[108:111], v143 offset:19456
	ds_read_b128 v[112:115], v143 offset:20480
	ds_read_b128 v[116:119], v143 offset:21504
	ds_read_b128 v[120:123], v143 offset:22528
	ds_read_b128 v[124:127], v143 offset:23552
	global_load_lds_dwordx4 v[134:135], off
	v_lshl_add_u64 v[134:135], v[172:173], 0, s[68:69]
	s_mov_b32 m0, s11
	s_addc_u32 s65, s23, 0
	s_add_i32 s17, s17, s43
	global_load_lds_dwordx4 v[134:135], off
	v_lshl_add_u64 v[134:135], s[64:65], 0, v[176:177]
	s_mov_b32 m0, s17
	s_add_i32 s57, s17, 0x2000
	global_load_lds_dwordx4 v[134:135], off
	v_lshl_add_u64 v[134:135], s[64:65], 0, v[128:129]
	s_mov_b32 m0, s57
	v_lshl_add_u64 v[220:221], s[20:21], 0, v[132:133]
	global_load_lds_dwordx4 v[134:135], off
	v_lshl_add_u64 v[134:135], v[220:221], 0, s[68:69]
	s_mov_b32 m0, s19
	v_lshl_add_u64 v[222:223], s[20:21], 0, v[130:131]
	global_load_lds_dwordx4 v[134:135], off
	v_lshl_add_u64 v[134:135], v[222:223], 0, s[68:69]
	s_mov_b32 m0, s51
	s_nop 0
	global_load_lds_dwordx4 v[134:135], off
	s_waitcnt vmcnt(8) lgkmcnt(0)
	s_barrier
	s_setprio 1
	v_mfma_f32_16x16x32_bf16 v[134:137], v[0:3], v[60:63], 0
	v_mfma_f32_16x16x32_bf16 v[148:151], v[0:3], v[104:107], 0
	v_mfma_f32_16x16x32_bf16 v[156:159], v[0:3], v[112:115], 0
	v_mfma_f32_16x16x32_bf16 v[0:3], v[0:3], v[120:123], 0
	v_mfma_f32_16x16x32_bf16 v[134:137], v[4:7], v[100:103], v[134:137]
	v_mfma_f32_16x16x32_bf16 v[148:151], v[4:7], v[108:111], v[148:151]
	v_mfma_f32_16x16x32_bf16 v[156:159], v[4:7], v[116:119], v[156:159]
	v_mfma_f32_16x16x32_bf16 v[0:3], v[4:7], v[124:127], v[0:3]
	v_mfma_f32_16x16x32_bf16 v[4:7], v[8:11], v[120:123], 0
	v_mfma_f32_16x16x32_bf16 v[144:147], v[8:11], v[60:63], 0
	v_mfma_f32_16x16x32_bf16 v[152:155], v[8:11], v[104:107], 0
	v_mfma_f32_16x16x32_bf16 v[160:163], v[8:11], v[112:115], 0
	v_mfma_f32_16x16x32_bf16 v[4:7], v[12:15], v[124:127], v[4:7]
	v_mfma_f32_16x16x32_bf16 v[144:147], v[12:15], v[100:103], v[144:147]
	v_mfma_f32_16x16x32_bf16 v[152:155], v[12:15], v[108:111], v[152:155]
	v_mfma_f32_16x16x32_bf16 v[160:163], v[12:15], v[116:119], v[160:163]
	v_mfma_f32_16x16x32_bf16 v[8:11], v[16:19], v[60:63], 0
	v_mfma_f32_16x16x32_bf16 v[12:15], v[24:27], v[60:63], 0
	v_mfma_f32_16x16x32_bf16 v[8:11], v[20:23], v[100:103], v[8:11]
	v_mfma_f32_16x16x32_bf16 v[12:15], v[28:31], v[100:103], v[12:15]
	v_mfma_f32_16x16x32_bf16 v[60:63], v[16:19], v[104:107], 0
	v_mfma_f32_16x16x32_bf16 v[100:103], v[24:27], v[104:107], 0
	v_mfma_f32_16x16x32_bf16 v[104:107], v[16:19], v[112:115], 0
	v_mfma_f32_16x16x32_bf16 v[16:19], v[16:19], v[120:123], 0
	v_mfma_f32_16x16x32_bf16 v[60:63], v[20:23], v[108:111], v[60:63]
	v_mfma_f32_16x16x32_bf16 v[100:103], v[28:31], v[108:111], v[100:103]
	v_mfma_f32_16x16x32_bf16 v[104:107], v[20:23], v[116:119], v[104:107]
	v_mfma_f32_16x16x32_bf16 v[108:111], v[24:27], v[112:115], 0
	s_setprio 2
	s_barrier
	v_mfma_f32_16x16x32_bf16 v[16:19], v[20:23], v[124:127], v[16:19]
	v_mfma_f32_16x16x32_bf16 v[20:23], v[24:27], v[120:123], 0
	v_mfma_f32_16x16x32_bf16 v[108:111], v[28:31], v[116:119], v[108:111]
	v_mfma_f32_16x16x32_bf16 v[20:23], v[28:31], v[124:127], v[20:23]
	s_setprio 0
	s_add_i32 s63, 0, 0x18000
	s_add_i32 s68, 0, 0x1c000
	v_add_u32_e32 v179, s63, v141
	v_add_u32_e32 v232, s68, v141
	ds_read_b128 v[24:27], v179
	ds_read_b128 v[28:31], v179 offset:1024
	ds_read_b128 v[112:115], v179 offset:2048
	ds_read_b128 v[116:119], v179 offset:3072
	ds_read_b128 v[120:123], v232
	ds_read_b128 v[124:127], v232 offset:1024
	ds_read_b128 v[164:167], v232 offset:2048
	ds_read_b128 v[168:171], v232 offset:3072
	s_add_u32 s64, s20, 0x20100
	s_addc_u32 s65, s21, 0
	s_mov_b32 m0, s52
	v_lshl_add_u64 v[226:227], s[64:65], 0, v[132:133]
	ds_read_b128 v[182:185], v143 offset:32768
	ds_read_b128 v[186:189], v143 offset:33792
	ds_read_b128 v[190:193], v143 offset:34816
	ds_read_b128 v[194:197], v143 offset:35840
	ds_read_b128 v[198:201], v143 offset:36864
	ds_read_b128 v[202:205], v143 offset:37888
	ds_read_b128 v[206:209], v143 offset:38912
	ds_read_b128 v[210:213], v143 offset:39936
	global_load_lds_dwordx4 v[226:227], off
	v_lshl_add_u64 v[226:227], s[64:65], 0, v[130:131]
	s_mov_b32 m0, s53
	s_nop 0
	global_load_lds_dwordx4 v[226:227], off
	s_waitcnt vmcnt(8) lgkmcnt(0)
	s_barrier
	s_setprio 1
	v_mfma_f32_16x16x32_bf16 v[64:67], v[24:27], v[182:185], v[64:67]
	v_mfma_f32_16x16x32_bf16 v[68:71], v[112:115], v[182:185], v[68:71]
	v_mfma_f32_16x16x32_bf16 v[72:75], v[24:27], v[190:193], v[72:75]
	v_mfma_f32_16x16x32_bf16 v[76:79], v[112:115], v[190:193], v[76:79]
	v_mfma_f32_16x16x32_bf16 v[80:83], v[24:27], v[198:201], v[80:83]
	v_mfma_f32_16x16x32_bf16 v[84:87], v[112:115], v[198:201], v[84:87]
	v_mfma_f32_16x16x32_bf16 v[88:91], v[24:27], v[206:209], v[88:91]
	v_mfma_f32_16x16x32_bf16 v[92:95], v[112:115], v[206:209], v[92:95]
	v_mfma_f32_16x16x32_bf16 v[64:67], v[28:31], v[186:189], v[64:67]
	v_mfma_f32_16x16x32_bf16 v[68:71], v[116:119], v[186:189], v[68:71]
	v_mfma_f32_16x16x32_bf16 v[72:75], v[28:31], v[194:197], v[72:75]
	v_mfma_f32_16x16x32_bf16 v[76:79], v[116:119], v[194:197], v[76:79]
	v_mfma_f32_16x16x32_bf16 v[80:83], v[28:31], v[202:205], v[80:83]
	v_mfma_f32_16x16x32_bf16 v[84:87], v[116:119], v[202:205], v[84:87]
	v_mfma_f32_16x16x32_bf16 v[88:91], v[28:31], v[210:213], v[88:91]
	v_mfma_f32_16x16x32_bf16 v[92:95], v[116:119], v[210:213], v[92:95]
	v_mfma_f32_16x16x32_bf16 v[96:99], v[120:123], v[182:185], v[96:99]
	v_mfma_f32_16x16x32_bf16 v[32:35], v[164:167], v[182:185], v[32:35]
	v_mfma_f32_16x16x32_bf16 v[36:39], v[120:123], v[190:193], v[36:39]
	v_mfma_f32_16x16x32_bf16 v[40:43], v[164:167], v[190:193], v[40:43]
	v_mfma_f32_16x16x32_bf16 v[44:47], v[120:123], v[198:201], v[44:47]
	v_mfma_f32_16x16x32_bf16 v[48:51], v[164:167], v[198:201], v[48:51]
	v_mfma_f32_16x16x32_bf16 v[52:55], v[120:123], v[206:209], v[52:55]
	v_mfma_f32_16x16x32_bf16 v[56:59], v[164:167], v[206:209], v[56:59]
	v_mfma_f32_16x16x32_bf16 v[96:99], v[124:127], v[186:189], v[96:99]
	v_mfma_f32_16x16x32_bf16 v[32:35], v[168:171], v[186:189], v[32:35]
	v_mfma_f32_16x16x32_bf16 v[36:39], v[124:127], v[194:197], v[36:39]
	v_mfma_f32_16x16x32_bf16 v[40:43], v[168:171], v[194:197], v[40:43]
	s_setprio 2
	s_barrier
	v_mfma_f32_16x16x32_bf16 v[44:47], v[124:127], v[202:205], v[44:47]
	v_mfma_f32_16x16x32_bf16 v[48:51], v[168:171], v[202:205], v[48:51]
	v_mfma_f32_16x16x32_bf16 v[52:55], v[124:127], v[210:213], v[52:55]
	v_mfma_f32_16x16x32_bf16 v[56:59], v[168:171], v[210:213], v[56:59]
	s_setprio 0
	s_add_i32 s63, s63, s43
	s_mov_b64 s[72:73], 0x180
	s_add_i32 s59, s63, 0x2000
	v_lshl_add_u64 v[138:139], v[138:139], 0, s[72:73]
	s_mov_b32 m0, s63
	s_add_u32 s64, s22, 0x10180
	ds_read_b128 v[182:185], v143 offset:49152
	ds_read_b128 v[186:189], v143 offset:50176
	ds_read_b128 v[190:193], v143 offset:51200
	ds_read_b128 v[194:197], v143 offset:52224
	ds_read_b128 v[198:201], v143 offset:53248
	ds_read_b128 v[202:205], v143 offset:54272
	ds_read_b128 v[206:209], v143 offset:55296
	ds_read_b128 v[210:213], v143 offset:56320
	global_load_lds_dwordx4 v[138:139], off
	v_lshl_add_u64 v[138:139], v[172:173], 0, s[72:73]
	s_mov_b32 m0, s59
	s_addc_u32 s65, s23, 0
	s_add_i32 s22, s68, s43
	global_load_lds_dwordx4 v[138:139], off
	v_lshl_add_u64 v[138:139], s[64:65], 0, v[176:177]
	s_mov_b32 m0, s22
	s_add_i32 s23, s22, 0x2000
	global_load_lds_dwordx4 v[138:139], off
	v_lshl_add_u64 v[138:139], s[64:65], 0, v[128:129]
	s_mov_b32 m0, s23
	s_nop 0
	global_load_lds_dwordx4 v[138:139], off
	v_lshl_add_u64 v[138:139], v[220:221], 0, s[72:73]
	s_mov_b32 m0, s54
	s_nop 0
	global_load_lds_dwordx4 v[138:139], off
	v_lshl_add_u64 v[138:139], v[222:223], 0, s[72:73]
	s_mov_b32 m0, s55
	s_nop 0
	global_load_lds_dwordx4 v[138:139], off
	s_waitcnt vmcnt(8) lgkmcnt(0)
	s_barrier
	s_setprio 1
	v_mfma_f32_16x16x32_bf16 v[0:3], v[24:27], v[206:209], v[0:3]
	v_mfma_f32_16x16x32_bf16 v[4:7], v[112:115], v[206:209], v[4:7]
	v_mfma_f32_16x16x32_bf16 v[134:137], v[24:27], v[182:185], v[134:137]
	v_mfma_f32_16x16x32_bf16 v[144:147], v[112:115], v[182:185], v[144:147]
	v_mfma_f32_16x16x32_bf16 v[148:151], v[24:27], v[190:193], v[148:151]
	v_mfma_f32_16x16x32_bf16 v[152:155], v[112:115], v[190:193], v[152:155]
	v_mfma_f32_16x16x32_bf16 v[156:159], v[24:27], v[198:201], v[156:159]
	v_mfma_f32_16x16x32_bf16 v[160:163], v[112:115], v[198:201], v[160:163]
	v_mfma_f32_16x16x32_bf16 v[0:3], v[28:31], v[210:213], v[0:3]
	v_mfma_f32_16x16x32_bf16 v[4:7], v[116:119], v[210:213], v[4:7]
	v_mfma_f32_16x16x32_bf16 v[134:137], v[28:31], v[186:189], v[134:137]
	v_mfma_f32_16x16x32_bf16 v[144:147], v[116:119], v[186:189], v[144:147]
	v_mfma_f32_16x16x32_bf16 v[148:151], v[28:31], v[194:197], v[148:151]
	v_mfma_f32_16x16x32_bf16 v[152:155], v[116:119], v[194:197], v[152:155]
	v_mfma_f32_16x16x32_bf16 v[156:159], v[28:31], v[202:205], v[156:159]
	v_mfma_f32_16x16x32_bf16 v[160:163], v[116:119], v[202:205], v[160:163]
	v_mfma_f32_16x16x32_bf16 v[8:11], v[120:123], v[182:185], v[8:11]
	v_mfma_f32_16x16x32_bf16 v[12:15], v[164:167], v[182:185], v[12:15]
	v_mfma_f32_16x16x32_bf16 v[24:27], v[120:123], v[190:193], v[60:63]
	v_mfma_f32_16x16x32_bf16 v[28:31], v[164:167], v[190:193], v[100:103]
	v_mfma_f32_16x16x32_bf16 v[60:63], v[120:123], v[198:201], v[104:107]
	v_mfma_f32_16x16x32_bf16 v[100:103], v[164:167], v[198:201], v[108:111]
	v_mfma_f32_16x16x32_bf16 v[16:19], v[120:123], v[206:209], v[16:19]
	v_mfma_f32_16x16x32_bf16 v[20:23], v[164:167], v[206:209], v[20:23]
	v_mfma_f32_16x16x32_bf16 v[8:11], v[124:127], v[186:189], v[8:11]
	v_mfma_f32_16x16x32_bf16 v[12:15], v[168:171], v[186:189], v[12:15]
	v_mfma_f32_16x16x32_bf16 v[24:27], v[124:127], v[194:197], v[24:27]
	v_mfma_f32_16x16x32_bf16 v[28:31], v[168:171], v[194:197], v[28:31]
	s_setprio 2
	s_barrier
	v_mfma_f32_16x16x32_bf16 v[60:63], v[124:127], v[202:205], v[60:63]
	v_mfma_f32_16x16x32_bf16 v[100:103], v[168:171], v[202:205], v[100:103]
	v_mfma_f32_16x16x32_bf16 v[16:19], v[124:127], v[210:213], v[16:19]
	v_mfma_f32_16x16x32_bf16 v[20:23], v[168:171], v[210:213], v[20:23]
	s_setprio 0
	ds_read_b128 v[104:107], v175
	ds_read_b128 v[108:111], v175 offset:1024
	ds_read_b128 v[112:115], v175 offset:2048
	ds_read_b128 v[116:119], v175 offset:3072
	ds_read_b128 v[120:123], v178
	ds_read_b128 v[124:127], v178 offset:1024
	ds_read_b128 v[164:167], v178 offset:2048
	ds_read_b128 v[168:171], v178 offset:3072
	s_add_u32 s20, s20, 0x20180
	s_addc_u32 s21, s21, 0
	s_mov_b32 m0, s62
	v_lshl_add_u64 v[138:139], s[20:21], 0, v[132:133]
	ds_read_b128 v[182:185], v143
	ds_read_b128 v[186:189], v143 offset:1024
	ds_read_b128 v[190:193], v143 offset:2048
	ds_read_b128 v[194:197], v143 offset:3072
	ds_read_b128 v[198:201], v143 offset:4096
	ds_read_b128 v[202:205], v143 offset:5120
	ds_read_b128 v[206:209], v143 offset:6144
	ds_read_b128 v[210:213], v143 offset:7168
	global_load_lds_dwordx4 v[138:139], off
	v_lshl_add_u64 v[138:139], s[20:21], 0, v[130:131]
	s_mov_b32 m0, s9
	s_nop 0
	global_load_lds_dwordx4 v[138:139], off
	s_waitcnt vmcnt(8) lgkmcnt(0)
	s_barrier
	s_setprio 1
	v_mfma_f32_16x16x32_bf16 v[64:67], v[104:107], v[182:185], v[64:67]
	v_mfma_f32_16x16x32_bf16 v[68:71], v[112:115], v[182:185], v[68:71]
	v_mfma_f32_16x16x32_bf16 v[72:75], v[104:107], v[190:193], v[72:75]
	v_mfma_f32_16x16x32_bf16 v[76:79], v[112:115], v[190:193], v[76:79]
	v_mfma_f32_16x16x32_bf16 v[80:83], v[104:107], v[198:201], v[80:83]
	v_mfma_f32_16x16x32_bf16 v[84:87], v[112:115], v[198:201], v[84:87]
	v_mfma_f32_16x16x32_bf16 v[88:91], v[104:107], v[206:209], v[88:91]
	v_mfma_f32_16x16x32_bf16 v[92:95], v[112:115], v[206:209], v[92:95]
	v_mfma_f32_16x16x32_bf16 v[64:67], v[108:111], v[186:189], v[64:67]
	v_mfma_f32_16x16x32_bf16 v[68:71], v[116:119], v[186:189], v[68:71]
	v_mfma_f32_16x16x32_bf16 v[72:75], v[108:111], v[194:197], v[72:75]
	v_mfma_f32_16x16x32_bf16 v[76:79], v[116:119], v[194:197], v[76:79]
	v_mfma_f32_16x16x32_bf16 v[80:83], v[108:111], v[202:205], v[80:83]
	v_mfma_f32_16x16x32_bf16 v[84:87], v[116:119], v[202:205], v[84:87]
	v_mfma_f32_16x16x32_bf16 v[88:91], v[108:111], v[210:213], v[88:91]
	v_mfma_f32_16x16x32_bf16 v[92:95], v[116:119], v[210:213], v[92:95]
	v_mfma_f32_16x16x32_bf16 v[32:35], v[164:167], v[182:185], v[32:35]
	v_mfma_f32_16x16x32_bf16 v[36:39], v[120:123], v[190:193], v[36:39]
	v_mfma_f32_16x16x32_bf16 v[40:43], v[164:167], v[190:193], v[40:43]
	v_mfma_f32_16x16x32_bf16 v[44:47], v[120:123], v[198:201], v[44:47]
	v_mfma_f32_16x16x32_bf16 v[48:51], v[164:167], v[198:201], v[48:51]
	v_mfma_f32_16x16x32_bf16 v[52:55], v[120:123], v[206:209], v[52:55]
	v_mfma_f32_16x16x32_bf16 v[56:59], v[164:167], v[206:209], v[56:59]
	v_mfma_f32_16x16x32_bf16 v[96:99], v[120:123], v[182:185], v[96:99]
	v_mfma_f32_16x16x32_bf16 v[32:35], v[168:171], v[186:189], v[32:35]
	v_mfma_f32_16x16x32_bf16 v[36:39], v[124:127], v[194:197], v[36:39]
	v_mfma_f32_16x16x32_bf16 v[40:43], v[168:171], v[194:197], v[40:43]
	v_mfma_f32_16x16x32_bf16 v[44:47], v[124:127], v[202:205], v[44:47]
	s_setprio 2
	s_barrier
	v_mfma_f32_16x16x32_bf16 v[48:51], v[168:171], v[202:205], v[48:51]
	v_mfma_f32_16x16x32_bf16 v[52:55], v[124:127], v[210:213], v[52:55]
	v_mfma_f32_16x16x32_bf16 v[56:59], v[168:171], v[210:213], v[56:59]
	v_mfma_f32_16x16x32_bf16 v[228:231], v[124:127], v[186:189], v[96:99]
	s_setprio 0
	s_mov_b32 m0, s58
	v_lshl_add_u64 v[138:139], s[24:25], 0, v[176:177]
	s_add_u32 s20, s24, 0x10000
	ds_read_b128 v[96:99], v143 offset:16384
	ds_read_b128 v[182:185], v143 offset:17408
	ds_read_b128 v[186:189], v143 offset:18432
	ds_read_b128 v[190:193], v143 offset:19456
	ds_read_b128 v[194:197], v143 offset:20480
	ds_read_b128 v[198:201], v143 offset:21504
	ds_read_b128 v[202:205], v143 offset:22528
	ds_read_b128 v[206:209], v143 offset:23552
	global_load_lds_dwordx4 v[138:139], off
	v_lshl_add_u64 v[172:173], s[24:25], 0, v[128:129]
	s_mov_b32 m0, s11
	s_addc_u32 s21, s25, 0
	global_load_lds_dwordx4 v[172:173], off
	v_lshl_add_u64 v[210:211], s[20:21], 0, v[176:177]
	s_mov_b32 m0, s17
	v_lshl_add_u64 v[226:227], s[26:27], 0, v[132:133]
	global_load_lds_dwordx4 v[210:211], off
	v_lshl_add_u64 v[210:211], s[20:21], 0, v[128:129]
	s_mov_b32 m0, s57
	v_lshl_add_u64 v[252:253], s[26:27], 0, v[130:131]
	global_load_lds_dwordx4 v[210:211], off
	s_mov_b32 m0, s19
	s_nop 0
	global_load_lds_dwordx4 v[226:227], off
	s_mov_b32 m0, s51
	s_nop 0
	global_load_lds_dwordx4 v[252:253], off
	s_waitcnt vmcnt(8) lgkmcnt(0)
	s_barrier
	s_setprio 1
	v_mfma_f32_16x16x32_bf16 v[0:3], v[104:107], v[202:205], v[0:3]
	v_mfma_f32_16x16x32_bf16 v[4:7], v[112:115], v[202:205], v[4:7]
	v_mfma_f32_16x16x32_bf16 v[134:137], v[104:107], v[96:99], v[134:137]
	v_mfma_f32_16x16x32_bf16 v[144:147], v[112:115], v[96:99], v[144:147]
	v_mfma_f32_16x16x32_bf16 v[148:151], v[104:107], v[186:189], v[148:151]
	v_mfma_f32_16x16x32_bf16 v[152:155], v[112:115], v[186:189], v[152:155]
	v_mfma_f32_16x16x32_bf16 v[156:159], v[104:107], v[194:197], v[156:159]
	v_mfma_f32_16x16x32_bf16 v[160:163], v[112:115], v[194:197], v[160:163]
	v_mfma_f32_16x16x32_bf16 v[0:3], v[108:111], v[206:209], v[0:3]
	v_mfma_f32_16x16x32_bf16 v[4:7], v[116:119], v[206:209], v[4:7]
	v_mfma_f32_16x16x32_bf16 v[134:137], v[108:111], v[182:185], v[134:137]
	v_mfma_f32_16x16x32_bf16 v[144:147], v[116:119], v[182:185], v[144:147]
	v_mfma_f32_16x16x32_bf16 v[148:151], v[108:111], v[190:193], v[148:151]
	v_mfma_f32_16x16x32_bf16 v[152:155], v[116:119], v[190:193], v[152:155]
	v_mfma_f32_16x16x32_bf16 v[156:159], v[108:111], v[198:201], v[156:159]
	v_mfma_f32_16x16x32_bf16 v[160:163], v[116:119], v[198:201], v[160:163]
	v_mfma_f32_16x16x32_bf16 v[8:11], v[120:123], v[96:99], v[8:11]
	v_mfma_f32_16x16x32_bf16 v[12:15], v[164:167], v[96:99], v[12:15]
	v_mfma_f32_16x16x32_bf16 v[24:27], v[120:123], v[186:189], v[24:27]
	v_mfma_f32_16x16x32_bf16 v[28:31], v[164:167], v[186:189], v[28:31]
	v_mfma_f32_16x16x32_bf16 v[60:63], v[120:123], v[194:197], v[60:63]
	v_mfma_f32_16x16x32_bf16 v[16:19], v[120:123], v[202:205], v[16:19]
	v_mfma_f32_16x16x32_bf16 v[8:11], v[124:127], v[182:185], v[8:11]
	v_mfma_f32_16x16x32_bf16 v[12:15], v[168:171], v[182:185], v[12:15]
	v_mfma_f32_16x16x32_bf16 v[24:27], v[124:127], v[190:193], v[24:27]
	v_mfma_f32_16x16x32_bf16 v[28:31], v[168:171], v[190:193], v[28:31]
	v_mfma_f32_16x16x32_bf16 v[182:185], v[124:127], v[198:201], v[60:63]
	v_mfma_f32_16x16x32_bf16 v[60:63], v[164:167], v[194:197], v[100:103]
	s_setprio 2
	s_barrier
	v_mfma_f32_16x16x32_bf16 v[190:193], v[124:127], v[206:209], v[16:19]
	v_mfma_f32_16x16x32_bf16 v[16:19], v[164:167], v[202:205], v[20:23]
	v_mfma_f32_16x16x32_bf16 v[186:189], v[168:171], v[198:201], v[60:63]
	v_mfma_f32_16x16x32_bf16 v[164:167], v[168:171], v[206:209], v[16:19]
	s_setprio 0
	s_nop 1
	ds_read_b128 v[60:63], v179
	ds_read_b128 v[168:171], v179 offset:1024
	ds_read_b128 v[194:197], v179 offset:2048
	ds_read_b128 v[198:201], v179 offset:3072
	ds_read_b128 v[202:205], v232
	ds_read_b128 v[206:209], v232 offset:1024
	ds_read_b128 v[210:213], v232 offset:2048
	ds_read_b128 v[232:235], v232 offset:3072
	s_add_u32 s20, s26, 0x20000
	s_addc_u32 s21, s27, 0
	s_mov_b32 m0, s52
	v_lshl_add_u64 v[96:97], s[20:21], 0, v[132:133]
	ds_read_b128 v[16:19], v143 offset:32768
	ds_read_b128 v[20:23], v143 offset:33792
	ds_read_b128 v[108:111], v143 offset:34816
	ds_read_b128 v[236:239], v143 offset:35840
	ds_read_b128 v[240:243], v143 offset:36864
	ds_read_b128 v[244:247], v143 offset:37888
	ds_read_b128 v[248:251], v143 offset:38912
	ds_read_b128 v[220:223], v143 offset:39936
	global_load_lds_dwordx4 v[96:97], off
	v_lshl_add_u64 v[96:97], s[20:21], 0, v[130:131]
	s_mov_b32 m0, s53
	s_nop 0
	global_load_lds_dwordx4 v[96:97], off
	s_waitcnt vmcnt(8) lgkmcnt(0)
	s_barrier
	s_setprio 1
	v_mfma_f32_16x16x32_bf16 v[64:67], v[60:63], v[16:19], v[64:67]
	v_mfma_f32_16x16x32_bf16 v[112:115], v[168:171], v[20:23], v[64:67]
	v_mfma_f32_16x16x32_bf16 v[64:67], v[194:197], v[16:19], v[68:71]
	v_mfma_f32_16x16x32_bf16 v[116:119], v[198:201], v[20:23], v[64:67]
	v_mfma_f32_16x16x32_bf16 v[64:67], v[60:63], v[108:111], v[72:75]
	v_mfma_f32_16x16x32_bf16 v[96:99], v[168:171], v[236:239], v[64:67]
	v_mfma_f32_16x16x32_bf16 v[64:67], v[194:197], v[108:111], v[76:79]
	v_mfma_f32_16x16x32_bf16 v[100:103], v[198:201], v[236:239], v[64:67]
	v_mfma_f32_16x16x32_bf16 v[64:67], v[60:63], v[240:243], v[80:83]
	v_mfma_f32_16x16x32_bf16 v[80:83], v[168:171], v[244:247], v[64:67]
	v_mfma_f32_16x16x32_bf16 v[64:67], v[194:197], v[240:243], v[84:87]
	v_mfma_f32_16x16x32_bf16 v[84:87], v[198:201], v[244:247], v[64:67]
	v_mfma_f32_16x16x32_bf16 v[64:67], v[60:63], v[248:251], v[88:91]
	v_mfma_f32_16x16x32_bf16 v[68:71], v[194:197], v[248:251], v[92:95]
	v_mfma_f32_16x16x32_bf16 v[64:67], v[168:171], v[220:223], v[64:67]
	v_mfma_f32_16x16x32_bf16 v[68:71], v[198:201], v[220:223], v[68:71]
	v_mfma_f32_16x16x32_bf16 v[72:75], v[202:205], v[16:19], v[228:231]
	v_mfma_f32_16x16x32_bf16 v[16:19], v[210:213], v[16:19], v[32:35]
	v_mfma_f32_16x16x32_bf16 v[124:127], v[232:235], v[20:23], v[16:19]
	v_mfma_f32_16x16x32_bf16 v[16:19], v[202:205], v[108:111], v[36:39]
	v_mfma_f32_16x16x32_bf16 v[104:107], v[206:209], v[236:239], v[16:19]
	v_mfma_f32_16x16x32_bf16 v[16:19], v[210:213], v[108:111], v[40:43]
	v_mfma_f32_16x16x32_bf16 v[108:111], v[232:235], v[236:239], v[16:19]
	v_mfma_f32_16x16x32_bf16 v[16:19], v[202:205], v[240:243], v[44:47]
	v_mfma_f32_16x16x32_bf16 v[88:91], v[206:209], v[244:247], v[16:19]
	v_mfma_f32_16x16x32_bf16 v[16:19], v[210:213], v[240:243], v[48:51]
	v_mfma_f32_16x16x32_bf16 v[92:95], v[232:235], v[244:247], v[16:19]
	v_mfma_f32_16x16x32_bf16 v[16:19], v[202:205], v[248:251], v[52:55]
	s_setprio 2
	s_barrier
	v_mfma_f32_16x16x32_bf16 v[120:123], v[206:209], v[20:23], v[72:75]
	v_mfma_f32_16x16x32_bf16 v[72:75], v[206:209], v[220:223], v[16:19]
	v_mfma_f32_16x16x32_bf16 v[16:19], v[210:213], v[248:251], v[56:59]
	v_mfma_f32_16x16x32_bf16 v[76:79], v[232:235], v[220:223], v[16:19]
	s_setprio 0
	s_mov_b32 m0, s63
	s_nop 3
	v_lshl_add_u64 v[16:17], v[138:139], 0, s[34:35]
	s_add_u32 s20, s24, 0x10080
	ds_read_b128 v[40:43], v143 offset:49152
	ds_read_b128 v[44:47], v143 offset:50176
	ds_read_b128 v[220:223], v143 offset:51200
	ds_read_b128 v[228:231], v143 offset:52224
	ds_read_b128 v[236:239], v143 offset:53248
	ds_read_b128 v[240:243], v143 offset:54272
	ds_read_b128 v[244:247], v143 offset:55296
	ds_read_b128 v[248:251], v143 offset:56320
	global_load_lds_dwordx4 v[16:17], off
	v_lshl_add_u64 v[16:17], v[172:173], 0, s[34:35]
	s_mov_b32 m0, s59
	s_addc_u32 s21, s25, 0
	global_load_lds_dwordx4 v[16:17], off
	v_lshl_add_u64 v[16:17], s[20:21], 0, v[176:177]
	s_mov_b32 m0, s22
	s_nop 0
	global_load_lds_dwordx4 v[16:17], off
	v_lshl_add_u64 v[16:17], s[20:21], 0, v[128:129]
	s_mov_b32 m0, s23
	s_nop 0
	global_load_lds_dwordx4 v[16:17], off
	v_lshl_add_u64 v[16:17], v[226:227], 0, s[34:35]
	s_mov_b32 m0, s54
	s_nop 0
	global_load_lds_dwordx4 v[16:17], off
	v_lshl_add_u64 v[16:17], v[252:253], 0, s[34:35]
	s_mov_b32 m0, s55
	s_nop 0
	global_load_lds_dwordx4 v[16:17], off
	s_waitcnt vmcnt(8) lgkmcnt(0)
	s_barrier
	s_setprio 1
	v_mfma_f32_16x16x32_bf16 v[16:19], v[60:63], v[40:43], v[134:137]
	v_mfma_f32_16x16x32_bf16 v[48:51], v[168:171], v[44:47], v[16:19]
	v_mfma_f32_16x16x32_bf16 v[16:19], v[194:197], v[40:43], v[144:147]
	v_mfma_f32_16x16x32_bf16 v[52:55], v[198:201], v[44:47], v[16:19]
	v_mfma_f32_16x16x32_bf16 v[16:19], v[60:63], v[220:223], v[148:151]
	v_mfma_f32_16x16x32_bf16 v[32:35], v[168:171], v[228:231], v[16:19]
	v_mfma_f32_16x16x32_bf16 v[16:19], v[194:197], v[220:223], v[152:155]
	v_mfma_f32_16x16x32_bf16 v[36:39], v[198:201], v[228:231], v[16:19]
	v_mfma_f32_16x16x32_bf16 v[16:19], v[60:63], v[236:239], v[156:159]
	v_mfma_f32_16x16x32_bf16 v[20:23], v[194:197], v[236:239], v[160:163]
	v_mfma_f32_16x16x32_bf16 v[0:3], v[60:63], v[244:247], v[0:3]
	v_mfma_f32_16x16x32_bf16 v[4:7], v[194:197], v[244:247], v[4:7]
	v_mfma_f32_16x16x32_bf16 v[16:19], v[168:171], v[240:243], v[16:19]
	v_mfma_f32_16x16x32_bf16 v[20:23], v[198:201], v[240:243], v[20:23]
	v_mfma_f32_16x16x32_bf16 v[0:3], v[168:171], v[248:251], v[0:3]
	v_mfma_f32_16x16x32_bf16 v[4:7], v[198:201], v[248:251], v[4:7]
	v_mfma_f32_16x16x32_bf16 v[8:11], v[202:205], v[40:43], v[8:11]
	v_mfma_f32_16x16x32_bf16 v[56:59], v[206:209], v[44:47], v[8:11]
	v_mfma_f32_16x16x32_bf16 v[8:11], v[210:213], v[40:43], v[12:15]
	v_mfma_f32_16x16x32_bf16 v[60:63], v[232:235], v[44:47], v[8:11]
	v_mfma_f32_16x16x32_bf16 v[8:11], v[202:205], v[220:223], v[24:27]
	v_mfma_f32_16x16x32_bf16 v[40:43], v[206:209], v[228:231], v[8:11]
	v_mfma_f32_16x16x32_bf16 v[8:11], v[210:213], v[220:223], v[28:31]
	v_mfma_f32_16x16x32_bf16 v[44:47], v[232:235], v[228:231], v[8:11]
	v_mfma_f32_16x16x32_bf16 v[8:11], v[202:205], v[236:239], v[182:185]
	v_mfma_f32_16x16x32_bf16 v[24:27], v[206:209], v[240:243], v[8:11]
	v_mfma_f32_16x16x32_bf16 v[8:11], v[210:213], v[236:239], v[186:189]
	v_mfma_f32_16x16x32_bf16 v[28:31], v[232:235], v[240:243], v[8:11]
	s_setprio 2
	s_barrier
	v_mfma_f32_16x16x32_bf16 v[8:11], v[202:205], v[244:247], v[190:193]
	v_mfma_f32_16x16x32_bf16 v[12:15], v[210:213], v[244:247], v[164:167]
	v_mfma_f32_16x16x32_bf16 v[8:11], v[206:209], v[248:251], v[8:11]
	v_mfma_f32_16x16x32_bf16 v[12:15], v[232:235], v[248:251], v[12:15]
	s_setprio 0
	s_andn2_b64 vcc, exec, s[4:5]
	s_cbranch_vccnz .LBB0_414
	s_barrier

.LBB0_426:
	s_ashr_i32 s11, s10, 31
	s_lshl_b64 s[12:13], s[10:11], 18
	s_add_u32 s12, s25, s12
	s_addc_u32 s13, s26, s13
	s_and_b64 s[14:15], s[2:3], exec
	s_cselect_b32 s23, s13, s21
	s_cselect_b32 s22, s12, s20
	s_ashr_i32 s9, s8, 31
	s_lshl_b64 s[14:15], s[8:9], 16
	s_add_u32 s14, s27, s14
	s_addc_u32 s15, s28, s15
	s_add_u32 s56, s20, 0x20080
	s_addc_u32 s57, s21, 0
	s_add_u32 s20, s22, 0x20000
	s_addc_u32 s21, s23, 0
	s_add_i32 s9, 0, 0x10000
	s_and_b64 s[58:59], s[2:3], exec
	s_cselect_b32 s18, s14, s18
	s_cselect_b32 s19, s15, s19
	s_add_u32 s58, s18, 0x8000
	s_addc_u32 s59, s19, 0
	s_add_i32 s11, 0, 0x14000
	v_add_u32_e32 v12, s9, v139
	v_add_u32_e32 v28, s11, v139
	ds_read_b128 v[0:3], v12
	ds_read_b128 v[4:7], v12 offset:1024
	ds_read_b128 v[8:11], v12 offset:2048
	ds_read_b128 v[12:15], v12 offset:3072
	ds_read_b128 v[16:19], v28
	ds_read_b128 v[20:23], v28 offset:1024
	ds_read_b128 v[24:27], v28 offset:2048
	ds_read_b128 v[28:31], v28 offset:3072
	v_lshl_add_u64 v[64:65], s[56:57], 0, v[134:135]
	s_add_i32 m0, s43, 0xc000
	ds_read_b128 v[32:35], v140
	ds_read_b128 v[36:39], v140 offset:1024
	ds_read_b128 v[40:43], v140 offset:2048
	ds_read_b128 v[44:47], v140 offset:3072
	ds_read_b128 v[48:51], v140 offset:4096
	ds_read_b128 v[52:55], v140 offset:5120
	ds_read_b128 v[56:59], v140 offset:6144
	ds_read_b128 v[60:63], v140 offset:7168
	global_load_lds_dwordx4 v[64:65], off
	v_lshl_add_u64 v[64:65], s[56:57], 0, v[130:131]
	s_add_i32 m0, s43, 0xe000
	s_nop 0
	global_load_lds_dwordx4 v[64:65], off
	s_waitcnt vmcnt(8) lgkmcnt(0)
	s_barrier
	s_setprio 1
	v_mfma_f32_16x16x32_bf16 v[64:67], v[0:3], v[32:35], 0
	v_mfma_f32_16x16x32_bf16 v[68:71], v[8:11], v[32:35], 0
	v_mfma_f32_16x16x32_bf16 v[72:75], v[0:3], v[40:43], 0
	v_mfma_f32_16x16x32_bf16 v[76:79], v[8:11], v[40:43], 0
	v_mfma_f32_16x16x32_bf16 v[80:83], v[0:3], v[48:51], 0
	v_mfma_f32_16x16x32_bf16 v[84:87], v[8:11], v[48:51], 0
	v_mfma_f32_16x16x32_bf16 v[88:91], v[0:3], v[56:59], 0
	v_mfma_f32_16x16x32_bf16 v[92:95], v[8:11], v[56:59], 0
	v_mfma_f32_16x16x32_bf16 v[64:67], v[4:7], v[36:39], v[64:67]
	v_mfma_f32_16x16x32_bf16 v[68:71], v[12:15], v[36:39], v[68:71]
	v_mfma_f32_16x16x32_bf16 v[72:75], v[4:7], v[44:47], v[72:75]
	v_mfma_f32_16x16x32_bf16 v[76:79], v[12:15], v[44:47], v[76:79]
	v_mfma_f32_16x16x32_bf16 v[80:83], v[4:7], v[52:55], v[80:83]
	v_mfma_f32_16x16x32_bf16 v[84:87], v[12:15], v[52:55], v[84:87]
	v_mfma_f32_16x16x32_bf16 v[88:91], v[4:7], v[60:63], v[88:91]
	v_mfma_f32_16x16x32_bf16 v[92:95], v[12:15], v[60:63], v[92:95]
	v_mfma_f32_16x16x32_bf16 v[96:99], v[16:19], v[32:35], 0
	v_mfma_f32_16x16x32_bf16 v[32:35], v[24:27], v[32:35], 0
	v_mfma_f32_16x16x32_bf16 v[104:107], v[20:23], v[36:39], v[96:99]
	v_mfma_f32_16x16x32_bf16 v[32:35], v[28:31], v[36:39], v[32:35]
	v_mfma_f32_16x16x32_bf16 v[36:39], v[16:19], v[40:43], 0
	v_mfma_f32_16x16x32_bf16 v[40:43], v[24:27], v[40:43], 0
	v_mfma_f32_16x16x32_bf16 v[36:39], v[20:23], v[44:47], v[36:39]
	v_mfma_f32_16x16x32_bf16 v[40:43], v[28:31], v[44:47], v[40:43]
	v_mfma_f32_16x16x32_bf16 v[44:47], v[16:19], v[48:51], 0
	v_mfma_f32_16x16x32_bf16 v[48:51], v[24:27], v[48:51], 0
	v_mfma_f32_16x16x32_bf16 v[44:47], v[20:23], v[52:55], v[44:47]
	v_mfma_f32_16x16x32_bf16 v[48:51], v[28:31], v[52:55], v[48:51]
	s_setprio 2
	s_barrier
	v_mfma_f32_16x16x32_bf16 v[52:55], v[16:19], v[56:59], 0
	v_mfma_f32_16x16x32_bf16 v[56:59], v[24:27], v[56:59], 0
	v_mfma_f32_16x16x32_bf16 v[52:55], v[20:23], v[60:63], v[52:55]
	v_mfma_f32_16x16x32_bf16 v[56:59], v[28:31], v[60:63], v[56:59]
	s_setprio 0
	s_add_i32 s9, s9, s29
	v_lshl_add_u64 v[136:137], s[18:19], 0, v[132:133]
	s_mov_b32 m0, s9
	ds_read_b128 v[60:63], v140 offset:16384
	ds_read_b128 v[96:99], v140 offset:17408
	ds_read_b128 v[100:103], v140 offset:18432
	ds_read_b128 v[108:111], v140 offset:19456
	ds_read_b128 v[112:115], v140 offset:20480
	ds_read_b128 v[116:119], v140 offset:21504
	ds_read_b128 v[120:123], v140 offset:22528
	ds_read_b128 v[124:127], v140 offset:23552
	global_load_lds_dwordx4 v[136:137], off
	v_lshl_add_u64 v[226:227], s[18:19], 0, v[128:129]
	s_add_i32 m0, s9, 0x2000
	s_add_i32 s9, s11, s29
	global_load_lds_dwordx4 v[226:227], off
	v_lshl_add_u64 v[142:143], s[58:59], 0, v[132:133]
	s_mov_b32 m0, s9
	v_lshl_add_u64 v[252:253], s[22:23], 0, v[134:135]
	global_load_lds_dwordx4 v[142:143], off
	v_lshl_add_u64 v[142:143], s[58:59], 0, v[128:129]
	s_add_i32 m0, s9, 0x2000
	v_lshl_add_u64 v[178:179], s[22:23], 0, v[130:131]
	global_load_lds_dwordx4 v[142:143], off
	s_mov_b32 m0, s43
	s_nop 0
	global_load_lds_dwordx4 v[252:253], off
	s_mov_b32 m0, s44
	s_nop 0
	global_load_lds_dwordx4 v[178:179], off
	s_waitcnt vmcnt(8) lgkmcnt(0)
	s_barrier
	s_setprio 1
	v_mfma_f32_16x16x32_bf16 v[142:145], v[0:3], v[60:63], 0
	v_mfma_f32_16x16x32_bf16 v[150:153], v[0:3], v[100:103], 0
	v_mfma_f32_16x16x32_bf16 v[158:161], v[0:3], v[112:115], 0
	v_mfma_f32_16x16x32_bf16 v[0:3], v[0:3], v[120:123], 0
	v_mfma_f32_16x16x32_bf16 v[142:145], v[4:7], v[96:99], v[142:145]
	v_mfma_f32_16x16x32_bf16 v[150:153], v[4:7], v[108:111], v[150:153]
	v_mfma_f32_16x16x32_bf16 v[158:161], v[4:7], v[116:119], v[158:161]
	v_mfma_f32_16x16x32_bf16 v[0:3], v[4:7], v[124:127], v[0:3]
	v_mfma_f32_16x16x32_bf16 v[4:7], v[8:11], v[120:123], 0
	v_mfma_f32_16x16x32_bf16 v[146:149], v[8:11], v[60:63], 0
	v_mfma_f32_16x16x32_bf16 v[154:157], v[8:11], v[100:103], 0
	v_mfma_f32_16x16x32_bf16 v[162:165], v[8:11], v[112:115], 0
	v_mfma_f32_16x16x32_bf16 v[4:7], v[12:15], v[124:127], v[4:7]
	v_mfma_f32_16x16x32_bf16 v[146:149], v[12:15], v[96:99], v[146:149]
	v_mfma_f32_16x16x32_bf16 v[154:157], v[12:15], v[108:111], v[154:157]
	v_mfma_f32_16x16x32_bf16 v[162:165], v[12:15], v[116:119], v[162:165]
	v_mfma_f32_16x16x32_bf16 v[8:11], v[16:19], v[60:63], 0
	v_mfma_f32_16x16x32_bf16 v[12:15], v[24:27], v[60:63], 0
	v_mfma_f32_16x16x32_bf16 v[60:63], v[16:19], v[100:103], 0
	v_mfma_f32_16x16x32_bf16 v[166:169], v[20:23], v[108:111], v[60:63]
	v_mfma_f32_16x16x32_bf16 v[60:63], v[24:27], v[100:103], 0
	v_mfma_f32_16x16x32_bf16 v[170:173], v[28:31], v[108:111], v[60:63]
	v_mfma_f32_16x16x32_bf16 v[60:63], v[16:19], v[112:115], 0
	v_mfma_f32_16x16x32_bf16 v[16:19], v[16:19], v[120:123], 0
	v_mfma_f32_16x16x32_bf16 v[8:11], v[20:23], v[96:99], v[8:11]
	v_mfma_f32_16x16x32_bf16 v[12:15], v[28:31], v[96:99], v[12:15]
	v_mfma_f32_16x16x32_bf16 v[182:185], v[20:23], v[116:119], v[60:63]
	v_mfma_f32_16x16x32_bf16 v[60:63], v[24:27], v[112:115], 0
	s_setprio 2
	s_barrier
	v_mfma_f32_16x16x32_bf16 v[190:193], v[20:23], v[124:127], v[16:19]
	v_mfma_f32_16x16x32_bf16 v[16:19], v[24:27], v[120:123], 0
	v_mfma_f32_16x16x32_bf16 v[186:189], v[28:31], v[116:119], v[60:63]
	v_mfma_f32_16x16x32_bf16 v[194:197], v[28:31], v[124:127], v[16:19]
	s_setprio 0
	s_add_i32 s9, 0, 0x18000
	s_nop 2
	v_add_u32_e32 v16, s9, v139
	s_add_i32 s11, 0, 0x1c000
	ds_read_b128 v[24:27], v16
	ds_read_b128 v[28:31], v16 offset:1024
	ds_read_b128 v[60:63], v16 offset:2048
	ds_read_b128 v[198:201], v16 offset:3072
	v_add_u32_e32 v16, s11, v139
	ds_read_b128 v[202:205], v16
	ds_read_b128 v[206:209], v16 offset:1024
	ds_read_b128 v[210:213], v16 offset:2048
	ds_read_b128 v[220:223], v16 offset:3072
	s_mov_b32 m0, s50
	v_lshl_add_u64 v[96:97], s[20:21], 0, v[134:135]
	ds_read_b128 v[16:19], v140 offset:32768
	ds_read_b128 v[20:23], v140 offset:33792
	ds_read_b128 v[108:111], v140 offset:34816
	ds_read_b128 v[228:231], v140 offset:35840
	ds_read_b128 v[232:235], v140 offset:36864
	ds_read_b128 v[236:239], v140 offset:37888
	ds_read_b128 v[240:243], v140 offset:38912
	ds_read_b128 v[244:247], v140 offset:39936
	global_load_lds_dwordx4 v[96:97], off
	v_lshl_add_u64 v[96:97], s[20:21], 0, v[130:131]
	s_mov_b32 m0, s51
	s_nop 0
	global_load_lds_dwordx4 v[96:97], off
	s_waitcnt vmcnt(8) lgkmcnt(0)
	s_barrier
	s_setprio 1
	v_mfma_f32_16x16x32_bf16 v[64:67], v[24:27], v[16:19], v[64:67]
	v_mfma_f32_16x16x32_bf16 v[120:123], v[28:31], v[20:23], v[64:67]
	v_mfma_f32_16x16x32_bf16 v[64:67], v[60:63], v[16:19], v[68:71]
	v_mfma_f32_16x16x32_bf16 v[124:127], v[198:201], v[20:23], v[64:67]
	v_mfma_f32_16x16x32_bf16 v[64:67], v[24:27], v[108:111], v[72:75]
	v_mfma_f32_16x16x32_bf16 v[96:99], v[28:31], v[228:231], v[64:67]
	v_mfma_f32_16x16x32_bf16 v[64:67], v[60:63], v[108:111], v[76:79]
	v_mfma_f32_16x16x32_bf16 v[100:103], v[198:201], v[228:231], v[64:67]
	v_mfma_f32_16x16x32_bf16 v[64:67], v[24:27], v[232:235], v[80:83]
	v_mfma_f32_16x16x32_bf16 v[80:83], v[28:31], v[236:239], v[64:67]
	v_mfma_f32_16x16x32_bf16 v[64:67], v[60:63], v[232:235], v[84:87]
	v_mfma_f32_16x16x32_bf16 v[84:87], v[198:201], v[236:239], v[64:67]
	v_mfma_f32_16x16x32_bf16 v[64:67], v[24:27], v[240:243], v[88:91]
	v_mfma_f32_16x16x32_bf16 v[68:71], v[60:63], v[240:243], v[92:95]
	v_mfma_f32_16x16x32_bf16 v[64:67], v[28:31], v[244:247], v[64:67]
	v_mfma_f32_16x16x32_bf16 v[68:71], v[198:201], v[244:247], v[68:71]
	v_mfma_f32_16x16x32_bf16 v[72:75], v[202:205], v[16:19], v[104:107]
	v_mfma_f32_16x16x32_bf16 v[16:19], v[210:213], v[16:19], v[32:35]
	v_mfma_f32_16x16x32_bf16 v[116:119], v[220:223], v[20:23], v[16:19]
	v_mfma_f32_16x16x32_bf16 v[16:19], v[202:205], v[108:111], v[36:39]
	v_mfma_f32_16x16x32_bf16 v[104:107], v[206:209], v[228:231], v[16:19]
	v_mfma_f32_16x16x32_bf16 v[16:19], v[210:213], v[108:111], v[40:43]
	v_mfma_f32_16x16x32_bf16 v[108:111], v[220:223], v[228:231], v[16:19]
	v_mfma_f32_16x16x32_bf16 v[16:19], v[202:205], v[232:235], v[44:47]
	v_mfma_f32_16x16x32_bf16 v[88:91], v[206:209], v[236:239], v[16:19]
	v_mfma_f32_16x16x32_bf16 v[16:19], v[210:213], v[232:235], v[48:51]
	v_mfma_f32_16x16x32_bf16 v[92:95], v[220:223], v[236:239], v[16:19]
	v_mfma_f32_16x16x32_bf16 v[16:19], v[202:205], v[240:243], v[52:55]
	s_setprio 2
	s_barrier
	v_mfma_f32_16x16x32_bf16 v[112:115], v[206:209], v[20:23], v[72:75]
	v_mfma_f32_16x16x32_bf16 v[72:75], v[206:209], v[244:247], v[16:19]
	v_mfma_f32_16x16x32_bf16 v[16:19], v[210:213], v[240:243], v[56:59]
	v_mfma_f32_16x16x32_bf16 v[76:79], v[220:223], v[244:247], v[16:19]
	s_setprio 0
	s_add_i32 s9, s9, s29
	s_nop 3
	v_lshl_add_u64 v[16:17], v[136:137], 0, s[34:35]
	s_mov_b32 m0, s9
	ds_read_b128 v[40:43], v140 offset:49152
	ds_read_b128 v[44:47], v140 offset:50176
	ds_read_b128 v[228:231], v140 offset:51200
	ds_read_b128 v[232:235], v140 offset:52224
	ds_read_b128 v[236:239], v140 offset:53248
	ds_read_b128 v[240:243], v140 offset:54272
	ds_read_b128 v[244:247], v140 offset:55296
	ds_read_b128 v[248:251], v140 offset:56320
	global_load_lds_dwordx4 v[16:17], off
	s_add_i32 m0, s9, 0x2000
	s_add_u32 s18, s18, 0x8080
	v_lshl_add_u64 v[16:17], v[226:227], 0, s[34:35]
	s_addc_u32 s19, s19, 0
	s_add_i32 s9, s11, s29
	global_load_lds_dwordx4 v[16:17], off
	v_lshl_add_u64 v[16:17], s[18:19], 0, v[132:133]
	s_mov_b32 m0, s9
	s_nop 0
	global_load_lds_dwordx4 v[16:17], off
	v_lshl_add_u64 v[16:17], s[18:19], 0, v[128:129]
	s_add_i32 m0, s9, 0x2000
	s_nop 0
	global_load_lds_dwordx4 v[16:17], off
	v_lshl_add_u64 v[16:17], v[252:253], 0, s[34:35]
	s_mov_b32 m0, s52
	s_nop 0
	global_load_lds_dwordx4 v[16:17], off
	v_lshl_add_u64 v[16:17], v[178:179], 0, s[34:35]
	s_mov_b32 m0, s53
	s_nop 0
	global_load_lds_dwordx4 v[16:17], off
	s_waitcnt vmcnt(8) lgkmcnt(0)
	s_barrier
	s_setprio 1
	v_mfma_f32_16x16x32_bf16 v[16:19], v[24:27], v[40:43], v[142:145]
	v_mfma_f32_16x16x32_bf16 v[48:51], v[28:31], v[44:47], v[16:19]
	v_mfma_f32_16x16x32_bf16 v[16:19], v[60:63], v[40:43], v[146:149]
	v_mfma_f32_16x16x32_bf16 v[52:55], v[198:201], v[44:47], v[16:19]
	v_mfma_f32_16x16x32_bf16 v[16:19], v[24:27], v[228:231], v[150:153]
	v_mfma_f32_16x16x32_bf16 v[32:35], v[28:31], v[232:235], v[16:19]
	v_mfma_f32_16x16x32_bf16 v[16:19], v[60:63], v[228:231], v[154:157]
	v_mfma_f32_16x16x32_bf16 v[36:39], v[198:201], v[232:235], v[16:19]
	v_mfma_f32_16x16x32_bf16 v[16:19], v[24:27], v[236:239], v[158:161]
	v_mfma_f32_16x16x32_bf16 v[20:23], v[60:63], v[236:239], v[162:165]
	v_mfma_f32_16x16x32_bf16 v[0:3], v[24:27], v[244:247], v[0:3]
	v_mfma_f32_16x16x32_bf16 v[4:7], v[60:63], v[244:247], v[4:7]
	v_mfma_f32_16x16x32_bf16 v[16:19], v[28:31], v[240:243], v[16:19]
	v_mfma_f32_16x16x32_bf16 v[20:23], v[198:201], v[240:243], v[20:23]
	v_mfma_f32_16x16x32_bf16 v[0:3], v[28:31], v[248:251], v[0:3]
	v_mfma_f32_16x16x32_bf16 v[4:7], v[198:201], v[248:251], v[4:7]
	v_mfma_f32_16x16x32_bf16 v[8:11], v[202:205], v[40:43], v[8:11]
	v_mfma_f32_16x16x32_bf16 v[56:59], v[206:209], v[44:47], v[8:11]
	v_mfma_f32_16x16x32_bf16 v[8:11], v[210:213], v[40:43], v[12:15]
	v_mfma_f32_16x16x32_bf16 v[60:63], v[220:223], v[44:47], v[8:11]
	v_mfma_f32_16x16x32_bf16 v[8:11], v[202:205], v[228:231], v[166:169]
	v_mfma_f32_16x16x32_bf16 v[40:43], v[206:209], v[232:235], v[8:11]
	v_mfma_f32_16x16x32_bf16 v[8:11], v[210:213], v[228:231], v[170:173]
	v_mfma_f32_16x16x32_bf16 v[44:47], v[220:223], v[232:235], v[8:11]
	v_mfma_f32_16x16x32_bf16 v[8:11], v[202:205], v[236:239], v[182:185]
	v_mfma_f32_16x16x32_bf16 v[24:27], v[206:209], v[240:243], v[8:11]
	v_mfma_f32_16x16x32_bf16 v[8:11], v[210:213], v[236:239], v[186:189]
	v_mfma_f32_16x16x32_bf16 v[28:31], v[220:223], v[240:243], v[8:11]
	s_setprio 2
	s_barrier
	v_mfma_f32_16x16x32_bf16 v[8:11], v[202:205], v[244:247], v[190:193]
	v_mfma_f32_16x16x32_bf16 v[12:15], v[210:213], v[244:247], v[194:197]
	v_mfma_f32_16x16x32_bf16 v[8:11], v[206:209], v[248:251], v[8:11]
	v_mfma_f32_16x16x32_bf16 v[12:15], v[220:223], v[248:251], v[12:15]
	s_setprio 0
	s_andn2_b64 vcc, exec, s[4:5]
	s_cbranch_vccnz .LBB0_428
	s_barrier

.LBB0_432:
	ds_read_b32 v0, v214
	s_waitcnt lgkmcnt(0)
	v_readfirstlane_b32 s43, v0
	ds_read_b32 v0, v215
	s_getreg_b32 s0, hwreg(HW_REG_XCC_ID, 0, 4)
	s_waitcnt vmcnt(0) lgkmcnt(0)
	s_barrier
	v_readfirstlane_b32 s44, v0
	s_mov_b64 s[40:41], exec
	v_readlane_b32 s2, v255, 0
	v_readlane_b32 s3, v255, 1
	s_and_b64 s[2:3], s[40:41], s[2:3]
	s_mov_b64 exec, s[2:3]
	s_cbranch_execz .LBB0_476
	s_waitcnt vmcnt(0) expcnt(0) lgkmcnt(0)
	buffer_inv sc1
	ds_read_b32 v2, v217
	ds_read_b32 v0, v218
	s_and_b32 s62, s0, 15
	s_waitcnt lgkmcnt(1)
	v_cmp_ne_u32_e32 vcc, 0, v2
	s_cbranch_vccnz .LBB0_447
	s_add_u32 s0, s43, 0x600200
	s_addc_u32 s1, s44, 0
	s_add_u32 s2, s43, 0x600400
	s_addc_u32 s3, s44, 0
	s_add_u32 s4, s43, 0x600500
	s_addc_u32 s5, s44, 0
	s_add_u32 s6, s43, 0x600600
	s_addc_u32 s7, s44, 0
	s_add_u32 s8, s43, 0x600700
	s_addc_u32 s9, s44, 0
	s_add_u32 s10, s43, 0x600800
	s_addc_u32 s11, s44, 0
	s_add_u32 s12, s43, 0x600900
	s_addc_u32 s13, s44, 0
	s_add_u32 s14, s43, 0x600a00
	s_addc_u32 s15, s44, 0
	s_add_u32 s16, s43, 0x600b00
	s_addc_u32 s17, s44, 0
	s_add_u32 s18, s43, 0x600c00
	s_addc_u32 s19, s44, 0
	s_add_u32 s20, s43, 0x600d00
	s_addc_u32 s21, s44, 0
	s_add_u32 s22, s43, 0x600e00
	s_addc_u32 s23, s44, 0
	s_add_u32 s24, s43, 0x600f00
	s_addc_u32 s25, s44, 0
	s_add_u32 s26, s43, 0x601000
	s_addc_u32 s27, s44, 0
	s_add_u32 s28, s43, 0x601100
	s_addc_u32 s29, s44, 0
	s_add_u32 s50, s43, 0x601200
	s_addc_u32 s51, s44, 0
	s_add_u32 s52, s43, 0x601300
	s_addc_u32 s53, s44, 0
	s_mov_b32 s63, 1
	s_mov_b64 s[54:55], 0
	s_branch .LBB0_437

.LBB0_509:
	ds_read_b32 v0, v214
	s_waitcnt lgkmcnt(0)
	v_readfirstlane_b32 s43, v0
	ds_read_b32 v0, v215
	s_getreg_b32 s0, hwreg(HW_REG_XCC_ID, 0, 4)
	s_waitcnt vmcnt(0) lgkmcnt(0)
	s_barrier
	v_readfirstlane_b32 s44, v0
	s_mov_b64 s[48:49], exec
	v_readlane_b32 s2, v255, 0
	v_readlane_b32 s3, v255, 1
	s_and_b64 s[2:3], s[48:49], s[2:3]
	s_mov_b64 exec, s[2:3]
	s_cbranch_execz .LBB0_553
	s_waitcnt vmcnt(0) expcnt(0) lgkmcnt(0)
	buffer_inv sc1
	ds_read_b32 v2, v217
	ds_read_b32 v0, v218
	s_and_b32 s62, s0, 15
	s_waitcnt lgkmcnt(1)
	v_cmp_ne_u32_e32 vcc, 0, v2
	s_cbranch_vccnz .LBB0_524
	s_add_u32 s0, s43, 0x600200
	s_addc_u32 s1, s44, 0
	s_add_u32 s2, s43, 0x600400
	s_addc_u32 s3, s44, 0
	s_add_u32 s4, s43, 0x600500
	s_addc_u32 s5, s44, 0
	s_add_u32 s6, s43, 0x600600
	s_addc_u32 s7, s44, 0
	s_add_u32 s8, s43, 0x600700
	s_addc_u32 s9, s44, 0
	s_add_u32 s10, s43, 0x600800
	s_addc_u32 s11, s44, 0
	s_add_u32 s12, s43, 0x600900
	s_addc_u32 s13, s44, 0
	s_add_u32 s14, s43, 0x600a00
	s_addc_u32 s15, s44, 0
	s_add_u32 s16, s43, 0x600b00
	s_addc_u32 s17, s44, 0
	s_add_u32 s18, s43, 0x600c00
	s_addc_u32 s19, s44, 0
	s_add_u32 s20, s43, 0x600d00
	s_addc_u32 s21, s44, 0
	s_add_u32 s22, s43, 0x600e00
	s_addc_u32 s23, s44, 0
	s_add_u32 s24, s43, 0x600f00
	s_addc_u32 s25, s44, 0
	s_add_u32 s26, s43, 0x601000
	s_addc_u32 s27, s44, 0
	s_add_u32 s28, s43, 0x601100
	s_addc_u32 s29, s44, 0
	s_add_u32 s52, s43, 0x601200
	s_addc_u32 s53, s44, 0
	s_add_u32 s54, s43, 0x601300
	s_addc_u32 s55, s44, 0
	s_mov_b32 s63, 1
	s_mov_b64 s[56:57], 0
	s_branch .LBB0_514

.LBB0_579:
	ds_read_b32 v0, v214
	s_waitcnt lgkmcnt(0)
	v_readfirstlane_b32 s43, v0
	ds_read_b32 v0, v215
	s_getreg_b32 s0, hwreg(HW_REG_XCC_ID, 0, 4)
	s_waitcnt vmcnt(0) lgkmcnt(0)
	s_barrier
	v_readfirstlane_b32 s44, v0
	s_mov_b64 s[38:39], exec
	v_readlane_b32 s2, v255, 0
	v_readlane_b32 s3, v255, 1
	s_and_b64 s[2:3], s[38:39], s[2:3]
	s_mov_b64 exec, s[2:3]
	s_cbranch_execz .LBB0_623
	s_waitcnt vmcnt(0) expcnt(0) lgkmcnt(0)
	buffer_inv sc1
	ds_read_b32 v2, v217
	ds_read_b32 v0, v218
	s_and_b32 s62, s0, 15
	s_waitcnt lgkmcnt(1)
	v_cmp_ne_u32_e32 vcc, 0, v2
	s_cbranch_vccnz .LBB0_594
	s_add_u32 s0, s43, 0x600200
	s_addc_u32 s1, s44, 0
	s_add_u32 s2, s43, 0x600400
	s_addc_u32 s3, s44, 0
	s_add_u32 s4, s43, 0x600500
	s_addc_u32 s5, s44, 0
	s_add_u32 s6, s43, 0x600600
	s_addc_u32 s7, s44, 0
	s_add_u32 s8, s43, 0x600700
	s_addc_u32 s9, s44, 0
	s_add_u32 s10, s43, 0x600800
	s_addc_u32 s11, s44, 0
	s_add_u32 s12, s43, 0x600900
	s_addc_u32 s13, s44, 0
	s_add_u32 s14, s43, 0x600a00
	s_addc_u32 s15, s44, 0
	s_add_u32 s16, s43, 0x600b00
	s_addc_u32 s17, s44, 0
	s_add_u32 s18, s43, 0x600c00
	s_addc_u32 s19, s44, 0
	s_add_u32 s20, s43, 0x600d00
	s_addc_u32 s21, s44, 0
	s_add_u32 s22, s43, 0x600e00
	s_addc_u32 s23, s44, 0
	s_add_u32 s24, s43, 0x600f00
	s_addc_u32 s25, s44, 0
	s_add_u32 s26, s43, 0x601000
	s_addc_u32 s27, s44, 0
	s_add_u32 s28, s43, 0x601100
	s_addc_u32 s29, s44, 0
	s_add_u32 s40, s43, 0x601200
	s_addc_u32 s41, s44, 0
	s_add_u32 s46, s43, 0x601300
	s_addc_u32 s47, s44, 0
	s_mov_b32 s63, 1
	s_mov_b64 s[48:49], 0
	s_branch .LBB0_584

.LBB0_633:
	s_ashr_i32 s13, s12, 31
	s_lshl_b64 s[14:15], s[12:13], 19
	s_add_u32 s14, s37, s14
	s_addc_u32 s15, s42, s15
	s_and_b64 s[16:17], s[4:5], exec
	s_cselect_b32 s13, s15, s23
	s_cselect_b32 s19, s14, s22
	s_ashr_i32 s11, s10, 31
	s_lshl_b64 s[16:17], s[10:11], 19
	s_add_u32 s16, s29, s16
	s_addc_u32 s17, s43, s17
	s_and_b64 s[24:25], s[4:5], exec
	s_cselect_b32 s11, s17, s21
	s_cselect_b32 s60, s16, s20
	s_add_u32 s61, s20, 0x100
	s_addc_u32 s62, s21, 0
	s_add_u32 s20, s22, 0x40080
	s_addc_u32 s21, s23, 0
	s_mov_b32 s63, -2
	s_add_u32 s22, s20, 0xfffc0080
	s_addc_u32 s23, s21, -1
	s_add_i32 s64, 0, 0x10000
	s_cmp_eq_u32 s63, 12
	s_cselect_b32 s25, s13, s23
	s_cselect_b32 s24, s19, s22
	s_cselect_b32 s23, s11, s62
	s_cselect_b32 s22, s60, s61
	s_add_i32 s68, 0, 0x14000
	s_waitcnt lgkmcnt(0)
	s_lshl_b32 s74, s18, 8
	v_add_u32_e32 v178, s74, v182
	v_ashrrev_i32_e32 v179, 31, v178
	v_lshlrev_b64 v[178:179], 6, v[178:179]
	v_lshl_add_u64 v[178:179], s[70:71], 0, v[178:179]
	s_and_saveexec_b64 s[78:79], s[2:3]
	global_load_dwordx4 v[238:241], v[178:179], off
	global_load_dwordx4 v[242:245], v[178:179], off offset:16
	global_load_dwordx4 v[246:249], v[178:179], off offset:32
	global_load_dwordx4 v[250:253], v[178:179], off offset:48
	s_mov_b64 exec, s[78:79]
	v_add_u32_e32 v140, s64, v175
	v_add_u32_e32 v170, s68, v175
	ds_read_b128 v[128:131], v140
	ds_read_b128 v[132:135], v140 offset:1024
	ds_read_b128 v[136:139], v140 offset:2048
	ds_read_b128 v[140:143], v140 offset:3072
	ds_read_b128 v[144:147], v170
	ds_read_b128 v[162:165], v170 offset:1024
	ds_read_b128 v[166:169], v170 offset:2048
	ds_read_b128 v[170:173], v170 offset:3072
	s_add_i32 m0, s50, 0xc000
	ds_read_b128 v[186:189], v185
	ds_read_b128 v[190:193], v185 offset:1024
	ds_read_b128 v[194:197], v185 offset:2048
	ds_read_b128 v[198:201], v185 offset:3072
	ds_read_b128 v[202:205], v185 offset:4096
	ds_read_b128 v[206:209], v185 offset:5120
	ds_read_b128 v[210:213], v185 offset:6144
	ds_read_b128 v[228:231], v185 offset:7168
	global_load_lds_dwordx4 v160, s[20:21]
	s_add_i32 m0, s50, 0xe000
	s_nop 0
	global_load_lds_dwordx4 v158, s[20:21]
	s_waitcnt vmcnt(16) lgkmcnt(0)
	s_barrier
	s_setprio 1
	v_mfma_f32_16x16x32_bf16 v[124:127], v[128:131], v[186:189], 0
	v_mfma_f32_16x16x32_bf16 v[120:123], v[136:139], v[186:189], 0
	v_mfma_f32_16x16x32_bf16 v[108:111], v[128:131], v[194:197], 0
	v_mfma_f32_16x16x32_bf16 v[104:107], v[136:139], v[194:197], 0
	v_mfma_f32_16x16x32_bf16 v[92:95], v[128:131], v[202:205], 0
	v_mfma_f32_16x16x32_bf16 v[88:91], v[136:139], v[202:205], 0
	v_mfma_f32_16x16x32_bf16 v[76:79], v[128:131], v[210:213], 0
	v_mfma_f32_16x16x32_bf16 v[72:75], v[136:139], v[210:213], 0
	v_mfma_f32_16x16x32_bf16 v[124:127], v[132:135], v[190:193], v[124:127]
	v_mfma_f32_16x16x32_bf16 v[120:123], v[140:143], v[190:193], v[120:123]
	v_mfma_f32_16x16x32_bf16 v[108:111], v[132:135], v[198:201], v[108:111]
	v_mfma_f32_16x16x32_bf16 v[104:107], v[140:143], v[198:201], v[104:107]
	v_mfma_f32_16x16x32_bf16 v[92:95], v[132:135], v[206:209], v[92:95]
	v_mfma_f32_16x16x32_bf16 v[88:91], v[140:143], v[206:209], v[88:91]
	v_mfma_f32_16x16x32_bf16 v[76:79], v[132:135], v[228:231], v[76:79]
	v_mfma_f32_16x16x32_bf16 v[72:75], v[140:143], v[228:231], v[72:75]
	v_mfma_f32_16x16x32_bf16 v[116:119], v[144:147], v[186:189], 0
	v_mfma_f32_16x16x32_bf16 v[112:115], v[166:169], v[186:189], 0
	v_mfma_f32_16x16x32_bf16 v[100:103], v[144:147], v[194:197], 0
	v_mfma_f32_16x16x32_bf16 v[96:99], v[166:169], v[194:197], 0
	v_mfma_f32_16x16x32_bf16 v[84:87], v[144:147], v[202:205], 0
	v_mfma_f32_16x16x32_bf16 v[80:83], v[166:169], v[202:205], 0
	v_mfma_f32_16x16x32_bf16 v[68:71], v[144:147], v[210:213], 0
	v_mfma_f32_16x16x32_bf16 v[64:67], v[166:169], v[210:213], 0
	v_mfma_f32_16x16x32_bf16 v[116:119], v[162:165], v[190:193], v[116:119]
	v_mfma_f32_16x16x32_bf16 v[112:115], v[170:173], v[190:193], v[112:115]
	v_mfma_f32_16x16x32_bf16 v[100:103], v[162:165], v[198:201], v[100:103]
	v_mfma_f32_16x16x32_bf16 v[96:99], v[170:173], v[198:201], v[96:99]
	s_setprio 2
	s_barrier
	v_mfma_f32_16x16x32_bf16 v[84:87], v[162:165], v[206:209], v[84:87]
	v_mfma_f32_16x16x32_bf16 v[80:83], v[170:173], v[206:209], v[80:83]
	v_mfma_f32_16x16x32_bf16 v[68:71], v[162:165], v[228:231], v[68:71]
	v_mfma_f32_16x16x32_bf16 v[64:67], v[170:173], v[228:231], v[64:67]
	s_setprio 0
	s_add_i32 s64, s64, s46
	s_add_u32 s94, s22, s34
	s_addc_u32 s95, s23, s35
	s_mov_b32 m0, s64
	ds_read_b128 v[186:189], v185 offset:16384
	ds_read_b128 v[190:193], v185 offset:17408
	ds_read_b128 v[194:197], v185 offset:18432
	ds_read_b128 v[198:201], v185 offset:19456
	ds_read_b128 v[202:205], v185 offset:20480
	ds_read_b128 v[206:209], v185 offset:21504
	ds_read_b128 v[210:213], v185 offset:22528
	ds_read_b128 v[228:231], v185 offset:23552
	global_load_lds_dwordx4 v152, s[22:23]
	s_add_i32 m0, s64, 0x2000
	s_add_u32 s64, s22, 0x40000
	s_addc_u32 s65, s23, 0
	s_add_i32 s68, s68, s46
	global_load_lds_dwordx4 v148, s[22:23]
	s_mov_b32 m0, s68
	s_nop 0
	global_load_lds_dwordx4 v152, s[64:65]
	s_add_i32 m0, s68, 0x2000
	s_nop 0
	global_load_lds_dwordx4 v148, s[64:65]
	s_add_u32 s98, s24, s34
	s_addc_u32 s99, s25, s35
	s_mov_b32 m0, s50
	s_nop 0
	global_load_lds_dwordx4 v154, s[24:25]
	s_mov_b32 m0, s51
	s_nop 0
	global_load_lds_dwordx4 v150, s[24:25]
	s_waitcnt vmcnt(8) lgkmcnt(0)
	s_barrier
	s_setprio 1
	v_mfma_f32_16x16x32_bf16 v[60:63], v[128:131], v[186:189], 0
	v_mfma_f32_16x16x32_bf16 v[56:59], v[136:139], v[186:189], 0
	v_mfma_f32_16x16x32_bf16 v[48:51], v[128:131], v[194:197], 0
	v_mfma_f32_16x16x32_bf16 v[40:43], v[136:139], v[194:197], 0
	v_mfma_f32_16x16x32_bf16 v[32:35], v[128:131], v[202:205], 0
	v_mfma_f32_16x16x32_bf16 v[24:27], v[136:139], v[202:205], 0
	v_mfma_f32_16x16x32_bf16 v[16:19], v[128:131], v[210:213], 0
	v_mfma_f32_16x16x32_bf16 v[8:11], v[136:139], v[210:213], 0
	v_mfma_f32_16x16x32_bf16 v[60:63], v[132:135], v[190:193], v[60:63]
	v_mfma_f32_16x16x32_bf16 v[56:59], v[140:143], v[190:193], v[56:59]
	v_mfma_f32_16x16x32_bf16 v[48:51], v[132:135], v[198:201], v[48:51]
	v_mfma_f32_16x16x32_bf16 v[40:43], v[140:143], v[198:201], v[40:43]
	v_mfma_f32_16x16x32_bf16 v[32:35], v[132:135], v[206:209], v[32:35]
	v_mfma_f32_16x16x32_bf16 v[24:27], v[140:143], v[206:209], v[24:27]
	v_mfma_f32_16x16x32_bf16 v[16:19], v[132:135], v[228:231], v[16:19]
	v_mfma_f32_16x16x32_bf16 v[8:11], v[140:143], v[228:231], v[8:11]
	v_mfma_f32_16x16x32_bf16 v[52:55], v[144:147], v[186:189], 0
	v_mfma_f32_16x16x32_bf16 v[44:47], v[166:169], v[186:189], 0
	v_mfma_f32_16x16x32_bf16 v[36:39], v[144:147], v[194:197], 0
	v_mfma_f32_16x16x32_bf16 v[28:31], v[166:169], v[194:197], 0
	v_mfma_f32_16x16x32_bf16 v[20:23], v[144:147], v[202:205], 0
	v_mfma_f32_16x16x32_bf16 v[12:15], v[166:169], v[202:205], 0
	v_mfma_f32_16x16x32_bf16 v[4:7], v[144:147], v[210:213], 0
	v_mfma_f32_16x16x32_bf16 v[0:3], v[166:169], v[210:213], 0
	v_mfma_f32_16x16x32_bf16 v[52:55], v[162:165], v[190:193], v[52:55]
	v_mfma_f32_16x16x32_bf16 v[44:47], v[170:173], v[190:193], v[44:47]
	v_mfma_f32_16x16x32_bf16 v[36:39], v[162:165], v[198:201], v[36:39]
	v_mfma_f32_16x16x32_bf16 v[28:31], v[170:173], v[198:201], v[28:31]
	s_setprio 2
	s_barrier
	v_mfma_f32_16x16x32_bf16 v[20:23], v[162:165], v[206:209], v[20:23]
	v_mfma_f32_16x16x32_bf16 v[12:15], v[170:173], v[206:209], v[12:15]
	v_mfma_f32_16x16x32_bf16 v[4:7], v[162:165], v[228:231], v[4:7]
	v_mfma_f32_16x16x32_bf16 v[0:3], v[170:173], v[228:231], v[0:3]
	s_setprio 0
	s_and_saveexec_b64 s[78:79], s[2:3]
	v_add_f32_e32 v238, v238, v239
	v_add_f32_e32 v240, v240, v241
	v_add_f32_e32 v242, v242, v243
	v_add_f32_e32 v244, v244, v245
	v_add_f32_e32 v246, v246, v247
	v_add_f32_e32 v248, v248, v249
	v_add_f32_e32 v250, v250, v251
	v_add_f32_e32 v252, v252, v253
	v_add_f32_e32 v238, v238, v240
	v_add_f32_e32 v242, v242, v244
	v_add_f32_e32 v246, v246, v248
	v_add_f32_e32 v250, v250, v252
	v_add_f32_e32 v238, v238, v242
	v_add_f32_e32 v246, v246, v250
	v_add_f32_e32 v238, v238, v246
	v_fmamk_f32 v238, v238, 0x3a800000, v216
	v_rsq_f32_e32 v238, v238
	s_nop 0
	ds_write_b32 v183, v238
	s_mov_b64 exec, s[78:79]
	s_add_i32 s64, 0, 0x18000
	s_add_i32 s65, 0, 0x1c000
	v_add_u32_e32 v140, s64, v175
	v_add_u32_e32 v170, s65, v175
	ds_read_b128 v[128:131], v140
	ds_read_b128 v[132:135], v140 offset:1024
	ds_read_b128 v[136:139], v140 offset:2048
	ds_read_b128 v[140:143], v140 offset:3072
	ds_read_b128 v[144:147], v170
	ds_read_b128 v[162:165], v170 offset:1024
	ds_read_b128 v[166:169], v170 offset:2048
	ds_read_b128 v[170:173], v170 offset:3072
	s_add_u32 s24, s24, 0x40000
	s_addc_u32 s25, s25, 0
	s_mov_b32 m0, s52
	ds_read_b128 v[186:189], v185 offset:32768
	ds_read_b128 v[190:193], v185 offset:33792
	ds_read_b128 v[194:197], v185 offset:34816
	ds_read_b128 v[198:201], v185 offset:35840
	ds_read_b128 v[202:205], v185 offset:36864
	ds_read_b128 v[206:209], v185 offset:37888
	ds_read_b128 v[210:213], v185 offset:38912
	ds_read_b128 v[228:231], v185 offset:39936
	global_load_lds_dwordx4 v154, s[24:25]
	s_mov_b32 m0, s53
	s_nop 0
	global_load_lds_dwordx4 v150, s[24:25]
	s_waitcnt vmcnt(8) lgkmcnt(0)
	s_barrier
	s_setprio 1
	v_mfma_f32_16x16x32_bf16 v[124:127], v[128:131], v[186:189], v[124:127]
	v_mfma_f32_16x16x32_bf16 v[120:123], v[136:139], v[186:189], v[120:123]
	v_mfma_f32_16x16x32_bf16 v[108:111], v[128:131], v[194:197], v[108:111]
	v_mfma_f32_16x16x32_bf16 v[104:107], v[136:139], v[194:197], v[104:107]
	v_mfma_f32_16x16x32_bf16 v[92:95], v[128:131], v[202:205], v[92:95]
	v_mfma_f32_16x16x32_bf16 v[88:91], v[136:139], v[202:205], v[88:91]
	v_mfma_f32_16x16x32_bf16 v[76:79], v[128:131], v[210:213], v[76:79]
	v_mfma_f32_16x16x32_bf16 v[72:75], v[136:139], v[210:213], v[72:75]
	v_mfma_f32_16x16x32_bf16 v[124:127], v[132:135], v[190:193], v[124:127]
	v_mfma_f32_16x16x32_bf16 v[120:123], v[140:143], v[190:193], v[120:123]
	v_mfma_f32_16x16x32_bf16 v[108:111], v[132:135], v[198:201], v[108:111]
	v_mfma_f32_16x16x32_bf16 v[104:107], v[140:143], v[198:201], v[104:107]
	v_mfma_f32_16x16x32_bf16 v[92:95], v[132:135], v[206:209], v[92:95]
	v_mfma_f32_16x16x32_bf16 v[88:91], v[140:143], v[206:209], v[88:91]
	v_mfma_f32_16x16x32_bf16 v[76:79], v[132:135], v[228:231], v[76:79]
	v_mfma_f32_16x16x32_bf16 v[72:75], v[140:143], v[228:231], v[72:75]
	v_mfma_f32_16x16x32_bf16 v[116:119], v[144:147], v[186:189], v[116:119]
	v_mfma_f32_16x16x32_bf16 v[112:115], v[166:169], v[186:189], v[112:115]
	v_mfma_f32_16x16x32_bf16 v[100:103], v[144:147], v[194:197], v[100:103]
	v_mfma_f32_16x16x32_bf16 v[96:99], v[166:169], v[194:197], v[96:99]
	v_mfma_f32_16x16x32_bf16 v[84:87], v[144:147], v[202:205], v[84:87]
	v_mfma_f32_16x16x32_bf16 v[80:83], v[166:169], v[202:205], v[80:83]
	v_mfma_f32_16x16x32_bf16 v[68:71], v[144:147], v[210:213], v[68:71]
	v_mfma_f32_16x16x32_bf16 v[64:67], v[166:169], v[210:213], v[64:67]
	v_mfma_f32_16x16x32_bf16 v[116:119], v[162:165], v[190:193], v[116:119]
	v_mfma_f32_16x16x32_bf16 v[112:115], v[170:173], v[190:193], v[112:115]
	v_mfma_f32_16x16x32_bf16 v[100:103], v[162:165], v[198:201], v[100:103]
	v_mfma_f32_16x16x32_bf16 v[96:99], v[170:173], v[198:201], v[96:99]
	s_setprio 2
	s_barrier
	v_mfma_f32_16x16x32_bf16 v[84:87], v[162:165], v[206:209], v[84:87]
	v_mfma_f32_16x16x32_bf16 v[80:83], v[170:173], v[206:209], v[80:83]
	v_mfma_f32_16x16x32_bf16 v[68:71], v[162:165], v[228:231], v[68:71]
	v_mfma_f32_16x16x32_bf16 v[64:67], v[170:173], v[228:231], v[64:67]
	s_setprio 0
	s_min_i32 s74, s18, 0x80
	s_ashr_i32 s74, s74, 3
	s_mul_hi_i32 s75, s74, 0x3000
	s_mulk_i32 s74, 0x3000
	s_add_u32 s74, s54, s74
	s_addc_u32 s75, s55, s75
	s_lshl_b32 s76, s44, 8
	s_ashr_i32 s77, s76, 31
	s_lshl_b64 s[76:77], s[76:77], 2
	s_add_u32 s74, s74, s76
	s_addc_u32 s75, s75, s77
	v_lshl_add_u64 v[178:179], s[74:75], 0, v[176:177]
	global_load_dwordx4 v[238:241], v[178:179], off
	global_load_dwordx4 v[242:245], v[178:179], off offset:16
	global_load_dwordx4 v[246:249], v[178:179], off offset:512
	global_load_dwordx4 v[250:253], v[178:179], off offset:528
	s_add_i32 s24, s64, s46
	s_mov_b32 m0, s24
	ds_read_b128 v[186:189], v185 offset:49152
	ds_read_b128 v[190:193], v185 offset:50176
	ds_read_b128 v[194:197], v185 offset:51200
	ds_read_b128 v[198:201], v185 offset:52224
	ds_read_b128 v[202:205], v185 offset:53248
	ds_read_b128 v[206:209], v185 offset:54272
	ds_read_b128 v[210:213], v185 offset:55296
	ds_read_b128 v[228:231], v185 offset:56320
	global_load_lds_dwordx4 v152, s[94:95]
	s_add_i32 m0, s24, 0x2000
	s_add_u32 s22, s22, 0x40080
	s_addc_u32 s23, s23, 0
	s_add_i32 s24, s65, s46
	global_load_lds_dwordx4 v148, s[94:95]
	s_mov_b32 m0, s24
	s_nop 0
	global_load_lds_dwordx4 v152, s[22:23]
	s_add_i32 m0, s24, 0x2000
	s_nop 0
	global_load_lds_dwordx4 v148, s[22:23]
	s_mov_b32 m0, s56
	s_nop 0
	global_load_lds_dwordx4 v154, s[98:99]
	s_mov_b32 m0, s57
	s_nop 0
	global_load_lds_dwordx4 v150, s[98:99]
	s_waitcnt vmcnt(12) lgkmcnt(0)
	s_barrier
	s_setprio 1
	v_mfma_f32_16x16x32_bf16 v[60:63], v[128:131], v[186:189], v[60:63]
	v_mfma_f32_16x16x32_bf16 v[56:59], v[136:139], v[186:189], v[56:59]
	v_mfma_f32_16x16x32_bf16 v[48:51], v[128:131], v[194:197], v[48:51]
	v_mfma_f32_16x16x32_bf16 v[40:43], v[136:139], v[194:197], v[40:43]
	v_mfma_f32_16x16x32_bf16 v[32:35], v[128:131], v[202:205], v[32:35]
	v_mfma_f32_16x16x32_bf16 v[24:27], v[136:139], v[202:205], v[24:27]
	v_mfma_f32_16x16x32_bf16 v[16:19], v[128:131], v[210:213], v[16:19]
	v_mfma_f32_16x16x32_bf16 v[8:11], v[136:139], v[210:213], v[8:11]
	v_mfma_f32_16x16x32_bf16 v[60:63], v[132:135], v[190:193], v[60:63]
	v_mfma_f32_16x16x32_bf16 v[56:59], v[140:143], v[190:193], v[56:59]
	v_mfma_f32_16x16x32_bf16 v[48:51], v[132:135], v[198:201], v[48:51]
	v_mfma_f32_16x16x32_bf16 v[40:43], v[140:143], v[198:201], v[40:43]
	v_mfma_f32_16x16x32_bf16 v[32:35], v[132:135], v[206:209], v[32:35]
	v_mfma_f32_16x16x32_bf16 v[24:27], v[140:143], v[206:209], v[24:27]
	v_mfma_f32_16x16x32_bf16 v[16:19], v[132:135], v[228:231], v[16:19]
	v_mfma_f32_16x16x32_bf16 v[8:11], v[140:143], v[228:231], v[8:11]
	v_mfma_f32_16x16x32_bf16 v[52:55], v[144:147], v[186:189], v[52:55]
	v_mfma_f32_16x16x32_bf16 v[44:47], v[166:169], v[186:189], v[44:47]
	v_mfma_f32_16x16x32_bf16 v[36:39], v[144:147], v[194:197], v[36:39]
	v_mfma_f32_16x16x32_bf16 v[28:31], v[166:169], v[194:197], v[28:31]
	v_mfma_f32_16x16x32_bf16 v[20:23], v[144:147], v[202:205], v[20:23]
	v_mfma_f32_16x16x32_bf16 v[12:15], v[166:169], v[202:205], v[12:15]
	v_mfma_f32_16x16x32_bf16 v[4:7], v[144:147], v[210:213], v[4:7]
	v_mfma_f32_16x16x32_bf16 v[0:3], v[166:169], v[210:213], v[0:3]
	v_mfma_f32_16x16x32_bf16 v[52:55], v[162:165], v[190:193], v[52:55]
	v_mfma_f32_16x16x32_bf16 v[44:47], v[170:173], v[190:193], v[44:47]
	v_mfma_f32_16x16x32_bf16 v[36:39], v[162:165], v[198:201], v[36:39]
	v_mfma_f32_16x16x32_bf16 v[28:31], v[170:173], v[198:201], v[28:31]
	s_setprio 2
	s_barrier
	v_mfma_f32_16x16x32_bf16 v[20:23], v[162:165], v[206:209], v[20:23]
	v_mfma_f32_16x16x32_bf16 v[12:15], v[170:173], v[206:209], v[12:15]
	v_mfma_f32_16x16x32_bf16 v[4:7], v[162:165], v[228:231], v[4:7]
	v_mfma_f32_16x16x32_bf16 v[0:3], v[170:173], v[228:231], v[0:3]
	s_setprio 0
	s_add_i32 s63, s63, 2
	s_add_u32 s61, s61, 0x100
	s_addc_u32 s62, s62, 0
	s_add_u32 s20, s20, 0x100
	s_addc_u32 s21, s21, 0
	s_cmp_gt_u32 s63, 13
	s_cbranch_scc1 .Lpeel_exit_1
.LBB0_634:
	s_add_u32 s22, s20, 0xfffc0080
	s_addc_u32 s23, s21, -1
	s_add_i32 s64, 0, 0x10000
	s_cmp_eq_u32 s63, 12
	s_cselect_b32 s25, s13, s23
	s_cselect_b32 s24, s19, s22
	s_cselect_b32 s23, s11, s62
	s_cselect_b32 s22, s60, s61
	s_add_i32 s68, 0, 0x14000
	s_waitcnt lgkmcnt(0)
	v_add_u32_e32 v140, s64, v175
	v_add_u32_e32 v170, s68, v175
	ds_read_b128 v[128:131], v140
	ds_read_b128 v[132:135], v140 offset:1024
	ds_read_b128 v[136:139], v140 offset:2048
	ds_read_b128 v[140:143], v140 offset:3072
	ds_read_b128 v[144:147], v170
	ds_read_b128 v[162:165], v170 offset:1024
	ds_read_b128 v[166:169], v170 offset:2048
	ds_read_b128 v[170:173], v170 offset:3072
	s_add_i32 m0, s50, 0xc000
	ds_read_b128 v[186:189], v185
	ds_read_b128 v[190:193], v185 offset:1024
	ds_read_b128 v[194:197], v185 offset:2048
	ds_read_b128 v[198:201], v185 offset:3072
	ds_read_b128 v[202:205], v185 offset:4096
	ds_read_b128 v[206:209], v185 offset:5120
	ds_read_b128 v[210:213], v185 offset:6144
	ds_read_b128 v[228:231], v185 offset:7168
	global_load_lds_dwordx4 v160, s[20:21]
	s_add_i32 m0, s50, 0xe000
	s_nop 0
	global_load_lds_dwordx4 v158, s[20:21]
	s_waitcnt vmcnt(8) lgkmcnt(0)
	s_barrier
	s_setprio 1
	v_mfma_f32_16x16x32_bf16 v[124:127], v[128:131], v[186:189], v[124:127]
	v_mfma_f32_16x16x32_bf16 v[120:123], v[136:139], v[186:189], v[120:123]
	v_mfma_f32_16x16x32_bf16 v[108:111], v[128:131], v[194:197], v[108:111]
	v_mfma_f32_16x16x32_bf16 v[104:107], v[136:139], v[194:197], v[104:107]
	v_mfma_f32_16x16x32_bf16 v[92:95], v[128:131], v[202:205], v[92:95]
	v_mfma_f32_16x16x32_bf16 v[88:91], v[136:139], v[202:205], v[88:91]
	v_mfma_f32_16x16x32_bf16 v[76:79], v[128:131], v[210:213], v[76:79]
	v_mfma_f32_16x16x32_bf16 v[72:75], v[136:139], v[210:213], v[72:75]
	v_mfma_f32_16x16x32_bf16 v[124:127], v[132:135], v[190:193], v[124:127]
	v_mfma_f32_16x16x32_bf16 v[120:123], v[140:143], v[190:193], v[120:123]
	v_mfma_f32_16x16x32_bf16 v[108:111], v[132:135], v[198:201], v[108:111]
	v_mfma_f32_16x16x32_bf16 v[104:107], v[140:143], v[198:201], v[104:107]
	v_mfma_f32_16x16x32_bf16 v[92:95], v[132:135], v[206:209], v[92:95]
	v_mfma_f32_16x16x32_bf16 v[88:91], v[140:143], v[206:209], v[88:91]
	v_mfma_f32_16x16x32_bf16 v[76:79], v[132:135], v[228:231], v[76:79]
	v_mfma_f32_16x16x32_bf16 v[72:75], v[140:143], v[228:231], v[72:75]
	v_mfma_f32_16x16x32_bf16 v[116:119], v[144:147], v[186:189], v[116:119]
	v_mfma_f32_16x16x32_bf16 v[112:115], v[166:169], v[186:189], v[112:115]
	v_mfma_f32_16x16x32_bf16 v[100:103], v[144:147], v[194:197], v[100:103]
	v_mfma_f32_16x16x32_bf16 v[96:99], v[166:169], v[194:197], v[96:99]
	v_mfma_f32_16x16x32_bf16 v[84:87], v[144:147], v[202:205], v[84:87]
	v_mfma_f32_16x16x32_bf16 v[80:83], v[166:169], v[202:205], v[80:83]
	v_mfma_f32_16x16x32_bf16 v[68:71], v[144:147], v[210:213], v[68:71]
	v_mfma_f32_16x16x32_bf16 v[64:67], v[166:169], v[210:213], v[64:67]
	v_mfma_f32_16x16x32_bf16 v[116:119], v[162:165], v[190:193], v[116:119]
	v_mfma_f32_16x16x32_bf16 v[112:115], v[170:173], v[190:193], v[112:115]
	v_mfma_f32_16x16x32_bf16 v[100:103], v[162:165], v[198:201], v[100:103]
	v_mfma_f32_16x16x32_bf16 v[96:99], v[170:173], v[198:201], v[96:99]
	s_setprio 2
	s_barrier
	v_mfma_f32_16x16x32_bf16 v[84:87], v[162:165], v[206:209], v[84:87]
	v_mfma_f32_16x16x32_bf16 v[80:83], v[170:173], v[206:209], v[80:83]
	v_mfma_f32_16x16x32_bf16 v[68:71], v[162:165], v[228:231], v[68:71]
	v_mfma_f32_16x16x32_bf16 v[64:67], v[170:173], v[228:231], v[64:67]
	s_setprio 0
	s_add_i32 s64, s64, s46
	s_add_u32 s94, s22, s34
	s_addc_u32 s95, s23, s35
	s_mov_b32 m0, s64
	ds_read_b128 v[186:189], v185 offset:16384
	ds_read_b128 v[190:193], v185 offset:17408
	ds_read_b128 v[194:197], v185 offset:18432
	ds_read_b128 v[198:201], v185 offset:19456
	ds_read_b128 v[202:205], v185 offset:20480
	ds_read_b128 v[206:209], v185 offset:21504
	ds_read_b128 v[210:213], v185 offset:22528
	ds_read_b128 v[228:231], v185 offset:23552
	global_load_lds_dwordx4 v152, s[22:23]
	s_add_i32 m0, s64, 0x2000
	s_add_u32 s64, s22, 0x40000
	s_addc_u32 s65, s23, 0
	s_add_i32 s68, s68, s46
	global_load_lds_dwordx4 v148, s[22:23]
	s_mov_b32 m0, s68
	s_nop 0
	global_load_lds_dwordx4 v152, s[64:65]
	s_add_i32 m0, s68, 0x2000
	s_nop 0
	global_load_lds_dwordx4 v148, s[64:65]
	s_add_u32 s98, s24, s34
	s_addc_u32 s99, s25, s35
	s_mov_b32 m0, s50
	s_nop 0
	global_load_lds_dwordx4 v154, s[24:25]
	s_mov_b32 m0, s51
	s_nop 0
	global_load_lds_dwordx4 v150, s[24:25]
	s_waitcnt vmcnt(8) lgkmcnt(0)
	s_barrier
	s_setprio 1
	v_mfma_f32_16x16x32_bf16 v[60:63], v[128:131], v[186:189], v[60:63]
	v_mfma_f32_16x16x32_bf16 v[56:59], v[136:139], v[186:189], v[56:59]
	v_mfma_f32_16x16x32_bf16 v[48:51], v[128:131], v[194:197], v[48:51]
	v_mfma_f32_16x16x32_bf16 v[40:43], v[136:139], v[194:197], v[40:43]
	v_mfma_f32_16x16x32_bf16 v[32:35], v[128:131], v[202:205], v[32:35]
	v_mfma_f32_16x16x32_bf16 v[24:27], v[136:139], v[202:205], v[24:27]
	v_mfma_f32_16x16x32_bf16 v[16:19], v[128:131], v[210:213], v[16:19]
	v_mfma_f32_16x16x32_bf16 v[8:11], v[136:139], v[210:213], v[8:11]
	v_mfma_f32_16x16x32_bf16 v[60:63], v[132:135], v[190:193], v[60:63]
	v_mfma_f32_16x16x32_bf16 v[56:59], v[140:143], v[190:193], v[56:59]
	v_mfma_f32_16x16x32_bf16 v[48:51], v[132:135], v[198:201], v[48:51]
	v_mfma_f32_16x16x32_bf16 v[40:43], v[140:143], v[198:201], v[40:43]
	v_mfma_f32_16x16x32_bf16 v[32:35], v[132:135], v[206:209], v[32:35]
	v_mfma_f32_16x16x32_bf16 v[24:27], v[140:143], v[206:209], v[24:27]
	v_mfma_f32_16x16x32_bf16 v[16:19], v[132:135], v[228:231], v[16:19]
	v_mfma_f32_16x16x32_bf16 v[8:11], v[140:143], v[228:231], v[8:11]
	v_mfma_f32_16x16x32_bf16 v[52:55], v[144:147], v[186:189], v[52:55]
	v_mfma_f32_16x16x32_bf16 v[44:47], v[166:169], v[186:189], v[44:47]
	v_mfma_f32_16x16x32_bf16 v[36:39], v[144:147], v[194:197], v[36:39]
	v_mfma_f32_16x16x32_bf16 v[28:31], v[166:169], v[194:197], v[28:31]
	v_mfma_f32_16x16x32_bf16 v[20:23], v[144:147], v[202:205], v[20:23]
	v_mfma_f32_16x16x32_bf16 v[12:15], v[166:169], v[202:205], v[12:15]
	v_mfma_f32_16x16x32_bf16 v[4:7], v[144:147], v[210:213], v[4:7]
	v_mfma_f32_16x16x32_bf16 v[0:3], v[166:169], v[210:213], v[0:3]
	v_mfma_f32_16x16x32_bf16 v[52:55], v[162:165], v[190:193], v[52:55]
	v_mfma_f32_16x16x32_bf16 v[44:47], v[170:173], v[190:193], v[44:47]
	v_mfma_f32_16x16x32_bf16 v[36:39], v[162:165], v[198:201], v[36:39]
	v_mfma_f32_16x16x32_bf16 v[28:31], v[170:173], v[198:201], v[28:31]
	s_setprio 2
	s_barrier
	v_mfma_f32_16x16x32_bf16 v[20:23], v[162:165], v[206:209], v[20:23]
	v_mfma_f32_16x16x32_bf16 v[12:15], v[170:173], v[206:209], v[12:15]
	v_mfma_f32_16x16x32_bf16 v[4:7], v[162:165], v[228:231], v[4:7]
	v_mfma_f32_16x16x32_bf16 v[0:3], v[170:173], v[228:231], v[0:3]
	s_setprio 0
	s_add_i32 s64, 0, 0x18000
	s_add_i32 s65, 0, 0x1c000
	v_add_u32_e32 v140, s64, v175
	v_add_u32_e32 v170, s65, v175
	ds_read_b128 v[128:131], v140
	ds_read_b128 v[132:135], v140 offset:1024
	ds_read_b128 v[136:139], v140 offset:2048
	ds_read_b128 v[140:143], v140 offset:3072
	ds_read_b128 v[144:147], v170
	ds_read_b128 v[162:165], v170 offset:1024
	ds_read_b128 v[166:169], v170 offset:2048
	ds_read_b128 v[170:173], v170 offset:3072
	s_add_u32 s24, s24, 0x40000
	s_addc_u32 s25, s25, 0
	s_mov_b32 m0, s52
	ds_read_b128 v[186:189], v185 offset:32768
	ds_read_b128 v[190:193], v185 offset:33792
	ds_read_b128 v[194:197], v185 offset:34816
	ds_read_b128 v[198:201], v185 offset:35840
	ds_read_b128 v[202:205], v185 offset:36864
	ds_read_b128 v[206:209], v185 offset:37888
	ds_read_b128 v[210:213], v185 offset:38912
	ds_read_b128 v[228:231], v185 offset:39936
	global_load_lds_dwordx4 v154, s[24:25]
	s_mov_b32 m0, s53
	s_nop 0
	global_load_lds_dwordx4 v150, s[24:25]
	s_waitcnt vmcnt(8) lgkmcnt(0)
	s_barrier
	s_setprio 1
	v_mfma_f32_16x16x32_bf16 v[124:127], v[128:131], v[186:189], v[124:127]
	v_mfma_f32_16x16x32_bf16 v[120:123], v[136:139], v[186:189], v[120:123]
	v_mfma_f32_16x16x32_bf16 v[108:111], v[128:131], v[194:197], v[108:111]
	v_mfma_f32_16x16x32_bf16 v[104:107], v[136:139], v[194:197], v[104:107]
	v_mfma_f32_16x16x32_bf16 v[92:95], v[128:131], v[202:205], v[92:95]
	v_mfma_f32_16x16x32_bf16 v[88:91], v[136:139], v[202:205], v[88:91]
	v_mfma_f32_16x16x32_bf16 v[76:79], v[128:131], v[210:213], v[76:79]
	v_mfma_f32_16x16x32_bf16 v[72:75], v[136:139], v[210:213], v[72:75]
	v_mfma_f32_16x16x32_bf16 v[124:127], v[132:135], v[190:193], v[124:127]
	v_mfma_f32_16x16x32_bf16 v[120:123], v[140:143], v[190:193], v[120:123]
	v_mfma_f32_16x16x32_bf16 v[108:111], v[132:135], v[198:201], v[108:111]
	v_mfma_f32_16x16x32_bf16 v[104:107], v[140:143], v[198:201], v[104:107]
	v_mfma_f32_16x16x32_bf16 v[92:95], v[132:135], v[206:209], v[92:95]
	v_mfma_f32_16x16x32_bf16 v[88:91], v[140:143], v[206:209], v[88:91]
	v_mfma_f32_16x16x32_bf16 v[76:79], v[132:135], v[228:231], v[76:79]
	v_mfma_f32_16x16x32_bf16 v[72:75], v[140:143], v[228:231], v[72:75]
	v_mfma_f32_16x16x32_bf16 v[116:119], v[144:147], v[186:189], v[116:119]
	v_mfma_f32_16x16x32_bf16 v[112:115], v[166:169], v[186:189], v[112:115]
	v_mfma_f32_16x16x32_bf16 v[100:103], v[144:147], v[194:197], v[100:103]
	v_mfma_f32_16x16x32_bf16 v[96:99], v[166:169], v[194:197], v[96:99]
	v_mfma_f32_16x16x32_bf16 v[84:87], v[144:147], v[202:205], v[84:87]
	v_mfma_f32_16x16x32_bf16 v[80:83], v[166:169], v[202:205], v[80:83]
	v_mfma_f32_16x16x32_bf16 v[68:71], v[144:147], v[210:213], v[68:71]
	v_mfma_f32_16x16x32_bf16 v[64:67], v[166:169], v[210:213], v[64:67]
	v_mfma_f32_16x16x32_bf16 v[116:119], v[162:165], v[190:193], v[116:119]
	v_mfma_f32_16x16x32_bf16 v[112:115], v[170:173], v[190:193], v[112:115]
	v_mfma_f32_16x16x32_bf16 v[100:103], v[162:165], v[198:201], v[100:103]
	v_mfma_f32_16x16x32_bf16 v[96:99], v[170:173], v[198:201], v[96:99]
	s_setprio 2
	s_barrier
	v_mfma_f32_16x16x32_bf16 v[84:87], v[162:165], v[206:209], v[84:87]
	v_mfma_f32_16x16x32_bf16 v[80:83], v[170:173], v[206:209], v[80:83]
	v_mfma_f32_16x16x32_bf16 v[68:71], v[162:165], v[228:231], v[68:71]
	v_mfma_f32_16x16x32_bf16 v[64:67], v[170:173], v[228:231], v[64:67]
	s_setprio 0
	s_add_i32 s24, s64, s46
	s_mov_b32 m0, s24
	ds_read_b128 v[186:189], v185 offset:49152
	ds_read_b128 v[190:193], v185 offset:50176
	ds_read_b128 v[194:197], v185 offset:51200
	ds_read_b128 v[198:201], v185 offset:52224
	ds_read_b128 v[202:205], v185 offset:53248
	ds_read_b128 v[206:209], v185 offset:54272
	ds_read_b128 v[210:213], v185 offset:55296
	ds_read_b128 v[228:231], v185 offset:56320
	global_load_lds_dwordx4 v152, s[94:95]
	s_add_i32 m0, s24, 0x2000
	s_add_u32 s22, s22, 0x40080
	s_addc_u32 s23, s23, 0
	s_add_i32 s24, s65, s46
	global_load_lds_dwordx4 v148, s[94:95]
	s_mov_b32 m0, s24
	s_nop 0
	global_load_lds_dwordx4 v152, s[22:23]
	s_add_i32 m0, s24, 0x2000
	s_nop 0
	global_load_lds_dwordx4 v148, s[22:23]
	s_mov_b32 m0, s56
	s_nop 0
	global_load_lds_dwordx4 v154, s[98:99]
	s_mov_b32 m0, s57
	s_nop 0
	global_load_lds_dwordx4 v150, s[98:99]
	s_waitcnt vmcnt(8) lgkmcnt(0)
	s_barrier
	s_setprio 1
	v_mfma_f32_16x16x32_bf16 v[60:63], v[128:131], v[186:189], v[60:63]
	v_mfma_f32_16x16x32_bf16 v[56:59], v[136:139], v[186:189], v[56:59]
	v_mfma_f32_16x16x32_bf16 v[48:51], v[128:131], v[194:197], v[48:51]
	v_mfma_f32_16x16x32_bf16 v[40:43], v[136:139], v[194:197], v[40:43]
	v_mfma_f32_16x16x32_bf16 v[32:35], v[128:131], v[202:205], v[32:35]
	v_mfma_f32_16x16x32_bf16 v[24:27], v[136:139], v[202:205], v[24:27]
	v_mfma_f32_16x16x32_bf16 v[16:19], v[128:131], v[210:213], v[16:19]
	v_mfma_f32_16x16x32_bf16 v[8:11], v[136:139], v[210:213], v[8:11]
	v_mfma_f32_16x16x32_bf16 v[60:63], v[132:135], v[190:193], v[60:63]
	v_mfma_f32_16x16x32_bf16 v[56:59], v[140:143], v[190:193], v[56:59]
	v_mfma_f32_16x16x32_bf16 v[48:51], v[132:135], v[198:201], v[48:51]
	v_mfma_f32_16x16x32_bf16 v[40:43], v[140:143], v[198:201], v[40:43]
	v_mfma_f32_16x16x32_bf16 v[32:35], v[132:135], v[206:209], v[32:35]
	v_mfma_f32_16x16x32_bf16 v[24:27], v[140:143], v[206:209], v[24:27]
	v_mfma_f32_16x16x32_bf16 v[16:19], v[132:135], v[228:231], v[16:19]
	v_mfma_f32_16x16x32_bf16 v[8:11], v[140:143], v[228:231], v[8:11]
	v_mfma_f32_16x16x32_bf16 v[52:55], v[144:147], v[186:189], v[52:55]
	v_mfma_f32_16x16x32_bf16 v[44:47], v[166:169], v[186:189], v[44:47]
	v_mfma_f32_16x16x32_bf16 v[36:39], v[144:147], v[194:197], v[36:39]
	v_mfma_f32_16x16x32_bf16 v[28:31], v[166:169], v[194:197], v[28:31]
	v_mfma_f32_16x16x32_bf16 v[20:23], v[144:147], v[202:205], v[20:23]
	v_mfma_f32_16x16x32_bf16 v[12:15], v[166:169], v[202:205], v[12:15]
	v_mfma_f32_16x16x32_bf16 v[4:7], v[144:147], v[210:213], v[4:7]
	v_mfma_f32_16x16x32_bf16 v[0:3], v[166:169], v[210:213], v[0:3]
	v_mfma_f32_16x16x32_bf16 v[52:55], v[162:165], v[190:193], v[52:55]
	v_mfma_f32_16x16x32_bf16 v[44:47], v[170:173], v[190:193], v[44:47]
	v_mfma_f32_16x16x32_bf16 v[36:39], v[162:165], v[198:201], v[36:39]
	v_mfma_f32_16x16x32_bf16 v[28:31], v[170:173], v[198:201], v[28:31]
	s_setprio 2
	s_barrier
	v_mfma_f32_16x16x32_bf16 v[20:23], v[162:165], v[206:209], v[20:23]
	v_mfma_f32_16x16x32_bf16 v[12:15], v[170:173], v[206:209], v[12:15]
	v_mfma_f32_16x16x32_bf16 v[4:7], v[162:165], v[228:231], v[4:7]
	v_mfma_f32_16x16x32_bf16 v[0:3], v[170:173], v[228:231], v[0:3]
	s_setprio 0
	s_add_i32 s63, s63, 2
	s_add_u32 s61, s61, 0x100
	s_addc_u32 s62, s62, 0
	s_add_u32 s20, s20, 0x100
	s_addc_u32 s21, s21, 0
	s_cmp_gt_u32 s63, 13
	s_cbranch_scc0 .LBB0_634

.LBB0_700:
	s_or_b64 exec, exec, s[16:17]
	ds_read_b32 v0, v214
	s_waitcnt lgkmcnt(0)
	v_readfirstlane_b32 s37, v0
	ds_read_b32 v0, v215
	s_getreg_b32 s0, hwreg(HW_REG_XCC_ID, 0, 4)
	s_waitcnt vmcnt(0) lgkmcnt(0)
	s_barrier
	v_readfirstlane_b32 s42, v0
	s_mov_b64 s[38:39], exec
	v_readlane_b32 s2, v255, 0
	v_readlane_b32 s3, v255, 1
	s_and_b64 s[2:3], s[38:39], s[2:3]
	s_mov_b64 exec, s[2:3]
	s_cbranch_execz .LBB0_744
	s_waitcnt vmcnt(0) expcnt(0) lgkmcnt(0)
	buffer_inv sc1
	ds_read_b32 v2, v217
	ds_read_b32 v0, v218
	s_and_b32 s43, s0, 15
	s_waitcnt lgkmcnt(1)
	v_cmp_ne_u32_e32 vcc, 0, v2
	s_cbranch_vccnz .LBB0_715
	s_add_u32 s0, s37, 0x600200
	s_addc_u32 s1, s42, 0
	s_add_u32 s2, s37, 0x600400
	s_addc_u32 s3, s42, 0
	s_add_u32 s4, s37, 0x600500
	s_addc_u32 s5, s42, 0
	s_add_u32 s6, s37, 0x600600
	s_addc_u32 s7, s42, 0
	s_add_u32 s8, s37, 0x600700
	s_addc_u32 s9, s42, 0
	s_add_u32 s10, s37, 0x600800
	s_addc_u32 s11, s42, 0
	s_add_u32 s12, s37, 0x600900
	s_addc_u32 s13, s42, 0
	s_add_u32 s14, s37, 0x600a00
	s_addc_u32 s15, s42, 0
	s_add_u32 s16, s37, 0x600b00
	s_addc_u32 s17, s42, 0
	s_add_u32 s18, s37, 0x600c00
	s_addc_u32 s19, s42, 0
	s_add_u32 s20, s37, 0x600d00
	s_addc_u32 s21, s42, 0
	s_add_u32 s22, s37, 0x600e00
	s_addc_u32 s23, s42, 0
	s_add_u32 s24, s37, 0x600f00
	s_addc_u32 s25, s42, 0
	s_add_u32 s26, s37, 0x601000
	s_addc_u32 s27, s42, 0
	s_add_u32 s28, s37, 0x601100
	s_addc_u32 s29, s42, 0
	s_add_u32 s40, s37, 0x601200
	s_addc_u32 s41, s42, 0
	s_add_u32 s46, s37, 0x601300
	s_addc_u32 s47, s42, 0
	s_mov_b32 s44, 1
	s_mov_b64 s[48:49], 0
	s_branch .LBB0_705

.LBB0_768:
	s_add_u32 s44, s40, 0x100
	s_addc_u32 s55, s41, 0
	s_mov_b32 s92, -2
	s_add_u32 s40, s8, 0x100
	s_addc_u32 s41, s9, 0
	s_add_i32 s64, 0, 0x10000
	s_cmp_eq_u32 s92, 40
	s_cselect_b32 s53, s1, s41
	s_cselect_b32 s52, s0, s40
	s_cselect_b32 s51, s39, s55
	s_cselect_b32 s50, s38, s44
	s_add_i32 s65, 0, 0x14000
	v_add_u32_e32 v140, s64, v228
	v_add_u32_e32 v156, s65, v228
	ds_read_b128 v[128:131], v140
	ds_read_b128 v[132:135], v140 offset:1024
	ds_read_b128 v[136:139], v140 offset:2048
	ds_read_b128 v[140:143], v140 offset:3072
	ds_read_b128 v[144:147], v156
	ds_read_b128 v[148:151], v156 offset:1024
	ds_read_b128 v[152:155], v156 offset:2048
	ds_read_b128 v[156:159], v156 offset:3072
	s_add_i32 m0, s62, 0xc000
	ds_read_b128 v[160:163], v231
	ds_read_b128 v[164:167], v231 offset:1024
	ds_read_b128 v[186:189], v231 offset:2048
	ds_read_b128 v[190:193], v231 offset:3072
	ds_read_b128 v[194:197], v231 offset:4096
	ds_read_b128 v[198:201], v231 offset:5120
	ds_read_b128 v[202:205], v231 offset:6144
	ds_read_b128 v[206:209], v231 offset:7168
	global_load_lds_dwordx4 v184, s[8:9]
	s_add_i32 m0, s62, 0xe000
	s_nop 0
	global_load_lds_dwordx4 v182, s[8:9]
	s_waitcnt vmcnt(24) lgkmcnt(0)
	s_barrier
	s_setprio 1
	v_mfma_f32_16x16x32_bf16 v[124:127], v[128:131], v[160:163], 0
	v_mfma_f32_16x16x32_bf16 v[120:123], v[136:139], v[160:163], 0
	v_mfma_f32_16x16x32_bf16 v[108:111], v[128:131], v[186:189], 0
	v_mfma_f32_16x16x32_bf16 v[104:107], v[136:139], v[186:189], 0
	v_mfma_f32_16x16x32_bf16 v[92:95], v[128:131], v[194:197], 0
	v_mfma_f32_16x16x32_bf16 v[88:91], v[136:139], v[194:197], 0
	v_mfma_f32_16x16x32_bf16 v[76:79], v[128:131], v[202:205], 0
	v_mfma_f32_16x16x32_bf16 v[72:75], v[136:139], v[202:205], 0
	v_mfma_f32_16x16x32_bf16 v[124:127], v[132:135], v[164:167], v[124:127]
	v_mfma_f32_16x16x32_bf16 v[120:123], v[140:143], v[164:167], v[120:123]
	v_mfma_f32_16x16x32_bf16 v[108:111], v[132:135], v[190:193], v[108:111]
	v_mfma_f32_16x16x32_bf16 v[104:107], v[140:143], v[190:193], v[104:107]
	v_mfma_f32_16x16x32_bf16 v[92:95], v[132:135], v[198:201], v[92:95]
	v_mfma_f32_16x16x32_bf16 v[88:91], v[140:143], v[198:201], v[88:91]
	v_mfma_f32_16x16x32_bf16 v[76:79], v[132:135], v[206:209], v[76:79]
	v_mfma_f32_16x16x32_bf16 v[72:75], v[140:143], v[206:209], v[72:75]
	v_mfma_f32_16x16x32_bf16 v[116:119], v[144:147], v[160:163], 0
	v_mfma_f32_16x16x32_bf16 v[112:115], v[152:155], v[160:163], 0
	v_mfma_f32_16x16x32_bf16 v[100:103], v[144:147], v[186:189], 0
	v_mfma_f32_16x16x32_bf16 v[96:99], v[152:155], v[186:189], 0
	v_mfma_f32_16x16x32_bf16 v[84:87], v[144:147], v[194:197], 0
	v_mfma_f32_16x16x32_bf16 v[80:83], v[152:155], v[194:197], 0
	v_mfma_f32_16x16x32_bf16 v[68:71], v[144:147], v[202:205], 0
	v_mfma_f32_16x16x32_bf16 v[64:67], v[152:155], v[202:205], 0
	v_mfma_f32_16x16x32_bf16 v[116:119], v[148:151], v[164:167], v[116:119]
	v_mfma_f32_16x16x32_bf16 v[112:115], v[156:159], v[164:167], v[112:115]
	v_mfma_f32_16x16x32_bf16 v[100:103], v[148:151], v[190:193], v[100:103]
	v_mfma_f32_16x16x32_bf16 v[96:99], v[156:159], v[190:193], v[96:99]
	s_setprio 2
	s_barrier
	v_mfma_f32_16x16x32_bf16 v[84:87], v[148:151], v[198:201], v[84:87]
	v_mfma_f32_16x16x32_bf16 v[80:83], v[156:159], v[198:201], v[80:83]
	v_mfma_f32_16x16x32_bf16 v[68:71], v[148:151], v[206:209], v[68:71]
	v_mfma_f32_16x16x32_bf16 v[64:67], v[156:159], v[206:209], v[64:67]
	s_setprio 0
	s_add_i32 s8, s64, s37
	s_add_u32 s98, s50, s34
	s_addc_u32 s99, s51, s35
	s_mov_b32 m0, s8
	ds_read_b128 v[160:163], v231 offset:16384
	ds_read_b128 v[164:167], v231 offset:17408
	ds_read_b128 v[186:189], v231 offset:18432
	ds_read_b128 v[190:193], v231 offset:19456
	ds_read_b128 v[194:197], v231 offset:20480
	ds_read_b128 v[198:201], v231 offset:21504
	ds_read_b128 v[202:205], v231 offset:22528
	ds_read_b128 v[206:209], v231 offset:23552
	global_load_lds_dwordx4 v170, s[50:51]
	s_add_i32 m0, s8, 0x2000
	s_add_u32 s8, s50, 0xb0000
	s_addc_u32 s9, s51, 0
	s_add_i32 s64, s65, s37
	global_load_lds_dwordx4 v174, s[50:51]
	s_mov_b32 m0, s64
	s_nop 0
	global_load_lds_dwordx4 v170, s[8:9]
	s_add_i32 m0, s64, 0x2000
	s_nop 0
	global_load_lds_dwordx4 v174, s[8:9]
	s_add_u32 s100, s52, s34
	s_addc_u32 s101, s53, s35
	s_mov_b32 m0, s62
	s_nop 0
	global_load_lds_dwordx4 v168, s[52:53]
	s_mov_b32 m0, s63
	s_nop 0
	global_load_lds_dwordx4 v172, s[52:53]
	s_waitcnt vmcnt(8) lgkmcnt(0)
	s_barrier
	s_setprio 1
	v_mfma_f32_16x16x32_bf16 v[60:63], v[128:131], v[160:163], 0
	v_mfma_f32_16x16x32_bf16 v[56:59], v[136:139], v[160:163], 0
	v_mfma_f32_16x16x32_bf16 v[44:47], v[128:131], v[186:189], 0
	v_mfma_f32_16x16x32_bf16 v[40:43], v[136:139], v[186:189], 0
	v_mfma_f32_16x16x32_bf16 v[28:31], v[128:131], v[194:197], 0
	v_mfma_f32_16x16x32_bf16 v[24:27], v[136:139], v[194:197], 0
	v_mfma_f32_16x16x32_bf16 v[12:15], v[128:131], v[202:205], 0
	v_mfma_f32_16x16x32_bf16 v[8:11], v[136:139], v[202:205], 0
	v_mfma_f32_16x16x32_bf16 v[60:63], v[132:135], v[164:167], v[60:63]
	v_mfma_f32_16x16x32_bf16 v[56:59], v[140:143], v[164:167], v[56:59]
	v_mfma_f32_16x16x32_bf16 v[44:47], v[132:135], v[190:193], v[44:47]
	v_mfma_f32_16x16x32_bf16 v[40:43], v[140:143], v[190:193], v[40:43]
	v_mfma_f32_16x16x32_bf16 v[28:31], v[132:135], v[198:201], v[28:31]
	v_mfma_f32_16x16x32_bf16 v[24:27], v[140:143], v[198:201], v[24:27]
	v_mfma_f32_16x16x32_bf16 v[12:15], v[132:135], v[206:209], v[12:15]
	v_mfma_f32_16x16x32_bf16 v[8:11], v[140:143], v[206:209], v[8:11]
	v_mfma_f32_16x16x32_bf16 v[52:55], v[144:147], v[160:163], 0
	v_mfma_f32_16x16x32_bf16 v[48:51], v[152:155], v[160:163], 0
	v_mfma_f32_16x16x32_bf16 v[36:39], v[144:147], v[186:189], 0
	v_mfma_f32_16x16x32_bf16 v[32:35], v[152:155], v[186:189], 0
	v_mfma_f32_16x16x32_bf16 v[20:23], v[144:147], v[194:197], 0
	v_mfma_f32_16x16x32_bf16 v[16:19], v[152:155], v[194:197], 0
	v_mfma_f32_16x16x32_bf16 v[4:7], v[144:147], v[202:205], 0
	v_mfma_f32_16x16x32_bf16 v[0:3], v[152:155], v[202:205], 0
	v_mfma_f32_16x16x32_bf16 v[52:55], v[148:151], v[164:167], v[52:55]
	v_mfma_f32_16x16x32_bf16 v[48:51], v[156:159], v[164:167], v[48:51]
	v_mfma_f32_16x16x32_bf16 v[36:39], v[148:151], v[190:193], v[36:39]
	v_mfma_f32_16x16x32_bf16 v[32:35], v[156:159], v[190:193], v[32:35]
	s_setprio 2
	s_barrier
	v_mfma_f32_16x16x32_bf16 v[20:23], v[148:151], v[198:201], v[20:23]
	v_mfma_f32_16x16x32_bf16 v[16:19], v[156:159], v[198:201], v[16:19]
	v_mfma_f32_16x16x32_bf16 v[4:7], v[148:151], v[206:209], v[4:7]
	v_mfma_f32_16x16x32_bf16 v[0:3], v[156:159], v[206:209], v[0:3]
	s_setprio 0
	s_add_i32 s64, 0, 0x18000
	s_add_i32 s65, 0, 0x1c000
	v_add_u32_e32 v140, s64, v228
	v_add_u32_e32 v156, s65, v228
	ds_read_b128 v[128:131], v140
	ds_read_b128 v[132:135], v140 offset:1024
	ds_read_b128 v[136:139], v140 offset:2048
	ds_read_b128 v[140:143], v140 offset:3072
	ds_read_b128 v[144:147], v156
	ds_read_b128 v[148:151], v156 offset:1024
	ds_read_b128 v[152:155], v156 offset:2048
	ds_read_b128 v[156:159], v156 offset:3072
	s_add_u32 s8, s52, 0xb0000
	s_addc_u32 s9, s53, 0
	s_mov_b32 m0, s68
	ds_read_b128 v[160:163], v231 offset:32768
	ds_read_b128 v[164:167], v231 offset:33792
	ds_read_b128 v[186:189], v231 offset:34816
	ds_read_b128 v[190:193], v231 offset:35840
	ds_read_b128 v[194:197], v231 offset:36864
	ds_read_b128 v[198:201], v231 offset:37888
	ds_read_b128 v[202:205], v231 offset:38912
	ds_read_b128 v[206:209], v231 offset:39936
	global_load_lds_dwordx4 v168, s[8:9]
	s_mov_b32 m0, s69
	s_nop 0
	global_load_lds_dwordx4 v172, s[8:9]
	s_waitcnt vmcnt(8) lgkmcnt(0)
	s_barrier
	s_setprio 1
	v_mfma_f32_16x16x32_bf16 v[124:127], v[128:131], v[160:163], v[124:127]
	v_mfma_f32_16x16x32_bf16 v[120:123], v[136:139], v[160:163], v[120:123]
	v_mfma_f32_16x16x32_bf16 v[108:111], v[128:131], v[186:189], v[108:111]
	v_mfma_f32_16x16x32_bf16 v[104:107], v[136:139], v[186:189], v[104:107]
	v_mfma_f32_16x16x32_bf16 v[92:95], v[128:131], v[194:197], v[92:95]
	v_mfma_f32_16x16x32_bf16 v[88:91], v[136:139], v[194:197], v[88:91]
	v_mfma_f32_16x16x32_bf16 v[76:79], v[128:131], v[202:205], v[76:79]
	v_mfma_f32_16x16x32_bf16 v[72:75], v[136:139], v[202:205], v[72:75]
	v_mfma_f32_16x16x32_bf16 v[124:127], v[132:135], v[164:167], v[124:127]
	v_mfma_f32_16x16x32_bf16 v[120:123], v[140:143], v[164:167], v[120:123]
	v_mfma_f32_16x16x32_bf16 v[108:111], v[132:135], v[190:193], v[108:111]
	v_mfma_f32_16x16x32_bf16 v[104:107], v[140:143], v[190:193], v[104:107]
	v_mfma_f32_16x16x32_bf16 v[92:95], v[132:135], v[198:201], v[92:95]
	v_mfma_f32_16x16x32_bf16 v[88:91], v[140:143], v[198:201], v[88:91]
	v_mfma_f32_16x16x32_bf16 v[76:79], v[132:135], v[206:209], v[76:79]
	v_mfma_f32_16x16x32_bf16 v[72:75], v[140:143], v[206:209], v[72:75]
	v_mfma_f32_16x16x32_bf16 v[116:119], v[144:147], v[160:163], v[116:119]
	v_mfma_f32_16x16x32_bf16 v[112:115], v[152:155], v[160:163], v[112:115]
	v_mfma_f32_16x16x32_bf16 v[100:103], v[144:147], v[186:189], v[100:103]
	v_mfma_f32_16x16x32_bf16 v[96:99], v[152:155], v[186:189], v[96:99]
	v_mfma_f32_16x16x32_bf16 v[84:87], v[144:147], v[194:197], v[84:87]
	v_mfma_f32_16x16x32_bf16 v[80:83], v[152:155], v[194:197], v[80:83]
	v_mfma_f32_16x16x32_bf16 v[68:71], v[144:147], v[202:205], v[68:71]
	v_mfma_f32_16x16x32_bf16 v[64:67], v[152:155], v[202:205], v[64:67]
	v_mfma_f32_16x16x32_bf16 v[116:119], v[148:151], v[164:167], v[116:119]
	v_mfma_f32_16x16x32_bf16 v[112:115], v[156:159], v[164:167], v[112:115]
	v_mfma_f32_16x16x32_bf16 v[100:103], v[148:151], v[190:193], v[100:103]
	v_mfma_f32_16x16x32_bf16 v[96:99], v[156:159], v[190:193], v[96:99]
	s_setprio 2
	s_barrier
	v_mfma_f32_16x16x32_bf16 v[84:87], v[148:151], v[198:201], v[84:87]
	v_mfma_f32_16x16x32_bf16 v[80:83], v[156:159], v[198:201], v[80:83]
	v_mfma_f32_16x16x32_bf16 v[68:71], v[148:151], v[206:209], v[68:71]
	v_mfma_f32_16x16x32_bf16 v[64:67], v[156:159], v[206:209], v[64:67]
	s_setprio 0
	s_add_i32 s8, s64, s37
	s_mov_b32 m0, s8
	ds_read_b128 v[160:163], v231 offset:49152
	ds_read_b128 v[164:167], v231 offset:50176
	ds_read_b128 v[186:189], v231 offset:51200
	ds_read_b128 v[190:193], v231 offset:52224
	ds_read_b128 v[194:197], v231 offset:53248
	ds_read_b128 v[198:201], v231 offset:54272
	ds_read_b128 v[202:205], v231 offset:55296
	ds_read_b128 v[206:209], v231 offset:56320
	global_load_lds_dwordx4 v170, s[98:99]
	s_add_i32 m0, s8, 0x2000
	s_add_u32 s8, s50, 0xb0080
	s_addc_u32 s9, s51, 0
	s_add_i32 s50, s65, s37
	global_load_lds_dwordx4 v174, s[98:99]
	s_mov_b32 m0, s50
	s_nop 0
	global_load_lds_dwordx4 v170, s[8:9]
	s_add_i32 m0, s50, 0x2000
	s_nop 0
	global_load_lds_dwordx4 v174, s[8:9]
	s_mov_b32 m0, s73
	s_nop 0
	global_load_lds_dwordx4 v168, s[100:101]
	s_mov_b32 m0, s74
	s_nop 0
	global_load_lds_dwordx4 v172, s[100:101]
	s_waitcnt vmcnt(8) lgkmcnt(0)
	s_barrier
	s_setprio 1
	v_mfma_f32_16x16x32_bf16 v[60:63], v[128:131], v[160:163], v[60:63]
	v_mfma_f32_16x16x32_bf16 v[56:59], v[136:139], v[160:163], v[56:59]
	v_mfma_f32_16x16x32_bf16 v[44:47], v[128:131], v[186:189], v[44:47]
	v_mfma_f32_16x16x32_bf16 v[40:43], v[136:139], v[186:189], v[40:43]
	v_mfma_f32_16x16x32_bf16 v[28:31], v[128:131], v[194:197], v[28:31]
	v_mfma_f32_16x16x32_bf16 v[24:27], v[136:139], v[194:197], v[24:27]
	v_mfma_f32_16x16x32_bf16 v[12:15], v[128:131], v[202:205], v[12:15]
	v_mfma_f32_16x16x32_bf16 v[8:11], v[136:139], v[202:205], v[8:11]
	v_mfma_f32_16x16x32_bf16 v[60:63], v[132:135], v[164:167], v[60:63]
	v_mfma_f32_16x16x32_bf16 v[56:59], v[140:143], v[164:167], v[56:59]
	v_mfma_f32_16x16x32_bf16 v[44:47], v[132:135], v[190:193], v[44:47]
	v_mfma_f32_16x16x32_bf16 v[40:43], v[140:143], v[190:193], v[40:43]
	v_mfma_f32_16x16x32_bf16 v[28:31], v[132:135], v[198:201], v[28:31]
	v_mfma_f32_16x16x32_bf16 v[24:27], v[140:143], v[198:201], v[24:27]
	v_mfma_f32_16x16x32_bf16 v[12:15], v[132:135], v[206:209], v[12:15]
	v_mfma_f32_16x16x32_bf16 v[8:11], v[140:143], v[206:209], v[8:11]
	v_mfma_f32_16x16x32_bf16 v[52:55], v[144:147], v[160:163], v[52:55]
	v_mfma_f32_16x16x32_bf16 v[48:51], v[152:155], v[160:163], v[48:51]
	v_mfma_f32_16x16x32_bf16 v[36:39], v[144:147], v[186:189], v[36:39]
	v_mfma_f32_16x16x32_bf16 v[32:35], v[152:155], v[186:189], v[32:35]
	v_mfma_f32_16x16x32_bf16 v[20:23], v[144:147], v[194:197], v[20:23]
	v_mfma_f32_16x16x32_bf16 v[16:19], v[152:155], v[194:197], v[16:19]
	v_mfma_f32_16x16x32_bf16 v[4:7], v[144:147], v[202:205], v[4:7]
	v_mfma_f32_16x16x32_bf16 v[0:3], v[152:155], v[202:205], v[0:3]
	v_mfma_f32_16x16x32_bf16 v[52:55], v[148:151], v[164:167], v[52:55]
	v_mfma_f32_16x16x32_bf16 v[48:51], v[156:159], v[164:167], v[48:51]
	v_mfma_f32_16x16x32_bf16 v[36:39], v[148:151], v[190:193], v[36:39]
	v_mfma_f32_16x16x32_bf16 v[32:35], v[156:159], v[190:193], v[32:35]
	s_setprio 2
	s_barrier
	v_mfma_f32_16x16x32_bf16 v[20:23], v[148:151], v[198:201], v[20:23]
	v_mfma_f32_16x16x32_bf16 v[16:19], v[156:159], v[198:201], v[16:19]
	v_mfma_f32_16x16x32_bf16 v[4:7], v[148:151], v[206:209], v[4:7]
	v_mfma_f32_16x16x32_bf16 v[0:3], v[156:159], v[206:209], v[0:3]
	s_setprio 0
	s_add_i32 s92, s92, 2
	s_add_u32 s44, s44, 0x100
	s_addc_u32 s55, s55, 0
	s_cmp_gt_u32 s92, 41
	s_mov_b64 s[8:9], s[40:41]
	s_cbranch_scc1 .Lpeel_exit_2
.LBB0_769:
	s_add_u32 s40, s8, 0x100
	s_addc_u32 s41, s9, 0
	s_add_i32 s64, 0, 0x10000
	s_cmp_eq_u32 s92, 40
	s_cselect_b32 s53, s1, s41
	s_cselect_b32 s52, s0, s40
	s_cselect_b32 s51, s39, s55
	s_cselect_b32 s50, s38, s44
	s_add_i32 s65, 0, 0x14000
	v_add_u32_e32 v140, s64, v228
	v_add_u32_e32 v156, s65, v228
	ds_read_b128 v[128:131], v140
	ds_read_b128 v[132:135], v140 offset:1024
	ds_read_b128 v[136:139], v140 offset:2048
	ds_read_b128 v[140:143], v140 offset:3072
	ds_read_b128 v[144:147], v156
	ds_read_b128 v[148:151], v156 offset:1024
	ds_read_b128 v[152:155], v156 offset:2048
	ds_read_b128 v[156:159], v156 offset:3072
	s_add_i32 m0, s62, 0xc000
	ds_read_b128 v[160:163], v231
	ds_read_b128 v[164:167], v231 offset:1024
	ds_read_b128 v[186:189], v231 offset:2048
	ds_read_b128 v[190:193], v231 offset:3072
	ds_read_b128 v[194:197], v231 offset:4096
	ds_read_b128 v[198:201], v231 offset:5120
	ds_read_b128 v[202:205], v231 offset:6144
	ds_read_b128 v[206:209], v231 offset:7168
	global_load_lds_dwordx4 v184, s[8:9]
	s_add_i32 m0, s62, 0xe000
	s_nop 0
	global_load_lds_dwordx4 v182, s[8:9]
	s_waitcnt vmcnt(8) lgkmcnt(0)
	s_barrier
	s_setprio 1
	v_mfma_f32_16x16x32_bf16 v[124:127], v[128:131], v[160:163], v[124:127]
	v_mfma_f32_16x16x32_bf16 v[120:123], v[136:139], v[160:163], v[120:123]
	v_mfma_f32_16x16x32_bf16 v[108:111], v[128:131], v[186:189], v[108:111]
	v_mfma_f32_16x16x32_bf16 v[104:107], v[136:139], v[186:189], v[104:107]
	v_mfma_f32_16x16x32_bf16 v[92:95], v[128:131], v[194:197], v[92:95]
	v_mfma_f32_16x16x32_bf16 v[88:91], v[136:139], v[194:197], v[88:91]
	v_mfma_f32_16x16x32_bf16 v[76:79], v[128:131], v[202:205], v[76:79]
	v_mfma_f32_16x16x32_bf16 v[72:75], v[136:139], v[202:205], v[72:75]
	v_mfma_f32_16x16x32_bf16 v[124:127], v[132:135], v[164:167], v[124:127]
	v_mfma_f32_16x16x32_bf16 v[120:123], v[140:143], v[164:167], v[120:123]
	v_mfma_f32_16x16x32_bf16 v[108:111], v[132:135], v[190:193], v[108:111]
	v_mfma_f32_16x16x32_bf16 v[104:107], v[140:143], v[190:193], v[104:107]
	v_mfma_f32_16x16x32_bf16 v[92:95], v[132:135], v[198:201], v[92:95]
	v_mfma_f32_16x16x32_bf16 v[88:91], v[140:143], v[198:201], v[88:91]
	v_mfma_f32_16x16x32_bf16 v[76:79], v[132:135], v[206:209], v[76:79]
	v_mfma_f32_16x16x32_bf16 v[72:75], v[140:143], v[206:209], v[72:75]
	v_mfma_f32_16x16x32_bf16 v[116:119], v[144:147], v[160:163], v[116:119]
	v_mfma_f32_16x16x32_bf16 v[112:115], v[152:155], v[160:163], v[112:115]
	v_mfma_f32_16x16x32_bf16 v[100:103], v[144:147], v[186:189], v[100:103]
	v_mfma_f32_16x16x32_bf16 v[96:99], v[152:155], v[186:189], v[96:99]
	v_mfma_f32_16x16x32_bf16 v[84:87], v[144:147], v[194:197], v[84:87]
	v_mfma_f32_16x16x32_bf16 v[80:83], v[152:155], v[194:197], v[80:83]
	v_mfma_f32_16x16x32_bf16 v[68:71], v[144:147], v[202:205], v[68:71]
	v_mfma_f32_16x16x32_bf16 v[64:67], v[152:155], v[202:205], v[64:67]
	v_mfma_f32_16x16x32_bf16 v[116:119], v[148:151], v[164:167], v[116:119]
	v_mfma_f32_16x16x32_bf16 v[112:115], v[156:159], v[164:167], v[112:115]
	v_mfma_f32_16x16x32_bf16 v[100:103], v[148:151], v[190:193], v[100:103]
	v_mfma_f32_16x16x32_bf16 v[96:99], v[156:159], v[190:193], v[96:99]
	s_setprio 2
	s_barrier
	v_mfma_f32_16x16x32_bf16 v[84:87], v[148:151], v[198:201], v[84:87]
	v_mfma_f32_16x16x32_bf16 v[80:83], v[156:159], v[198:201], v[80:83]
	v_mfma_f32_16x16x32_bf16 v[68:71], v[148:151], v[206:209], v[68:71]
	v_mfma_f32_16x16x32_bf16 v[64:67], v[156:159], v[206:209], v[64:67]
	s_setprio 0
	s_add_i32 s8, s64, s37
	s_add_u32 s98, s50, s34
	s_addc_u32 s99, s51, s35
	s_mov_b32 m0, s8
	ds_read_b128 v[160:163], v231 offset:16384
	ds_read_b128 v[164:167], v231 offset:17408
	ds_read_b128 v[186:189], v231 offset:18432
	ds_read_b128 v[190:193], v231 offset:19456
	ds_read_b128 v[194:197], v231 offset:20480
	ds_read_b128 v[198:201], v231 offset:21504
	ds_read_b128 v[202:205], v231 offset:22528
	ds_read_b128 v[206:209], v231 offset:23552
	global_load_lds_dwordx4 v170, s[50:51]
	s_add_i32 m0, s8, 0x2000
	s_add_u32 s8, s50, 0xb0000
	s_addc_u32 s9, s51, 0
	s_add_i32 s64, s65, s37
	global_load_lds_dwordx4 v174, s[50:51]
	s_mov_b32 m0, s64
	s_nop 0
	global_load_lds_dwordx4 v170, s[8:9]
	s_add_i32 m0, s64, 0x2000
	s_nop 0
	global_load_lds_dwordx4 v174, s[8:9]
	s_add_u32 s100, s52, s34
	s_addc_u32 s101, s53, s35
	s_mov_b32 m0, s62
	s_nop 0
	global_load_lds_dwordx4 v168, s[52:53]
	s_mov_b32 m0, s63
	s_nop 0
	global_load_lds_dwordx4 v172, s[52:53]
	s_waitcnt vmcnt(8) lgkmcnt(0)
	s_barrier
	s_setprio 1
	v_mfma_f32_16x16x32_bf16 v[60:63], v[128:131], v[160:163], v[60:63]
	v_mfma_f32_16x16x32_bf16 v[56:59], v[136:139], v[160:163], v[56:59]
	v_mfma_f32_16x16x32_bf16 v[44:47], v[128:131], v[186:189], v[44:47]
	v_mfma_f32_16x16x32_bf16 v[40:43], v[136:139], v[186:189], v[40:43]
	v_mfma_f32_16x16x32_bf16 v[28:31], v[128:131], v[194:197], v[28:31]
	v_mfma_f32_16x16x32_bf16 v[24:27], v[136:139], v[194:197], v[24:27]
	v_mfma_f32_16x16x32_bf16 v[12:15], v[128:131], v[202:205], v[12:15]
	v_mfma_f32_16x16x32_bf16 v[8:11], v[136:139], v[202:205], v[8:11]
	v_mfma_f32_16x16x32_bf16 v[60:63], v[132:135], v[164:167], v[60:63]
	v_mfma_f32_16x16x32_bf16 v[56:59], v[140:143], v[164:167], v[56:59]
	v_mfma_f32_16x16x32_bf16 v[44:47], v[132:135], v[190:193], v[44:47]
	v_mfma_f32_16x16x32_bf16 v[40:43], v[140:143], v[190:193], v[40:43]
	v_mfma_f32_16x16x32_bf16 v[28:31], v[132:135], v[198:201], v[28:31]
	v_mfma_f32_16x16x32_bf16 v[24:27], v[140:143], v[198:201], v[24:27]
	v_mfma_f32_16x16x32_bf16 v[12:15], v[132:135], v[206:209], v[12:15]
	v_mfma_f32_16x16x32_bf16 v[8:11], v[140:143], v[206:209], v[8:11]
	v_mfma_f32_16x16x32_bf16 v[52:55], v[144:147], v[160:163], v[52:55]
	v_mfma_f32_16x16x32_bf16 v[48:51], v[152:155], v[160:163], v[48:51]
	v_mfma_f32_16x16x32_bf16 v[36:39], v[144:147], v[186:189], v[36:39]
	v_mfma_f32_16x16x32_bf16 v[32:35], v[152:155], v[186:189], v[32:35]
	v_mfma_f32_16x16x32_bf16 v[20:23], v[144:147], v[194:197], v[20:23]
	v_mfma_f32_16x16x32_bf16 v[16:19], v[152:155], v[194:197], v[16:19]
	v_mfma_f32_16x16x32_bf16 v[4:7], v[144:147], v[202:205], v[4:7]
	v_mfma_f32_16x16x32_bf16 v[0:3], v[152:155], v[202:205], v[0:3]
	v_mfma_f32_16x16x32_bf16 v[52:55], v[148:151], v[164:167], v[52:55]
	v_mfma_f32_16x16x32_bf16 v[48:51], v[156:159], v[164:167], v[48:51]
	v_mfma_f32_16x16x32_bf16 v[36:39], v[148:151], v[190:193], v[36:39]
	v_mfma_f32_16x16x32_bf16 v[32:35], v[156:159], v[190:193], v[32:35]
	s_setprio 2
	s_barrier
	v_mfma_f32_16x16x32_bf16 v[20:23], v[148:151], v[198:201], v[20:23]
	v_mfma_f32_16x16x32_bf16 v[16:19], v[156:159], v[198:201], v[16:19]
	v_mfma_f32_16x16x32_bf16 v[4:7], v[148:151], v[206:209], v[4:7]
	v_mfma_f32_16x16x32_bf16 v[0:3], v[156:159], v[206:209], v[0:3]
	s_setprio 0
	s_add_i32 s64, 0, 0x18000
	s_add_i32 s65, 0, 0x1c000
	v_add_u32_e32 v140, s64, v228
	v_add_u32_e32 v156, s65, v228
	ds_read_b128 v[128:131], v140
	ds_read_b128 v[132:135], v140 offset:1024
	ds_read_b128 v[136:139], v140 offset:2048
	ds_read_b128 v[140:143], v140 offset:3072
	ds_read_b128 v[144:147], v156
	ds_read_b128 v[148:151], v156 offset:1024
	ds_read_b128 v[152:155], v156 offset:2048
	ds_read_b128 v[156:159], v156 offset:3072
	s_add_u32 s8, s52, 0xb0000
	s_addc_u32 s9, s53, 0
	s_mov_b32 m0, s68
	ds_read_b128 v[160:163], v231 offset:32768
	ds_read_b128 v[164:167], v231 offset:33792
	ds_read_b128 v[186:189], v231 offset:34816
	ds_read_b128 v[190:193], v231 offset:35840
	ds_read_b128 v[194:197], v231 offset:36864
	ds_read_b128 v[198:201], v231 offset:37888
	ds_read_b128 v[202:205], v231 offset:38912
	ds_read_b128 v[206:209], v231 offset:39936
	global_load_lds_dwordx4 v168, s[8:9]
	s_mov_b32 m0, s69
	s_nop 0
	global_load_lds_dwordx4 v172, s[8:9]
	s_waitcnt vmcnt(8) lgkmcnt(0)
	s_barrier
	s_setprio 1
	v_mfma_f32_16x16x32_bf16 v[124:127], v[128:131], v[160:163], v[124:127]
	v_mfma_f32_16x16x32_bf16 v[120:123], v[136:139], v[160:163], v[120:123]
	v_mfma_f32_16x16x32_bf16 v[108:111], v[128:131], v[186:189], v[108:111]
	v_mfma_f32_16x16x32_bf16 v[104:107], v[136:139], v[186:189], v[104:107]
	v_mfma_f32_16x16x32_bf16 v[92:95], v[128:131], v[194:197], v[92:95]
	v_mfma_f32_16x16x32_bf16 v[88:91], v[136:139], v[194:197], v[88:91]
	v_mfma_f32_16x16x32_bf16 v[76:79], v[128:131], v[202:205], v[76:79]
	v_mfma_f32_16x16x32_bf16 v[72:75], v[136:139], v[202:205], v[72:75]
	v_mfma_f32_16x16x32_bf16 v[124:127], v[132:135], v[164:167], v[124:127]
	v_mfma_f32_16x16x32_bf16 v[120:123], v[140:143], v[164:167], v[120:123]
	v_mfma_f32_16x16x32_bf16 v[108:111], v[132:135], v[190:193], v[108:111]
	v_mfma_f32_16x16x32_bf16 v[104:107], v[140:143], v[190:193], v[104:107]
	v_mfma_f32_16x16x32_bf16 v[92:95], v[132:135], v[198:201], v[92:95]
	v_mfma_f32_16x16x32_bf16 v[88:91], v[140:143], v[198:201], v[88:91]
	v_mfma_f32_16x16x32_bf16 v[76:79], v[132:135], v[206:209], v[76:79]
	v_mfma_f32_16x16x32_bf16 v[72:75], v[140:143], v[206:209], v[72:75]
	v_mfma_f32_16x16x32_bf16 v[116:119], v[144:147], v[160:163], v[116:119]
	v_mfma_f32_16x16x32_bf16 v[112:115], v[152:155], v[160:163], v[112:115]
	v_mfma_f32_16x16x32_bf16 v[100:103], v[144:147], v[186:189], v[100:103]
	v_mfma_f32_16x16x32_bf16 v[96:99], v[152:155], v[186:189], v[96:99]
	v_mfma_f32_16x16x32_bf16 v[84:87], v[144:147], v[194:197], v[84:87]
	v_mfma_f32_16x16x32_bf16 v[80:83], v[152:155], v[194:197], v[80:83]
	v_mfma_f32_16x16x32_bf16 v[68:71], v[144:147], v[202:205], v[68:71]
	v_mfma_f32_16x16x32_bf16 v[64:67], v[152:155], v[202:205], v[64:67]
	v_mfma_f32_16x16x32_bf16 v[116:119], v[148:151], v[164:167], v[116:119]
	v_mfma_f32_16x16x32_bf16 v[112:115], v[156:159], v[164:167], v[112:115]
	v_mfma_f32_16x16x32_bf16 v[100:103], v[148:151], v[190:193], v[100:103]
	v_mfma_f32_16x16x32_bf16 v[96:99], v[156:159], v[190:193], v[96:99]
	s_setprio 2
	s_barrier
	v_mfma_f32_16x16x32_bf16 v[84:87], v[148:151], v[198:201], v[84:87]
	v_mfma_f32_16x16x32_bf16 v[80:83], v[156:159], v[198:201], v[80:83]
	v_mfma_f32_16x16x32_bf16 v[68:71], v[148:151], v[206:209], v[68:71]
	v_mfma_f32_16x16x32_bf16 v[64:67], v[156:159], v[206:209], v[64:67]
	s_setprio 0
	s_add_i32 s8, s64, s37
	s_mov_b32 m0, s8
	ds_read_b128 v[160:163], v231 offset:49152
	ds_read_b128 v[164:167], v231 offset:50176
	ds_read_b128 v[186:189], v231 offset:51200
	ds_read_b128 v[190:193], v231 offset:52224
	ds_read_b128 v[194:197], v231 offset:53248
	ds_read_b128 v[198:201], v231 offset:54272
	ds_read_b128 v[202:205], v231 offset:55296
	ds_read_b128 v[206:209], v231 offset:56320
	global_load_lds_dwordx4 v170, s[98:99]
	s_add_i32 m0, s8, 0x2000
	s_add_u32 s8, s50, 0xb0080
	s_addc_u32 s9, s51, 0
	s_add_i32 s50, s65, s37
	global_load_lds_dwordx4 v174, s[98:99]
	s_mov_b32 m0, s50
	s_nop 0
	global_load_lds_dwordx4 v170, s[8:9]
	s_add_i32 m0, s50, 0x2000
	s_nop 0
	global_load_lds_dwordx4 v174, s[8:9]
	s_mov_b32 m0, s73
	s_nop 0
	global_load_lds_dwordx4 v168, s[100:101]
	s_mov_b32 m0, s74
	s_nop 0
	global_load_lds_dwordx4 v172, s[100:101]
	s_waitcnt vmcnt(8) lgkmcnt(0)
	s_barrier
	s_setprio 1
	v_mfma_f32_16x16x32_bf16 v[60:63], v[128:131], v[160:163], v[60:63]
	v_mfma_f32_16x16x32_bf16 v[56:59], v[136:139], v[160:163], v[56:59]
	v_mfma_f32_16x16x32_bf16 v[44:47], v[128:131], v[186:189], v[44:47]
	v_mfma_f32_16x16x32_bf16 v[40:43], v[136:139], v[186:189], v[40:43]
	v_mfma_f32_16x16x32_bf16 v[28:31], v[128:131], v[194:197], v[28:31]
	v_mfma_f32_16x16x32_bf16 v[24:27], v[136:139], v[194:197], v[24:27]
	v_mfma_f32_16x16x32_bf16 v[12:15], v[128:131], v[202:205], v[12:15]
	v_mfma_f32_16x16x32_bf16 v[8:11], v[136:139], v[202:205], v[8:11]
	v_mfma_f32_16x16x32_bf16 v[60:63], v[132:135], v[164:167], v[60:63]
	v_mfma_f32_16x16x32_bf16 v[56:59], v[140:143], v[164:167], v[56:59]
	v_mfma_f32_16x16x32_bf16 v[44:47], v[132:135], v[190:193], v[44:47]
	v_mfma_f32_16x16x32_bf16 v[40:43], v[140:143], v[190:193], v[40:43]
	v_mfma_f32_16x16x32_bf16 v[28:31], v[132:135], v[198:201], v[28:31]
	v_mfma_f32_16x16x32_bf16 v[24:27], v[140:143], v[198:201], v[24:27]
	v_mfma_f32_16x16x32_bf16 v[12:15], v[132:135], v[206:209], v[12:15]
	v_mfma_f32_16x16x32_bf16 v[8:11], v[140:143], v[206:209], v[8:11]
	v_mfma_f32_16x16x32_bf16 v[52:55], v[144:147], v[160:163], v[52:55]
	v_mfma_f32_16x16x32_bf16 v[48:51], v[152:155], v[160:163], v[48:51]
	v_mfma_f32_16x16x32_bf16 v[36:39], v[144:147], v[186:189], v[36:39]
	v_mfma_f32_16x16x32_bf16 v[32:35], v[152:155], v[186:189], v[32:35]
	v_mfma_f32_16x16x32_bf16 v[20:23], v[144:147], v[194:197], v[20:23]
	v_mfma_f32_16x16x32_bf16 v[16:19], v[152:155], v[194:197], v[16:19]
	v_mfma_f32_16x16x32_bf16 v[4:7], v[144:147], v[202:205], v[4:7]
	v_mfma_f32_16x16x32_bf16 v[0:3], v[152:155], v[202:205], v[0:3]
	v_mfma_f32_16x16x32_bf16 v[52:55], v[148:151], v[164:167], v[52:55]
	v_mfma_f32_16x16x32_bf16 v[48:51], v[156:159], v[164:167], v[48:51]
	v_mfma_f32_16x16x32_bf16 v[36:39], v[148:151], v[190:193], v[36:39]
	v_mfma_f32_16x16x32_bf16 v[32:35], v[156:159], v[190:193], v[32:35]
	s_setprio 2
	s_barrier
	v_mfma_f32_16x16x32_bf16 v[20:23], v[148:151], v[198:201], v[20:23]
	v_mfma_f32_16x16x32_bf16 v[16:19], v[156:159], v[198:201], v[16:19]
	v_mfma_f32_16x16x32_bf16 v[4:7], v[148:151], v[206:209], v[4:7]
	v_mfma_f32_16x16x32_bf16 v[0:3], v[156:159], v[206:209], v[0:3]
	s_setprio 0
	s_add_i32 s92, s92, 2
	s_add_u32 s44, s44, 0x100
	s_addc_u32 s55, s55, 0
	s_cmp_gt_u32 s92, 41
	s_mov_b64 s[8:9], s[40:41]
	s_cbranch_scc0 .LBB0_769

.LBB0_862:
	s_add_i32 s27, s63, -2
	s_add_u32 vcc_lo, s40, 0x100
	s_addc_u32 vcc_hi, s41, 0
	s_mov_b32 s50, 0
	s_add_i32 s64, s50, 2
	s_add_u32 s40, s8, 0x100
	s_addc_u32 s41, s9, 0
	s_add_i32 s65, 0, 0x10000
	s_cmp_eq_u32 s27, s50
	s_cselect_b32 s53, s29, s41
	s_cselect_b32 s52, s28, s40
	s_cselect_b32 s51, s39, vcc_hi
	s_cselect_b32 s50, s38, vcc_lo
	s_add_i32 s66, 0, 0x14000
	v_add_u32_e32 v140, s65, v228
	v_add_u32_e32 v156, s66, v228
	ds_read_b128 v[128:131], v140
	ds_read_b128 v[132:135], v140 offset:1024
	ds_read_b128 v[136:139], v140 offset:2048
	ds_read_b128 v[140:143], v140 offset:3072
	ds_read_b128 v[144:147], v156
	ds_read_b128 v[148:151], v156 offset:1024
	ds_read_b128 v[152:155], v156 offset:2048
	ds_read_b128 v[156:159], v156 offset:3072
	s_add_i32 m0, s74, 0xc000
	ds_read_b128 v[160:163], v232
	ds_read_b128 v[164:167], v232 offset:1024
	ds_read_b128 v[186:189], v232 offset:2048
	ds_read_b128 v[190:193], v232 offset:3072
	ds_read_b128 v[194:197], v232 offset:4096
	ds_read_b128 v[198:201], v232 offset:5120
	ds_read_b128 v[202:205], v232 offset:6144
	ds_read_b128 v[206:209], v232 offset:7168
	global_load_lds_dwordx4 v184, s[8:9]
	s_add_i32 m0, s74, 0xe000
	s_nop 0
	global_load_lds_dwordx4 v182, s[8:9]
	s_waitcnt vmcnt(24) lgkmcnt(0)
	s_barrier
	s_setprio 1
	v_mfma_f32_16x16x32_bf16 v[124:127], v[128:131], v[160:163], 0
	v_mfma_f32_16x16x32_bf16 v[120:123], v[136:139], v[160:163], 0
	v_mfma_f32_16x16x32_bf16 v[108:111], v[128:131], v[186:189], 0
	v_mfma_f32_16x16x32_bf16 v[104:107], v[136:139], v[186:189], 0
	v_mfma_f32_16x16x32_bf16 v[92:95], v[128:131], v[194:197], 0
	v_mfma_f32_16x16x32_bf16 v[88:91], v[136:139], v[194:197], 0
	v_mfma_f32_16x16x32_bf16 v[76:79], v[128:131], v[202:205], 0
	v_mfma_f32_16x16x32_bf16 v[72:75], v[136:139], v[202:205], 0
	v_mfma_f32_16x16x32_bf16 v[124:127], v[132:135], v[164:167], v[124:127]
	v_mfma_f32_16x16x32_bf16 v[120:123], v[140:143], v[164:167], v[120:123]
	v_mfma_f32_16x16x32_bf16 v[108:111], v[132:135], v[190:193], v[108:111]
	v_mfma_f32_16x16x32_bf16 v[104:107], v[140:143], v[190:193], v[104:107]
	v_mfma_f32_16x16x32_bf16 v[92:95], v[132:135], v[198:201], v[92:95]
	v_mfma_f32_16x16x32_bf16 v[88:91], v[140:143], v[198:201], v[88:91]
	v_mfma_f32_16x16x32_bf16 v[76:79], v[132:135], v[206:209], v[76:79]
	v_mfma_f32_16x16x32_bf16 v[72:75], v[140:143], v[206:209], v[72:75]
	v_mfma_f32_16x16x32_bf16 v[116:119], v[144:147], v[160:163], 0
	v_mfma_f32_16x16x32_bf16 v[112:115], v[152:155], v[160:163], 0
	v_mfma_f32_16x16x32_bf16 v[100:103], v[144:147], v[186:189], 0
	v_mfma_f32_16x16x32_bf16 v[96:99], v[152:155], v[186:189], 0
	v_mfma_f32_16x16x32_bf16 v[84:87], v[144:147], v[194:197], 0
	v_mfma_f32_16x16x32_bf16 v[80:83], v[152:155], v[194:197], 0
	v_mfma_f32_16x16x32_bf16 v[68:71], v[144:147], v[202:205], 0
	v_mfma_f32_16x16x32_bf16 v[64:67], v[152:155], v[202:205], 0
	v_mfma_f32_16x16x32_bf16 v[116:119], v[148:151], v[164:167], v[116:119]
	v_mfma_f32_16x16x32_bf16 v[112:115], v[156:159], v[164:167], v[112:115]
	v_mfma_f32_16x16x32_bf16 v[100:103], v[148:151], v[190:193], v[100:103]
	v_mfma_f32_16x16x32_bf16 v[96:99], v[156:159], v[190:193], v[96:99]
	s_setprio 2
	s_barrier
	v_mfma_f32_16x16x32_bf16 v[84:87], v[148:151], v[198:201], v[84:87]
	v_mfma_f32_16x16x32_bf16 v[80:83], v[156:159], v[198:201], v[80:83]
	v_mfma_f32_16x16x32_bf16 v[68:71], v[148:151], v[206:209], v[68:71]
	v_mfma_f32_16x16x32_bf16 v[64:67], v[156:159], v[206:209], v[64:67]
	s_setprio 0
	s_add_i32 s8, s65, s72
	s_add_u32 s98, s50, s34
	s_addc_u32 s99, s51, s35
	s_mov_b32 m0, s8
	ds_read_b128 v[160:163], v232 offset:16384
	ds_read_b128 v[164:167], v232 offset:17408
	ds_read_b128 v[186:189], v232 offset:18432
	ds_read_b128 v[190:193], v232 offset:19456
	ds_read_b128 v[194:197], v232 offset:20480
	ds_read_b128 v[198:201], v232 offset:21504
	ds_read_b128 v[202:205], v232 offset:22528
	ds_read_b128 v[206:209], v232 offset:23552
	global_load_lds_dwordx4 v170, s[50:51]
	s_add_i32 m0, s8, 0x2000
	s_add_u32 s8, s50, 0xb0000
	s_addc_u32 s9, s51, 0
	s_add_i32 s65, s66, s72
	global_load_lds_dwordx4 v174, s[50:51]
	s_mov_b32 m0, s65
	s_nop 0
	global_load_lds_dwordx4 v170, s[8:9]
	s_add_i32 m0, s65, 0x2000
	s_nop 0
	global_load_lds_dwordx4 v174, s[8:9]
	s_add_u32 s100, s52, s34
	s_addc_u32 s101, s53, s35
	s_mov_b32 m0, s74
	s_nop 0
	global_load_lds_dwordx4 v168, s[52:53]
	s_mov_b32 m0, s75
	s_nop 0
	global_load_lds_dwordx4 v172, s[52:53]
	s_waitcnt vmcnt(8) lgkmcnt(0)
	s_barrier
	s_setprio 1
	v_mfma_f32_16x16x32_bf16 v[60:63], v[128:131], v[160:163], 0
	v_mfma_f32_16x16x32_bf16 v[56:59], v[136:139], v[160:163], 0
	v_mfma_f32_16x16x32_bf16 v[44:47], v[128:131], v[186:189], 0
	v_mfma_f32_16x16x32_bf16 v[40:43], v[136:139], v[186:189], 0
	v_mfma_f32_16x16x32_bf16 v[28:31], v[128:131], v[194:197], 0
	v_mfma_f32_16x16x32_bf16 v[24:27], v[136:139], v[194:197], 0
	v_mfma_f32_16x16x32_bf16 v[12:15], v[128:131], v[202:205], 0
	v_mfma_f32_16x16x32_bf16 v[8:11], v[136:139], v[202:205], 0
	v_mfma_f32_16x16x32_bf16 v[60:63], v[132:135], v[164:167], v[60:63]
	v_mfma_f32_16x16x32_bf16 v[56:59], v[140:143], v[164:167], v[56:59]
	v_mfma_f32_16x16x32_bf16 v[44:47], v[132:135], v[190:193], v[44:47]
	v_mfma_f32_16x16x32_bf16 v[40:43], v[140:143], v[190:193], v[40:43]
	v_mfma_f32_16x16x32_bf16 v[28:31], v[132:135], v[198:201], v[28:31]
	v_mfma_f32_16x16x32_bf16 v[24:27], v[140:143], v[198:201], v[24:27]
	v_mfma_f32_16x16x32_bf16 v[12:15], v[132:135], v[206:209], v[12:15]
	v_mfma_f32_16x16x32_bf16 v[8:11], v[140:143], v[206:209], v[8:11]
	v_mfma_f32_16x16x32_bf16 v[52:55], v[144:147], v[160:163], 0
	v_mfma_f32_16x16x32_bf16 v[48:51], v[152:155], v[160:163], 0
	v_mfma_f32_16x16x32_bf16 v[36:39], v[144:147], v[186:189], 0
	v_mfma_f32_16x16x32_bf16 v[32:35], v[152:155], v[186:189], 0
	v_mfma_f32_16x16x32_bf16 v[20:23], v[144:147], v[194:197], 0
	v_mfma_f32_16x16x32_bf16 v[16:19], v[152:155], v[194:197], 0
	v_mfma_f32_16x16x32_bf16 v[4:7], v[144:147], v[202:205], 0
	v_mfma_f32_16x16x32_bf16 v[0:3], v[152:155], v[202:205], 0
	v_mfma_f32_16x16x32_bf16 v[52:55], v[148:151], v[164:167], v[52:55]
	v_mfma_f32_16x16x32_bf16 v[48:51], v[156:159], v[164:167], v[48:51]
	v_mfma_f32_16x16x32_bf16 v[36:39], v[148:151], v[190:193], v[36:39]
	v_mfma_f32_16x16x32_bf16 v[32:35], v[156:159], v[190:193], v[32:35]
	s_setprio 2
	s_barrier
	v_mfma_f32_16x16x32_bf16 v[20:23], v[148:151], v[198:201], v[20:23]
	v_mfma_f32_16x16x32_bf16 v[16:19], v[156:159], v[198:201], v[16:19]
	v_mfma_f32_16x16x32_bf16 v[4:7], v[148:151], v[206:209], v[4:7]
	v_mfma_f32_16x16x32_bf16 v[0:3], v[156:159], v[206:209], v[0:3]
	s_setprio 0
	s_add_i32 s65, 0, 0x18000
	s_add_i32 s66, 0, 0x1c000
	v_add_u32_e32 v140, s65, v228
	v_add_u32_e32 v156, s66, v228
	ds_read_b128 v[128:131], v140
	ds_read_b128 v[132:135], v140 offset:1024
	ds_read_b128 v[136:139], v140 offset:2048
	ds_read_b128 v[140:143], v140 offset:3072
	ds_read_b128 v[144:147], v156
	ds_read_b128 v[148:151], v156 offset:1024
	ds_read_b128 v[152:155], v156 offset:2048
	ds_read_b128 v[156:159], v156 offset:3072
	s_add_u32 s8, s52, 0xb0000
	s_addc_u32 s9, s53, 0
	s_mov_b32 m0, s80
	ds_read_b128 v[160:163], v232 offset:32768
	ds_read_b128 v[164:167], v232 offset:33792
	ds_read_b128 v[186:189], v232 offset:34816
	ds_read_b128 v[190:193], v232 offset:35840
	ds_read_b128 v[194:197], v232 offset:36864
	ds_read_b128 v[198:201], v232 offset:37888
	ds_read_b128 v[202:205], v232 offset:38912
	ds_read_b128 v[206:209], v232 offset:39936
	global_load_lds_dwordx4 v168, s[8:9]
	s_mov_b32 m0, s81
	s_nop 0
	global_load_lds_dwordx4 v172, s[8:9]
	s_waitcnt vmcnt(8) lgkmcnt(0)
	s_barrier
	s_setprio 1
	v_mfma_f32_16x16x32_bf16 v[124:127], v[128:131], v[160:163], v[124:127]
	v_mfma_f32_16x16x32_bf16 v[120:123], v[136:139], v[160:163], v[120:123]
	v_mfma_f32_16x16x32_bf16 v[108:111], v[128:131], v[186:189], v[108:111]
	v_mfma_f32_16x16x32_bf16 v[104:107], v[136:139], v[186:189], v[104:107]
	v_mfma_f32_16x16x32_bf16 v[92:95], v[128:131], v[194:197], v[92:95]
	v_mfma_f32_16x16x32_bf16 v[88:91], v[136:139], v[194:197], v[88:91]
	v_mfma_f32_16x16x32_bf16 v[76:79], v[128:131], v[202:205], v[76:79]
	v_mfma_f32_16x16x32_bf16 v[72:75], v[136:139], v[202:205], v[72:75]
	v_mfma_f32_16x16x32_bf16 v[124:127], v[132:135], v[164:167], v[124:127]
	v_mfma_f32_16x16x32_bf16 v[120:123], v[140:143], v[164:167], v[120:123]
	v_mfma_f32_16x16x32_bf16 v[108:111], v[132:135], v[190:193], v[108:111]
	v_mfma_f32_16x16x32_bf16 v[104:107], v[140:143], v[190:193], v[104:107]
	v_mfma_f32_16x16x32_bf16 v[92:95], v[132:135], v[198:201], v[92:95]
	v_mfma_f32_16x16x32_bf16 v[88:91], v[140:143], v[198:201], v[88:91]
	v_mfma_f32_16x16x32_bf16 v[76:79], v[132:135], v[206:209], v[76:79]
	v_mfma_f32_16x16x32_bf16 v[72:75], v[140:143], v[206:209], v[72:75]
	v_mfma_f32_16x16x32_bf16 v[116:119], v[144:147], v[160:163], v[116:119]
	v_mfma_f32_16x16x32_bf16 v[112:115], v[152:155], v[160:163], v[112:115]
	v_mfma_f32_16x16x32_bf16 v[100:103], v[144:147], v[186:189], v[100:103]
	v_mfma_f32_16x16x32_bf16 v[96:99], v[152:155], v[186:189], v[96:99]
	v_mfma_f32_16x16x32_bf16 v[84:87], v[144:147], v[194:197], v[84:87]
	v_mfma_f32_16x16x32_bf16 v[80:83], v[152:155], v[194:197], v[80:83]
	v_mfma_f32_16x16x32_bf16 v[68:71], v[144:147], v[202:205], v[68:71]
	v_mfma_f32_16x16x32_bf16 v[64:67], v[152:155], v[202:205], v[64:67]
	v_mfma_f32_16x16x32_bf16 v[116:119], v[148:151], v[164:167], v[116:119]
	v_mfma_f32_16x16x32_bf16 v[112:115], v[156:159], v[164:167], v[112:115]
	v_mfma_f32_16x16x32_bf16 v[100:103], v[148:151], v[190:193], v[100:103]
	v_mfma_f32_16x16x32_bf16 v[96:99], v[156:159], v[190:193], v[96:99]
	s_setprio 2
	s_barrier
	v_mfma_f32_16x16x32_bf16 v[84:87], v[148:151], v[198:201], v[84:87]
	v_mfma_f32_16x16x32_bf16 v[80:83], v[156:159], v[198:201], v[80:83]
	v_mfma_f32_16x16x32_bf16 v[68:71], v[148:151], v[206:209], v[68:71]
	v_mfma_f32_16x16x32_bf16 v[64:67], v[156:159], v[206:209], v[64:67]
	s_setprio 0
	s_add_i32 s8, s65, s72
	s_mov_b32 m0, s8
	ds_read_b128 v[160:163], v232 offset:49152
	ds_read_b128 v[164:167], v232 offset:50176
	ds_read_b128 v[186:189], v232 offset:51200
	ds_read_b128 v[190:193], v232 offset:52224
	ds_read_b128 v[194:197], v232 offset:53248
	ds_read_b128 v[198:201], v232 offset:54272
	ds_read_b128 v[202:205], v232 offset:55296
	ds_read_b128 v[206:209], v232 offset:56320
	global_load_lds_dwordx4 v170, s[98:99]
	s_add_i32 m0, s8, 0x2000
	s_add_u32 s8, s50, 0xb0080
	s_addc_u32 s9, s51, 0
	s_add_i32 s50, s66, s72
	global_load_lds_dwordx4 v174, s[98:99]
	s_mov_b32 m0, s50
	s_nop 0
	global_load_lds_dwordx4 v170, s[8:9]
	s_add_i32 m0, s50, 0x2000
	s_nop 0
	global_load_lds_dwordx4 v174, s[8:9]
	s_mov_b32 m0, s83
	s_nop 0
	global_load_lds_dwordx4 v168, s[100:101]
	s_mov_b32 m0, s91
	s_nop 0
	global_load_lds_dwordx4 v172, s[100:101]
	s_waitcnt vmcnt(8) lgkmcnt(0)
	s_barrier
	s_setprio 1
	v_mfma_f32_16x16x32_bf16 v[60:63], v[128:131], v[160:163], v[60:63]
	v_mfma_f32_16x16x32_bf16 v[56:59], v[136:139], v[160:163], v[56:59]
	v_mfma_f32_16x16x32_bf16 v[44:47], v[128:131], v[186:189], v[44:47]
	v_mfma_f32_16x16x32_bf16 v[40:43], v[136:139], v[186:189], v[40:43]
	v_mfma_f32_16x16x32_bf16 v[28:31], v[128:131], v[194:197], v[28:31]
	v_mfma_f32_16x16x32_bf16 v[24:27], v[136:139], v[194:197], v[24:27]
	v_mfma_f32_16x16x32_bf16 v[12:15], v[128:131], v[202:205], v[12:15]
	v_mfma_f32_16x16x32_bf16 v[8:11], v[136:139], v[202:205], v[8:11]
	v_mfma_f32_16x16x32_bf16 v[60:63], v[132:135], v[164:167], v[60:63]
	v_mfma_f32_16x16x32_bf16 v[56:59], v[140:143], v[164:167], v[56:59]
	v_mfma_f32_16x16x32_bf16 v[44:47], v[132:135], v[190:193], v[44:47]
	v_mfma_f32_16x16x32_bf16 v[40:43], v[140:143], v[190:193], v[40:43]
	v_mfma_f32_16x16x32_bf16 v[28:31], v[132:135], v[198:201], v[28:31]
	v_mfma_f32_16x16x32_bf16 v[24:27], v[140:143], v[198:201], v[24:27]
	v_mfma_f32_16x16x32_bf16 v[12:15], v[132:135], v[206:209], v[12:15]
	v_mfma_f32_16x16x32_bf16 v[8:11], v[140:143], v[206:209], v[8:11]
	v_mfma_f32_16x16x32_bf16 v[52:55], v[144:147], v[160:163], v[52:55]
	v_mfma_f32_16x16x32_bf16 v[48:51], v[152:155], v[160:163], v[48:51]
	v_mfma_f32_16x16x32_bf16 v[36:39], v[144:147], v[186:189], v[36:39]
	v_mfma_f32_16x16x32_bf16 v[32:35], v[152:155], v[186:189], v[32:35]
	v_mfma_f32_16x16x32_bf16 v[20:23], v[144:147], v[194:197], v[20:23]
	v_mfma_f32_16x16x32_bf16 v[16:19], v[152:155], v[194:197], v[16:19]
	v_mfma_f32_16x16x32_bf16 v[4:7], v[144:147], v[202:205], v[4:7]
	v_mfma_f32_16x16x32_bf16 v[0:3], v[152:155], v[202:205], v[0:3]
	v_mfma_f32_16x16x32_bf16 v[52:55], v[148:151], v[164:167], v[52:55]
	v_mfma_f32_16x16x32_bf16 v[48:51], v[156:159], v[164:167], v[48:51]
	v_mfma_f32_16x16x32_bf16 v[36:39], v[148:151], v[190:193], v[36:39]
	v_mfma_f32_16x16x32_bf16 v[32:35], v[156:159], v[190:193], v[32:35]
	s_setprio 2
	s_barrier
	v_mfma_f32_16x16x32_bf16 v[20:23], v[148:151], v[198:201], v[20:23]
	v_mfma_f32_16x16x32_bf16 v[16:19], v[156:159], v[198:201], v[16:19]
	v_mfma_f32_16x16x32_bf16 v[4:7], v[148:151], v[206:209], v[4:7]
	v_mfma_f32_16x16x32_bf16 v[0:3], v[156:159], v[206:209], v[0:3]
	s_setprio 0
	s_add_u32 vcc_lo, vcc_lo, 0x100
	s_addc_u32 vcc_hi, vcc_hi, 0
	s_cmp_ge_i32 s64, s63
	s_mov_b64 s[8:9], s[40:41]
	s_mov_b32 s50, s64
	s_cbranch_scc1 .Lpeel_exit_3
.LBB0_863:
	s_add_i32 s64, s50, 2
	s_add_u32 s40, s8, 0x100
	s_addc_u32 s41, s9, 0
	s_add_i32 s65, 0, 0x10000
	s_cmp_eq_u32 s27, s50
	s_cselect_b32 s53, s29, s41
	s_cselect_b32 s52, s28, s40
	s_cselect_b32 s51, s39, vcc_hi
	s_cselect_b32 s50, s38, vcc_lo
	s_add_i32 s66, 0, 0x14000
	v_add_u32_e32 v140, s65, v228
	v_add_u32_e32 v156, s66, v228
	ds_read_b128 v[128:131], v140
	ds_read_b128 v[132:135], v140 offset:1024
	ds_read_b128 v[136:139], v140 offset:2048
	ds_read_b128 v[140:143], v140 offset:3072
	ds_read_b128 v[144:147], v156
	ds_read_b128 v[148:151], v156 offset:1024
	ds_read_b128 v[152:155], v156 offset:2048
	ds_read_b128 v[156:159], v156 offset:3072
	s_add_i32 m0, s74, 0xc000
	ds_read_b128 v[160:163], v232
	ds_read_b128 v[164:167], v232 offset:1024
	ds_read_b128 v[186:189], v232 offset:2048
	ds_read_b128 v[190:193], v232 offset:3072
	ds_read_b128 v[194:197], v232 offset:4096
	ds_read_b128 v[198:201], v232 offset:5120
	ds_read_b128 v[202:205], v232 offset:6144
	ds_read_b128 v[206:209], v232 offset:7168
	global_load_lds_dwordx4 v184, s[8:9]
	s_add_i32 m0, s74, 0xe000
	s_nop 0
	global_load_lds_dwordx4 v182, s[8:9]
	s_waitcnt vmcnt(8) lgkmcnt(0)
	s_barrier
	s_setprio 1
	v_mfma_f32_16x16x32_bf16 v[124:127], v[128:131], v[160:163], v[124:127]
	v_mfma_f32_16x16x32_bf16 v[120:123], v[136:139], v[160:163], v[120:123]
	v_mfma_f32_16x16x32_bf16 v[108:111], v[128:131], v[186:189], v[108:111]
	v_mfma_f32_16x16x32_bf16 v[104:107], v[136:139], v[186:189], v[104:107]
	v_mfma_f32_16x16x32_bf16 v[92:95], v[128:131], v[194:197], v[92:95]
	v_mfma_f32_16x16x32_bf16 v[88:91], v[136:139], v[194:197], v[88:91]
	v_mfma_f32_16x16x32_bf16 v[76:79], v[128:131], v[202:205], v[76:79]
	v_mfma_f32_16x16x32_bf16 v[72:75], v[136:139], v[202:205], v[72:75]
	v_mfma_f32_16x16x32_bf16 v[124:127], v[132:135], v[164:167], v[124:127]
	v_mfma_f32_16x16x32_bf16 v[120:123], v[140:143], v[164:167], v[120:123]
	v_mfma_f32_16x16x32_bf16 v[108:111], v[132:135], v[190:193], v[108:111]
	v_mfma_f32_16x16x32_bf16 v[104:107], v[140:143], v[190:193], v[104:107]
	v_mfma_f32_16x16x32_bf16 v[92:95], v[132:135], v[198:201], v[92:95]
	v_mfma_f32_16x16x32_bf16 v[88:91], v[140:143], v[198:201], v[88:91]
	v_mfma_f32_16x16x32_bf16 v[76:79], v[132:135], v[206:209], v[76:79]
	v_mfma_f32_16x16x32_bf16 v[72:75], v[140:143], v[206:209], v[72:75]
	v_mfma_f32_16x16x32_bf16 v[116:119], v[144:147], v[160:163], v[116:119]
	v_mfma_f32_16x16x32_bf16 v[112:115], v[152:155], v[160:163], v[112:115]
	v_mfma_f32_16x16x32_bf16 v[100:103], v[144:147], v[186:189], v[100:103]
	v_mfma_f32_16x16x32_bf16 v[96:99], v[152:155], v[186:189], v[96:99]
	v_mfma_f32_16x16x32_bf16 v[84:87], v[144:147], v[194:197], v[84:87]
	v_mfma_f32_16x16x32_bf16 v[80:83], v[152:155], v[194:197], v[80:83]
	v_mfma_f32_16x16x32_bf16 v[68:71], v[144:147], v[202:205], v[68:71]
	v_mfma_f32_16x16x32_bf16 v[64:67], v[152:155], v[202:205], v[64:67]
	v_mfma_f32_16x16x32_bf16 v[116:119], v[148:151], v[164:167], v[116:119]
	v_mfma_f32_16x16x32_bf16 v[112:115], v[156:159], v[164:167], v[112:115]
	v_mfma_f32_16x16x32_bf16 v[100:103], v[148:151], v[190:193], v[100:103]
	v_mfma_f32_16x16x32_bf16 v[96:99], v[156:159], v[190:193], v[96:99]
	s_setprio 2
	s_barrier
	v_mfma_f32_16x16x32_bf16 v[84:87], v[148:151], v[198:201], v[84:87]
	v_mfma_f32_16x16x32_bf16 v[80:83], v[156:159], v[198:201], v[80:83]
	v_mfma_f32_16x16x32_bf16 v[68:71], v[148:151], v[206:209], v[68:71]
	v_mfma_f32_16x16x32_bf16 v[64:67], v[156:159], v[206:209], v[64:67]
	s_setprio 0
	s_add_i32 s8, s65, s72
	s_add_u32 s98, s50, s34
	s_addc_u32 s99, s51, s35
	s_mov_b32 m0, s8
	ds_read_b128 v[160:163], v232 offset:16384
	ds_read_b128 v[164:167], v232 offset:17408
	ds_read_b128 v[186:189], v232 offset:18432
	ds_read_b128 v[190:193], v232 offset:19456
	ds_read_b128 v[194:197], v232 offset:20480
	ds_read_b128 v[198:201], v232 offset:21504
	ds_read_b128 v[202:205], v232 offset:22528
	ds_read_b128 v[206:209], v232 offset:23552
	global_load_lds_dwordx4 v170, s[50:51]
	s_add_i32 m0, s8, 0x2000
	s_add_u32 s8, s50, 0xb0000
	s_addc_u32 s9, s51, 0
	s_add_i32 s65, s66, s72
	global_load_lds_dwordx4 v174, s[50:51]
	s_mov_b32 m0, s65
	s_nop 0
	global_load_lds_dwordx4 v170, s[8:9]
	s_add_i32 m0, s65, 0x2000
	s_nop 0
	global_load_lds_dwordx4 v174, s[8:9]
	s_add_u32 s100, s52, s34
	s_addc_u32 s101, s53, s35
	s_mov_b32 m0, s74
	s_nop 0
	global_load_lds_dwordx4 v168, s[52:53]
	s_mov_b32 m0, s75
	s_nop 0
	global_load_lds_dwordx4 v172, s[52:53]
	s_waitcnt vmcnt(8) lgkmcnt(0)
	s_barrier
	s_setprio 1
	v_mfma_f32_16x16x32_bf16 v[60:63], v[128:131], v[160:163], v[60:63]
	v_mfma_f32_16x16x32_bf16 v[56:59], v[136:139], v[160:163], v[56:59]
	v_mfma_f32_16x16x32_bf16 v[44:47], v[128:131], v[186:189], v[44:47]
	v_mfma_f32_16x16x32_bf16 v[40:43], v[136:139], v[186:189], v[40:43]
	v_mfma_f32_16x16x32_bf16 v[28:31], v[128:131], v[194:197], v[28:31]
	v_mfma_f32_16x16x32_bf16 v[24:27], v[136:139], v[194:197], v[24:27]
	v_mfma_f32_16x16x32_bf16 v[12:15], v[128:131], v[202:205], v[12:15]
	v_mfma_f32_16x16x32_bf16 v[8:11], v[136:139], v[202:205], v[8:11]
	v_mfma_f32_16x16x32_bf16 v[60:63], v[132:135], v[164:167], v[60:63]
	v_mfma_f32_16x16x32_bf16 v[56:59], v[140:143], v[164:167], v[56:59]
	v_mfma_f32_16x16x32_bf16 v[44:47], v[132:135], v[190:193], v[44:47]
	v_mfma_f32_16x16x32_bf16 v[40:43], v[140:143], v[190:193], v[40:43]
	v_mfma_f32_16x16x32_bf16 v[28:31], v[132:135], v[198:201], v[28:31]
	v_mfma_f32_16x16x32_bf16 v[24:27], v[140:143], v[198:201], v[24:27]
	v_mfma_f32_16x16x32_bf16 v[12:15], v[132:135], v[206:209], v[12:15]
	v_mfma_f32_16x16x32_bf16 v[8:11], v[140:143], v[206:209], v[8:11]
	v_mfma_f32_16x16x32_bf16 v[52:55], v[144:147], v[160:163], v[52:55]
	v_mfma_f32_16x16x32_bf16 v[48:51], v[152:155], v[160:163], v[48:51]
	v_mfma_f32_16x16x32_bf16 v[36:39], v[144:147], v[186:189], v[36:39]
	v_mfma_f32_16x16x32_bf16 v[32:35], v[152:155], v[186:189], v[32:35]
	v_mfma_f32_16x16x32_bf16 v[20:23], v[144:147], v[194:197], v[20:23]
	v_mfma_f32_16x16x32_bf16 v[16:19], v[152:155], v[194:197], v[16:19]
	v_mfma_f32_16x16x32_bf16 v[4:7], v[144:147], v[202:205], v[4:7]
	v_mfma_f32_16x16x32_bf16 v[0:3], v[152:155], v[202:205], v[0:3]
	v_mfma_f32_16x16x32_bf16 v[52:55], v[148:151], v[164:167], v[52:55]
	v_mfma_f32_16x16x32_bf16 v[48:51], v[156:159], v[164:167], v[48:51]
	v_mfma_f32_16x16x32_bf16 v[36:39], v[148:151], v[190:193], v[36:39]
	v_mfma_f32_16x16x32_bf16 v[32:35], v[156:159], v[190:193], v[32:35]
	s_setprio 2
	s_barrier
	v_mfma_f32_16x16x32_bf16 v[20:23], v[148:151], v[198:201], v[20:23]
	v_mfma_f32_16x16x32_bf16 v[16:19], v[156:159], v[198:201], v[16:19]
	v_mfma_f32_16x16x32_bf16 v[4:7], v[148:151], v[206:209], v[4:7]
	v_mfma_f32_16x16x32_bf16 v[0:3], v[156:159], v[206:209], v[0:3]
	s_setprio 0
	s_add_i32 s65, 0, 0x18000
	s_add_i32 s66, 0, 0x1c000
	v_add_u32_e32 v140, s65, v228
	v_add_u32_e32 v156, s66, v228
	ds_read_b128 v[128:131], v140
	ds_read_b128 v[132:135], v140 offset:1024
	ds_read_b128 v[136:139], v140 offset:2048
	ds_read_b128 v[140:143], v140 offset:3072
	ds_read_b128 v[144:147], v156
	ds_read_b128 v[148:151], v156 offset:1024
	ds_read_b128 v[152:155], v156 offset:2048
	ds_read_b128 v[156:159], v156 offset:3072
	s_add_u32 s8, s52, 0xb0000
	s_addc_u32 s9, s53, 0
	s_mov_b32 m0, s80
	ds_read_b128 v[160:163], v232 offset:32768
	ds_read_b128 v[164:167], v232 offset:33792
	ds_read_b128 v[186:189], v232 offset:34816
	ds_read_b128 v[190:193], v232 offset:35840
	ds_read_b128 v[194:197], v232 offset:36864
	ds_read_b128 v[198:201], v232 offset:37888
	ds_read_b128 v[202:205], v232 offset:38912
	ds_read_b128 v[206:209], v232 offset:39936
	global_load_lds_dwordx4 v168, s[8:9]
	s_mov_b32 m0, s81
	s_nop 0
	global_load_lds_dwordx4 v172, s[8:9]
	s_waitcnt vmcnt(8) lgkmcnt(0)
	s_barrier
	s_setprio 1
	v_mfma_f32_16x16x32_bf16 v[124:127], v[128:131], v[160:163], v[124:127]
	v_mfma_f32_16x16x32_bf16 v[120:123], v[136:139], v[160:163], v[120:123]
	v_mfma_f32_16x16x32_bf16 v[108:111], v[128:131], v[186:189], v[108:111]
	v_mfma_f32_16x16x32_bf16 v[104:107], v[136:139], v[186:189], v[104:107]
	v_mfma_f32_16x16x32_bf16 v[92:95], v[128:131], v[194:197], v[92:95]
	v_mfma_f32_16x16x32_bf16 v[88:91], v[136:139], v[194:197], v[88:91]
	v_mfma_f32_16x16x32_bf16 v[76:79], v[128:131], v[202:205], v[76:79]
	v_mfma_f32_16x16x32_bf16 v[72:75], v[136:139], v[202:205], v[72:75]
	v_mfma_f32_16x16x32_bf16 v[124:127], v[132:135], v[164:167], v[124:127]
	v_mfma_f32_16x16x32_bf16 v[120:123], v[140:143], v[164:167], v[120:123]
	v_mfma_f32_16x16x32_bf16 v[108:111], v[132:135], v[190:193], v[108:111]
	v_mfma_f32_16x16x32_bf16 v[104:107], v[140:143], v[190:193], v[104:107]
	v_mfma_f32_16x16x32_bf16 v[92:95], v[132:135], v[198:201], v[92:95]
	v_mfma_f32_16x16x32_bf16 v[88:91], v[140:143], v[198:201], v[88:91]
	v_mfma_f32_16x16x32_bf16 v[76:79], v[132:135], v[206:209], v[76:79]
	v_mfma_f32_16x16x32_bf16 v[72:75], v[140:143], v[206:209], v[72:75]
	v_mfma_f32_16x16x32_bf16 v[116:119], v[144:147], v[160:163], v[116:119]
	v_mfma_f32_16x16x32_bf16 v[112:115], v[152:155], v[160:163], v[112:115]
	v_mfma_f32_16x16x32_bf16 v[100:103], v[144:147], v[186:189], v[100:103]
	v_mfma_f32_16x16x32_bf16 v[96:99], v[152:155], v[186:189], v[96:99]
	v_mfma_f32_16x16x32_bf16 v[84:87], v[144:147], v[194:197], v[84:87]
	v_mfma_f32_16x16x32_bf16 v[80:83], v[152:155], v[194:197], v[80:83]
	v_mfma_f32_16x16x32_bf16 v[68:71], v[144:147], v[202:205], v[68:71]
	v_mfma_f32_16x16x32_bf16 v[64:67], v[152:155], v[202:205], v[64:67]
	v_mfma_f32_16x16x32_bf16 v[116:119], v[148:151], v[164:167], v[116:119]
	v_mfma_f32_16x16x32_bf16 v[112:115], v[156:159], v[164:167], v[112:115]
	v_mfma_f32_16x16x32_bf16 v[100:103], v[148:151], v[190:193], v[100:103]
	v_mfma_f32_16x16x32_bf16 v[96:99], v[156:159], v[190:193], v[96:99]
	s_setprio 2
	s_barrier
	v_mfma_f32_16x16x32_bf16 v[84:87], v[148:151], v[198:201], v[84:87]
	v_mfma_f32_16x16x32_bf16 v[80:83], v[156:159], v[198:201], v[80:83]
	v_mfma_f32_16x16x32_bf16 v[68:71], v[148:151], v[206:209], v[68:71]
	v_mfma_f32_16x16x32_bf16 v[64:67], v[156:159], v[206:209], v[64:67]
	s_setprio 0
	s_add_i32 s8, s65, s72
	s_mov_b32 m0, s8
	ds_read_b128 v[160:163], v232 offset:49152
	ds_read_b128 v[164:167], v232 offset:50176
	ds_read_b128 v[186:189], v232 offset:51200
	ds_read_b128 v[190:193], v232 offset:52224
	ds_read_b128 v[194:197], v232 offset:53248
	ds_read_b128 v[198:201], v232 offset:54272
	ds_read_b128 v[202:205], v232 offset:55296
	ds_read_b128 v[206:209], v232 offset:56320
	global_load_lds_dwordx4 v170, s[98:99]
	s_add_i32 m0, s8, 0x2000
	s_add_u32 s8, s50, 0xb0080
	s_addc_u32 s9, s51, 0
	s_add_i32 s50, s66, s72
	global_load_lds_dwordx4 v174, s[98:99]
	s_mov_b32 m0, s50
	s_nop 0
	global_load_lds_dwordx4 v170, s[8:9]
	s_add_i32 m0, s50, 0x2000
	s_nop 0
	global_load_lds_dwordx4 v174, s[8:9]
	s_mov_b32 m0, s83
	s_nop 0
	global_load_lds_dwordx4 v168, s[100:101]
	s_mov_b32 m0, s91
	s_nop 0
	global_load_lds_dwordx4 v172, s[100:101]
	s_waitcnt vmcnt(8) lgkmcnt(0)
	s_barrier
	s_setprio 1
	v_mfma_f32_16x16x32_bf16 v[60:63], v[128:131], v[160:163], v[60:63]
	v_mfma_f32_16x16x32_bf16 v[56:59], v[136:139], v[160:163], v[56:59]
	v_mfma_f32_16x16x32_bf16 v[44:47], v[128:131], v[186:189], v[44:47]
	v_mfma_f32_16x16x32_bf16 v[40:43], v[136:139], v[186:189], v[40:43]
	v_mfma_f32_16x16x32_bf16 v[28:31], v[128:131], v[194:197], v[28:31]
	v_mfma_f32_16x16x32_bf16 v[24:27], v[136:139], v[194:197], v[24:27]
	v_mfma_f32_16x16x32_bf16 v[12:15], v[128:131], v[202:205], v[12:15]
	v_mfma_f32_16x16x32_bf16 v[8:11], v[136:139], v[202:205], v[8:11]
	v_mfma_f32_16x16x32_bf16 v[60:63], v[132:135], v[164:167], v[60:63]
	v_mfma_f32_16x16x32_bf16 v[56:59], v[140:143], v[164:167], v[56:59]
	v_mfma_f32_16x16x32_bf16 v[44:47], v[132:135], v[190:193], v[44:47]
	v_mfma_f32_16x16x32_bf16 v[40:43], v[140:143], v[190:193], v[40:43]
	v_mfma_f32_16x16x32_bf16 v[28:31], v[132:135], v[198:201], v[28:31]
	v_mfma_f32_16x16x32_bf16 v[24:27], v[140:143], v[198:201], v[24:27]
	v_mfma_f32_16x16x32_bf16 v[12:15], v[132:135], v[206:209], v[12:15]
	v_mfma_f32_16x16x32_bf16 v[8:11], v[140:143], v[206:209], v[8:11]
	v_mfma_f32_16x16x32_bf16 v[52:55], v[144:147], v[160:163], v[52:55]
	v_mfma_f32_16x16x32_bf16 v[48:51], v[152:155], v[160:163], v[48:51]
	v_mfma_f32_16x16x32_bf16 v[36:39], v[144:147], v[186:189], v[36:39]
	v_mfma_f32_16x16x32_bf16 v[32:35], v[152:155], v[186:189], v[32:35]
	v_mfma_f32_16x16x32_bf16 v[20:23], v[144:147], v[194:197], v[20:23]
	v_mfma_f32_16x16x32_bf16 v[16:19], v[152:155], v[194:197], v[16:19]
	v_mfma_f32_16x16x32_bf16 v[4:7], v[144:147], v[202:205], v[4:7]
	v_mfma_f32_16x16x32_bf16 v[0:3], v[152:155], v[202:205], v[0:3]
	v_mfma_f32_16x16x32_bf16 v[52:55], v[148:151], v[164:167], v[52:55]
	v_mfma_f32_16x16x32_bf16 v[48:51], v[156:159], v[164:167], v[48:51]
	v_mfma_f32_16x16x32_bf16 v[36:39], v[148:151], v[190:193], v[36:39]
	v_mfma_f32_16x16x32_bf16 v[32:35], v[156:159], v[190:193], v[32:35]
	s_setprio 2
	s_barrier
	v_mfma_f32_16x16x32_bf16 v[20:23], v[148:151], v[198:201], v[20:23]
	v_mfma_f32_16x16x32_bf16 v[16:19], v[156:159], v[198:201], v[16:19]
	v_mfma_f32_16x16x32_bf16 v[4:7], v[148:151], v[206:209], v[4:7]
	v_mfma_f32_16x16x32_bf16 v[0:3], v[156:159], v[206:209], v[0:3]
	s_setprio 0
	s_add_u32 vcc_lo, vcc_lo, 0x100
	s_addc_u32 vcc_hi, vcc_hi, 0
	s_cmp_ge_i32 s64, s63
	s_mov_b64 s[8:9], s[40:41]
	s_mov_b32 s50, s64
	s_cbranch_scc0 .LBB0_863

.LBB0_952:
	s_add_u32 s44, s38, 0x180
	s_addc_u32 s53, s39, 0
	s_mov_b32 s83, -2
	s_add_u32 s38, s8, 0x180
	s_addc_u32 s39, s9, 0
	s_add_i32 s64, 0, 0x10000
	s_cmp_eq_u32 s83, 12
	s_cselect_b32 s51, s1, s39
	s_cselect_b32 s50, s0, s38
	s_cselect_b32 s41, s29, s53
	s_cselect_b32 s40, s28, s44
	s_add_i32 s65, 0, 0x14000
	v_add_u32_e32 v68, s64, v228
	v_add_u32_e32 v156, s65, v228
	ds_read_b128 v[56:59], v68
	ds_read_b128 v[60:63], v68 offset:1024
	ds_read_b128 v[64:67], v68 offset:2048
	ds_read_b128 v[68:71], v68 offset:3072
	ds_read_b128 v[144:147], v156
	ds_read_b128 v[148:151], v156 offset:1024
	ds_read_b128 v[152:155], v156 offset:2048
	ds_read_b128 v[156:159], v156 offset:3072
	s_add_i32 m0, s60, 0xc000
	ds_read_b128 v[160:163], v231
	ds_read_b128 v[164:167], v231 offset:1024
	ds_read_b128 v[168:171], v231 offset:2048
	ds_read_b128 v[172:175], v231 offset:3072
	ds_read_b128 v[194:197], v231 offset:4096
	ds_read_b128 v[198:201], v231 offset:5120
	ds_read_b128 v[202:205], v231 offset:6144
	ds_read_b128 v[206:209], v231 offset:7168
	global_load_lds_dwordx4 v192, s[8:9]
	s_add_i32 m0, s60, 0xe000
	s_nop 0
	global_load_lds_dwordx4 v190, s[8:9]
	s_waitcnt vmcnt(24) lgkmcnt(0)
	s_barrier
	s_setprio 1
	v_mfma_f32_16x16x32_bf16 v[140:143], v[56:59], v[160:163], 0
	v_mfma_f32_16x16x32_bf16 v[136:139], v[64:67], v[160:163], 0
	v_mfma_f32_16x16x32_bf16 v[128:131], v[56:59], v[168:171], 0
	v_mfma_f32_16x16x32_bf16 v[120:123], v[64:67], v[168:171], 0
	v_mfma_f32_16x16x32_bf16 v[108:111], v[56:59], v[194:197], 0
	v_mfma_f32_16x16x32_bf16 v[104:107], v[64:67], v[194:197], 0
	v_mfma_f32_16x16x32_bf16 v[92:95], v[56:59], v[202:205], 0
	v_mfma_f32_16x16x32_bf16 v[88:91], v[64:67], v[202:205], 0
	v_mfma_f32_16x16x32_bf16 v[140:143], v[60:63], v[164:167], v[140:143]
	v_mfma_f32_16x16x32_bf16 v[136:139], v[68:71], v[164:167], v[136:139]
	v_mfma_f32_16x16x32_bf16 v[128:131], v[60:63], v[172:175], v[128:131]
	v_mfma_f32_16x16x32_bf16 v[120:123], v[68:71], v[172:175], v[120:123]
	v_mfma_f32_16x16x32_bf16 v[108:111], v[60:63], v[198:201], v[108:111]
	v_mfma_f32_16x16x32_bf16 v[104:107], v[68:71], v[198:201], v[104:107]
	v_mfma_f32_16x16x32_bf16 v[92:95], v[60:63], v[206:209], v[92:95]
	v_mfma_f32_16x16x32_bf16 v[88:91], v[68:71], v[206:209], v[88:91]
	v_mfma_f32_16x16x32_bf16 v[132:135], v[144:147], v[160:163], 0
	v_mfma_f32_16x16x32_bf16 v[124:127], v[152:155], v[160:163], 0
	v_mfma_f32_16x16x32_bf16 v[116:119], v[144:147], v[168:171], 0
	v_mfma_f32_16x16x32_bf16 v[112:115], v[152:155], v[168:171], 0
	v_mfma_f32_16x16x32_bf16 v[100:103], v[144:147], v[194:197], 0
	v_mfma_f32_16x16x32_bf16 v[96:99], v[152:155], v[194:197], 0
	v_mfma_f32_16x16x32_bf16 v[84:87], v[144:147], v[202:205], 0
	v_mfma_f32_16x16x32_bf16 v[80:83], v[152:155], v[202:205], 0
	v_mfma_f32_16x16x32_bf16 v[132:135], v[148:151], v[164:167], v[132:135]
	v_mfma_f32_16x16x32_bf16 v[124:127], v[156:159], v[164:167], v[124:127]
	v_mfma_f32_16x16x32_bf16 v[116:119], v[148:151], v[172:175], v[116:119]
	v_mfma_f32_16x16x32_bf16 v[112:115], v[156:159], v[172:175], v[112:115]
	s_setprio 2
	s_barrier
	v_mfma_f32_16x16x32_bf16 v[100:103], v[148:151], v[198:201], v[100:103]
	v_mfma_f32_16x16x32_bf16 v[96:99], v[156:159], v[198:201], v[96:99]
	v_mfma_f32_16x16x32_bf16 v[84:87], v[148:151], v[206:209], v[84:87]
	v_mfma_f32_16x16x32_bf16 v[80:83], v[156:159], v[206:209], v[80:83]
	s_setprio 0
	s_add_i32 s8, s64, s37
	s_add_u32 s98, s40, s34
	s_addc_u32 s99, s41, s35
	s_mov_b32 m0, s8
	ds_read_b128 v[160:163], v231 offset:16384
	ds_read_b128 v[164:167], v231 offset:17408
	ds_read_b128 v[168:171], v231 offset:18432
	ds_read_b128 v[172:175], v231 offset:19456
	ds_read_b128 v[194:197], v231 offset:20480
	ds_read_b128 v[198:201], v231 offset:21504
	ds_read_b128 v[202:205], v231 offset:22528
	ds_read_b128 v[206:209], v231 offset:23552
	global_load_lds_dwordx4 v184, s[40:41]
	s_add_i32 m0, s8, 0x2000
	s_add_u32 s8, s40, 0x60000
	s_addc_u32 s9, s41, 0
	s_add_i32 s64, s65, s37
	global_load_lds_dwordx4 v188, s[40:41]
	s_mov_b32 m0, s64
	s_nop 0
	global_load_lds_dwordx4 v184, s[8:9]
	s_add_i32 m0, s64, 0x2000
	s_nop 0
	global_load_lds_dwordx4 v188, s[8:9]
	s_add_u32 s100, s50, s34
	s_addc_u32 s101, s51, s35
	s_mov_b32 m0, s60
	s_nop 0
	global_load_lds_dwordx4 v182, s[50:51]
	s_mov_b32 m0, s61
	s_nop 0
	global_load_lds_dwordx4 v186, s[50:51]
	s_waitcnt vmcnt(8) lgkmcnt(0)
	s_barrier
	s_setprio 1
	v_mfma_f32_16x16x32_bf16 v[76:79], v[56:59], v[160:163], 0
	v_mfma_f32_16x16x32_bf16 v[72:75], v[64:67], v[160:163], 0
	v_mfma_f32_16x16x32_bf16 v[44:47], v[56:59], v[168:171], 0
	v_mfma_f32_16x16x32_bf16 v[40:43], v[64:67], v[168:171], 0
	v_mfma_f32_16x16x32_bf16 v[28:31], v[56:59], v[194:197], 0
	v_mfma_f32_16x16x32_bf16 v[24:27], v[64:67], v[194:197], 0
	v_mfma_f32_16x16x32_bf16 v[12:15], v[56:59], v[202:205], 0
	v_mfma_f32_16x16x32_bf16 v[8:11], v[64:67], v[202:205], 0
	v_mfma_f32_16x16x32_bf16 v[76:79], v[60:63], v[164:167], v[76:79]
	v_mfma_f32_16x16x32_bf16 v[72:75], v[68:71], v[164:167], v[72:75]
	v_mfma_f32_16x16x32_bf16 v[44:47], v[60:63], v[172:175], v[44:47]
	v_mfma_f32_16x16x32_bf16 v[40:43], v[68:71], v[172:175], v[40:43]
	v_mfma_f32_16x16x32_bf16 v[28:31], v[60:63], v[198:201], v[28:31]
	v_mfma_f32_16x16x32_bf16 v[24:27], v[68:71], v[198:201], v[24:27]
	v_mfma_f32_16x16x32_bf16 v[12:15], v[60:63], v[206:209], v[12:15]
	v_mfma_f32_16x16x32_bf16 v[8:11], v[68:71], v[206:209], v[8:11]
	v_mfma_f32_16x16x32_bf16 v[52:55], v[144:147], v[160:163], 0
	v_mfma_f32_16x16x32_bf16 v[48:51], v[152:155], v[160:163], 0
	v_mfma_f32_16x16x32_bf16 v[36:39], v[144:147], v[168:171], 0
	v_mfma_f32_16x16x32_bf16 v[32:35], v[152:155], v[168:171], 0
	v_mfma_f32_16x16x32_bf16 v[20:23], v[144:147], v[194:197], 0
	v_mfma_f32_16x16x32_bf16 v[16:19], v[152:155], v[194:197], 0
	v_mfma_f32_16x16x32_bf16 v[4:7], v[144:147], v[202:205], 0
	v_mfma_f32_16x16x32_bf16 v[0:3], v[152:155], v[202:205], 0
	v_mfma_f32_16x16x32_bf16 v[52:55], v[148:151], v[164:167], v[52:55]
	v_mfma_f32_16x16x32_bf16 v[48:51], v[156:159], v[164:167], v[48:51]
	v_mfma_f32_16x16x32_bf16 v[36:39], v[148:151], v[172:175], v[36:39]
	v_mfma_f32_16x16x32_bf16 v[32:35], v[156:159], v[172:175], v[32:35]
	s_setprio 2
	s_barrier
	v_mfma_f32_16x16x32_bf16 v[20:23], v[148:151], v[198:201], v[20:23]
	v_mfma_f32_16x16x32_bf16 v[16:19], v[156:159], v[198:201], v[16:19]
	v_mfma_f32_16x16x32_bf16 v[4:7], v[148:151], v[206:209], v[4:7]
	v_mfma_f32_16x16x32_bf16 v[0:3], v[156:159], v[206:209], v[0:3]
	s_setprio 0
	s_add_i32 s64, 0, 0x18000
	s_add_i32 s65, 0, 0x1c000
	v_add_u32_e32 v68, s64, v228
	v_add_u32_e32 v156, s65, v228
	ds_read_b128 v[56:59], v68
	ds_read_b128 v[60:63], v68 offset:1024
	ds_read_b128 v[64:67], v68 offset:2048
	ds_read_b128 v[68:71], v68 offset:3072
	ds_read_b128 v[144:147], v156
	ds_read_b128 v[148:151], v156 offset:1024
	ds_read_b128 v[152:155], v156 offset:2048
	ds_read_b128 v[156:159], v156 offset:3072
	s_add_u32 s8, s50, 0x60000
	s_addc_u32 s9, s51, 0
	s_mov_b32 m0, s62
	ds_read_b128 v[160:163], v231 offset:32768
	ds_read_b128 v[164:167], v231 offset:33792
	ds_read_b128 v[168:171], v231 offset:34816
	ds_read_b128 v[172:175], v231 offset:35840
	ds_read_b128 v[194:197], v231 offset:36864
	ds_read_b128 v[198:201], v231 offset:37888
	ds_read_b128 v[202:205], v231 offset:38912
	ds_read_b128 v[206:209], v231 offset:39936
	global_load_lds_dwordx4 v182, s[8:9]
	s_mov_b32 m0, s63
	s_nop 0
	global_load_lds_dwordx4 v186, s[8:9]
	s_waitcnt vmcnt(8) lgkmcnt(0)
	s_barrier
	s_setprio 1
	v_mfma_f32_16x16x32_bf16 v[140:143], v[56:59], v[160:163], v[140:143]
	v_mfma_f32_16x16x32_bf16 v[136:139], v[64:67], v[160:163], v[136:139]
	v_mfma_f32_16x16x32_bf16 v[128:131], v[56:59], v[168:171], v[128:131]
	v_mfma_f32_16x16x32_bf16 v[120:123], v[64:67], v[168:171], v[120:123]
	v_mfma_f32_16x16x32_bf16 v[108:111], v[56:59], v[194:197], v[108:111]
	v_mfma_f32_16x16x32_bf16 v[104:107], v[64:67], v[194:197], v[104:107]
	v_mfma_f32_16x16x32_bf16 v[92:95], v[56:59], v[202:205], v[92:95]
	v_mfma_f32_16x16x32_bf16 v[88:91], v[64:67], v[202:205], v[88:91]
	v_mfma_f32_16x16x32_bf16 v[140:143], v[60:63], v[164:167], v[140:143]
	v_mfma_f32_16x16x32_bf16 v[136:139], v[68:71], v[164:167], v[136:139]
	v_mfma_f32_16x16x32_bf16 v[128:131], v[60:63], v[172:175], v[128:131]
	v_mfma_f32_16x16x32_bf16 v[120:123], v[68:71], v[172:175], v[120:123]
	v_mfma_f32_16x16x32_bf16 v[108:111], v[60:63], v[198:201], v[108:111]
	v_mfma_f32_16x16x32_bf16 v[104:107], v[68:71], v[198:201], v[104:107]
	v_mfma_f32_16x16x32_bf16 v[92:95], v[60:63], v[206:209], v[92:95]
	v_mfma_f32_16x16x32_bf16 v[88:91], v[68:71], v[206:209], v[88:91]
	v_mfma_f32_16x16x32_bf16 v[132:135], v[144:147], v[160:163], v[132:135]
	v_mfma_f32_16x16x32_bf16 v[124:127], v[152:155], v[160:163], v[124:127]
	v_mfma_f32_16x16x32_bf16 v[116:119], v[144:147], v[168:171], v[116:119]
	v_mfma_f32_16x16x32_bf16 v[112:115], v[152:155], v[168:171], v[112:115]
	v_mfma_f32_16x16x32_bf16 v[100:103], v[144:147], v[194:197], v[100:103]
	v_mfma_f32_16x16x32_bf16 v[96:99], v[152:155], v[194:197], v[96:99]
	v_mfma_f32_16x16x32_bf16 v[84:87], v[144:147], v[202:205], v[84:87]
	v_mfma_f32_16x16x32_bf16 v[80:83], v[152:155], v[202:205], v[80:83]
	v_mfma_f32_16x16x32_bf16 v[132:135], v[148:151], v[164:167], v[132:135]
	v_mfma_f32_16x16x32_bf16 v[124:127], v[156:159], v[164:167], v[124:127]
	v_mfma_f32_16x16x32_bf16 v[116:119], v[148:151], v[172:175], v[116:119]
	v_mfma_f32_16x16x32_bf16 v[112:115], v[156:159], v[172:175], v[112:115]
	s_setprio 2
	s_barrier
	v_mfma_f32_16x16x32_bf16 v[100:103], v[148:151], v[198:201], v[100:103]
	v_mfma_f32_16x16x32_bf16 v[96:99], v[156:159], v[198:201], v[96:99]
	v_mfma_f32_16x16x32_bf16 v[84:87], v[148:151], v[206:209], v[84:87]
	v_mfma_f32_16x16x32_bf16 v[80:83], v[156:159], v[206:209], v[80:83]
	s_setprio 0
	s_add_i32 s8, s64, s37
	s_mov_b32 m0, s8
	ds_read_b128 v[160:163], v231 offset:49152
	ds_read_b128 v[164:167], v231 offset:50176
	ds_read_b128 v[168:171], v231 offset:51200
	ds_read_b128 v[172:175], v231 offset:52224
	ds_read_b128 v[194:197], v231 offset:53248
	ds_read_b128 v[198:201], v231 offset:54272
	ds_read_b128 v[202:205], v231 offset:55296
	ds_read_b128 v[206:209], v231 offset:56320
	global_load_lds_dwordx4 v184, s[98:99]
	s_add_i32 m0, s8, 0x2000
	s_add_u32 s8, s40, 0x60080
	s_addc_u32 s9, s41, 0
	s_add_i32 s40, s65, s37
	global_load_lds_dwordx4 v188, s[98:99]
	s_mov_b32 m0, s40
	s_nop 0
	global_load_lds_dwordx4 v184, s[8:9]
	s_add_i32 m0, s40, 0x2000
	s_nop 0
	global_load_lds_dwordx4 v188, s[8:9]
	s_mov_b32 m0, s69
	s_nop 0
	global_load_lds_dwordx4 v182, s[100:101]
	s_mov_b32 m0, s72
	s_nop 0
	global_load_lds_dwordx4 v186, s[100:101]
	s_waitcnt vmcnt(8) lgkmcnt(0)
	s_barrier
	s_setprio 1
	v_mfma_f32_16x16x32_bf16 v[76:79], v[56:59], v[160:163], v[76:79]
	v_mfma_f32_16x16x32_bf16 v[72:75], v[64:67], v[160:163], v[72:75]
	v_mfma_f32_16x16x32_bf16 v[44:47], v[56:59], v[168:171], v[44:47]
	v_mfma_f32_16x16x32_bf16 v[40:43], v[64:67], v[168:171], v[40:43]
	v_mfma_f32_16x16x32_bf16 v[28:31], v[56:59], v[194:197], v[28:31]
	v_mfma_f32_16x16x32_bf16 v[24:27], v[64:67], v[194:197], v[24:27]
	v_mfma_f32_16x16x32_bf16 v[12:15], v[56:59], v[202:205], v[12:15]
	v_mfma_f32_16x16x32_bf16 v[8:11], v[64:67], v[202:205], v[8:11]
	v_mfma_f32_16x16x32_bf16 v[76:79], v[60:63], v[164:167], v[76:79]
	v_mfma_f32_16x16x32_bf16 v[72:75], v[68:71], v[164:167], v[72:75]
	v_mfma_f32_16x16x32_bf16 v[44:47], v[60:63], v[172:175], v[44:47]
	v_mfma_f32_16x16x32_bf16 v[40:43], v[68:71], v[172:175], v[40:43]
	v_mfma_f32_16x16x32_bf16 v[28:31], v[60:63], v[198:201], v[28:31]
	v_mfma_f32_16x16x32_bf16 v[24:27], v[68:71], v[198:201], v[24:27]
	v_mfma_f32_16x16x32_bf16 v[12:15], v[60:63], v[206:209], v[12:15]
	v_mfma_f32_16x16x32_bf16 v[8:11], v[68:71], v[206:209], v[8:11]
	v_mfma_f32_16x16x32_bf16 v[52:55], v[144:147], v[160:163], v[52:55]
	v_mfma_f32_16x16x32_bf16 v[48:51], v[152:155], v[160:163], v[48:51]
	v_mfma_f32_16x16x32_bf16 v[36:39], v[144:147], v[168:171], v[36:39]
	v_mfma_f32_16x16x32_bf16 v[32:35], v[152:155], v[168:171], v[32:35]
	v_mfma_f32_16x16x32_bf16 v[20:23], v[144:147], v[194:197], v[20:23]
	v_mfma_f32_16x16x32_bf16 v[16:19], v[152:155], v[194:197], v[16:19]
	v_mfma_f32_16x16x32_bf16 v[4:7], v[144:147], v[202:205], v[4:7]
	v_mfma_f32_16x16x32_bf16 v[0:3], v[152:155], v[202:205], v[0:3]
	v_mfma_f32_16x16x32_bf16 v[52:55], v[148:151], v[164:167], v[52:55]
	v_mfma_f32_16x16x32_bf16 v[48:51], v[156:159], v[164:167], v[48:51]
	v_mfma_f32_16x16x32_bf16 v[36:39], v[148:151], v[172:175], v[36:39]
	v_mfma_f32_16x16x32_bf16 v[32:35], v[156:159], v[172:175], v[32:35]
	s_setprio 2
	s_barrier
	v_mfma_f32_16x16x32_bf16 v[20:23], v[148:151], v[198:201], v[20:23]
	v_mfma_f32_16x16x32_bf16 v[16:19], v[156:159], v[198:201], v[16:19]
	v_mfma_f32_16x16x32_bf16 v[4:7], v[148:151], v[206:209], v[4:7]
	v_mfma_f32_16x16x32_bf16 v[0:3], v[156:159], v[206:209], v[0:3]
	s_setprio 0
	s_add_i32 s83, s83, 2
	s_add_u32 s44, s44, 0x180
	s_addc_u32 s53, s53, 0
	s_cmp_gt_u32 s83, 13
	s_mov_b64 s[8:9], s[38:39]
	s_cbranch_scc1 .Lpeel_exit_4
.LBB0_953:
	s_add_u32 s38, s8, 0x180
	s_addc_u32 s39, s9, 0
	s_add_i32 s64, 0, 0x10000
	s_cmp_eq_u32 s83, 12
	s_cselect_b32 s51, s1, s39
	s_cselect_b32 s50, s0, s38
	s_cselect_b32 s41, s29, s53
	s_cselect_b32 s40, s28, s44
	s_add_i32 s65, 0, 0x14000
	v_add_u32_e32 v68, s64, v228
	v_add_u32_e32 v156, s65, v228
	ds_read_b128 v[56:59], v68
	ds_read_b128 v[60:63], v68 offset:1024
	ds_read_b128 v[64:67], v68 offset:2048
	ds_read_b128 v[68:71], v68 offset:3072
	ds_read_b128 v[144:147], v156
	ds_read_b128 v[148:151], v156 offset:1024
	ds_read_b128 v[152:155], v156 offset:2048
	ds_read_b128 v[156:159], v156 offset:3072
	s_add_i32 m0, s60, 0xc000
	ds_read_b128 v[160:163], v231
	ds_read_b128 v[164:167], v231 offset:1024
	ds_read_b128 v[168:171], v231 offset:2048
	ds_read_b128 v[172:175], v231 offset:3072
	ds_read_b128 v[194:197], v231 offset:4096
	ds_read_b128 v[198:201], v231 offset:5120
	ds_read_b128 v[202:205], v231 offset:6144
	ds_read_b128 v[206:209], v231 offset:7168
	global_load_lds_dwordx4 v192, s[8:9]
	s_add_i32 m0, s60, 0xe000
	s_nop 0
	global_load_lds_dwordx4 v190, s[8:9]
	s_waitcnt vmcnt(8) lgkmcnt(0)
	s_barrier
	s_setprio 1
	v_mfma_f32_16x16x32_bf16 v[140:143], v[56:59], v[160:163], v[140:143]
	v_mfma_f32_16x16x32_bf16 v[136:139], v[64:67], v[160:163], v[136:139]
	v_mfma_f32_16x16x32_bf16 v[128:131], v[56:59], v[168:171], v[128:131]
	v_mfma_f32_16x16x32_bf16 v[120:123], v[64:67], v[168:171], v[120:123]
	v_mfma_f32_16x16x32_bf16 v[108:111], v[56:59], v[194:197], v[108:111]
	v_mfma_f32_16x16x32_bf16 v[104:107], v[64:67], v[194:197], v[104:107]
	v_mfma_f32_16x16x32_bf16 v[92:95], v[56:59], v[202:205], v[92:95]
	v_mfma_f32_16x16x32_bf16 v[88:91], v[64:67], v[202:205], v[88:91]
	v_mfma_f32_16x16x32_bf16 v[140:143], v[60:63], v[164:167], v[140:143]
	v_mfma_f32_16x16x32_bf16 v[136:139], v[68:71], v[164:167], v[136:139]
	v_mfma_f32_16x16x32_bf16 v[128:131], v[60:63], v[172:175], v[128:131]
	v_mfma_f32_16x16x32_bf16 v[120:123], v[68:71], v[172:175], v[120:123]
	v_mfma_f32_16x16x32_bf16 v[108:111], v[60:63], v[198:201], v[108:111]
	v_mfma_f32_16x16x32_bf16 v[104:107], v[68:71], v[198:201], v[104:107]
	v_mfma_f32_16x16x32_bf16 v[92:95], v[60:63], v[206:209], v[92:95]
	v_mfma_f32_16x16x32_bf16 v[88:91], v[68:71], v[206:209], v[88:91]
	v_mfma_f32_16x16x32_bf16 v[132:135], v[144:147], v[160:163], v[132:135]
	v_mfma_f32_16x16x32_bf16 v[124:127], v[152:155], v[160:163], v[124:127]
	v_mfma_f32_16x16x32_bf16 v[116:119], v[144:147], v[168:171], v[116:119]
	v_mfma_f32_16x16x32_bf16 v[112:115], v[152:155], v[168:171], v[112:115]
	v_mfma_f32_16x16x32_bf16 v[100:103], v[144:147], v[194:197], v[100:103]
	v_mfma_f32_16x16x32_bf16 v[96:99], v[152:155], v[194:197], v[96:99]
	v_mfma_f32_16x16x32_bf16 v[84:87], v[144:147], v[202:205], v[84:87]
	v_mfma_f32_16x16x32_bf16 v[80:83], v[152:155], v[202:205], v[80:83]
	v_mfma_f32_16x16x32_bf16 v[132:135], v[148:151], v[164:167], v[132:135]
	v_mfma_f32_16x16x32_bf16 v[124:127], v[156:159], v[164:167], v[124:127]
	v_mfma_f32_16x16x32_bf16 v[116:119], v[148:151], v[172:175], v[116:119]
	v_mfma_f32_16x16x32_bf16 v[112:115], v[156:159], v[172:175], v[112:115]
	s_setprio 2
	s_barrier
	v_mfma_f32_16x16x32_bf16 v[100:103], v[148:151], v[198:201], v[100:103]
	v_mfma_f32_16x16x32_bf16 v[96:99], v[156:159], v[198:201], v[96:99]
	v_mfma_f32_16x16x32_bf16 v[84:87], v[148:151], v[206:209], v[84:87]
	v_mfma_f32_16x16x32_bf16 v[80:83], v[156:159], v[206:209], v[80:83]
	s_setprio 0
	s_add_i32 s8, s64, s37
	s_add_u32 s98, s40, s34
	s_addc_u32 s99, s41, s35
	s_mov_b32 m0, s8
	ds_read_b128 v[160:163], v231 offset:16384
	ds_read_b128 v[164:167], v231 offset:17408
	ds_read_b128 v[168:171], v231 offset:18432
	ds_read_b128 v[172:175], v231 offset:19456
	ds_read_b128 v[194:197], v231 offset:20480
	ds_read_b128 v[198:201], v231 offset:21504
	ds_read_b128 v[202:205], v231 offset:22528
	ds_read_b128 v[206:209], v231 offset:23552
	global_load_lds_dwordx4 v184, s[40:41]
	s_add_i32 m0, s8, 0x2000
	s_add_u32 s8, s40, 0x60000
	s_addc_u32 s9, s41, 0
	s_add_i32 s64, s65, s37
	global_load_lds_dwordx4 v188, s[40:41]
	s_mov_b32 m0, s64
	s_nop 0
	global_load_lds_dwordx4 v184, s[8:9]
	s_add_i32 m0, s64, 0x2000
	s_nop 0
	global_load_lds_dwordx4 v188, s[8:9]
	s_add_u32 s100, s50, s34
	s_addc_u32 s101, s51, s35
	s_mov_b32 m0, s60
	s_nop 0
	global_load_lds_dwordx4 v182, s[50:51]
	s_mov_b32 m0, s61
	s_nop 0
	global_load_lds_dwordx4 v186, s[50:51]
	s_waitcnt vmcnt(8) lgkmcnt(0)
	s_barrier
	s_setprio 1
	v_mfma_f32_16x16x32_bf16 v[76:79], v[56:59], v[160:163], v[76:79]
	v_mfma_f32_16x16x32_bf16 v[72:75], v[64:67], v[160:163], v[72:75]
	v_mfma_f32_16x16x32_bf16 v[44:47], v[56:59], v[168:171], v[44:47]
	v_mfma_f32_16x16x32_bf16 v[40:43], v[64:67], v[168:171], v[40:43]
	v_mfma_f32_16x16x32_bf16 v[28:31], v[56:59], v[194:197], v[28:31]
	v_mfma_f32_16x16x32_bf16 v[24:27], v[64:67], v[194:197], v[24:27]
	v_mfma_f32_16x16x32_bf16 v[12:15], v[56:59], v[202:205], v[12:15]
	v_mfma_f32_16x16x32_bf16 v[8:11], v[64:67], v[202:205], v[8:11]
	v_mfma_f32_16x16x32_bf16 v[76:79], v[60:63], v[164:167], v[76:79]
	v_mfma_f32_16x16x32_bf16 v[72:75], v[68:71], v[164:167], v[72:75]
	v_mfma_f32_16x16x32_bf16 v[44:47], v[60:63], v[172:175], v[44:47]
	v_mfma_f32_16x16x32_bf16 v[40:43], v[68:71], v[172:175], v[40:43]
	v_mfma_f32_16x16x32_bf16 v[28:31], v[60:63], v[198:201], v[28:31]
	v_mfma_f32_16x16x32_bf16 v[24:27], v[68:71], v[198:201], v[24:27]
	v_mfma_f32_16x16x32_bf16 v[12:15], v[60:63], v[206:209], v[12:15]
	v_mfma_f32_16x16x32_bf16 v[8:11], v[68:71], v[206:209], v[8:11]
	v_mfma_f32_16x16x32_bf16 v[52:55], v[144:147], v[160:163], v[52:55]
	v_mfma_f32_16x16x32_bf16 v[48:51], v[152:155], v[160:163], v[48:51]
	v_mfma_f32_16x16x32_bf16 v[36:39], v[144:147], v[168:171], v[36:39]
	v_mfma_f32_16x16x32_bf16 v[32:35], v[152:155], v[168:171], v[32:35]
	v_mfma_f32_16x16x32_bf16 v[20:23], v[144:147], v[194:197], v[20:23]
	v_mfma_f32_16x16x32_bf16 v[16:19], v[152:155], v[194:197], v[16:19]
	v_mfma_f32_16x16x32_bf16 v[4:7], v[144:147], v[202:205], v[4:7]
	v_mfma_f32_16x16x32_bf16 v[0:3], v[152:155], v[202:205], v[0:3]
	v_mfma_f32_16x16x32_bf16 v[52:55], v[148:151], v[164:167], v[52:55]
	v_mfma_f32_16x16x32_bf16 v[48:51], v[156:159], v[164:167], v[48:51]
	v_mfma_f32_16x16x32_bf16 v[36:39], v[148:151], v[172:175], v[36:39]
	v_mfma_f32_16x16x32_bf16 v[32:35], v[156:159], v[172:175], v[32:35]
	s_setprio 2
	s_barrier
	v_mfma_f32_16x16x32_bf16 v[20:23], v[148:151], v[198:201], v[20:23]
	v_mfma_f32_16x16x32_bf16 v[16:19], v[156:159], v[198:201], v[16:19]
	v_mfma_f32_16x16x32_bf16 v[4:7], v[148:151], v[206:209], v[4:7]
	v_mfma_f32_16x16x32_bf16 v[0:3], v[156:159], v[206:209], v[0:3]
	s_setprio 0
	s_add_i32 s64, 0, 0x18000
	s_add_i32 s65, 0, 0x1c000
	v_add_u32_e32 v68, s64, v228
	v_add_u32_e32 v156, s65, v228
	ds_read_b128 v[56:59], v68
	ds_read_b128 v[60:63], v68 offset:1024
	ds_read_b128 v[64:67], v68 offset:2048
	ds_read_b128 v[68:71], v68 offset:3072
	ds_read_b128 v[144:147], v156
	ds_read_b128 v[148:151], v156 offset:1024
	ds_read_b128 v[152:155], v156 offset:2048
	ds_read_b128 v[156:159], v156 offset:3072
	s_add_u32 s8, s50, 0x60000
	s_addc_u32 s9, s51, 0
	s_mov_b32 m0, s62
	ds_read_b128 v[160:163], v231 offset:32768
	ds_read_b128 v[164:167], v231 offset:33792
	ds_read_b128 v[168:171], v231 offset:34816
	ds_read_b128 v[172:175], v231 offset:35840
	ds_read_b128 v[194:197], v231 offset:36864
	ds_read_b128 v[198:201], v231 offset:37888
	ds_read_b128 v[202:205], v231 offset:38912
	ds_read_b128 v[206:209], v231 offset:39936
	global_load_lds_dwordx4 v182, s[8:9]
	s_mov_b32 m0, s63
	s_nop 0
	global_load_lds_dwordx4 v186, s[8:9]
	s_waitcnt vmcnt(8) lgkmcnt(0)
	s_barrier
	s_setprio 1
	v_mfma_f32_16x16x32_bf16 v[140:143], v[56:59], v[160:163], v[140:143]
	v_mfma_f32_16x16x32_bf16 v[136:139], v[64:67], v[160:163], v[136:139]
	v_mfma_f32_16x16x32_bf16 v[128:131], v[56:59], v[168:171], v[128:131]
	v_mfma_f32_16x16x32_bf16 v[120:123], v[64:67], v[168:171], v[120:123]
	v_mfma_f32_16x16x32_bf16 v[108:111], v[56:59], v[194:197], v[108:111]
	v_mfma_f32_16x16x32_bf16 v[104:107], v[64:67], v[194:197], v[104:107]
	v_mfma_f32_16x16x32_bf16 v[92:95], v[56:59], v[202:205], v[92:95]
	v_mfma_f32_16x16x32_bf16 v[88:91], v[64:67], v[202:205], v[88:91]
	v_mfma_f32_16x16x32_bf16 v[140:143], v[60:63], v[164:167], v[140:143]
	v_mfma_f32_16x16x32_bf16 v[136:139], v[68:71], v[164:167], v[136:139]
	v_mfma_f32_16x16x32_bf16 v[128:131], v[60:63], v[172:175], v[128:131]
	v_mfma_f32_16x16x32_bf16 v[120:123], v[68:71], v[172:175], v[120:123]
	v_mfma_f32_16x16x32_bf16 v[108:111], v[60:63], v[198:201], v[108:111]
	v_mfma_f32_16x16x32_bf16 v[104:107], v[68:71], v[198:201], v[104:107]
	v_mfma_f32_16x16x32_bf16 v[92:95], v[60:63], v[206:209], v[92:95]
	v_mfma_f32_16x16x32_bf16 v[88:91], v[68:71], v[206:209], v[88:91]
	v_mfma_f32_16x16x32_bf16 v[132:135], v[144:147], v[160:163], v[132:135]
	v_mfma_f32_16x16x32_bf16 v[124:127], v[152:155], v[160:163], v[124:127]
	v_mfma_f32_16x16x32_bf16 v[116:119], v[144:147], v[168:171], v[116:119]
	v_mfma_f32_16x16x32_bf16 v[112:115], v[152:155], v[168:171], v[112:115]
	v_mfma_f32_16x16x32_bf16 v[100:103], v[144:147], v[194:197], v[100:103]
	v_mfma_f32_16x16x32_bf16 v[96:99], v[152:155], v[194:197], v[96:99]
	v_mfma_f32_16x16x32_bf16 v[84:87], v[144:147], v[202:205], v[84:87]
	v_mfma_f32_16x16x32_bf16 v[80:83], v[152:155], v[202:205], v[80:83]
	v_mfma_f32_16x16x32_bf16 v[132:135], v[148:151], v[164:167], v[132:135]
	v_mfma_f32_16x16x32_bf16 v[124:127], v[156:159], v[164:167], v[124:127]
	v_mfma_f32_16x16x32_bf16 v[116:119], v[148:151], v[172:175], v[116:119]
	v_mfma_f32_16x16x32_bf16 v[112:115], v[156:159], v[172:175], v[112:115]
	s_setprio 2
	s_barrier
	v_mfma_f32_16x16x32_bf16 v[100:103], v[148:151], v[198:201], v[100:103]
	v_mfma_f32_16x16x32_bf16 v[96:99], v[156:159], v[198:201], v[96:99]
	v_mfma_f32_16x16x32_bf16 v[84:87], v[148:151], v[206:209], v[84:87]
	v_mfma_f32_16x16x32_bf16 v[80:83], v[156:159], v[206:209], v[80:83]
	s_setprio 0
	s_add_i32 s8, s64, s37
	s_mov_b32 m0, s8
	ds_read_b128 v[160:163], v231 offset:49152
	ds_read_b128 v[164:167], v231 offset:50176
	ds_read_b128 v[168:171], v231 offset:51200
	ds_read_b128 v[172:175], v231 offset:52224
	ds_read_b128 v[194:197], v231 offset:53248
	ds_read_b128 v[198:201], v231 offset:54272
	ds_read_b128 v[202:205], v231 offset:55296
	ds_read_b128 v[206:209], v231 offset:56320
	global_load_lds_dwordx4 v184, s[98:99]
	s_add_i32 m0, s8, 0x2000
	s_add_u32 s8, s40, 0x60080
	s_addc_u32 s9, s41, 0
	s_add_i32 s40, s65, s37
	global_load_lds_dwordx4 v188, s[98:99]
	s_mov_b32 m0, s40
	s_nop 0
	global_load_lds_dwordx4 v184, s[8:9]
	s_add_i32 m0, s40, 0x2000
	s_nop 0
	global_load_lds_dwordx4 v188, s[8:9]
	s_mov_b32 m0, s69
	s_nop 0
	global_load_lds_dwordx4 v182, s[100:101]
	s_mov_b32 m0, s72
	s_nop 0
	global_load_lds_dwordx4 v186, s[100:101]
	s_waitcnt vmcnt(8) lgkmcnt(0)
	s_barrier
	s_setprio 1
	v_mfma_f32_16x16x32_bf16 v[76:79], v[56:59], v[160:163], v[76:79]
	v_mfma_f32_16x16x32_bf16 v[72:75], v[64:67], v[160:163], v[72:75]
	v_mfma_f32_16x16x32_bf16 v[44:47], v[56:59], v[168:171], v[44:47]
	v_mfma_f32_16x16x32_bf16 v[40:43], v[64:67], v[168:171], v[40:43]
	v_mfma_f32_16x16x32_bf16 v[28:31], v[56:59], v[194:197], v[28:31]
	v_mfma_f32_16x16x32_bf16 v[24:27], v[64:67], v[194:197], v[24:27]
	v_mfma_f32_16x16x32_bf16 v[12:15], v[56:59], v[202:205], v[12:15]
	v_mfma_f32_16x16x32_bf16 v[8:11], v[64:67], v[202:205], v[8:11]
	v_mfma_f32_16x16x32_bf16 v[76:79], v[60:63], v[164:167], v[76:79]
	v_mfma_f32_16x16x32_bf16 v[72:75], v[68:71], v[164:167], v[72:75]
	v_mfma_f32_16x16x32_bf16 v[44:47], v[60:63], v[172:175], v[44:47]
	v_mfma_f32_16x16x32_bf16 v[40:43], v[68:71], v[172:175], v[40:43]
	v_mfma_f32_16x16x32_bf16 v[28:31], v[60:63], v[198:201], v[28:31]
	v_mfma_f32_16x16x32_bf16 v[24:27], v[68:71], v[198:201], v[24:27]
	v_mfma_f32_16x16x32_bf16 v[12:15], v[60:63], v[206:209], v[12:15]
	v_mfma_f32_16x16x32_bf16 v[8:11], v[68:71], v[206:209], v[8:11]
	v_mfma_f32_16x16x32_bf16 v[52:55], v[144:147], v[160:163], v[52:55]
	v_mfma_f32_16x16x32_bf16 v[48:51], v[152:155], v[160:163], v[48:51]
	v_mfma_f32_16x16x32_bf16 v[36:39], v[144:147], v[168:171], v[36:39]
	v_mfma_f32_16x16x32_bf16 v[32:35], v[152:155], v[168:171], v[32:35]
	v_mfma_f32_16x16x32_bf16 v[20:23], v[144:147], v[194:197], v[20:23]
	v_mfma_f32_16x16x32_bf16 v[16:19], v[152:155], v[194:197], v[16:19]
	v_mfma_f32_16x16x32_bf16 v[4:7], v[144:147], v[202:205], v[4:7]
	v_mfma_f32_16x16x32_bf16 v[0:3], v[152:155], v[202:205], v[0:3]
	v_mfma_f32_16x16x32_bf16 v[52:55], v[148:151], v[164:167], v[52:55]
	v_mfma_f32_16x16x32_bf16 v[48:51], v[156:159], v[164:167], v[48:51]
	v_mfma_f32_16x16x32_bf16 v[36:39], v[148:151], v[172:175], v[36:39]
	v_mfma_f32_16x16x32_bf16 v[32:35], v[156:159], v[172:175], v[32:35]
	s_setprio 2
	s_barrier
	v_mfma_f32_16x16x32_bf16 v[20:23], v[148:151], v[198:201], v[20:23]
	v_mfma_f32_16x16x32_bf16 v[16:19], v[156:159], v[198:201], v[16:19]
	v_mfma_f32_16x16x32_bf16 v[4:7], v[148:151], v[206:209], v[4:7]
	v_mfma_f32_16x16x32_bf16 v[0:3], v[156:159], v[206:209], v[0:3]
	s_setprio 0
	s_add_i32 s83, s83, 2
	s_add_u32 s44, s44, 0x180
	s_addc_u32 s53, s53, 0
	s_cmp_gt_u32 s83, 13
	s_mov_b64 s[8:9], s[38:39]
	s_cbranch_scc0 .LBB0_953

.LBB0_1045:
	s_add_i32 s25, s63, -2
	s_add_u32 s93, s38, 0x180
	s_addc_u32 s94, s39, 0
	s_mov_b32 s40, 0
	s_add_i32 s64, s40, 2
	s_add_u32 s38, s8, 0x180
	s_addc_u32 s39, s9, 0
	s_add_i32 s65, 0, 0x10000
	s_cmp_eq_u32 s25, s40
	s_cselect_b32 s51, s27, s39
	s_cselect_b32 s50, s26, s38
	s_cselect_b32 s41, s29, s94
	s_cselect_b32 s40, s28, s93
	s_add_i32 s66, 0, 0x14000
	v_add_u32_e32 v108, s65, v228
	v_add_u32_e32 v156, s66, v228
	ds_read_b128 v[88:91], v108
	ds_read_b128 v[92:95], v108 offset:1024
	ds_read_b128 v[104:107], v108 offset:2048
	ds_read_b128 v[108:111], v108 offset:3072
	ds_read_b128 v[144:147], v156
	ds_read_b128 v[148:151], v156 offset:1024
	ds_read_b128 v[152:155], v156 offset:2048
	ds_read_b128 v[156:159], v156 offset:3072
	s_add_i32 m0, s72, 0xc000
	ds_read_b128 v[160:163], v232
	ds_read_b128 v[164:167], v232 offset:1024
	ds_read_b128 v[168:171], v232 offset:2048
	ds_read_b128 v[172:175], v232 offset:3072
	ds_read_b128 v[194:197], v232 offset:4096
	ds_read_b128 v[198:201], v232 offset:5120
	ds_read_b128 v[202:205], v232 offset:6144
	ds_read_b128 v[206:209], v232 offset:7168
	global_load_lds_dwordx4 v192, s[8:9]
	s_add_i32 m0, s72, 0xe000
	s_nop 0
	global_load_lds_dwordx4 v190, s[8:9]
	s_waitcnt vmcnt(24) lgkmcnt(0)
	s_barrier
	s_setprio 1
	v_mfma_f32_16x16x32_bf16 v[140:143], v[88:91], v[160:163], 0
	v_mfma_f32_16x16x32_bf16 v[136:139], v[104:107], v[160:163], 0
	v_mfma_f32_16x16x32_bf16 v[124:127], v[88:91], v[168:171], 0
	v_mfma_f32_16x16x32_bf16 v[120:123], v[104:107], v[168:171], 0
	v_mfma_f32_16x16x32_bf16 v[100:103], v[88:91], v[194:197], 0
	v_mfma_f32_16x16x32_bf16 v[96:99], v[104:107], v[194:197], 0
	v_mfma_f32_16x16x32_bf16 v[76:79], v[88:91], v[202:205], 0
	v_mfma_f32_16x16x32_bf16 v[72:75], v[104:107], v[202:205], 0
	v_mfma_f32_16x16x32_bf16 v[140:143], v[92:95], v[164:167], v[140:143]
	v_mfma_f32_16x16x32_bf16 v[136:139], v[108:111], v[164:167], v[136:139]
	v_mfma_f32_16x16x32_bf16 v[124:127], v[92:95], v[172:175], v[124:127]
	v_mfma_f32_16x16x32_bf16 v[120:123], v[108:111], v[172:175], v[120:123]
	v_mfma_f32_16x16x32_bf16 v[100:103], v[92:95], v[198:201], v[100:103]
	v_mfma_f32_16x16x32_bf16 v[96:99], v[108:111], v[198:201], v[96:99]
	v_mfma_f32_16x16x32_bf16 v[76:79], v[92:95], v[206:209], v[76:79]
	v_mfma_f32_16x16x32_bf16 v[72:75], v[108:111], v[206:209], v[72:75]
	v_mfma_f32_16x16x32_bf16 v[132:135], v[144:147], v[160:163], 0
	v_mfma_f32_16x16x32_bf16 v[128:131], v[152:155], v[160:163], 0
	v_mfma_f32_16x16x32_bf16 v[116:119], v[144:147], v[168:171], 0
	v_mfma_f32_16x16x32_bf16 v[112:115], v[152:155], v[168:171], 0
	v_mfma_f32_16x16x32_bf16 v[84:87], v[144:147], v[194:197], 0
	v_mfma_f32_16x16x32_bf16 v[80:83], v[152:155], v[194:197], 0
	v_mfma_f32_16x16x32_bf16 v[68:71], v[144:147], v[202:205], 0
	v_mfma_f32_16x16x32_bf16 v[64:67], v[152:155], v[202:205], 0
	v_mfma_f32_16x16x32_bf16 v[132:135], v[148:151], v[164:167], v[132:135]
	v_mfma_f32_16x16x32_bf16 v[128:131], v[156:159], v[164:167], v[128:131]
	v_mfma_f32_16x16x32_bf16 v[116:119], v[148:151], v[172:175], v[116:119]
	v_mfma_f32_16x16x32_bf16 v[112:115], v[156:159], v[172:175], v[112:115]
	s_setprio 2
	s_barrier
	v_mfma_f32_16x16x32_bf16 v[84:87], v[148:151], v[198:201], v[84:87]
	v_mfma_f32_16x16x32_bf16 v[80:83], v[156:159], v[198:201], v[80:83]
	v_mfma_f32_16x16x32_bf16 v[68:71], v[148:151], v[206:209], v[68:71]
	v_mfma_f32_16x16x32_bf16 v[64:67], v[156:159], v[206:209], v[64:67]
	s_setprio 0
	s_add_i32 s8, s65, s68
	s_add_u32 s98, s40, s34
	s_addc_u32 s99, s41, s35
	s_mov_b32 m0, s8
	ds_read_b128 v[160:163], v232 offset:16384
	ds_read_b128 v[164:167], v232 offset:17408
	ds_read_b128 v[168:171], v232 offset:18432
	ds_read_b128 v[172:175], v232 offset:19456
	ds_read_b128 v[194:197], v232 offset:20480
	ds_read_b128 v[198:201], v232 offset:21504
	ds_read_b128 v[202:205], v232 offset:22528
	ds_read_b128 v[206:209], v232 offset:23552
	global_load_lds_dwordx4 v184, s[40:41]
	s_add_i32 m0, s8, 0x2000
	s_add_u32 s8, s40, 0x60000
	s_addc_u32 s9, s41, 0
	s_add_i32 s65, s66, s68
	global_load_lds_dwordx4 v188, s[40:41]
	s_mov_b32 m0, s65
	s_nop 0
	global_load_lds_dwordx4 v184, s[8:9]
	s_add_i32 m0, s65, 0x2000
	s_nop 0
	global_load_lds_dwordx4 v188, s[8:9]
	s_add_u32 s100, s50, s34
	s_addc_u32 s101, s51, s35
	s_mov_b32 m0, s72
	s_nop 0
	global_load_lds_dwordx4 v182, s[50:51]
	s_mov_b32 m0, s73
	s_nop 0
	global_load_lds_dwordx4 v186, s[50:51]
	s_waitcnt vmcnt(8) lgkmcnt(0)
	s_barrier
	s_setprio 1
	v_mfma_f32_16x16x32_bf16 v[60:63], v[88:91], v[160:163], 0
	v_mfma_f32_16x16x32_bf16 v[56:59], v[104:107], v[160:163], 0
	v_mfma_f32_16x16x32_bf16 v[44:47], v[88:91], v[168:171], 0
	v_mfma_f32_16x16x32_bf16 v[40:43], v[104:107], v[168:171], 0
	v_mfma_f32_16x16x32_bf16 v[28:31], v[88:91], v[194:197], 0
	v_mfma_f32_16x16x32_bf16 v[24:27], v[104:107], v[194:197], 0
	v_mfma_f32_16x16x32_bf16 v[12:15], v[88:91], v[202:205], 0
	v_mfma_f32_16x16x32_bf16 v[8:11], v[104:107], v[202:205], 0
	v_mfma_f32_16x16x32_bf16 v[60:63], v[92:95], v[164:167], v[60:63]
	v_mfma_f32_16x16x32_bf16 v[56:59], v[108:111], v[164:167], v[56:59]
	v_mfma_f32_16x16x32_bf16 v[44:47], v[92:95], v[172:175], v[44:47]
	v_mfma_f32_16x16x32_bf16 v[40:43], v[108:111], v[172:175], v[40:43]
	v_mfma_f32_16x16x32_bf16 v[28:31], v[92:95], v[198:201], v[28:31]
	v_mfma_f32_16x16x32_bf16 v[24:27], v[108:111], v[198:201], v[24:27]
	v_mfma_f32_16x16x32_bf16 v[12:15], v[92:95], v[206:209], v[12:15]
	v_mfma_f32_16x16x32_bf16 v[8:11], v[108:111], v[206:209], v[8:11]
	v_mfma_f32_16x16x32_bf16 v[52:55], v[144:147], v[160:163], 0
	v_mfma_f32_16x16x32_bf16 v[48:51], v[152:155], v[160:163], 0
	v_mfma_f32_16x16x32_bf16 v[36:39], v[144:147], v[168:171], 0
	v_mfma_f32_16x16x32_bf16 v[32:35], v[152:155], v[168:171], 0
	v_mfma_f32_16x16x32_bf16 v[20:23], v[144:147], v[194:197], 0
	v_mfma_f32_16x16x32_bf16 v[16:19], v[152:155], v[194:197], 0
	v_mfma_f32_16x16x32_bf16 v[4:7], v[144:147], v[202:205], 0
	v_mfma_f32_16x16x32_bf16 v[0:3], v[152:155], v[202:205], 0
	v_mfma_f32_16x16x32_bf16 v[52:55], v[148:151], v[164:167], v[52:55]
	v_mfma_f32_16x16x32_bf16 v[48:51], v[156:159], v[164:167], v[48:51]
	v_mfma_f32_16x16x32_bf16 v[36:39], v[148:151], v[172:175], v[36:39]
	v_mfma_f32_16x16x32_bf16 v[32:35], v[156:159], v[172:175], v[32:35]
	s_setprio 2
	s_barrier
	v_mfma_f32_16x16x32_bf16 v[20:23], v[148:151], v[198:201], v[20:23]
	v_mfma_f32_16x16x32_bf16 v[16:19], v[156:159], v[198:201], v[16:19]
	v_mfma_f32_16x16x32_bf16 v[4:7], v[148:151], v[206:209], v[4:7]
	v_mfma_f32_16x16x32_bf16 v[0:3], v[156:159], v[206:209], v[0:3]
	s_setprio 0
	s_add_i32 s65, 0, 0x18000
	s_add_i32 s66, 0, 0x1c000
	v_add_u32_e32 v108, s65, v228
	v_add_u32_e32 v156, s66, v228
	ds_read_b128 v[88:91], v108
	ds_read_b128 v[92:95], v108 offset:1024
	ds_read_b128 v[104:107], v108 offset:2048
	ds_read_b128 v[108:111], v108 offset:3072
	ds_read_b128 v[144:147], v156
	ds_read_b128 v[148:151], v156 offset:1024
	ds_read_b128 v[152:155], v156 offset:2048
	ds_read_b128 v[156:159], v156 offset:3072
	s_add_u32 s8, s50, 0x60000
	s_addc_u32 s9, s51, 0
	s_mov_b32 m0, s74
	ds_read_b128 v[160:163], v232 offset:32768
	ds_read_b128 v[164:167], v232 offset:33792
	ds_read_b128 v[168:171], v232 offset:34816
	ds_read_b128 v[172:175], v232 offset:35840
	ds_read_b128 v[194:197], v232 offset:36864
	ds_read_b128 v[198:201], v232 offset:37888
	ds_read_b128 v[202:205], v232 offset:38912
	ds_read_b128 v[206:209], v232 offset:39936
	global_load_lds_dwordx4 v182, s[8:9]
	s_mov_b32 m0, s75
	s_nop 0
	global_load_lds_dwordx4 v186, s[8:9]
	s_waitcnt vmcnt(8) lgkmcnt(0)
	s_barrier
	s_setprio 1
	v_mfma_f32_16x16x32_bf16 v[140:143], v[88:91], v[160:163], v[140:143]
	v_mfma_f32_16x16x32_bf16 v[136:139], v[104:107], v[160:163], v[136:139]
	v_mfma_f32_16x16x32_bf16 v[124:127], v[88:91], v[168:171], v[124:127]
	v_mfma_f32_16x16x32_bf16 v[120:123], v[104:107], v[168:171], v[120:123]
	v_mfma_f32_16x16x32_bf16 v[100:103], v[88:91], v[194:197], v[100:103]
	v_mfma_f32_16x16x32_bf16 v[96:99], v[104:107], v[194:197], v[96:99]
	v_mfma_f32_16x16x32_bf16 v[76:79], v[88:91], v[202:205], v[76:79]
	v_mfma_f32_16x16x32_bf16 v[72:75], v[104:107], v[202:205], v[72:75]
	v_mfma_f32_16x16x32_bf16 v[140:143], v[92:95], v[164:167], v[140:143]
	v_mfma_f32_16x16x32_bf16 v[136:139], v[108:111], v[164:167], v[136:139]
	v_mfma_f32_16x16x32_bf16 v[124:127], v[92:95], v[172:175], v[124:127]
	v_mfma_f32_16x16x32_bf16 v[120:123], v[108:111], v[172:175], v[120:123]
	v_mfma_f32_16x16x32_bf16 v[100:103], v[92:95], v[198:201], v[100:103]
	v_mfma_f32_16x16x32_bf16 v[96:99], v[108:111], v[198:201], v[96:99]
	v_mfma_f32_16x16x32_bf16 v[76:79], v[92:95], v[206:209], v[76:79]
	v_mfma_f32_16x16x32_bf16 v[72:75], v[108:111], v[206:209], v[72:75]
	v_mfma_f32_16x16x32_bf16 v[132:135], v[144:147], v[160:163], v[132:135]
	v_mfma_f32_16x16x32_bf16 v[128:131], v[152:155], v[160:163], v[128:131]
	v_mfma_f32_16x16x32_bf16 v[116:119], v[144:147], v[168:171], v[116:119]
	v_mfma_f32_16x16x32_bf16 v[112:115], v[152:155], v[168:171], v[112:115]
	v_mfma_f32_16x16x32_bf16 v[84:87], v[144:147], v[194:197], v[84:87]
	v_mfma_f32_16x16x32_bf16 v[80:83], v[152:155], v[194:197], v[80:83]
	v_mfma_f32_16x16x32_bf16 v[68:71], v[144:147], v[202:205], v[68:71]
	v_mfma_f32_16x16x32_bf16 v[64:67], v[152:155], v[202:205], v[64:67]
	v_mfma_f32_16x16x32_bf16 v[132:135], v[148:151], v[164:167], v[132:135]
	v_mfma_f32_16x16x32_bf16 v[128:131], v[156:159], v[164:167], v[128:131]
	v_mfma_f32_16x16x32_bf16 v[116:119], v[148:151], v[172:175], v[116:119]
	v_mfma_f32_16x16x32_bf16 v[112:115], v[156:159], v[172:175], v[112:115]
	s_setprio 2
	s_barrier
	v_mfma_f32_16x16x32_bf16 v[84:87], v[148:151], v[198:201], v[84:87]
	v_mfma_f32_16x16x32_bf16 v[80:83], v[156:159], v[198:201], v[80:83]
	v_mfma_f32_16x16x32_bf16 v[68:71], v[148:151], v[206:209], v[68:71]
	v_mfma_f32_16x16x32_bf16 v[64:67], v[156:159], v[206:209], v[64:67]
	s_setprio 0
	s_add_i32 s8, s65, s68
	s_mov_b32 m0, s8
	ds_read_b128 v[160:163], v232 offset:49152
	ds_read_b128 v[164:167], v232 offset:50176
	ds_read_b128 v[168:171], v232 offset:51200
	ds_read_b128 v[172:175], v232 offset:52224
	ds_read_b128 v[194:197], v232 offset:53248
	ds_read_b128 v[198:201], v232 offset:54272
	ds_read_b128 v[202:205], v232 offset:55296
	ds_read_b128 v[206:209], v232 offset:56320
	global_load_lds_dwordx4 v184, s[98:99]
	s_add_i32 m0, s8, 0x2000
	s_add_u32 s8, s40, 0x60080
	s_addc_u32 s9, s41, 0
	s_add_i32 s40, s66, s68
	global_load_lds_dwordx4 v188, s[98:99]
	s_mov_b32 m0, s40
	s_nop 0
	global_load_lds_dwordx4 v184, s[8:9]
	s_add_i32 m0, s40, 0x2000
	s_nop 0
	global_load_lds_dwordx4 v188, s[8:9]
	s_mov_b32 m0, s81
	s_nop 0
	global_load_lds_dwordx4 v182, s[100:101]
	s_mov_b32 m0, s82
	s_nop 0
	global_load_lds_dwordx4 v186, s[100:101]
	s_waitcnt vmcnt(8) lgkmcnt(0)
	s_barrier
	s_setprio 1
	v_mfma_f32_16x16x32_bf16 v[60:63], v[88:91], v[160:163], v[60:63]
	v_mfma_f32_16x16x32_bf16 v[56:59], v[104:107], v[160:163], v[56:59]
	v_mfma_f32_16x16x32_bf16 v[44:47], v[88:91], v[168:171], v[44:47]
	v_mfma_f32_16x16x32_bf16 v[40:43], v[104:107], v[168:171], v[40:43]
	v_mfma_f32_16x16x32_bf16 v[28:31], v[88:91], v[194:197], v[28:31]
	v_mfma_f32_16x16x32_bf16 v[24:27], v[104:107], v[194:197], v[24:27]
	v_mfma_f32_16x16x32_bf16 v[12:15], v[88:91], v[202:205], v[12:15]
	v_mfma_f32_16x16x32_bf16 v[8:11], v[104:107], v[202:205], v[8:11]
	v_mfma_f32_16x16x32_bf16 v[60:63], v[92:95], v[164:167], v[60:63]
	v_mfma_f32_16x16x32_bf16 v[56:59], v[108:111], v[164:167], v[56:59]
	v_mfma_f32_16x16x32_bf16 v[44:47], v[92:95], v[172:175], v[44:47]
	v_mfma_f32_16x16x32_bf16 v[40:43], v[108:111], v[172:175], v[40:43]
	v_mfma_f32_16x16x32_bf16 v[28:31], v[92:95], v[198:201], v[28:31]
	v_mfma_f32_16x16x32_bf16 v[24:27], v[108:111], v[198:201], v[24:27]
	v_mfma_f32_16x16x32_bf16 v[12:15], v[92:95], v[206:209], v[12:15]
	v_mfma_f32_16x16x32_bf16 v[8:11], v[108:111], v[206:209], v[8:11]
	v_mfma_f32_16x16x32_bf16 v[52:55], v[144:147], v[160:163], v[52:55]
	v_mfma_f32_16x16x32_bf16 v[48:51], v[152:155], v[160:163], v[48:51]
	v_mfma_f32_16x16x32_bf16 v[36:39], v[144:147], v[168:171], v[36:39]
	v_mfma_f32_16x16x32_bf16 v[32:35], v[152:155], v[168:171], v[32:35]
	v_mfma_f32_16x16x32_bf16 v[20:23], v[144:147], v[194:197], v[20:23]
	v_mfma_f32_16x16x32_bf16 v[16:19], v[152:155], v[194:197], v[16:19]
	v_mfma_f32_16x16x32_bf16 v[4:7], v[144:147], v[202:205], v[4:7]
	v_mfma_f32_16x16x32_bf16 v[0:3], v[152:155], v[202:205], v[0:3]
	v_mfma_f32_16x16x32_bf16 v[52:55], v[148:151], v[164:167], v[52:55]
	v_mfma_f32_16x16x32_bf16 v[48:51], v[156:159], v[164:167], v[48:51]
	v_mfma_f32_16x16x32_bf16 v[36:39], v[148:151], v[172:175], v[36:39]
	v_mfma_f32_16x16x32_bf16 v[32:35], v[156:159], v[172:175], v[32:35]
	s_setprio 2
	s_barrier
	v_mfma_f32_16x16x32_bf16 v[20:23], v[148:151], v[198:201], v[20:23]
	v_mfma_f32_16x16x32_bf16 v[16:19], v[156:159], v[198:201], v[16:19]
	v_mfma_f32_16x16x32_bf16 v[4:7], v[148:151], v[206:209], v[4:7]
	v_mfma_f32_16x16x32_bf16 v[0:3], v[156:159], v[206:209], v[0:3]
	s_setprio 0
	s_add_u32 s93, s93, 0x180
	s_addc_u32 s94, s94, 0
	s_cmp_ge_i32 s64, s63
	s_mov_b64 s[8:9], s[38:39]
	s_mov_b32 s40, s64
	s_cbranch_scc1 .Lpeel_exit_5
.LBB0_1046:
	s_add_i32 s64, s40, 2
	s_add_u32 s38, s8, 0x180
	s_addc_u32 s39, s9, 0
	s_add_i32 s65, 0, 0x10000
	s_cmp_eq_u32 s25, s40
	s_cselect_b32 s51, s27, s39
	s_cselect_b32 s50, s26, s38
	s_cselect_b32 s41, s29, s94
	s_cselect_b32 s40, s28, s93
	s_add_i32 s66, 0, 0x14000
	v_add_u32_e32 v108, s65, v228
	v_add_u32_e32 v156, s66, v228
	ds_read_b128 v[88:91], v108
	ds_read_b128 v[92:95], v108 offset:1024
	ds_read_b128 v[104:107], v108 offset:2048
	ds_read_b128 v[108:111], v108 offset:3072
	ds_read_b128 v[144:147], v156
	ds_read_b128 v[148:151], v156 offset:1024
	ds_read_b128 v[152:155], v156 offset:2048
	ds_read_b128 v[156:159], v156 offset:3072
	s_add_i32 m0, s72, 0xc000
	ds_read_b128 v[160:163], v232
	ds_read_b128 v[164:167], v232 offset:1024
	ds_read_b128 v[168:171], v232 offset:2048
	ds_read_b128 v[172:175], v232 offset:3072
	ds_read_b128 v[194:197], v232 offset:4096
	ds_read_b128 v[198:201], v232 offset:5120
	ds_read_b128 v[202:205], v232 offset:6144
	ds_read_b128 v[206:209], v232 offset:7168
	global_load_lds_dwordx4 v192, s[8:9]
	s_add_i32 m0, s72, 0xe000
	s_nop 0
	global_load_lds_dwordx4 v190, s[8:9]
	s_waitcnt vmcnt(8) lgkmcnt(0)
	s_barrier
	s_setprio 1
	v_mfma_f32_16x16x32_bf16 v[140:143], v[88:91], v[160:163], v[140:143]
	v_mfma_f32_16x16x32_bf16 v[136:139], v[104:107], v[160:163], v[136:139]
	v_mfma_f32_16x16x32_bf16 v[124:127], v[88:91], v[168:171], v[124:127]
	v_mfma_f32_16x16x32_bf16 v[120:123], v[104:107], v[168:171], v[120:123]
	v_mfma_f32_16x16x32_bf16 v[100:103], v[88:91], v[194:197], v[100:103]
	v_mfma_f32_16x16x32_bf16 v[96:99], v[104:107], v[194:197], v[96:99]
	v_mfma_f32_16x16x32_bf16 v[76:79], v[88:91], v[202:205], v[76:79]
	v_mfma_f32_16x16x32_bf16 v[72:75], v[104:107], v[202:205], v[72:75]
	v_mfma_f32_16x16x32_bf16 v[140:143], v[92:95], v[164:167], v[140:143]
	v_mfma_f32_16x16x32_bf16 v[136:139], v[108:111], v[164:167], v[136:139]
	v_mfma_f32_16x16x32_bf16 v[124:127], v[92:95], v[172:175], v[124:127]
	v_mfma_f32_16x16x32_bf16 v[120:123], v[108:111], v[172:175], v[120:123]
	v_mfma_f32_16x16x32_bf16 v[100:103], v[92:95], v[198:201], v[100:103]
	v_mfma_f32_16x16x32_bf16 v[96:99], v[108:111], v[198:201], v[96:99]
	v_mfma_f32_16x16x32_bf16 v[76:79], v[92:95], v[206:209], v[76:79]
	v_mfma_f32_16x16x32_bf16 v[72:75], v[108:111], v[206:209], v[72:75]
	v_mfma_f32_16x16x32_bf16 v[132:135], v[144:147], v[160:163], v[132:135]
	v_mfma_f32_16x16x32_bf16 v[128:131], v[152:155], v[160:163], v[128:131]
	v_mfma_f32_16x16x32_bf16 v[116:119], v[144:147], v[168:171], v[116:119]
	v_mfma_f32_16x16x32_bf16 v[112:115], v[152:155], v[168:171], v[112:115]
	v_mfma_f32_16x16x32_bf16 v[84:87], v[144:147], v[194:197], v[84:87]
	v_mfma_f32_16x16x32_bf16 v[80:83], v[152:155], v[194:197], v[80:83]
	v_mfma_f32_16x16x32_bf16 v[68:71], v[144:147], v[202:205], v[68:71]
	v_mfma_f32_16x16x32_bf16 v[64:67], v[152:155], v[202:205], v[64:67]
	v_mfma_f32_16x16x32_bf16 v[132:135], v[148:151], v[164:167], v[132:135]
	v_mfma_f32_16x16x32_bf16 v[128:131], v[156:159], v[164:167], v[128:131]
	v_mfma_f32_16x16x32_bf16 v[116:119], v[148:151], v[172:175], v[116:119]
	v_mfma_f32_16x16x32_bf16 v[112:115], v[156:159], v[172:175], v[112:115]
	s_setprio 2
	s_barrier
	v_mfma_f32_16x16x32_bf16 v[84:87], v[148:151], v[198:201], v[84:87]
	v_mfma_f32_16x16x32_bf16 v[80:83], v[156:159], v[198:201], v[80:83]
	v_mfma_f32_16x16x32_bf16 v[68:71], v[148:151], v[206:209], v[68:71]
	v_mfma_f32_16x16x32_bf16 v[64:67], v[156:159], v[206:209], v[64:67]
	s_setprio 0
	s_add_i32 s8, s65, s68
	s_add_u32 s98, s40, s34
	s_addc_u32 s99, s41, s35
	s_mov_b32 m0, s8
	ds_read_b128 v[160:163], v232 offset:16384
	ds_read_b128 v[164:167], v232 offset:17408
	ds_read_b128 v[168:171], v232 offset:18432
	ds_read_b128 v[172:175], v232 offset:19456
	ds_read_b128 v[194:197], v232 offset:20480
	ds_read_b128 v[198:201], v232 offset:21504
	ds_read_b128 v[202:205], v232 offset:22528
	ds_read_b128 v[206:209], v232 offset:23552
	global_load_lds_dwordx4 v184, s[40:41]
	s_add_i32 m0, s8, 0x2000
	s_add_u32 s8, s40, 0x60000
	s_addc_u32 s9, s41, 0
	s_add_i32 s65, s66, s68
	global_load_lds_dwordx4 v188, s[40:41]
	s_mov_b32 m0, s65
	s_nop 0
	global_load_lds_dwordx4 v184, s[8:9]
	s_add_i32 m0, s65, 0x2000
	s_nop 0
	global_load_lds_dwordx4 v188, s[8:9]
	s_add_u32 s100, s50, s34
	s_addc_u32 s101, s51, s35
	s_mov_b32 m0, s72
	s_nop 0
	global_load_lds_dwordx4 v182, s[50:51]
	s_mov_b32 m0, s73
	s_nop 0
	global_load_lds_dwordx4 v186, s[50:51]
	s_waitcnt vmcnt(8) lgkmcnt(0)
	s_barrier
	s_setprio 1
	v_mfma_f32_16x16x32_bf16 v[60:63], v[88:91], v[160:163], v[60:63]
	v_mfma_f32_16x16x32_bf16 v[56:59], v[104:107], v[160:163], v[56:59]
	v_mfma_f32_16x16x32_bf16 v[44:47], v[88:91], v[168:171], v[44:47]
	v_mfma_f32_16x16x32_bf16 v[40:43], v[104:107], v[168:171], v[40:43]
	v_mfma_f32_16x16x32_bf16 v[28:31], v[88:91], v[194:197], v[28:31]
	v_mfma_f32_16x16x32_bf16 v[24:27], v[104:107], v[194:197], v[24:27]
	v_mfma_f32_16x16x32_bf16 v[12:15], v[88:91], v[202:205], v[12:15]
	v_mfma_f32_16x16x32_bf16 v[8:11], v[104:107], v[202:205], v[8:11]
	v_mfma_f32_16x16x32_bf16 v[60:63], v[92:95], v[164:167], v[60:63]
	v_mfma_f32_16x16x32_bf16 v[56:59], v[108:111], v[164:167], v[56:59]
	v_mfma_f32_16x16x32_bf16 v[44:47], v[92:95], v[172:175], v[44:47]
	v_mfma_f32_16x16x32_bf16 v[40:43], v[108:111], v[172:175], v[40:43]
	v_mfma_f32_16x16x32_bf16 v[28:31], v[92:95], v[198:201], v[28:31]
	v_mfma_f32_16x16x32_bf16 v[24:27], v[108:111], v[198:201], v[24:27]
	v_mfma_f32_16x16x32_bf16 v[12:15], v[92:95], v[206:209], v[12:15]
	v_mfma_f32_16x16x32_bf16 v[8:11], v[108:111], v[206:209], v[8:11]
	v_mfma_f32_16x16x32_bf16 v[52:55], v[144:147], v[160:163], v[52:55]
	v_mfma_f32_16x16x32_bf16 v[48:51], v[152:155], v[160:163], v[48:51]
	v_mfma_f32_16x16x32_bf16 v[36:39], v[144:147], v[168:171], v[36:39]
	v_mfma_f32_16x16x32_bf16 v[32:35], v[152:155], v[168:171], v[32:35]
	v_mfma_f32_16x16x32_bf16 v[20:23], v[144:147], v[194:197], v[20:23]
	v_mfma_f32_16x16x32_bf16 v[16:19], v[152:155], v[194:197], v[16:19]
	v_mfma_f32_16x16x32_bf16 v[4:7], v[144:147], v[202:205], v[4:7]
	v_mfma_f32_16x16x32_bf16 v[0:3], v[152:155], v[202:205], v[0:3]
	v_mfma_f32_16x16x32_bf16 v[52:55], v[148:151], v[164:167], v[52:55]
	v_mfma_f32_16x16x32_bf16 v[48:51], v[156:159], v[164:167], v[48:51]
	v_mfma_f32_16x16x32_bf16 v[36:39], v[148:151], v[172:175], v[36:39]
	v_mfma_f32_16x16x32_bf16 v[32:35], v[156:159], v[172:175], v[32:35]
	s_setprio 2
	s_barrier
	v_mfma_f32_16x16x32_bf16 v[20:23], v[148:151], v[198:201], v[20:23]
	v_mfma_f32_16x16x32_bf16 v[16:19], v[156:159], v[198:201], v[16:19]
	v_mfma_f32_16x16x32_bf16 v[4:7], v[148:151], v[206:209], v[4:7]
	v_mfma_f32_16x16x32_bf16 v[0:3], v[156:159], v[206:209], v[0:3]
	s_setprio 0
	s_add_i32 s65, 0, 0x18000
	s_add_i32 s66, 0, 0x1c000
	v_add_u32_e32 v108, s65, v228
	v_add_u32_e32 v156, s66, v228
	ds_read_b128 v[88:91], v108
	ds_read_b128 v[92:95], v108 offset:1024
	ds_read_b128 v[104:107], v108 offset:2048
	ds_read_b128 v[108:111], v108 offset:3072
	ds_read_b128 v[144:147], v156
	ds_read_b128 v[148:151], v156 offset:1024
	ds_read_b128 v[152:155], v156 offset:2048
	ds_read_b128 v[156:159], v156 offset:3072
	s_add_u32 s8, s50, 0x60000
	s_addc_u32 s9, s51, 0
	s_mov_b32 m0, s74
	ds_read_b128 v[160:163], v232 offset:32768
	ds_read_b128 v[164:167], v232 offset:33792
	ds_read_b128 v[168:171], v232 offset:34816
	ds_read_b128 v[172:175], v232 offset:35840
	ds_read_b128 v[194:197], v232 offset:36864
	ds_read_b128 v[198:201], v232 offset:37888
	ds_read_b128 v[202:205], v232 offset:38912
	ds_read_b128 v[206:209], v232 offset:39936
	global_load_lds_dwordx4 v182, s[8:9]
	s_mov_b32 m0, s75
	s_nop 0
	global_load_lds_dwordx4 v186, s[8:9]
	s_waitcnt vmcnt(8) lgkmcnt(0)
	s_barrier
	s_setprio 1
	v_mfma_f32_16x16x32_bf16 v[140:143], v[88:91], v[160:163], v[140:143]
	v_mfma_f32_16x16x32_bf16 v[136:139], v[104:107], v[160:163], v[136:139]
	v_mfma_f32_16x16x32_bf16 v[124:127], v[88:91], v[168:171], v[124:127]
	v_mfma_f32_16x16x32_bf16 v[120:123], v[104:107], v[168:171], v[120:123]
	v_mfma_f32_16x16x32_bf16 v[100:103], v[88:91], v[194:197], v[100:103]
	v_mfma_f32_16x16x32_bf16 v[96:99], v[104:107], v[194:197], v[96:99]
	v_mfma_f32_16x16x32_bf16 v[76:79], v[88:91], v[202:205], v[76:79]
	v_mfma_f32_16x16x32_bf16 v[72:75], v[104:107], v[202:205], v[72:75]
	v_mfma_f32_16x16x32_bf16 v[140:143], v[92:95], v[164:167], v[140:143]
	v_mfma_f32_16x16x32_bf16 v[136:139], v[108:111], v[164:167], v[136:139]
	v_mfma_f32_16x16x32_bf16 v[124:127], v[92:95], v[172:175], v[124:127]
	v_mfma_f32_16x16x32_bf16 v[120:123], v[108:111], v[172:175], v[120:123]
	v_mfma_f32_16x16x32_bf16 v[100:103], v[92:95], v[198:201], v[100:103]
	v_mfma_f32_16x16x32_bf16 v[96:99], v[108:111], v[198:201], v[96:99]
	v_mfma_f32_16x16x32_bf16 v[76:79], v[92:95], v[206:209], v[76:79]
	v_mfma_f32_16x16x32_bf16 v[72:75], v[108:111], v[206:209], v[72:75]
	v_mfma_f32_16x16x32_bf16 v[132:135], v[144:147], v[160:163], v[132:135]
	v_mfma_f32_16x16x32_bf16 v[128:131], v[152:155], v[160:163], v[128:131]
	v_mfma_f32_16x16x32_bf16 v[116:119], v[144:147], v[168:171], v[116:119]
	v_mfma_f32_16x16x32_bf16 v[112:115], v[152:155], v[168:171], v[112:115]
	v_mfma_f32_16x16x32_bf16 v[84:87], v[144:147], v[194:197], v[84:87]
	v_mfma_f32_16x16x32_bf16 v[80:83], v[152:155], v[194:197], v[80:83]
	v_mfma_f32_16x16x32_bf16 v[68:71], v[144:147], v[202:205], v[68:71]
	v_mfma_f32_16x16x32_bf16 v[64:67], v[152:155], v[202:205], v[64:67]
	v_mfma_f32_16x16x32_bf16 v[132:135], v[148:151], v[164:167], v[132:135]
	v_mfma_f32_16x16x32_bf16 v[128:131], v[156:159], v[164:167], v[128:131]
	v_mfma_f32_16x16x32_bf16 v[116:119], v[148:151], v[172:175], v[116:119]
	v_mfma_f32_16x16x32_bf16 v[112:115], v[156:159], v[172:175], v[112:115]
	s_setprio 2
	s_barrier
	v_mfma_f32_16x16x32_bf16 v[84:87], v[148:151], v[198:201], v[84:87]
	v_mfma_f32_16x16x32_bf16 v[80:83], v[156:159], v[198:201], v[80:83]
	v_mfma_f32_16x16x32_bf16 v[68:71], v[148:151], v[206:209], v[68:71]
	v_mfma_f32_16x16x32_bf16 v[64:67], v[156:159], v[206:209], v[64:67]
	s_setprio 0
	s_add_i32 s8, s65, s68
	s_mov_b32 m0, s8
	ds_read_b128 v[160:163], v232 offset:49152
	ds_read_b128 v[164:167], v232 offset:50176
	ds_read_b128 v[168:171], v232 offset:51200
	ds_read_b128 v[172:175], v232 offset:52224
	ds_read_b128 v[194:197], v232 offset:53248
	ds_read_b128 v[198:201], v232 offset:54272
	ds_read_b128 v[202:205], v232 offset:55296
	ds_read_b128 v[206:209], v232 offset:56320
	global_load_lds_dwordx4 v184, s[98:99]
	s_add_i32 m0, s8, 0x2000
	s_add_u32 s8, s40, 0x60080
	s_addc_u32 s9, s41, 0
	s_add_i32 s40, s66, s68
	global_load_lds_dwordx4 v188, s[98:99]
	s_mov_b32 m0, s40
	s_nop 0
	global_load_lds_dwordx4 v184, s[8:9]
	s_add_i32 m0, s40, 0x2000
	s_nop 0
	global_load_lds_dwordx4 v188, s[8:9]
	s_mov_b32 m0, s81
	s_nop 0
	global_load_lds_dwordx4 v182, s[100:101]
	s_mov_b32 m0, s82
	s_nop 0
	global_load_lds_dwordx4 v186, s[100:101]
	s_waitcnt vmcnt(8) lgkmcnt(0)
	s_barrier
	s_setprio 1
	v_mfma_f32_16x16x32_bf16 v[60:63], v[88:91], v[160:163], v[60:63]
	v_mfma_f32_16x16x32_bf16 v[56:59], v[104:107], v[160:163], v[56:59]
	v_mfma_f32_16x16x32_bf16 v[44:47], v[88:91], v[168:171], v[44:47]
	v_mfma_f32_16x16x32_bf16 v[40:43], v[104:107], v[168:171], v[40:43]
	v_mfma_f32_16x16x32_bf16 v[28:31], v[88:91], v[194:197], v[28:31]
	v_mfma_f32_16x16x32_bf16 v[24:27], v[104:107], v[194:197], v[24:27]
	v_mfma_f32_16x16x32_bf16 v[12:15], v[88:91], v[202:205], v[12:15]
	v_mfma_f32_16x16x32_bf16 v[8:11], v[104:107], v[202:205], v[8:11]
	v_mfma_f32_16x16x32_bf16 v[60:63], v[92:95], v[164:167], v[60:63]
	v_mfma_f32_16x16x32_bf16 v[56:59], v[108:111], v[164:167], v[56:59]
	v_mfma_f32_16x16x32_bf16 v[44:47], v[92:95], v[172:175], v[44:47]
	v_mfma_f32_16x16x32_bf16 v[40:43], v[108:111], v[172:175], v[40:43]
	v_mfma_f32_16x16x32_bf16 v[28:31], v[92:95], v[198:201], v[28:31]
	v_mfma_f32_16x16x32_bf16 v[24:27], v[108:111], v[198:201], v[24:27]
	v_mfma_f32_16x16x32_bf16 v[12:15], v[92:95], v[206:209], v[12:15]
	v_mfma_f32_16x16x32_bf16 v[8:11], v[108:111], v[206:209], v[8:11]
	v_mfma_f32_16x16x32_bf16 v[52:55], v[144:147], v[160:163], v[52:55]
	v_mfma_f32_16x16x32_bf16 v[48:51], v[152:155], v[160:163], v[48:51]
	v_mfma_f32_16x16x32_bf16 v[36:39], v[144:147], v[168:171], v[36:39]
	v_mfma_f32_16x16x32_bf16 v[32:35], v[152:155], v[168:171], v[32:35]
	v_mfma_f32_16x16x32_bf16 v[20:23], v[144:147], v[194:197], v[20:23]
	v_mfma_f32_16x16x32_bf16 v[16:19], v[152:155], v[194:197], v[16:19]
	v_mfma_f32_16x16x32_bf16 v[4:7], v[144:147], v[202:205], v[4:7]
	v_mfma_f32_16x16x32_bf16 v[0:3], v[152:155], v[202:205], v[0:3]
	v_mfma_f32_16x16x32_bf16 v[52:55], v[148:151], v[164:167], v[52:55]
	v_mfma_f32_16x16x32_bf16 v[48:51], v[156:159], v[164:167], v[48:51]
	v_mfma_f32_16x16x32_bf16 v[36:39], v[148:151], v[172:175], v[36:39]
	v_mfma_f32_16x16x32_bf16 v[32:35], v[156:159], v[172:175], v[32:35]
	s_setprio 2
	s_barrier
	v_mfma_f32_16x16x32_bf16 v[20:23], v[148:151], v[198:201], v[20:23]
	v_mfma_f32_16x16x32_bf16 v[16:19], v[156:159], v[198:201], v[16:19]
	v_mfma_f32_16x16x32_bf16 v[4:7], v[148:151], v[206:209], v[4:7]
	v_mfma_f32_16x16x32_bf16 v[0:3], v[156:159], v[206:209], v[0:3]
	s_setprio 0
	s_add_u32 s93, s93, 0x180
	s_addc_u32 s94, s94, 0
	s_cmp_ge_i32 s64, s63
	s_mov_b64 s[8:9], s[38:39]
	s_mov_b32 s40, s64
	s_cbranch_scc0 .LBB0_1046

.LBB0_1131:
	s_add_u32 s42, s6, 0xfffc0080
	s_addc_u32 s43, s7, -1
	s_add_i32 s64, 0, 0x10000
	s_cmp_eq_u32 s92, 12
	s_cselect_b32 s51, s27, s43
	s_cselect_b32 s50, s41, s42
	s_cselect_b32 s43, s25, s53
	s_cselect_b32 s42, s44, s52
	s_add_i32 s66, 0, 0x14000
	v_add_u32_e32 v68, s64, v228
	v_add_u32_e32 v156, s66, v228
	ds_read_b128 v[56:59], v68
	ds_read_b128 v[60:63], v68 offset:1024
	ds_read_b128 v[64:67], v68 offset:2048
	ds_read_b128 v[68:71], v68 offset:3072
	ds_read_b128 v[144:147], v156
	ds_read_b128 v[148:151], v156 offset:1024
	ds_read_b128 v[152:155], v156 offset:2048
	ds_read_b128 v[156:159], v156 offset:3072
	v_lshl_add_u64 v[178:179], s[6:7], 0, v[192:193]
	s_add_i32 m0, s17, 0xc000
	ds_read_b128 v[160:163], v231
	ds_read_b128 v[164:167], v231 offset:1024
	ds_read_b128 v[168:171], v231 offset:2048
	ds_read_b128 v[172:175], v231 offset:3072
	ds_read_b128 v[194:197], v231 offset:4096
	ds_read_b128 v[198:201], v231 offset:5120
	ds_read_b128 v[202:205], v231 offset:6144
	ds_read_b128 v[206:209], v231 offset:7168
	global_load_lds_dwordx4 v[178:179], off
	v_lshl_add_u64 v[178:179], s[6:7], 0, v[190:191]
	s_add_i32 m0, s17, 0xe000
	s_nop 0
	global_load_lds_dwordx4 v[178:179], off
	s_waitcnt vmcnt(8) lgkmcnt(0)
	s_barrier
	s_setprio 1
	v_mfma_f32_16x16x32_bf16 v[140:143], v[56:59], v[160:163], v[140:143]
	v_mfma_f32_16x16x32_bf16 v[136:139], v[64:67], v[160:163], v[136:139]
	v_mfma_f32_16x16x32_bf16 v[128:131], v[56:59], v[168:171], v[128:131]
	v_mfma_f32_16x16x32_bf16 v[120:123], v[64:67], v[168:171], v[120:123]
	v_mfma_f32_16x16x32_bf16 v[108:111], v[56:59], v[194:197], v[108:111]
	v_mfma_f32_16x16x32_bf16 v[104:107], v[64:67], v[194:197], v[104:107]
	v_mfma_f32_16x16x32_bf16 v[92:95], v[56:59], v[202:205], v[92:95]
	v_mfma_f32_16x16x32_bf16 v[88:91], v[64:67], v[202:205], v[88:91]
	v_mfma_f32_16x16x32_bf16 v[140:143], v[60:63], v[164:167], v[140:143]
	v_mfma_f32_16x16x32_bf16 v[136:139], v[68:71], v[164:167], v[136:139]
	v_mfma_f32_16x16x32_bf16 v[128:131], v[60:63], v[172:175], v[128:131]
	v_mfma_f32_16x16x32_bf16 v[120:123], v[68:71], v[172:175], v[120:123]
	v_mfma_f32_16x16x32_bf16 v[108:111], v[60:63], v[198:201], v[108:111]
	v_mfma_f32_16x16x32_bf16 v[104:107], v[68:71], v[198:201], v[104:107]
	v_mfma_f32_16x16x32_bf16 v[92:95], v[60:63], v[206:209], v[92:95]
	v_mfma_f32_16x16x32_bf16 v[88:91], v[68:71], v[206:209], v[88:91]
	v_mfma_f32_16x16x32_bf16 v[132:135], v[144:147], v[160:163], v[132:135]
	v_mfma_f32_16x16x32_bf16 v[124:127], v[152:155], v[160:163], v[124:127]
	v_mfma_f32_16x16x32_bf16 v[116:119], v[144:147], v[168:171], v[116:119]
	v_mfma_f32_16x16x32_bf16 v[112:115], v[152:155], v[168:171], v[112:115]
	v_mfma_f32_16x16x32_bf16 v[100:103], v[144:147], v[194:197], v[100:103]
	v_mfma_f32_16x16x32_bf16 v[96:99], v[152:155], v[194:197], v[96:99]
	v_mfma_f32_16x16x32_bf16 v[84:87], v[144:147], v[202:205], v[84:87]
	v_mfma_f32_16x16x32_bf16 v[80:83], v[152:155], v[202:205], v[80:83]
	v_mfma_f32_16x16x32_bf16 v[132:135], v[148:151], v[164:167], v[132:135]
	v_mfma_f32_16x16x32_bf16 v[124:127], v[156:159], v[164:167], v[124:127]
	v_mfma_f32_16x16x32_bf16 v[116:119], v[148:151], v[172:175], v[116:119]
	v_mfma_f32_16x16x32_bf16 v[112:115], v[156:159], v[172:175], v[112:115]
	s_setprio 2
	s_barrier
	v_mfma_f32_16x16x32_bf16 v[100:103], v[148:151], v[198:201], v[100:103]
	v_mfma_f32_16x16x32_bf16 v[96:99], v[156:159], v[198:201], v[96:99]
	v_mfma_f32_16x16x32_bf16 v[84:87], v[148:151], v[206:209], v[84:87]
	v_mfma_f32_16x16x32_bf16 v[80:83], v[156:159], v[206:209], v[80:83]
	s_setprio 0
	s_add_i32 s64, s64, s68
	v_lshl_add_u64 v[178:179], s[42:43], 0, v[184:185]
	s_mov_b32 m0, s64
	ds_read_b128 v[160:163], v231 offset:16384
	ds_read_b128 v[164:167], v231 offset:17408
	ds_read_b128 v[168:171], v231 offset:18432
	ds_read_b128 v[172:175], v231 offset:19456
	ds_read_b128 v[194:197], v231 offset:20480
	ds_read_b128 v[198:201], v231 offset:21504
	ds_read_b128 v[202:205], v231 offset:22528
	ds_read_b128 v[206:209], v231 offset:23552
	global_load_lds_dwordx4 v[178:179], off
	s_add_i32 m0, s64, 0x2000
	s_add_u32 s64, s42, 0x40000
	v_lshl_add_u64 v[210:211], s[42:43], 0, v[188:189]
	s_addc_u32 s65, s43, 0
	s_add_i32 s66, s66, s68
	global_load_lds_dwordx4 v[210:211], off
	v_lshl_add_u64 v[212:213], s[64:65], 0, v[184:185]
	s_mov_b32 m0, s66
	v_lshl_add_u64 v[220:221], s[50:51], 0, v[186:187]
	global_load_lds_dwordx4 v[212:213], off
	v_lshl_add_u64 v[212:213], s[64:65], 0, v[188:189]
	s_add_i32 m0, s66, 0x2000
	s_nop 0
	global_load_lds_dwordx4 v[212:213], off
	v_lshl_add_u64 v[212:213], s[50:51], 0, v[182:183]
	s_mov_b32 m0, s17
	s_nop 0
	global_load_lds_dwordx4 v[212:213], off
	s_mov_b32 m0, s69
	s_nop 0
	global_load_lds_dwordx4 v[220:221], off
	s_waitcnt vmcnt(8) lgkmcnt(0)
	s_barrier
	s_setprio 1
	v_mfma_f32_16x16x32_bf16 v[76:79], v[56:59], v[160:163], v[76:79]
	v_mfma_f32_16x16x32_bf16 v[72:75], v[64:67], v[160:163], v[72:75]
	v_mfma_f32_16x16x32_bf16 v[44:47], v[56:59], v[168:171], v[44:47]
	v_mfma_f32_16x16x32_bf16 v[40:43], v[64:67], v[168:171], v[40:43]
	v_mfma_f32_16x16x32_bf16 v[28:31], v[56:59], v[194:197], v[28:31]
	v_mfma_f32_16x16x32_bf16 v[24:27], v[64:67], v[194:197], v[24:27]
	v_mfma_f32_16x16x32_bf16 v[12:15], v[56:59], v[202:205], v[12:15]
	v_mfma_f32_16x16x32_bf16 v[8:11], v[64:67], v[202:205], v[8:11]
	v_mfma_f32_16x16x32_bf16 v[76:79], v[60:63], v[164:167], v[76:79]
	v_mfma_f32_16x16x32_bf16 v[72:75], v[68:71], v[164:167], v[72:75]
	v_mfma_f32_16x16x32_bf16 v[44:47], v[60:63], v[172:175], v[44:47]
	v_mfma_f32_16x16x32_bf16 v[40:43], v[68:71], v[172:175], v[40:43]
	v_mfma_f32_16x16x32_bf16 v[28:31], v[60:63], v[198:201], v[28:31]
	v_mfma_f32_16x16x32_bf16 v[24:27], v[68:71], v[198:201], v[24:27]
	v_mfma_f32_16x16x32_bf16 v[12:15], v[60:63], v[206:209], v[12:15]
	v_mfma_f32_16x16x32_bf16 v[8:11], v[68:71], v[206:209], v[8:11]
	v_mfma_f32_16x16x32_bf16 v[52:55], v[144:147], v[160:163], v[52:55]
	v_mfma_f32_16x16x32_bf16 v[48:51], v[152:155], v[160:163], v[48:51]
	v_mfma_f32_16x16x32_bf16 v[36:39], v[144:147], v[168:171], v[36:39]
	v_mfma_f32_16x16x32_bf16 v[32:35], v[152:155], v[168:171], v[32:35]
	v_mfma_f32_16x16x32_bf16 v[20:23], v[144:147], v[194:197], v[20:23]
	v_mfma_f32_16x16x32_bf16 v[16:19], v[152:155], v[194:197], v[16:19]
	v_mfma_f32_16x16x32_bf16 v[4:7], v[144:147], v[202:205], v[4:7]
	v_mfma_f32_16x16x32_bf16 v[0:3], v[152:155], v[202:205], v[0:3]
	v_mfma_f32_16x16x32_bf16 v[52:55], v[148:151], v[164:167], v[52:55]
	v_mfma_f32_16x16x32_bf16 v[48:51], v[156:159], v[164:167], v[48:51]
	v_mfma_f32_16x16x32_bf16 v[36:39], v[148:151], v[172:175], v[36:39]
	v_mfma_f32_16x16x32_bf16 v[32:35], v[156:159], v[172:175], v[32:35]
	s_setprio 2
	s_barrier
	v_mfma_f32_16x16x32_bf16 v[20:23], v[148:151], v[198:201], v[20:23]
	v_mfma_f32_16x16x32_bf16 v[16:19], v[156:159], v[198:201], v[16:19]
	v_mfma_f32_16x16x32_bf16 v[4:7], v[148:151], v[206:209], v[4:7]
	v_mfma_f32_16x16x32_bf16 v[0:3], v[156:159], v[206:209], v[0:3]
	s_setprio 0
	s_add_i32 s64, 0, 0x18000
	s_add_i32 s65, 0, 0x1c000
	v_add_u32_e32 v68, s64, v228
	v_add_u32_e32 v156, s65, v228
	ds_read_b128 v[56:59], v68
	ds_read_b128 v[60:63], v68 offset:1024
	ds_read_b128 v[64:67], v68 offset:2048
	ds_read_b128 v[68:71], v68 offset:3072
	ds_read_b128 v[144:147], v156
	ds_read_b128 v[148:151], v156 offset:1024
	ds_read_b128 v[152:155], v156 offset:2048
	ds_read_b128 v[156:159], v156 offset:3072
	s_add_u32 s50, s50, 0x40000
	s_addc_u32 s51, s51, 0
	s_mov_b32 m0, s72
	v_lshl_add_u64 v[222:223], s[50:51], 0, v[182:183]
	ds_read_b128 v[160:163], v231 offset:32768
	ds_read_b128 v[164:167], v231 offset:33792
	ds_read_b128 v[168:171], v231 offset:34816
	ds_read_b128 v[172:175], v231 offset:35840
	ds_read_b128 v[194:197], v231 offset:36864
	ds_read_b128 v[198:201], v231 offset:37888
	ds_read_b128 v[202:205], v231 offset:38912
	ds_read_b128 v[206:209], v231 offset:39936
	global_load_lds_dwordx4 v[222:223], off
	v_lshl_add_u64 v[222:223], s[50:51], 0, v[186:187]
	s_mov_b32 m0, s73
	s_nop 0
	global_load_lds_dwordx4 v[222:223], off
	s_waitcnt vmcnt(8) lgkmcnt(0)
	s_barrier
	s_setprio 1
	v_mfma_f32_16x16x32_bf16 v[140:143], v[56:59], v[160:163], v[140:143]
	v_mfma_f32_16x16x32_bf16 v[136:139], v[64:67], v[160:163], v[136:139]
	v_mfma_f32_16x16x32_bf16 v[128:131], v[56:59], v[168:171], v[128:131]
	v_mfma_f32_16x16x32_bf16 v[120:123], v[64:67], v[168:171], v[120:123]
	v_mfma_f32_16x16x32_bf16 v[108:111], v[56:59], v[194:197], v[108:111]
	v_mfma_f32_16x16x32_bf16 v[104:107], v[64:67], v[194:197], v[104:107]
	v_mfma_f32_16x16x32_bf16 v[92:95], v[56:59], v[202:205], v[92:95]
	v_mfma_f32_16x16x32_bf16 v[88:91], v[64:67], v[202:205], v[88:91]
	v_mfma_f32_16x16x32_bf16 v[140:143], v[60:63], v[164:167], v[140:143]
	v_mfma_f32_16x16x32_bf16 v[136:139], v[68:71], v[164:167], v[136:139]
	v_mfma_f32_16x16x32_bf16 v[128:131], v[60:63], v[172:175], v[128:131]
	v_mfma_f32_16x16x32_bf16 v[120:123], v[68:71], v[172:175], v[120:123]
	v_mfma_f32_16x16x32_bf16 v[108:111], v[60:63], v[198:201], v[108:111]
	v_mfma_f32_16x16x32_bf16 v[104:107], v[68:71], v[198:201], v[104:107]
	v_mfma_f32_16x16x32_bf16 v[92:95], v[60:63], v[206:209], v[92:95]
	v_mfma_f32_16x16x32_bf16 v[88:91], v[68:71], v[206:209], v[88:91]
	v_mfma_f32_16x16x32_bf16 v[132:135], v[144:147], v[160:163], v[132:135]
	v_mfma_f32_16x16x32_bf16 v[124:127], v[152:155], v[160:163], v[124:127]
	v_mfma_f32_16x16x32_bf16 v[116:119], v[144:147], v[168:171], v[116:119]
	v_mfma_f32_16x16x32_bf16 v[112:115], v[152:155], v[168:171], v[112:115]
	v_mfma_f32_16x16x32_bf16 v[100:103], v[144:147], v[194:197], v[100:103]
	v_mfma_f32_16x16x32_bf16 v[96:99], v[152:155], v[194:197], v[96:99]
	v_mfma_f32_16x16x32_bf16 v[84:87], v[144:147], v[202:205], v[84:87]
	v_mfma_f32_16x16x32_bf16 v[80:83], v[152:155], v[202:205], v[80:83]
	v_mfma_f32_16x16x32_bf16 v[132:135], v[148:151], v[164:167], v[132:135]
	v_mfma_f32_16x16x32_bf16 v[124:127], v[156:159], v[164:167], v[124:127]
	v_mfma_f32_16x16x32_bf16 v[116:119], v[148:151], v[172:175], v[116:119]
	v_mfma_f32_16x16x32_bf16 v[112:115], v[156:159], v[172:175], v[112:115]
	s_setprio 2
	s_barrier
	v_mfma_f32_16x16x32_bf16 v[100:103], v[148:151], v[198:201], v[100:103]
	v_mfma_f32_16x16x32_bf16 v[96:99], v[156:159], v[198:201], v[96:99]
	v_mfma_f32_16x16x32_bf16 v[84:87], v[148:151], v[206:209], v[84:87]
	v_mfma_f32_16x16x32_bf16 v[80:83], v[156:159], v[206:209], v[80:83]
	s_setprio 0
	s_add_i32 s50, s64, s68
	v_lshl_add_u64 v[178:179], v[178:179], 0, s[34:35]
	s_mov_b32 m0, s50
	ds_read_b128 v[160:163], v231 offset:49152
	ds_read_b128 v[164:167], v231 offset:50176
	ds_read_b128 v[168:171], v231 offset:51200
	ds_read_b128 v[172:175], v231 offset:52224
	ds_read_b128 v[194:197], v231 offset:53248
	ds_read_b128 v[198:201], v231 offset:54272
	ds_read_b128 v[202:205], v231 offset:55296
	ds_read_b128 v[206:209], v231 offset:56320
	global_load_lds_dwordx4 v[178:179], off
	s_add_i32 m0, s50, 0x2000
	s_add_u32 s42, s42, 0x40080
	v_lshl_add_u64 v[178:179], v[210:211], 0, s[34:35]
	s_addc_u32 s43, s43, 0
	s_add_i32 s50, s65, s68
	global_load_lds_dwordx4 v[178:179], off
	v_lshl_add_u64 v[178:179], s[42:43], 0, v[184:185]
	s_mov_b32 m0, s50
	s_nop 0
	global_load_lds_dwordx4 v[178:179], off
	v_lshl_add_u64 v[178:179], s[42:43], 0, v[188:189]
	s_add_i32 m0, s50, 0x2000
	s_nop 0
	global_load_lds_dwordx4 v[178:179], off
	v_lshl_add_u64 v[178:179], v[212:213], 0, s[34:35]
	s_mov_b32 m0, s75
	s_nop 0
	global_load_lds_dwordx4 v[178:179], off
	v_lshl_add_u64 v[178:179], v[220:221], 0, s[34:35]
	s_mov_b32 m0, s80
	s_nop 0
	global_load_lds_dwordx4 v[178:179], off
	s_waitcnt vmcnt(8) lgkmcnt(0)
	s_barrier
	s_setprio 1
	v_mfma_f32_16x16x32_bf16 v[76:79], v[56:59], v[160:163], v[76:79]
	v_mfma_f32_16x16x32_bf16 v[72:75], v[64:67], v[160:163], v[72:75]
	v_mfma_f32_16x16x32_bf16 v[44:47], v[56:59], v[168:171], v[44:47]
	v_mfma_f32_16x16x32_bf16 v[40:43], v[64:67], v[168:171], v[40:43]
	v_mfma_f32_16x16x32_bf16 v[28:31], v[56:59], v[194:197], v[28:31]
	v_mfma_f32_16x16x32_bf16 v[24:27], v[64:67], v[194:197], v[24:27]
	v_mfma_f32_16x16x32_bf16 v[12:15], v[56:59], v[202:205], v[12:15]
	v_mfma_f32_16x16x32_bf16 v[8:11], v[64:67], v[202:205], v[8:11]
	v_mfma_f32_16x16x32_bf16 v[76:79], v[60:63], v[164:167], v[76:79]
	v_mfma_f32_16x16x32_bf16 v[72:75], v[68:71], v[164:167], v[72:75]
	v_mfma_f32_16x16x32_bf16 v[44:47], v[60:63], v[172:175], v[44:47]
	v_mfma_f32_16x16x32_bf16 v[40:43], v[68:71], v[172:175], v[40:43]
	v_mfma_f32_16x16x32_bf16 v[28:31], v[60:63], v[198:201], v[28:31]
	v_mfma_f32_16x16x32_bf16 v[24:27], v[68:71], v[198:201], v[24:27]
	v_mfma_f32_16x16x32_bf16 v[12:15], v[60:63], v[206:209], v[12:15]
	v_mfma_f32_16x16x32_bf16 v[8:11], v[68:71], v[206:209], v[8:11]
	v_mfma_f32_16x16x32_bf16 v[52:55], v[144:147], v[160:163], v[52:55]
	v_mfma_f32_16x16x32_bf16 v[48:51], v[152:155], v[160:163], v[48:51]
	v_mfma_f32_16x16x32_bf16 v[36:39], v[144:147], v[168:171], v[36:39]
	v_mfma_f32_16x16x32_bf16 v[32:35], v[152:155], v[168:171], v[32:35]
	v_mfma_f32_16x16x32_bf16 v[20:23], v[144:147], v[194:197], v[20:23]
	v_mfma_f32_16x16x32_bf16 v[16:19], v[152:155], v[194:197], v[16:19]
	v_mfma_f32_16x16x32_bf16 v[4:7], v[144:147], v[202:205], v[4:7]
	v_mfma_f32_16x16x32_bf16 v[0:3], v[152:155], v[202:205], v[0:3]
	v_mfma_f32_16x16x32_bf16 v[52:55], v[148:151], v[164:167], v[52:55]
	v_mfma_f32_16x16x32_bf16 v[48:51], v[156:159], v[164:167], v[48:51]
	v_mfma_f32_16x16x32_bf16 v[36:39], v[148:151], v[172:175], v[36:39]
	v_mfma_f32_16x16x32_bf16 v[32:35], v[156:159], v[172:175], v[32:35]
	s_setprio 2
	s_barrier
	v_mfma_f32_16x16x32_bf16 v[20:23], v[148:151], v[198:201], v[20:23]
	v_mfma_f32_16x16x32_bf16 v[16:19], v[156:159], v[198:201], v[16:19]
	v_mfma_f32_16x16x32_bf16 v[4:7], v[148:151], v[206:209], v[4:7]
	v_mfma_f32_16x16x32_bf16 v[0:3], v[156:159], v[206:209], v[0:3]
	s_setprio 0
	s_add_i32 s92, s92, 2
	s_add_u32 s52, s52, 0x100
	s_addc_u32 s53, s53, 0
	s_add_u32 s6, s6, 0x100
	s_addc_u32 s7, s7, 0
	s_cmp_gt_u32 s92, 13
	s_cbranch_scc0 .LBB0_1131
	s_and_b64 vcc, exec, s[20:21]
	s_cbranch_vccz .LBB0_1134
	s_barrier

.LBB0_1220:
	s_ashr_i32 s21, s20, 31
	s_lshl_b64 s[28:29], s[20:21], 19
	s_add_u32 s21, s54, s28
	s_addc_u32 s23, s55, s29
	s_ashr_i32 s27, s26, 31
	s_lshl_b64 s[38:39], s[26:27], 7
	s_add_u32 s28, s21, s38
	s_addc_u32 s29, s23, s39
	s_ashr_i32 s23, s22, 31
	s_lshl_b64 s[50:51], s[22:23], 19
	s_add_u32 s21, s58, s50
	s_addc_u32 s23, s59, s51
	s_add_u32 s38, s21, s38
	s_addc_u32 s39, s23, s39
	s_cmp_lt_i32 s52, 1
	s_cbranch_scc1 .LBB0_1227
	s_and_b64 s[50:51], s[24:25], exec
	s_cselect_b32 s21, s29, s43
	s_cselect_b32 s23, s28, s42
	s_cselect_b32 s27, s39, s5
	s_cselect_b32 s53, s38, s4
	s_add_i32 s63, s52, -2
	s_add_u32 s95, s4, 0x100
	s_addc_u32 vcc_lo, s5, 0
	s_add_u32 s4, s42, 0x40080
	s_addc_u32 s5, s43, 0
	s_mov_b32 s42, 0
	s_add_i32 vcc_hi, s42, 2
	s_add_u32 s43, s4, 0xfffc0080
	s_addc_u32 s50, s5, -1
	s_add_i32 s64, 0, 0x10000
	s_cmp_eq_u32 s63, s42
	s_cselect_b32 s51, s21, s50
	s_cselect_b32 s50, s23, s43
	s_cselect_b32 s43, s27, vcc_lo
	s_cselect_b32 s42, s53, s95
	s_add_i32 s66, 0, 0x14000
	v_add_u32_e32 v108, s64, v228
	v_add_u32_e32 v156, s66, v228
	ds_read_b128 v[88:91], v108
	ds_read_b128 v[92:95], v108 offset:1024
	ds_read_b128 v[104:107], v108 offset:2048
	ds_read_b128 v[108:111], v108 offset:3072
	ds_read_b128 v[144:147], v156
	ds_read_b128 v[148:151], v156 offset:1024
	ds_read_b128 v[152:155], v156 offset:2048
	ds_read_b128 v[156:159], v156 offset:3072
	s_add_i32 m0, s7, 0xc000
	ds_read_b128 v[160:163], v232
	ds_read_b128 v[164:167], v232 offset:1024
	ds_read_b128 v[168:171], v232 offset:2048
	ds_read_b128 v[172:175], v232 offset:3072
	ds_read_b128 v[194:197], v232 offset:4096
	ds_read_b128 v[198:201], v232 offset:5120
	ds_read_b128 v[202:205], v232 offset:6144
	ds_read_b128 v[206:209], v232 offset:7168
	global_load_lds_dwordx4 v192, s[4:5]
	s_add_i32 m0, s7, 0xe000
	s_nop 0
	global_load_lds_dwordx4 v190, s[4:5]
	s_waitcnt vmcnt(24) lgkmcnt(0)
	s_barrier
	s_setprio 1
	v_mfma_f32_16x16x32_bf16 v[140:143], v[88:91], v[160:163], 0
	v_mfma_f32_16x16x32_bf16 v[136:139], v[104:107], v[160:163], 0
	v_mfma_f32_16x16x32_bf16 v[124:127], v[88:91], v[168:171], 0
	v_mfma_f32_16x16x32_bf16 v[120:123], v[104:107], v[168:171], 0
	v_mfma_f32_16x16x32_bf16 v[100:103], v[88:91], v[194:197], 0
	v_mfma_f32_16x16x32_bf16 v[96:99], v[104:107], v[194:197], 0
	v_mfma_f32_16x16x32_bf16 v[76:79], v[88:91], v[202:205], 0
	v_mfma_f32_16x16x32_bf16 v[72:75], v[104:107], v[202:205], 0
	v_mfma_f32_16x16x32_bf16 v[140:143], v[92:95], v[164:167], v[140:143]
	v_mfma_f32_16x16x32_bf16 v[136:139], v[108:111], v[164:167], v[136:139]
	v_mfma_f32_16x16x32_bf16 v[124:127], v[92:95], v[172:175], v[124:127]
	v_mfma_f32_16x16x32_bf16 v[120:123], v[108:111], v[172:175], v[120:123]
	v_mfma_f32_16x16x32_bf16 v[100:103], v[92:95], v[198:201], v[100:103]
	v_mfma_f32_16x16x32_bf16 v[96:99], v[108:111], v[198:201], v[96:99]
	v_mfma_f32_16x16x32_bf16 v[76:79], v[92:95], v[206:209], v[76:79]
	v_mfma_f32_16x16x32_bf16 v[72:75], v[108:111], v[206:209], v[72:75]
	v_mfma_f32_16x16x32_bf16 v[132:135], v[144:147], v[160:163], 0
	v_mfma_f32_16x16x32_bf16 v[128:131], v[152:155], v[160:163], 0
	v_mfma_f32_16x16x32_bf16 v[116:119], v[144:147], v[168:171], 0
	v_mfma_f32_16x16x32_bf16 v[112:115], v[152:155], v[168:171], 0
	v_mfma_f32_16x16x32_bf16 v[84:87], v[144:147], v[194:197], 0
	v_mfma_f32_16x16x32_bf16 v[80:83], v[152:155], v[194:197], 0
	v_mfma_f32_16x16x32_bf16 v[68:71], v[144:147], v[202:205], 0
	v_mfma_f32_16x16x32_bf16 v[64:67], v[152:155], v[202:205], 0
	v_mfma_f32_16x16x32_bf16 v[132:135], v[148:151], v[164:167], v[132:135]
	v_mfma_f32_16x16x32_bf16 v[128:131], v[156:159], v[164:167], v[128:131]
	v_mfma_f32_16x16x32_bf16 v[116:119], v[148:151], v[172:175], v[116:119]
	v_mfma_f32_16x16x32_bf16 v[112:115], v[156:159], v[172:175], v[112:115]
	s_setprio 2
	s_barrier
	v_mfma_f32_16x16x32_bf16 v[84:87], v[148:151], v[198:201], v[84:87]
	v_mfma_f32_16x16x32_bf16 v[80:83], v[156:159], v[198:201], v[80:83]
	v_mfma_f32_16x16x32_bf16 v[68:71], v[148:151], v[206:209], v[68:71]
	v_mfma_f32_16x16x32_bf16 v[64:67], v[156:159], v[206:209], v[64:67]
	s_setprio 0
	s_add_i32 s64, s64, s72
	s_add_u32 s98, s42, s34
	s_addc_u32 s99, s43, s35
	s_mov_b32 m0, s64
	ds_read_b128 v[160:163], v232 offset:16384
	ds_read_b128 v[164:167], v232 offset:17408
	ds_read_b128 v[168:171], v232 offset:18432
	ds_read_b128 v[172:175], v232 offset:19456
	ds_read_b128 v[194:197], v232 offset:20480
	ds_read_b128 v[198:201], v232 offset:21504
	ds_read_b128 v[202:205], v232 offset:22528
	ds_read_b128 v[206:209], v232 offset:23552
	global_load_lds_dwordx4 v184, s[42:43]
	s_add_i32 m0, s64, 0x2000
	s_add_u32 s64, s42, 0x40000
	s_addc_u32 s65, s43, 0
	s_add_i32 s66, s66, s72
	global_load_lds_dwordx4 v188, s[42:43]
	s_mov_b32 m0, s66
	s_nop 0
	global_load_lds_dwordx4 v184, s[64:65]
	s_add_i32 m0, s66, 0x2000
	s_nop 0
	global_load_lds_dwordx4 v188, s[64:65]
	s_add_u32 s100, s50, s34
	s_addc_u32 s101, s51, s35
	s_mov_b32 m0, s7
	s_nop 0
	global_load_lds_dwordx4 v182, s[50:51]
	s_mov_b32 m0, s73
	s_nop 0
	global_load_lds_dwordx4 v186, s[50:51]
	s_waitcnt vmcnt(8) lgkmcnt(0)
	s_barrier
	s_setprio 1
	v_mfma_f32_16x16x32_bf16 v[60:63], v[88:91], v[160:163], 0
	v_mfma_f32_16x16x32_bf16 v[56:59], v[104:107], v[160:163], 0
	v_mfma_f32_16x16x32_bf16 v[44:47], v[88:91], v[168:171], 0
	v_mfma_f32_16x16x32_bf16 v[40:43], v[104:107], v[168:171], 0
	v_mfma_f32_16x16x32_bf16 v[28:31], v[88:91], v[194:197], 0
	v_mfma_f32_16x16x32_bf16 v[24:27], v[104:107], v[194:197], 0
	v_mfma_f32_16x16x32_bf16 v[12:15], v[88:91], v[202:205], 0
	v_mfma_f32_16x16x32_bf16 v[8:11], v[104:107], v[202:205], 0
	v_mfma_f32_16x16x32_bf16 v[60:63], v[92:95], v[164:167], v[60:63]
	v_mfma_f32_16x16x32_bf16 v[56:59], v[108:111], v[164:167], v[56:59]
	v_mfma_f32_16x16x32_bf16 v[44:47], v[92:95], v[172:175], v[44:47]
	v_mfma_f32_16x16x32_bf16 v[40:43], v[108:111], v[172:175], v[40:43]
	v_mfma_f32_16x16x32_bf16 v[28:31], v[92:95], v[198:201], v[28:31]
	v_mfma_f32_16x16x32_bf16 v[24:27], v[108:111], v[198:201], v[24:27]
	v_mfma_f32_16x16x32_bf16 v[12:15], v[92:95], v[206:209], v[12:15]
	v_mfma_f32_16x16x32_bf16 v[8:11], v[108:111], v[206:209], v[8:11]
	v_mfma_f32_16x16x32_bf16 v[52:55], v[144:147], v[160:163], 0
	v_mfma_f32_16x16x32_bf16 v[48:51], v[152:155], v[160:163], 0
	v_mfma_f32_16x16x32_bf16 v[36:39], v[144:147], v[168:171], 0
	v_mfma_f32_16x16x32_bf16 v[32:35], v[152:155], v[168:171], 0
	v_mfma_f32_16x16x32_bf16 v[20:23], v[144:147], v[194:197], 0
	v_mfma_f32_16x16x32_bf16 v[16:19], v[152:155], v[194:197], 0
	v_mfma_f32_16x16x32_bf16 v[4:7], v[144:147], v[202:205], 0
	v_mfma_f32_16x16x32_bf16 v[0:3], v[152:155], v[202:205], 0
	v_mfma_f32_16x16x32_bf16 v[52:55], v[148:151], v[164:167], v[52:55]
	v_mfma_f32_16x16x32_bf16 v[48:51], v[156:159], v[164:167], v[48:51]
	v_mfma_f32_16x16x32_bf16 v[36:39], v[148:151], v[172:175], v[36:39]
	v_mfma_f32_16x16x32_bf16 v[32:35], v[156:159], v[172:175], v[32:35]
	s_setprio 2
	s_barrier
	v_mfma_f32_16x16x32_bf16 v[20:23], v[148:151], v[198:201], v[20:23]
	v_mfma_f32_16x16x32_bf16 v[16:19], v[156:159], v[198:201], v[16:19]
	v_mfma_f32_16x16x32_bf16 v[4:7], v[148:151], v[206:209], v[4:7]
	v_mfma_f32_16x16x32_bf16 v[0:3], v[156:159], v[206:209], v[0:3]
	s_setprio 0
	s_add_i32 s64, 0, 0x18000
	s_add_i32 s65, 0, 0x1c000
	v_add_u32_e32 v108, s64, v228
	v_add_u32_e32 v156, s65, v228
	ds_read_b128 v[88:91], v108
	ds_read_b128 v[92:95], v108 offset:1024
	ds_read_b128 v[104:107], v108 offset:2048
	ds_read_b128 v[108:111], v108 offset:3072
	ds_read_b128 v[144:147], v156
	ds_read_b128 v[148:151], v156 offset:1024
	ds_read_b128 v[152:155], v156 offset:2048
	ds_read_b128 v[156:159], v156 offset:3072
	s_add_u32 s50, s50, 0x40000
	s_addc_u32 s51, s51, 0
	s_mov_b32 m0, s74
	ds_read_b128 v[160:163], v232 offset:32768
	ds_read_b128 v[164:167], v232 offset:33792
	ds_read_b128 v[168:171], v232 offset:34816
	ds_read_b128 v[172:175], v232 offset:35840
	ds_read_b128 v[194:197], v232 offset:36864
	ds_read_b128 v[198:201], v232 offset:37888
	ds_read_b128 v[202:205], v232 offset:38912
	ds_read_b128 v[206:209], v232 offset:39936
	global_load_lds_dwordx4 v182, s[50:51]
	s_mov_b32 m0, s75
	s_nop 0
	global_load_lds_dwordx4 v186, s[50:51]
	s_waitcnt vmcnt(8) lgkmcnt(0)
	s_barrier
	s_setprio 1
	v_mfma_f32_16x16x32_bf16 v[140:143], v[88:91], v[160:163], v[140:143]
	v_mfma_f32_16x16x32_bf16 v[136:139], v[104:107], v[160:163], v[136:139]
	v_mfma_f32_16x16x32_bf16 v[124:127], v[88:91], v[168:171], v[124:127]
	v_mfma_f32_16x16x32_bf16 v[120:123], v[104:107], v[168:171], v[120:123]
	v_mfma_f32_16x16x32_bf16 v[100:103], v[88:91], v[194:197], v[100:103]
	v_mfma_f32_16x16x32_bf16 v[96:99], v[104:107], v[194:197], v[96:99]
	v_mfma_f32_16x16x32_bf16 v[76:79], v[88:91], v[202:205], v[76:79]
	v_mfma_f32_16x16x32_bf16 v[72:75], v[104:107], v[202:205], v[72:75]
	v_mfma_f32_16x16x32_bf16 v[140:143], v[92:95], v[164:167], v[140:143]
	v_mfma_f32_16x16x32_bf16 v[136:139], v[108:111], v[164:167], v[136:139]
	v_mfma_f32_16x16x32_bf16 v[124:127], v[92:95], v[172:175], v[124:127]
	v_mfma_f32_16x16x32_bf16 v[120:123], v[108:111], v[172:175], v[120:123]
	v_mfma_f32_16x16x32_bf16 v[100:103], v[92:95], v[198:201], v[100:103]
	v_mfma_f32_16x16x32_bf16 v[96:99], v[108:111], v[198:201], v[96:99]
	v_mfma_f32_16x16x32_bf16 v[76:79], v[92:95], v[206:209], v[76:79]
	v_mfma_f32_16x16x32_bf16 v[72:75], v[108:111], v[206:209], v[72:75]
	v_mfma_f32_16x16x32_bf16 v[132:135], v[144:147], v[160:163], v[132:135]
	v_mfma_f32_16x16x32_bf16 v[128:131], v[152:155], v[160:163], v[128:131]
	v_mfma_f32_16x16x32_bf16 v[116:119], v[144:147], v[168:171], v[116:119]
	v_mfma_f32_16x16x32_bf16 v[112:115], v[152:155], v[168:171], v[112:115]
	v_mfma_f32_16x16x32_bf16 v[84:87], v[144:147], v[194:197], v[84:87]
	v_mfma_f32_16x16x32_bf16 v[80:83], v[152:155], v[194:197], v[80:83]
	v_mfma_f32_16x16x32_bf16 v[68:71], v[144:147], v[202:205], v[68:71]
	v_mfma_f32_16x16x32_bf16 v[64:67], v[152:155], v[202:205], v[64:67]
	v_mfma_f32_16x16x32_bf16 v[132:135], v[148:151], v[164:167], v[132:135]
	v_mfma_f32_16x16x32_bf16 v[128:131], v[156:159], v[164:167], v[128:131]
	v_mfma_f32_16x16x32_bf16 v[116:119], v[148:151], v[172:175], v[116:119]
	v_mfma_f32_16x16x32_bf16 v[112:115], v[156:159], v[172:175], v[112:115]
	s_setprio 2
	s_barrier
	v_mfma_f32_16x16x32_bf16 v[84:87], v[148:151], v[198:201], v[84:87]
	v_mfma_f32_16x16x32_bf16 v[80:83], v[156:159], v[198:201], v[80:83]
	v_mfma_f32_16x16x32_bf16 v[68:71], v[148:151], v[206:209], v[68:71]
	v_mfma_f32_16x16x32_bf16 v[64:67], v[156:159], v[206:209], v[64:67]
	s_setprio 0
	s_add_i32 s50, s64, s72
	s_mov_b32 m0, s50
	ds_read_b128 v[160:163], v232 offset:49152
	ds_read_b128 v[164:167], v232 offset:50176
	ds_read_b128 v[168:171], v232 offset:51200
	ds_read_b128 v[172:175], v232 offset:52224
	ds_read_b128 v[194:197], v232 offset:53248
	ds_read_b128 v[198:201], v232 offset:54272
	ds_read_b128 v[202:205], v232 offset:55296
	ds_read_b128 v[206:209], v232 offset:56320
	global_load_lds_dwordx4 v184, s[98:99]
	s_add_i32 m0, s50, 0x2000
	s_add_u32 s42, s42, 0x40080
	s_addc_u32 s43, s43, 0
	s_add_i32 s50, s65, s72
	global_load_lds_dwordx4 v188, s[98:99]
	s_mov_b32 m0, s50
	s_nop 0
	global_load_lds_dwordx4 v184, s[42:43]
	s_add_i32 m0, s50, 0x2000
	s_nop 0
	global_load_lds_dwordx4 v188, s[42:43]
	s_mov_b32 m0, s81
	s_nop 0
	global_load_lds_dwordx4 v182, s[100:101]
	s_mov_b32 m0, s82
	s_nop 0
	global_load_lds_dwordx4 v186, s[100:101]
	s_waitcnt vmcnt(8) lgkmcnt(0)
	s_barrier
	s_setprio 1
	v_mfma_f32_16x16x32_bf16 v[60:63], v[88:91], v[160:163], v[60:63]
	v_mfma_f32_16x16x32_bf16 v[56:59], v[104:107], v[160:163], v[56:59]
	v_mfma_f32_16x16x32_bf16 v[44:47], v[88:91], v[168:171], v[44:47]
	v_mfma_f32_16x16x32_bf16 v[40:43], v[104:107], v[168:171], v[40:43]
	v_mfma_f32_16x16x32_bf16 v[28:31], v[88:91], v[194:197], v[28:31]
	v_mfma_f32_16x16x32_bf16 v[24:27], v[104:107], v[194:197], v[24:27]
	v_mfma_f32_16x16x32_bf16 v[12:15], v[88:91], v[202:205], v[12:15]
	v_mfma_f32_16x16x32_bf16 v[8:11], v[104:107], v[202:205], v[8:11]
	v_mfma_f32_16x16x32_bf16 v[60:63], v[92:95], v[164:167], v[60:63]
	v_mfma_f32_16x16x32_bf16 v[56:59], v[108:111], v[164:167], v[56:59]
	v_mfma_f32_16x16x32_bf16 v[44:47], v[92:95], v[172:175], v[44:47]
	v_mfma_f32_16x16x32_bf16 v[40:43], v[108:111], v[172:175], v[40:43]
	v_mfma_f32_16x16x32_bf16 v[28:31], v[92:95], v[198:201], v[28:31]
	v_mfma_f32_16x16x32_bf16 v[24:27], v[108:111], v[198:201], v[24:27]
	v_mfma_f32_16x16x32_bf16 v[12:15], v[92:95], v[206:209], v[12:15]
	v_mfma_f32_16x16x32_bf16 v[8:11], v[108:111], v[206:209], v[8:11]
	v_mfma_f32_16x16x32_bf16 v[52:55], v[144:147], v[160:163], v[52:55]
	v_mfma_f32_16x16x32_bf16 v[48:51], v[152:155], v[160:163], v[48:51]
	v_mfma_f32_16x16x32_bf16 v[36:39], v[144:147], v[168:171], v[36:39]
	v_mfma_f32_16x16x32_bf16 v[32:35], v[152:155], v[168:171], v[32:35]
	v_mfma_f32_16x16x32_bf16 v[20:23], v[144:147], v[194:197], v[20:23]
	v_mfma_f32_16x16x32_bf16 v[16:19], v[152:155], v[194:197], v[16:19]
	v_mfma_f32_16x16x32_bf16 v[4:7], v[144:147], v[202:205], v[4:7]
	v_mfma_f32_16x16x32_bf16 v[0:3], v[152:155], v[202:205], v[0:3]
	v_mfma_f32_16x16x32_bf16 v[52:55], v[148:151], v[164:167], v[52:55]
	v_mfma_f32_16x16x32_bf16 v[48:51], v[156:159], v[164:167], v[48:51]
	v_mfma_f32_16x16x32_bf16 v[36:39], v[148:151], v[172:175], v[36:39]
	v_mfma_f32_16x16x32_bf16 v[32:35], v[156:159], v[172:175], v[32:35]
	s_setprio 2
	s_barrier
	v_mfma_f32_16x16x32_bf16 v[20:23], v[148:151], v[198:201], v[20:23]
	v_mfma_f32_16x16x32_bf16 v[16:19], v[156:159], v[198:201], v[16:19]
	v_mfma_f32_16x16x32_bf16 v[4:7], v[148:151], v[206:209], v[4:7]
	v_mfma_f32_16x16x32_bf16 v[0:3], v[156:159], v[206:209], v[0:3]
	s_setprio 0
	s_add_u32 s95, s95, 0x100
	s_addc_u32 vcc_lo, vcc_lo, 0
	s_add_u32 s4, s4, 0x100
	s_addc_u32 s5, s5, 0
	s_cmp_ge_i32 vcc_hi, s52
	s_mov_b32 s42, vcc_hi
	s_cbranch_scc1 .Lpeel_exit_6
.LBB0_1222:
	s_add_i32 vcc_hi, s42, 2
	s_add_u32 s43, s4, 0xfffc0080
	s_addc_u32 s50, s5, -1
	s_add_i32 s64, 0, 0x10000
	s_cmp_eq_u32 s63, s42
	s_cselect_b32 s51, s21, s50
	s_cselect_b32 s50, s23, s43
	s_cselect_b32 s43, s27, vcc_lo
	s_cselect_b32 s42, s53, s95
	s_add_i32 s66, 0, 0x14000
	v_add_u32_e32 v108, s64, v228
	v_add_u32_e32 v156, s66, v228
	ds_read_b128 v[88:91], v108
	ds_read_b128 v[92:95], v108 offset:1024
	ds_read_b128 v[104:107], v108 offset:2048
	ds_read_b128 v[108:111], v108 offset:3072
	ds_read_b128 v[144:147], v156
	ds_read_b128 v[148:151], v156 offset:1024
	ds_read_b128 v[152:155], v156 offset:2048
	ds_read_b128 v[156:159], v156 offset:3072
	s_add_i32 m0, s7, 0xc000
	ds_read_b128 v[160:163], v232
	ds_read_b128 v[164:167], v232 offset:1024
	ds_read_b128 v[168:171], v232 offset:2048
	ds_read_b128 v[172:175], v232 offset:3072
	ds_read_b128 v[194:197], v232 offset:4096
	ds_read_b128 v[198:201], v232 offset:5120
	ds_read_b128 v[202:205], v232 offset:6144
	ds_read_b128 v[206:209], v232 offset:7168
	global_load_lds_dwordx4 v192, s[4:5]
	s_add_i32 m0, s7, 0xe000
	s_nop 0
	global_load_lds_dwordx4 v190, s[4:5]
	s_waitcnt vmcnt(8) lgkmcnt(0)
	s_barrier
	s_setprio 1
	v_mfma_f32_16x16x32_bf16 v[140:143], v[88:91], v[160:163], v[140:143]
	v_mfma_f32_16x16x32_bf16 v[136:139], v[104:107], v[160:163], v[136:139]
	v_mfma_f32_16x16x32_bf16 v[124:127], v[88:91], v[168:171], v[124:127]
	v_mfma_f32_16x16x32_bf16 v[120:123], v[104:107], v[168:171], v[120:123]
	v_mfma_f32_16x16x32_bf16 v[100:103], v[88:91], v[194:197], v[100:103]
	v_mfma_f32_16x16x32_bf16 v[96:99], v[104:107], v[194:197], v[96:99]
	v_mfma_f32_16x16x32_bf16 v[76:79], v[88:91], v[202:205], v[76:79]
	v_mfma_f32_16x16x32_bf16 v[72:75], v[104:107], v[202:205], v[72:75]
	v_mfma_f32_16x16x32_bf16 v[140:143], v[92:95], v[164:167], v[140:143]
	v_mfma_f32_16x16x32_bf16 v[136:139], v[108:111], v[164:167], v[136:139]
	v_mfma_f32_16x16x32_bf16 v[124:127], v[92:95], v[172:175], v[124:127]
	v_mfma_f32_16x16x32_bf16 v[120:123], v[108:111], v[172:175], v[120:123]
	v_mfma_f32_16x16x32_bf16 v[100:103], v[92:95], v[198:201], v[100:103]
	v_mfma_f32_16x16x32_bf16 v[96:99], v[108:111], v[198:201], v[96:99]
	v_mfma_f32_16x16x32_bf16 v[76:79], v[92:95], v[206:209], v[76:79]
	v_mfma_f32_16x16x32_bf16 v[72:75], v[108:111], v[206:209], v[72:75]
	v_mfma_f32_16x16x32_bf16 v[132:135], v[144:147], v[160:163], v[132:135]
	v_mfma_f32_16x16x32_bf16 v[128:131], v[152:155], v[160:163], v[128:131]
	v_mfma_f32_16x16x32_bf16 v[116:119], v[144:147], v[168:171], v[116:119]
	v_mfma_f32_16x16x32_bf16 v[112:115], v[152:155], v[168:171], v[112:115]
	v_mfma_f32_16x16x32_bf16 v[84:87], v[144:147], v[194:197], v[84:87]
	v_mfma_f32_16x16x32_bf16 v[80:83], v[152:155], v[194:197], v[80:83]
	v_mfma_f32_16x16x32_bf16 v[68:71], v[144:147], v[202:205], v[68:71]
	v_mfma_f32_16x16x32_bf16 v[64:67], v[152:155], v[202:205], v[64:67]
	v_mfma_f32_16x16x32_bf16 v[132:135], v[148:151], v[164:167], v[132:135]
	v_mfma_f32_16x16x32_bf16 v[128:131], v[156:159], v[164:167], v[128:131]
	v_mfma_f32_16x16x32_bf16 v[116:119], v[148:151], v[172:175], v[116:119]
	v_mfma_f32_16x16x32_bf16 v[112:115], v[156:159], v[172:175], v[112:115]
	s_setprio 2
	s_barrier
	v_mfma_f32_16x16x32_bf16 v[84:87], v[148:151], v[198:201], v[84:87]
	v_mfma_f32_16x16x32_bf16 v[80:83], v[156:159], v[198:201], v[80:83]
	v_mfma_f32_16x16x32_bf16 v[68:71], v[148:151], v[206:209], v[68:71]
	v_mfma_f32_16x16x32_bf16 v[64:67], v[156:159], v[206:209], v[64:67]
	s_setprio 0
	s_add_i32 s64, s64, s72
	s_add_u32 s98, s42, s34
	s_addc_u32 s99, s43, s35
	s_mov_b32 m0, s64
	ds_read_b128 v[160:163], v232 offset:16384
	ds_read_b128 v[164:167], v232 offset:17408
	ds_read_b128 v[168:171], v232 offset:18432
	ds_read_b128 v[172:175], v232 offset:19456
	ds_read_b128 v[194:197], v232 offset:20480
	ds_read_b128 v[198:201], v232 offset:21504
	ds_read_b128 v[202:205], v232 offset:22528
	ds_read_b128 v[206:209], v232 offset:23552
	global_load_lds_dwordx4 v184, s[42:43]
	s_add_i32 m0, s64, 0x2000
	s_add_u32 s64, s42, 0x40000
	s_addc_u32 s65, s43, 0
	s_add_i32 s66, s66, s72
	global_load_lds_dwordx4 v188, s[42:43]
	s_mov_b32 m0, s66
	s_nop 0
	global_load_lds_dwordx4 v184, s[64:65]
	s_add_i32 m0, s66, 0x2000
	s_nop 0
	global_load_lds_dwordx4 v188, s[64:65]
	s_add_u32 s100, s50, s34
	s_addc_u32 s101, s51, s35
	s_mov_b32 m0, s7
	s_nop 0
	global_load_lds_dwordx4 v182, s[50:51]
	s_mov_b32 m0, s73
	s_nop 0
	global_load_lds_dwordx4 v186, s[50:51]
	s_waitcnt vmcnt(8) lgkmcnt(0)
	s_barrier
	s_setprio 1
	v_mfma_f32_16x16x32_bf16 v[60:63], v[88:91], v[160:163], v[60:63]
	v_mfma_f32_16x16x32_bf16 v[56:59], v[104:107], v[160:163], v[56:59]
	v_mfma_f32_16x16x32_bf16 v[44:47], v[88:91], v[168:171], v[44:47]
	v_mfma_f32_16x16x32_bf16 v[40:43], v[104:107], v[168:171], v[40:43]
	v_mfma_f32_16x16x32_bf16 v[28:31], v[88:91], v[194:197], v[28:31]
	v_mfma_f32_16x16x32_bf16 v[24:27], v[104:107], v[194:197], v[24:27]
	v_mfma_f32_16x16x32_bf16 v[12:15], v[88:91], v[202:205], v[12:15]
	v_mfma_f32_16x16x32_bf16 v[8:11], v[104:107], v[202:205], v[8:11]
	v_mfma_f32_16x16x32_bf16 v[60:63], v[92:95], v[164:167], v[60:63]
	v_mfma_f32_16x16x32_bf16 v[56:59], v[108:111], v[164:167], v[56:59]
	v_mfma_f32_16x16x32_bf16 v[44:47], v[92:95], v[172:175], v[44:47]
	v_mfma_f32_16x16x32_bf16 v[40:43], v[108:111], v[172:175], v[40:43]
	v_mfma_f32_16x16x32_bf16 v[28:31], v[92:95], v[198:201], v[28:31]
	v_mfma_f32_16x16x32_bf16 v[24:27], v[108:111], v[198:201], v[24:27]
	v_mfma_f32_16x16x32_bf16 v[12:15], v[92:95], v[206:209], v[12:15]
	v_mfma_f32_16x16x32_bf16 v[8:11], v[108:111], v[206:209], v[8:11]
	v_mfma_f32_16x16x32_bf16 v[52:55], v[144:147], v[160:163], v[52:55]
	v_mfma_f32_16x16x32_bf16 v[48:51], v[152:155], v[160:163], v[48:51]
	v_mfma_f32_16x16x32_bf16 v[36:39], v[144:147], v[168:171], v[36:39]
	v_mfma_f32_16x16x32_bf16 v[32:35], v[152:155], v[168:171], v[32:35]
	v_mfma_f32_16x16x32_bf16 v[20:23], v[144:147], v[194:197], v[20:23]
	v_mfma_f32_16x16x32_bf16 v[16:19], v[152:155], v[194:197], v[16:19]
	v_mfma_f32_16x16x32_bf16 v[4:7], v[144:147], v[202:205], v[4:7]
	v_mfma_f32_16x16x32_bf16 v[0:3], v[152:155], v[202:205], v[0:3]
	v_mfma_f32_16x16x32_bf16 v[52:55], v[148:151], v[164:167], v[52:55]
	v_mfma_f32_16x16x32_bf16 v[48:51], v[156:159], v[164:167], v[48:51]
	v_mfma_f32_16x16x32_bf16 v[36:39], v[148:151], v[172:175], v[36:39]
	v_mfma_f32_16x16x32_bf16 v[32:35], v[156:159], v[172:175], v[32:35]
	s_setprio 2
	s_barrier
	v_mfma_f32_16x16x32_bf16 v[20:23], v[148:151], v[198:201], v[20:23]
	v_mfma_f32_16x16x32_bf16 v[16:19], v[156:159], v[198:201], v[16:19]
	v_mfma_f32_16x16x32_bf16 v[4:7], v[148:151], v[206:209], v[4:7]
	v_mfma_f32_16x16x32_bf16 v[0:3], v[156:159], v[206:209], v[0:3]
	s_setprio 0
	s_add_i32 s64, 0, 0x18000
	s_add_i32 s65, 0, 0x1c000
	v_add_u32_e32 v108, s64, v228
	v_add_u32_e32 v156, s65, v228
	ds_read_b128 v[88:91], v108
	ds_read_b128 v[92:95], v108 offset:1024
	ds_read_b128 v[104:107], v108 offset:2048
	ds_read_b128 v[108:111], v108 offset:3072
	ds_read_b128 v[144:147], v156
	ds_read_b128 v[148:151], v156 offset:1024
	ds_read_b128 v[152:155], v156 offset:2048
	ds_read_b128 v[156:159], v156 offset:3072
	s_add_u32 s50, s50, 0x40000
	s_addc_u32 s51, s51, 0
	s_mov_b32 m0, s74
	ds_read_b128 v[160:163], v232 offset:32768
	ds_read_b128 v[164:167], v232 offset:33792
	ds_read_b128 v[168:171], v232 offset:34816
	ds_read_b128 v[172:175], v232 offset:35840
	ds_read_b128 v[194:197], v232 offset:36864
	ds_read_b128 v[198:201], v232 offset:37888
	ds_read_b128 v[202:205], v232 offset:38912
	ds_read_b128 v[206:209], v232 offset:39936
	global_load_lds_dwordx4 v182, s[50:51]
	s_mov_b32 m0, s75
	s_nop 0
	global_load_lds_dwordx4 v186, s[50:51]
	s_waitcnt vmcnt(8) lgkmcnt(0)
	s_barrier
	s_setprio 1
	v_mfma_f32_16x16x32_bf16 v[140:143], v[88:91], v[160:163], v[140:143]
	v_mfma_f32_16x16x32_bf16 v[136:139], v[104:107], v[160:163], v[136:139]
	v_mfma_f32_16x16x32_bf16 v[124:127], v[88:91], v[168:171], v[124:127]
	v_mfma_f32_16x16x32_bf16 v[120:123], v[104:107], v[168:171], v[120:123]
	v_mfma_f32_16x16x32_bf16 v[100:103], v[88:91], v[194:197], v[100:103]
	v_mfma_f32_16x16x32_bf16 v[96:99], v[104:107], v[194:197], v[96:99]
	v_mfma_f32_16x16x32_bf16 v[76:79], v[88:91], v[202:205], v[76:79]
	v_mfma_f32_16x16x32_bf16 v[72:75], v[104:107], v[202:205], v[72:75]
	v_mfma_f32_16x16x32_bf16 v[140:143], v[92:95], v[164:167], v[140:143]
	v_mfma_f32_16x16x32_bf16 v[136:139], v[108:111], v[164:167], v[136:139]
	v_mfma_f32_16x16x32_bf16 v[124:127], v[92:95], v[172:175], v[124:127]
	v_mfma_f32_16x16x32_bf16 v[120:123], v[108:111], v[172:175], v[120:123]
	v_mfma_f32_16x16x32_bf16 v[100:103], v[92:95], v[198:201], v[100:103]
	v_mfma_f32_16x16x32_bf16 v[96:99], v[108:111], v[198:201], v[96:99]
	v_mfma_f32_16x16x32_bf16 v[76:79], v[92:95], v[206:209], v[76:79]
	v_mfma_f32_16x16x32_bf16 v[72:75], v[108:111], v[206:209], v[72:75]
	v_mfma_f32_16x16x32_bf16 v[132:135], v[144:147], v[160:163], v[132:135]
	v_mfma_f32_16x16x32_bf16 v[128:131], v[152:155], v[160:163], v[128:131]
	v_mfma_f32_16x16x32_bf16 v[116:119], v[144:147], v[168:171], v[116:119]
	v_mfma_f32_16x16x32_bf16 v[112:115], v[152:155], v[168:171], v[112:115]
	v_mfma_f32_16x16x32_bf16 v[84:87], v[144:147], v[194:197], v[84:87]
	v_mfma_f32_16x16x32_bf16 v[80:83], v[152:155], v[194:197], v[80:83]
	v_mfma_f32_16x16x32_bf16 v[68:71], v[144:147], v[202:205], v[68:71]
	v_mfma_f32_16x16x32_bf16 v[64:67], v[152:155], v[202:205], v[64:67]
	v_mfma_f32_16x16x32_bf16 v[132:135], v[148:151], v[164:167], v[132:135]
	v_mfma_f32_16x16x32_bf16 v[128:131], v[156:159], v[164:167], v[128:131]
	v_mfma_f32_16x16x32_bf16 v[116:119], v[148:151], v[172:175], v[116:119]
	v_mfma_f32_16x16x32_bf16 v[112:115], v[156:159], v[172:175], v[112:115]
	s_setprio 2
	s_barrier
	v_mfma_f32_16x16x32_bf16 v[84:87], v[148:151], v[198:201], v[84:87]
	v_mfma_f32_16x16x32_bf16 v[80:83], v[156:159], v[198:201], v[80:83]
	v_mfma_f32_16x16x32_bf16 v[68:71], v[148:151], v[206:209], v[68:71]
	v_mfma_f32_16x16x32_bf16 v[64:67], v[156:159], v[206:209], v[64:67]
	s_setprio 0
	s_add_i32 s50, s64, s72
	s_mov_b32 m0, s50
	ds_read_b128 v[160:163], v232 offset:49152
	ds_read_b128 v[164:167], v232 offset:50176
	ds_read_b128 v[168:171], v232 offset:51200
	ds_read_b128 v[172:175], v232 offset:52224
	ds_read_b128 v[194:197], v232 offset:53248
	ds_read_b128 v[198:201], v232 offset:54272
	ds_read_b128 v[202:205], v232 offset:55296
	ds_read_b128 v[206:209], v232 offset:56320
	global_load_lds_dwordx4 v184, s[98:99]
	s_add_i32 m0, s50, 0x2000
	s_add_u32 s42, s42, 0x40080
	s_addc_u32 s43, s43, 0
	s_add_i32 s50, s65, s72
	global_load_lds_dwordx4 v188, s[98:99]
	s_mov_b32 m0, s50
	s_nop 0
	global_load_lds_dwordx4 v184, s[42:43]
	s_add_i32 m0, s50, 0x2000
	s_nop 0
	global_load_lds_dwordx4 v188, s[42:43]
	s_mov_b32 m0, s81
	s_nop 0
	global_load_lds_dwordx4 v182, s[100:101]
	s_mov_b32 m0, s82
	s_nop 0
	global_load_lds_dwordx4 v186, s[100:101]
	s_waitcnt vmcnt(8) lgkmcnt(0)
	s_barrier
	s_setprio 1
	v_mfma_f32_16x16x32_bf16 v[60:63], v[88:91], v[160:163], v[60:63]
	v_mfma_f32_16x16x32_bf16 v[56:59], v[104:107], v[160:163], v[56:59]
	v_mfma_f32_16x16x32_bf16 v[44:47], v[88:91], v[168:171], v[44:47]
	v_mfma_f32_16x16x32_bf16 v[40:43], v[104:107], v[168:171], v[40:43]
	v_mfma_f32_16x16x32_bf16 v[28:31], v[88:91], v[194:197], v[28:31]
	v_mfma_f32_16x16x32_bf16 v[24:27], v[104:107], v[194:197], v[24:27]
	v_mfma_f32_16x16x32_bf16 v[12:15], v[88:91], v[202:205], v[12:15]
	v_mfma_f32_16x16x32_bf16 v[8:11], v[104:107], v[202:205], v[8:11]
	v_mfma_f32_16x16x32_bf16 v[60:63], v[92:95], v[164:167], v[60:63]
	v_mfma_f32_16x16x32_bf16 v[56:59], v[108:111], v[164:167], v[56:59]
	v_mfma_f32_16x16x32_bf16 v[44:47], v[92:95], v[172:175], v[44:47]
	v_mfma_f32_16x16x32_bf16 v[40:43], v[108:111], v[172:175], v[40:43]
	v_mfma_f32_16x16x32_bf16 v[28:31], v[92:95], v[198:201], v[28:31]
	v_mfma_f32_16x16x32_bf16 v[24:27], v[108:111], v[198:201], v[24:27]
	v_mfma_f32_16x16x32_bf16 v[12:15], v[92:95], v[206:209], v[12:15]
	v_mfma_f32_16x16x32_bf16 v[8:11], v[108:111], v[206:209], v[8:11]
	v_mfma_f32_16x16x32_bf16 v[52:55], v[144:147], v[160:163], v[52:55]
	v_mfma_f32_16x16x32_bf16 v[48:51], v[152:155], v[160:163], v[48:51]
	v_mfma_f32_16x16x32_bf16 v[36:39], v[144:147], v[168:171], v[36:39]
	v_mfma_f32_16x16x32_bf16 v[32:35], v[152:155], v[168:171], v[32:35]
	v_mfma_f32_16x16x32_bf16 v[20:23], v[144:147], v[194:197], v[20:23]
	v_mfma_f32_16x16x32_bf16 v[16:19], v[152:155], v[194:197], v[16:19]
	v_mfma_f32_16x16x32_bf16 v[4:7], v[144:147], v[202:205], v[4:7]
	v_mfma_f32_16x16x32_bf16 v[0:3], v[152:155], v[202:205], v[0:3]
	v_mfma_f32_16x16x32_bf16 v[52:55], v[148:151], v[164:167], v[52:55]
	v_mfma_f32_16x16x32_bf16 v[48:51], v[156:159], v[164:167], v[48:51]
	v_mfma_f32_16x16x32_bf16 v[36:39], v[148:151], v[172:175], v[36:39]
	v_mfma_f32_16x16x32_bf16 v[32:35], v[156:159], v[172:175], v[32:35]
	s_setprio 2
	s_barrier
	v_mfma_f32_16x16x32_bf16 v[20:23], v[148:151], v[198:201], v[20:23]
	v_mfma_f32_16x16x32_bf16 v[16:19], v[156:159], v[198:201], v[16:19]
	v_mfma_f32_16x16x32_bf16 v[4:7], v[148:151], v[206:209], v[4:7]
	v_mfma_f32_16x16x32_bf16 v[0:3], v[156:159], v[206:209], v[0:3]
	s_setprio 0
	s_add_u32 s95, s95, 0x100
	s_addc_u32 vcc_lo, vcc_lo, 0
	s_add_u32 s4, s4, 0x100
	s_addc_u32 s5, s5, 0
	s_cmp_ge_i32 vcc_hi, s52
	s_mov_b32 s42, vcc_hi
	s_cbranch_scc0 .LBB0_1222
